# v68: P2/P7/P9 epilogues: dead per-element row<T guards removed (tail tile rows beyond T are already skipped)
# speedup vs baseline: 1.0101x; 1.0007x over previous
.Lrt0_f:
	v_mov_b32_e32 v172, v208
	s_nop 0
	v_ashrrev_i32_e32 v0, 1, v172
	v_and_b32_e32 v0, 0xffffff80, v0
	s_waitcnt vmcnt(7)
	v_lshrrev_b32_e32 v130, 3, v172
	v_and_b32_e32 v173, 4, v130
	v_add_u32_e32 v174, s9, v0
	s_waitcnt vmcnt(6)
	v_or_b32_e32 v136, v174, v173
	v_min_i32_e32 v0, 0x403f, v136
	v_mul_hi_i32 v130, v0, s30
	v_lshrrev_b32_e32 v131, 31, v130
	v_ashrrev_i32_e32 v130, 11, v130
	v_add_u32_e32 v130, v130, v131
	v_mad_i32_i24 v0, v130, s31, v0
	v_cmp_lt_i32_e32 vcc, 15, v0
	s_and_saveexec_b64 s[0:1], vcc
	s_xor_b64 s[0:1], exec, s[0:1]
	v_lshlrev_b32_e32 v130, 12, v130
	v_add3_u32 v130, v130, v0, -16
	v_ashrrev_i32_e32 v131, 31, v130
	v_lshlrev_b64 v[130:131], 12, v[130:131]
	v_lshl_add_u64 v[132:133], s[56:57], 0, v[130:131]
	s_andn2_saveexec_b64 s[0:1], s[0:1]
	v_lshlrev_b32_e32 v130, 10, v0
	v_ashrrev_i32_e32 v131, 31, v130
	v_lshl_add_u64 v[132:133], v[130:131], 2, s[58:59]
	s_or_b64 exec, exec, s[0:1]
	v_bfe_u32 v0, v172, 6, 2
	v_and_b32_e32 v175, 31, v172
	v_lshlrev_b32_e32 v130, 6, v0
	v_or3_b32 v130, v130, s8, v175
	v_ashrrev_i32_e32 v131, 31, v130
	v_lshl_add_u64 v[132:133], v[130:131], 2, v[132:133]
	global_load_dword v176, v[132:133], off
	global_load_dword v177, v[132:133], off offset:128
	v_or_b32_e32 v166, 1, v136
	v_min_i32_e32 v132, 0x403f, v166
	v_mul_hi_i32 v133, v132, s30
	v_lshrrev_b32_e32 v134, 31, v133
	v_ashrrev_i32_e32 v133, 11, v133
	v_add_u32_e32 v135, v133, v134
	v_mad_i32_i24 v134, v135, s31, v132
	v_cmp_lt_i32_e32 vcc, 15, v134
	s_and_saveexec_b64 s[0:1], vcc
	s_xor_b64 s[0:1], exec, s[0:1]
	v_lshlrev_b32_e32 v132, 12, v135
	v_add3_u32 v132, v132, v134, -16
	v_ashrrev_i32_e32 v133, 31, v132
	v_lshlrev_b64 v[132:133], 12, v[132:133]
	v_lshl_add_u64 v[132:133], s[56:57], 0, v[132:133]
	s_andn2_saveexec_b64 s[0:1], s[0:1]
	v_lshlrev_b32_e32 v132, 10, v134
	v_ashrrev_i32_e32 v133, 31, v132
	v_lshl_add_u64 v[132:133], v[132:133], 2, s[58:59]
	s_or_b64 exec, exec, s[0:1]
	v_lshl_add_u64 v[132:133], v[130:131], 2, v[132:133]
	global_load_dword v181, v[132:133], off
	global_load_dword v182, v[132:133], off offset:128
	v_or_b32_e32 v164, 2, v136
	v_min_i32_e32 v132, 0x403f, v164
	v_mul_hi_i32 v133, v132, s30
	v_lshrrev_b32_e32 v134, 31, v133
	v_ashrrev_i32_e32 v133, 11, v133
	v_add_u32_e32 v135, v133, v134
	v_mad_i32_i24 v134, v135, s31, v132
	v_cmp_lt_i32_e32 vcc, 15, v134
	s_and_saveexec_b64 s[0:1], vcc
	s_xor_b64 s[0:1], exec, s[0:1]
	v_lshlrev_b32_e32 v132, 12, v135
	v_add3_u32 v132, v132, v134, -16
	v_ashrrev_i32_e32 v133, 31, v132
	v_lshlrev_b64 v[132:133], 12, v[132:133]
	v_lshl_add_u64 v[132:133], s[56:57], 0, v[132:133]
	s_andn2_saveexec_b64 s[0:1], s[0:1]
	v_lshlrev_b32_e32 v132, 10, v134
	v_ashrrev_i32_e32 v133, 31, v132
	v_lshl_add_u64 v[132:133], v[132:133], 2, s[58:59]
	s_or_b64 exec, exec, s[0:1]
	v_lshl_add_u64 v[132:133], v[130:131], 2, v[132:133]
	global_load_dword v183, v[132:133], off
	global_load_dword v184, v[132:133], off offset:128
	v_or_b32_e32 v162, 3, v136
	v_min_i32_e32 v132, 0x403f, v162
	v_mul_hi_i32 v133, v132, s30
	v_lshrrev_b32_e32 v134, 31, v133
	v_ashrrev_i32_e32 v133, 11, v133
	v_add_u32_e32 v135, v133, v134
	v_mad_i32_i24 v134, v135, s31, v132
	v_cmp_lt_i32_e32 vcc, 15, v134
	s_and_saveexec_b64 s[0:1], vcc
	s_xor_b64 s[0:1], exec, s[0:1]
	v_lshlrev_b32_e32 v132, 12, v135
	v_add3_u32 v132, v132, v134, -16
	v_ashrrev_i32_e32 v133, 31, v132
	v_lshlrev_b64 v[132:133], 12, v[132:133]
	v_lshl_add_u64 v[132:133], s[56:57], 0, v[132:133]
	s_andn2_saveexec_b64 s[0:1], s[0:1]
	v_lshlrev_b32_e32 v132, 10, v134
	v_ashrrev_i32_e32 v133, 31, v132
	v_lshl_add_u64 v[132:133], v[132:133], 2, s[58:59]
	s_or_b64 exec, exec, s[0:1]
	v_lshl_add_u64 v[132:133], v[130:131], 2, v[132:133]
	global_load_dword v185, v[132:133], off
	global_load_dword v186, v[132:133], off offset:128
	s_waitcnt vmcnt(13)
	v_or_b32_e32 v160, 8, v136
	v_min_i32_e32 v132, 0x403f, v160
	v_mul_hi_i32 v133, v132, s30
	v_lshrrev_b32_e32 v134, 31, v133
	v_ashrrev_i32_e32 v133, 11, v133
	v_add_u32_e32 v135, v133, v134
	v_mad_i32_i24 v134, v135, s31, v132
	v_cmp_lt_i32_e32 vcc, 15, v134
	s_and_saveexec_b64 s[0:1], vcc
	s_xor_b64 s[0:1], exec, s[0:1]
	v_lshlrev_b32_e32 v132, 12, v135
	v_add3_u32 v132, v132, v134, -16
	v_ashrrev_i32_e32 v133, 31, v132
	v_lshlrev_b64 v[132:133], 12, v[132:133]
	v_lshl_add_u64 v[132:133], s[56:57], 0, v[132:133]
	s_andn2_saveexec_b64 s[0:1], s[0:1]
	v_lshlrev_b32_e32 v132, 10, v134
	v_ashrrev_i32_e32 v133, 31, v132
	v_lshl_add_u64 v[132:133], v[132:133], 2, s[58:59]
	s_or_b64 exec, exec, s[0:1]
	v_lshl_add_u64 v[132:133], v[130:131], 2, v[132:133]
	global_load_dword v187, v[132:133], off
	global_load_dword v188, v[132:133], off offset:128
	v_or_b32_e32 v158, 9, v136
	v_min_i32_e32 v132, 0x403f, v158
	v_mul_hi_i32 v133, v132, s30
	v_lshrrev_b32_e32 v134, 31, v133
	v_ashrrev_i32_e32 v133, 11, v133
	v_add_u32_e32 v135, v133, v134
	v_mad_i32_i24 v134, v135, s31, v132
	v_cmp_lt_i32_e32 vcc, 15, v134
	s_and_saveexec_b64 s[0:1], vcc
	s_xor_b64 s[0:1], exec, s[0:1]
	v_lshlrev_b32_e32 v132, 12, v135
	v_add3_u32 v132, v132, v134, -16
	v_ashrrev_i32_e32 v133, 31, v132
	v_lshlrev_b64 v[132:133], 12, v[132:133]
	v_lshl_add_u64 v[132:133], s[56:57], 0, v[132:133]
	s_andn2_saveexec_b64 s[0:1], s[0:1]
	v_lshlrev_b32_e32 v132, 10, v134
	v_ashrrev_i32_e32 v133, 31, v132
	v_lshl_add_u64 v[132:133], v[132:133], 2, s[58:59]
	s_or_b64 exec, exec, s[0:1]
	v_lshl_add_u64 v[132:133], v[130:131], 2, v[132:133]
	global_load_dword v189, v[132:133], off
	global_load_dword v190, v[132:133], off offset:128
	s_waitcnt vmcnt(12)
	v_or_b32_e32 v156, 10, v136
	v_min_i32_e32 v132, 0x403f, v156
	v_mul_hi_i32 v133, v132, s30
	v_lshrrev_b32_e32 v134, 31, v133
	v_ashrrev_i32_e32 v133, 11, v133
	v_add_u32_e32 v135, v133, v134
	v_mad_i32_i24 v134, v135, s31, v132
	v_cmp_lt_i32_e32 vcc, 15, v134
	s_and_saveexec_b64 s[0:1], vcc
	s_xor_b64 s[0:1], exec, s[0:1]
	v_lshlrev_b32_e32 v132, 12, v135
	v_add3_u32 v132, v132, v134, -16
	v_ashrrev_i32_e32 v133, 31, v132
	v_lshlrev_b64 v[132:133], 12, v[132:133]
	v_lshl_add_u64 v[132:133], s[56:57], 0, v[132:133]
	s_andn2_saveexec_b64 s[0:1], s[0:1]
	v_lshlrev_b32_e32 v132, 10, v134
	v_ashrrev_i32_e32 v133, 31, v132
	v_lshl_add_u64 v[132:133], v[132:133], 2, s[58:59]
	s_or_b64 exec, exec, s[0:1]
	v_lshl_add_u64 v[132:133], v[130:131], 2, v[132:133]
	global_load_dword v191, v[132:133], off
	global_load_dword v192, v[132:133], off offset:128
	v_or_b32_e32 v154, 11, v136
	v_min_i32_e32 v132, 0x403f, v154
	v_mul_hi_i32 v133, v132, s30
	v_lshrrev_b32_e32 v134, 31, v133
	v_ashrrev_i32_e32 v133, 11, v133
	v_add_u32_e32 v135, v133, v134
	v_mad_i32_i24 v134, v135, s31, v132
	v_cmp_lt_i32_e32 vcc, 15, v134
	s_and_saveexec_b64 s[0:1], vcc
	s_xor_b64 s[0:1], exec, s[0:1]
	v_lshlrev_b32_e32 v132, 12, v135
	v_add3_u32 v132, v132, v134, -16
	v_ashrrev_i32_e32 v133, 31, v132
	v_lshlrev_b64 v[132:133], 12, v[132:133]
	v_lshl_add_u64 v[132:133], s[56:57], 0, v[132:133]
	s_andn2_saveexec_b64 s[0:1], s[0:1]
	v_lshlrev_b32_e32 v132, 10, v134
	v_ashrrev_i32_e32 v133, 31, v132
	v_lshl_add_u64 v[132:133], v[132:133], 2, s[58:59]
	s_or_b64 exec, exec, s[0:1]
	v_lshl_add_u64 v[132:133], v[130:131], 2, v[132:133]
	global_load_dword v193, v[132:133], off
	global_load_dword v194, v[132:133], off offset:128
	v_or_b32_e32 v152, 16, v136
	v_min_i32_e32 v132, 0x403f, v152
	v_mul_hi_i32 v133, v132, s30
	v_lshrrev_b32_e32 v134, 31, v133
	v_ashrrev_i32_e32 v133, 11, v133
	v_add_u32_e32 v135, v133, v134
	v_mad_i32_i24 v134, v135, s31, v132
	v_cmp_lt_i32_e32 vcc, 15, v134
	s_and_saveexec_b64 s[0:1], vcc
	s_xor_b64 s[0:1], exec, s[0:1]
	v_lshlrev_b32_e32 v132, 12, v135
	v_add3_u32 v132, v132, v134, -16
	v_ashrrev_i32_e32 v133, 31, v132
	v_lshlrev_b64 v[132:133], 12, v[132:133]
	v_lshl_add_u64 v[132:133], s[56:57], 0, v[132:133]
	s_andn2_saveexec_b64 s[0:1], s[0:1]
	v_lshlrev_b32_e32 v132, 10, v134
	v_ashrrev_i32_e32 v133, 31, v132
	v_lshl_add_u64 v[132:133], v[132:133], 2, s[58:59]
	s_or_b64 exec, exec, s[0:1]
	v_lshl_add_u64 v[132:133], v[130:131], 2, v[132:133]
	global_load_dword v195, v[132:133], off
	global_load_dword v196, v[132:133], off offset:128
	v_or_b32_e32 v150, 17, v136
	v_min_i32_e32 v132, 0x403f, v150
	v_mul_hi_i32 v133, v132, s30
	v_lshrrev_b32_e32 v134, 31, v133
	v_ashrrev_i32_e32 v133, 11, v133
	v_add_u32_e32 v135, v133, v134
	v_mad_i32_i24 v134, v135, s31, v132
	v_cmp_lt_i32_e32 vcc, 15, v134
	s_and_saveexec_b64 s[0:1], vcc
	s_xor_b64 s[0:1], exec, s[0:1]
	v_lshlrev_b32_e32 v132, 12, v135
	v_add3_u32 v132, v132, v134, -16
	v_ashrrev_i32_e32 v133, 31, v132
	v_lshlrev_b64 v[132:133], 12, v[132:133]
	v_lshl_add_u64 v[132:133], s[56:57], 0, v[132:133]
	s_andn2_saveexec_b64 s[0:1], s[0:1]
	v_lshlrev_b32_e32 v132, 10, v134
	v_ashrrev_i32_e32 v133, 31, v132
	v_lshl_add_u64 v[132:133], v[132:133], 2, s[58:59]
	s_or_b64 exec, exec, s[0:1]
	v_lshl_add_u64 v[132:133], v[130:131], 2, v[132:133]
	global_load_dword v197, v[132:133], off
	global_load_dword v198, v[132:133], off offset:128
	v_or_b32_e32 v148, 18, v136
	v_min_i32_e32 v132, 0x403f, v148
	v_mul_hi_i32 v133, v132, s30
	v_lshrrev_b32_e32 v134, 31, v133
	v_ashrrev_i32_e32 v133, 11, v133
	v_add_u32_e32 v135, v133, v134
	v_mad_i32_i24 v134, v135, s31, v132
	v_cmp_lt_i32_e32 vcc, 15, v134
	s_and_saveexec_b64 s[0:1], vcc
	s_xor_b64 s[0:1], exec, s[0:1]
	v_lshlrev_b32_e32 v132, 12, v135
	v_add3_u32 v132, v132, v134, -16
	v_ashrrev_i32_e32 v133, 31, v132
	v_lshlrev_b64 v[132:133], 12, v[132:133]
	v_lshl_add_u64 v[132:133], s[56:57], 0, v[132:133]
	s_andn2_saveexec_b64 s[0:1], s[0:1]
	v_lshlrev_b32_e32 v132, 10, v134
	v_ashrrev_i32_e32 v133, 31, v132
	v_lshl_add_u64 v[132:133], v[132:133], 2, s[58:59]
	s_or_b64 exec, exec, s[0:1]
	v_lshl_add_u64 v[132:133], v[130:131], 2, v[132:133]
	global_load_dword v199, v[132:133], off
	global_load_dword v200, v[132:133], off offset:128
	v_or_b32_e32 v146, 19, v136
	v_min_i32_e32 v132, 0x403f, v146
	v_mul_hi_i32 v133, v132, s30
	v_lshrrev_b32_e32 v134, 31, v133
	v_ashrrev_i32_e32 v133, 11, v133
	v_add_u32_e32 v135, v133, v134
	v_mad_i32_i24 v134, v135, s31, v132
	v_cmp_lt_i32_e32 vcc, 15, v134
	s_and_saveexec_b64 s[0:1], vcc
	s_xor_b64 s[0:1], exec, s[0:1]
	v_lshlrev_b32_e32 v132, 12, v135
	v_add3_u32 v132, v132, v134, -16
	v_ashrrev_i32_e32 v133, 31, v132
	v_lshlrev_b64 v[132:133], 12, v[132:133]
	v_lshl_add_u64 v[132:133], s[56:57], 0, v[132:133]
	s_andn2_saveexec_b64 s[0:1], s[0:1]
	v_lshlrev_b32_e32 v132, 10, v134
	v_ashrrev_i32_e32 v133, 31, v132
	v_lshl_add_u64 v[132:133], v[132:133], 2, s[58:59]
	s_or_b64 exec, exec, s[0:1]
	v_lshl_add_u64 v[132:133], v[130:131], 2, v[132:133]
	global_load_dword v201, v[132:133], off
	global_load_dword v202, v[132:133], off offset:128
	v_or_b32_e32 v144, 24, v136
	v_min_i32_e32 v132, 0x403f, v144
	v_mul_hi_i32 v133, v132, s30
	v_lshrrev_b32_e32 v134, 31, v133
	v_ashrrev_i32_e32 v133, 11, v133
	v_add_u32_e32 v135, v133, v134
	v_mad_i32_i24 v134, v135, s31, v132
	v_cmp_lt_i32_e32 vcc, 15, v134
	s_and_saveexec_b64 s[0:1], vcc
	s_xor_b64 s[0:1], exec, s[0:1]
	v_lshlrev_b32_e32 v132, 12, v135
	v_add3_u32 v132, v132, v134, -16
	v_ashrrev_i32_e32 v133, 31, v132
	v_lshlrev_b64 v[132:133], 12, v[132:133]
	v_lshl_add_u64 v[132:133], s[56:57], 0, v[132:133]
	s_andn2_saveexec_b64 s[0:1], s[0:1]
	v_lshlrev_b32_e32 v132, 10, v134
	v_ashrrev_i32_e32 v133, 31, v132
	v_lshl_add_u64 v[132:133], v[132:133], 2, s[58:59]
	s_or_b64 exec, exec, s[0:1]
	v_lshl_add_u64 v[132:133], v[130:131], 2, v[132:133]
	global_load_dword v203, v[132:133], off
	global_load_dword v204, v[132:133], off offset:128
	v_or_b32_e32 v142, 25, v136
	v_min_i32_e32 v132, 0x403f, v142
	v_mul_hi_i32 v133, v132, s30
	v_lshrrev_b32_e32 v134, 31, v133
	v_ashrrev_i32_e32 v133, 11, v133
	v_add_u32_e32 v135, v133, v134
	v_mad_i32_i24 v134, v135, s31, v132
	v_cmp_lt_i32_e32 vcc, 15, v134
	s_and_saveexec_b64 s[0:1], vcc
	s_xor_b64 s[0:1], exec, s[0:1]
	v_lshlrev_b32_e32 v132, 12, v135
	v_add3_u32 v132, v132, v134, -16
	v_ashrrev_i32_e32 v133, 31, v132
	v_lshlrev_b64 v[132:133], 12, v[132:133]
	v_lshl_add_u64 v[132:133], s[56:57], 0, v[132:133]
	s_andn2_saveexec_b64 s[0:1], s[0:1]
	v_lshlrev_b32_e32 v132, 10, v134
	v_ashrrev_i32_e32 v133, 31, v132
	v_lshl_add_u64 v[132:133], v[132:133], 2, s[58:59]
	s_or_b64 exec, exec, s[0:1]
	v_lshl_add_u64 v[132:133], v[130:131], 2, v[132:133]
	global_load_dword v205, v[132:133], off
	global_load_dword v206, v[132:133], off offset:128
	v_or_b32_e32 v140, 26, v136
	v_min_i32_e32 v132, 0x403f, v140
	v_mul_hi_i32 v133, v132, s30
	v_lshrrev_b32_e32 v134, 31, v133
	v_ashrrev_i32_e32 v133, 11, v133
	v_add_u32_e32 v135, v133, v134
	v_mad_i32_i24 v134, v135, s31, v132
	v_cmp_lt_i32_e32 vcc, 15, v134
	s_and_saveexec_b64 s[0:1], vcc
	s_xor_b64 s[0:1], exec, s[0:1]
	v_lshlrev_b32_e32 v132, 12, v135
	v_add3_u32 v132, v132, v134, -16
	v_ashrrev_i32_e32 v133, 31, v132
	v_lshlrev_b64 v[132:133], 12, v[132:133]
	v_lshl_add_u64 v[132:133], s[56:57], 0, v[132:133]
	s_andn2_saveexec_b64 s[0:1], s[0:1]
	v_lshlrev_b32_e32 v132, 10, v134
	v_ashrrev_i32_e32 v133, 31, v132
	v_lshl_add_u64 v[132:133], v[132:133], 2, s[58:59]
	s_or_b64 exec, exec, s[0:1]
	v_lshl_add_u64 v[132:133], v[130:131], 2, v[132:133]
	global_load_dword v207, v[132:133], off
	global_load_dword v210, v[132:133], off offset:128
	v_or_b32_e32 v138, 27, v136
	v_min_i32_e32 v132, 0x403f, v138
	v_mul_hi_i32 v133, v132, s30
	v_lshrrev_b32_e32 v134, 31, v133
	v_ashrrev_i32_e32 v133, 11, v133
	v_add_u32_e32 v135, v133, v134
	v_mad_i32_i24 v134, v135, s31, v132
	v_cmp_lt_i32_e32 vcc, 15, v134
	s_and_saveexec_b64 s[0:1], vcc
	s_xor_b64 s[0:1], exec, s[0:1]
	v_lshlrev_b32_e32 v132, 12, v135
	v_add3_u32 v132, v132, v134, -16
	v_ashrrev_i32_e32 v133, 31, v132
	v_lshlrev_b64 v[132:133], 12, v[132:133]
	v_lshl_add_u64 v[132:133], s[56:57], 0, v[132:133]
	s_andn2_saveexec_b64 s[0:1], s[0:1]
	v_lshlrev_b32_e32 v132, 10, v134
	v_ashrrev_i32_e32 v133, 31, v132
	v_lshl_add_u64 v[132:133], v[132:133], 2, s[58:59]
	s_or_b64 exec, exec, s[0:1]
	v_lshl_add_u64 v[132:133], v[130:131], 2, v[132:133]
	global_load_dword v211, v[132:133], off
	global_load_dword v212, v[132:133], off offset:128
	v_cmp_gt_i32_e32 vcc, s34, v136
	s_nop 1
	v_cndmask_b32_e32 v132, v179, v136, vcc
	v_mul_hi_i32 v133, v132, s30
	v_lshrrev_b32_e32 v134, 31, v133
	v_ashrrev_i32_e32 v133, 11, v133
	v_add_u32_e32 v134, v133, v134
	v_mad_i32_i24 v135, v134, s31, v132
	v_cmp_lt_i32_e64 s[0:1], 15, v135
	s_and_saveexec_b64 s[2:3], s[0:1]
	s_xor_b64 s[0:1], exec, s[2:3]
	v_lshlrev_b32_e32 v132, 12, v134
	v_add3_u32 v132, v132, v135, -16
	v_ashrrev_i32_e32 v133, 31, v132
	v_lshlrev_b64 v[132:133], 12, v[132:133]
	v_lshl_add_u64 v[132:133], s[88:89], 0, v[132:133]
	s_andn2_saveexec_b64 s[0:1], s[0:1]
	v_lshlrev_b32_e32 v132, 14, v134
	v_lshl_add_u32 v132, v135, 10, v132
	v_ashrrev_i32_e32 v133, 31, v132
	v_lshl_add_u64 v[132:133], v[132:133], 2, s[12:13]
	s_or_b64 exec, exec, s[0:1]
	v_ashrrev_i32_e32 v137, 31, v136
	v_lshlrev_b64 v[134:135], 11, v[136:137]
	v_lshl_add_u64 v[168:169], s[62:63], 0, v[134:135]
	v_lshlrev_b64 v[134:135], 2, v[130:131]
	s_waitcnt vmcnt(31)
	v_fmac_f32_e32 v176, 0.5, v114
	v_lshl_add_u64 v[168:169], v[130:131], 1, v[168:169]
	v_lshl_add_u64 v[170:171], v[132:133], 0, v[134:135]
	v_lshl_add_u64 v[132:133], s[68:69], 0, v[134:135]
	global_load_dword v242, v[132:133], off
	global_load_dword v243, v[132:133], off offset:128
	s_waitcnt vmcnt(0)
	global_store_dword v[170:171], v176, off
	v_mul_f32_e32 v114, v176, v242
	v_cvt_pk_bf16_f32 v114, v114, s0
	global_store_short v[168:169], v114, off
.LBB0_729:
	s_waitcnt vmcnt(30)
	v_fmac_f32_e32 v177, 0.5, v98
	global_store_dword v[170:171], v177, off offset:128
	v_mul_f32_e32 v98, v177, v243
	v_cvt_pk_bf16_f32 v98, v98, s0
	global_store_short v[168:169], v98, off offset:64
.LBB0_731:
	v_cmp_gt_i32_e32 vcc, s34, v166
	s_nop 1
	v_cndmask_b32_e32 v114, v179, v166, vcc
	v_mul_hi_i32 v98, v114, s30
	v_lshrrev_b32_e32 v137, 31, v98
	v_ashrrev_i32_e32 v98, 11, v98
	v_add_u32_e32 v98, v98, v137
	v_mad_i32_i24 v114, v98, s31, v114
	v_cmp_lt_i32_e64 s[0:1], 15, v114
	s_and_saveexec_b64 s[2:3], s[0:1]
	s_xor_b64 s[0:1], exec, s[2:3]
	v_lshlrev_b32_e32 v98, 12, v98
	v_add3_u32 v168, v98, v114, -16
	v_ashrrev_i32_e32 v169, 31, v168
	v_lshlrev_b64 v[168:169], 12, v[168:169]
	v_lshl_add_u64 v[168:169], s[88:89], 0, v[168:169]
	s_andn2_saveexec_b64 s[0:1], s[0:1]
	v_lshlrev_b32_e32 v98, 14, v98
	v_lshl_add_u32 v168, v114, 10, v98
	v_ashrrev_i32_e32 v169, 31, v168
	v_lshl_add_u64 v[168:169], v[168:169], 2, s[12:13]
	s_or_b64 exec, exec, s[0:1]
	v_ashrrev_i32_e32 v167, 31, v166
	v_lshlrev_b64 v[166:167], 11, v[166:167]
	v_lshl_add_u64 v[166:167], s[62:63], 0, v[166:167]
	s_waitcnt vmcnt(29)
	v_fmac_f32_e32 v181, 0.5, v115
	v_lshl_add_u64 v[114:115], v[130:131], 1, v[166:167]
	v_lshl_add_u64 v[166:167], v[168:169], 0, v[134:135]
	global_store_dword v[166:167], v181, off
	v_mul_f32_e32 v98, v181, v242
	v_cvt_pk_bf16_f32 v98, v98, s0
	global_store_short v[114:115], v98, off
.LBB0_737:
	s_waitcnt vmcnt(28)
	v_fmac_f32_e32 v182, 0.5, v99
	global_store_dword v[166:167], v182, off offset:128
	v_mul_f32_e32 v98, v182, v243
	v_cvt_pk_bf16_f32 v98, v98, s0
	global_store_short v[114:115], v98, off offset:64
.LBB0_739:
	v_cmp_gt_i32_e32 vcc, s34, v164
	s_nop 1
	v_cndmask_b32_e32 v98, v179, v164, vcc
	v_mul_hi_i32 v99, v98, s30
	v_lshrrev_b32_e32 v114, 31, v99
	v_ashrrev_i32_e32 v99, 11, v99
	v_add_u32_e32 v114, v99, v114
	v_mad_i32_i24 v115, v114, s31, v98
	v_cmp_lt_i32_e64 s[0:1], 15, v115
	s_and_saveexec_b64 s[2:3], s[0:1]
	s_xor_b64 s[0:1], exec, s[2:3]
	v_lshlrev_b32_e32 v98, 12, v114
	v_add3_u32 v98, v98, v115, -16
	v_ashrrev_i32_e32 v99, 31, v98
	v_lshlrev_b64 v[98:99], 12, v[98:99]
	v_lshl_add_u64 v[98:99], s[88:89], 0, v[98:99]
	s_andn2_saveexec_b64 s[0:1], s[0:1]
	v_lshlrev_b32_e32 v98, 14, v114
	v_lshl_add_u32 v98, v115, 10, v98
	v_ashrrev_i32_e32 v99, 31, v98
	v_lshl_add_u64 v[98:99], v[98:99], 2, s[12:13]
	s_or_b64 exec, exec, s[0:1]
	v_ashrrev_i32_e32 v165, 31, v164
	v_lshlrev_b64 v[114:115], 11, v[164:165]
	v_lshl_add_u64 v[114:115], s[62:63], 0, v[114:115]
	s_waitcnt vmcnt(27)
	v_fmac_f32_e32 v183, 0.5, v116
	v_lshl_add_u64 v[114:115], v[130:131], 1, v[114:115]
	v_lshl_add_u64 v[98:99], v[98:99], 0, v[134:135]
	global_store_dword v[98:99], v183, off
	v_mul_f32_e32 v116, v183, v242
	v_cvt_pk_bf16_f32 v116, v116, s0
	global_store_short v[114:115], v116, off
.LBB0_745:
	s_waitcnt vmcnt(26)
	v_fmac_f32_e32 v184, 0.5, v100
	global_store_dword v[98:99], v184, off offset:128
	v_mul_f32_e32 v98, v184, v243
	v_cvt_pk_bf16_f32 v98, v98, s0
	global_store_short v[114:115], v98, off offset:64
.LBB0_747:
	v_cmp_gt_i32_e32 vcc, s34, v162
	s_nop 1
	v_cndmask_b32_e32 v98, v179, v162, vcc
	v_mul_hi_i32 v99, v98, s30
	v_lshrrev_b32_e32 v100, 31, v99
	v_ashrrev_i32_e32 v99, 11, v99
	v_add_u32_e32 v100, v99, v100
	v_mad_i32_i24 v114, v100, s31, v98
	v_cmp_lt_i32_e64 s[0:1], 15, v114
	s_and_saveexec_b64 s[2:3], s[0:1]
	s_xor_b64 s[0:1], exec, s[2:3]
	v_lshlrev_b32_e32 v98, 12, v100
	v_add3_u32 v98, v98, v114, -16
	v_ashrrev_i32_e32 v99, 31, v98
	v_lshlrev_b64 v[98:99], 12, v[98:99]
	v_lshl_add_u64 v[98:99], s[88:89], 0, v[98:99]
	s_andn2_saveexec_b64 s[0:1], s[0:1]
	v_lshlrev_b32_e32 v98, 14, v100
	v_lshl_add_u32 v98, v114, 10, v98
	v_ashrrev_i32_e32 v99, 31, v98
	v_lshl_add_u64 v[98:99], v[98:99], 2, s[12:13]
	s_or_b64 exec, exec, s[0:1]
	v_ashrrev_i32_e32 v163, 31, v162
	v_lshlrev_b64 v[114:115], 11, v[162:163]
	v_lshl_add_u64 v[114:115], s[62:63], 0, v[114:115]
	s_waitcnt vmcnt(25)
	v_fmac_f32_e32 v185, 0.5, v117
	v_lshl_add_u64 v[114:115], v[130:131], 1, v[114:115]
	v_lshl_add_u64 v[98:99], v[98:99], 0, v[134:135]
	global_store_dword v[98:99], v185, off
	v_mul_f32_e32 v100, v185, v242
	v_cvt_pk_bf16_f32 v100, v100, s0
	global_store_short v[114:115], v100, off
.LBB0_753:
	s_waitcnt vmcnt(24)
	v_fmac_f32_e32 v186, 0.5, v101
	global_store_dword v[98:99], v186, off offset:128
	v_mul_f32_e32 v98, v186, v243
	v_cvt_pk_bf16_f32 v98, v98, s0
	global_store_short v[114:115], v98, off offset:64
.LBB0_755:
	v_cmp_gt_i32_e32 vcc, s34, v160
	s_nop 1
	v_cndmask_b32_e32 v98, v179, v160, vcc
	v_mul_hi_i32 v99, v98, s30
	v_lshrrev_b32_e32 v100, 31, v99
	v_ashrrev_i32_e32 v99, 11, v99
	v_add_u32_e32 v100, v99, v100
	v_mad_i32_i24 v101, v100, s31, v98
	v_cmp_lt_i32_e64 s[0:1], 15, v101
	s_and_saveexec_b64 s[2:3], s[0:1]
	s_xor_b64 s[0:1], exec, s[2:3]
	v_lshlrev_b32_e32 v98, 12, v100
	v_add3_u32 v98, v98, v101, -16
	v_ashrrev_i32_e32 v99, 31, v98
	v_lshlrev_b64 v[98:99], 12, v[98:99]
	v_lshl_add_u64 v[98:99], s[88:89], 0, v[98:99]
	s_andn2_saveexec_b64 s[0:1], s[0:1]
	v_lshlrev_b32_e32 v98, 14, v100
	v_lshl_add_u32 v98, v101, 10, v98
	v_ashrrev_i32_e32 v99, 31, v98
	v_lshl_add_u64 v[98:99], v[98:99], 2, s[12:13]
	s_or_b64 exec, exec, s[0:1]
	v_ashrrev_i32_e32 v161, 31, v160
	v_lshlrev_b64 v[100:101], 11, v[160:161]
	v_lshl_add_u64 v[100:101], s[62:63], 0, v[100:101]
	s_waitcnt vmcnt(23)
	v_fmac_f32_e32 v187, 0.5, v118
	v_lshl_add_u64 v[100:101], v[130:131], 1, v[100:101]
	v_lshl_add_u64 v[98:99], v[98:99], 0, v[134:135]
	global_store_dword v[98:99], v187, off
	v_mul_f32_e32 v114, v187, v242
	v_cvt_pk_bf16_f32 v114, v114, s0
	global_store_short v[100:101], v114, off
.LBB0_761:
	s_waitcnt vmcnt(22)
	v_fmac_f32_e32 v188, 0.5, v102
	global_store_dword v[98:99], v188, off offset:128
	v_mul_f32_e32 v98, v188, v243
	v_cvt_pk_bf16_f32 v98, v98, s0
	global_store_short v[100:101], v98, off offset:64
.LBB0_763:
	v_cmp_gt_i32_e32 vcc, s34, v158
	s_nop 1
	v_cndmask_b32_e32 v98, v179, v158, vcc
	v_mul_hi_i32 v99, v98, s30
	v_lshrrev_b32_e32 v100, 31, v99
	v_ashrrev_i32_e32 v99, 11, v99
	v_add_u32_e32 v100, v99, v100
	v_mad_i32_i24 v101, v100, s31, v98
	v_cmp_lt_i32_e64 s[0:1], 15, v101
	s_and_saveexec_b64 s[2:3], s[0:1]
	s_xor_b64 s[0:1], exec, s[2:3]
	v_lshlrev_b32_e32 v98, 12, v100
	v_add3_u32 v98, v98, v101, -16
	v_ashrrev_i32_e32 v99, 31, v98
	v_lshlrev_b64 v[98:99], 12, v[98:99]
	v_lshl_add_u64 v[98:99], s[88:89], 0, v[98:99]
	s_andn2_saveexec_b64 s[0:1], s[0:1]
	v_lshlrev_b32_e32 v98, 14, v100
	v_lshl_add_u32 v98, v101, 10, v98
	v_ashrrev_i32_e32 v99, 31, v98
	v_lshl_add_u64 v[98:99], v[98:99], 2, s[12:13]
	s_or_b64 exec, exec, s[0:1]
	v_ashrrev_i32_e32 v159, 31, v158
	v_lshlrev_b64 v[100:101], 11, v[158:159]
	v_lshl_add_u64 v[100:101], s[62:63], 0, v[100:101]
	s_waitcnt vmcnt(21)
	v_fmac_f32_e32 v189, 0.5, v119
	v_lshl_add_u64 v[100:101], v[130:131], 1, v[100:101]
	v_lshl_add_u64 v[98:99], v[98:99], 0, v[134:135]
	global_store_dword v[98:99], v189, off
	v_mul_f32_e32 v102, v189, v242
	v_cvt_pk_bf16_f32 v102, v102, s0
	global_store_short v[100:101], v102, off
.LBB0_769:
	s_waitcnt vmcnt(20)
	v_fmac_f32_e32 v190, 0.5, v103
	global_store_dword v[98:99], v190, off offset:128
	v_mul_f32_e32 v98, v190, v243
	v_cvt_pk_bf16_f32 v98, v98, s0
	global_store_short v[100:101], v98, off offset:64
.LBB0_771:
	v_cmp_gt_i32_e32 vcc, s34, v156
	s_nop 1
	v_cndmask_b32_e32 v98, v179, v156, vcc
	v_mul_hi_i32 v99, v98, s30
	v_lshrrev_b32_e32 v100, 31, v99
	v_ashrrev_i32_e32 v99, 11, v99
	v_add_u32_e32 v100, v99, v100
	v_mad_i32_i24 v101, v100, s31, v98
	v_cmp_lt_i32_e64 s[0:1], 15, v101
	s_and_saveexec_b64 s[2:3], s[0:1]
	s_xor_b64 s[0:1], exec, s[2:3]
	v_lshlrev_b32_e32 v98, 12, v100
	v_add3_u32 v98, v98, v101, -16
	v_ashrrev_i32_e32 v99, 31, v98
	v_lshlrev_b64 v[98:99], 12, v[98:99]
	v_lshl_add_u64 v[98:99], s[88:89], 0, v[98:99]
	s_andn2_saveexec_b64 s[0:1], s[0:1]
	v_lshlrev_b32_e32 v98, 14, v100
	v_lshl_add_u32 v98, v101, 10, v98
	v_ashrrev_i32_e32 v99, 31, v98
	v_lshl_add_u64 v[98:99], v[98:99], 2, s[12:13]
	s_or_b64 exec, exec, s[0:1]
	v_ashrrev_i32_e32 v157, 31, v156
	v_lshlrev_b64 v[100:101], 11, v[156:157]
	v_lshl_add_u64 v[100:101], s[62:63], 0, v[100:101]
	s_waitcnt vmcnt(19)
	v_fmac_f32_e32 v191, 0.5, v120
	v_lshl_add_u64 v[100:101], v[130:131], 1, v[100:101]
	v_lshl_add_u64 v[98:99], v[98:99], 0, v[134:135]
	global_store_dword v[98:99], v191, off
	v_mul_f32_e32 v102, v191, v242
	v_cvt_pk_bf16_f32 v102, v102, s0
	global_store_short v[100:101], v102, off
.LBB0_777:
	s_waitcnt vmcnt(18)
	v_fmac_f32_e32 v192, 0.5, v104
	global_store_dword v[98:99], v192, off offset:128
	v_mul_f32_e32 v98, v192, v243
	v_cvt_pk_bf16_f32 v98, v98, s0
	global_store_short v[100:101], v98, off offset:64
.LBB0_779:
	v_cmp_gt_i32_e32 vcc, s34, v154
	s_nop 1
	v_cndmask_b32_e32 v98, v179, v154, vcc
	v_mul_hi_i32 v99, v98, s30
	v_lshrrev_b32_e32 v100, 31, v99
	v_ashrrev_i32_e32 v99, 11, v99
	v_add_u32_e32 v100, v99, v100
	v_mad_i32_i24 v101, v100, s31, v98
	v_cmp_lt_i32_e64 s[0:1], 15, v101
	s_and_saveexec_b64 s[2:3], s[0:1]
	s_xor_b64 s[0:1], exec, s[2:3]
	v_lshlrev_b32_e32 v98, 12, v100
	v_add3_u32 v98, v98, v101, -16
	v_ashrrev_i32_e32 v99, 31, v98
	v_lshlrev_b64 v[98:99], 12, v[98:99]
	v_lshl_add_u64 v[98:99], s[88:89], 0, v[98:99]
	s_andn2_saveexec_b64 s[0:1], s[0:1]
	v_lshlrev_b32_e32 v98, 14, v100
	v_lshl_add_u32 v98, v101, 10, v98
	v_ashrrev_i32_e32 v99, 31, v98
	v_lshl_add_u64 v[98:99], v[98:99], 2, s[12:13]
	s_or_b64 exec, exec, s[0:1]
	v_ashrrev_i32_e32 v155, 31, v154
	v_lshlrev_b64 v[100:101], 11, v[154:155]
	v_lshl_add_u64 v[100:101], s[62:63], 0, v[100:101]
	s_waitcnt vmcnt(17)
	v_fmac_f32_e32 v193, 0.5, v121
	v_lshl_add_u64 v[100:101], v[130:131], 1, v[100:101]
	v_lshl_add_u64 v[98:99], v[98:99], 0, v[134:135]
	global_store_dword v[98:99], v193, off
	v_mul_f32_e32 v102, v193, v242
	v_cvt_pk_bf16_f32 v102, v102, s0
	global_store_short v[100:101], v102, off
.LBB0_785:
	s_waitcnt vmcnt(16)
	v_fmac_f32_e32 v194, 0.5, v105
	global_store_dword v[98:99], v194, off offset:128
	v_mul_f32_e32 v98, v194, v243
	v_cvt_pk_bf16_f32 v98, v98, s0
	global_store_short v[100:101], v98, off offset:64
.LBB0_787:
	v_cmp_gt_i32_e32 vcc, s34, v152
	s_nop 1
	v_cndmask_b32_e32 v98, v179, v152, vcc
	v_mul_hi_i32 v99, v98, s30
	v_lshrrev_b32_e32 v100, 31, v99
	v_ashrrev_i32_e32 v99, 11, v99
	v_add_u32_e32 v100, v99, v100
	v_mad_i32_i24 v101, v100, s31, v98
	v_cmp_lt_i32_e64 s[0:1], 15, v101
	s_and_saveexec_b64 s[2:3], s[0:1]
	s_xor_b64 s[0:1], exec, s[2:3]
	v_lshlrev_b32_e32 v98, 12, v100
	v_add3_u32 v98, v98, v101, -16
	v_ashrrev_i32_e32 v99, 31, v98
	v_lshlrev_b64 v[98:99], 12, v[98:99]
	v_lshl_add_u64 v[98:99], s[88:89], 0, v[98:99]
	s_andn2_saveexec_b64 s[0:1], s[0:1]
	v_lshlrev_b32_e32 v98, 14, v100
	v_lshl_add_u32 v98, v101, 10, v98
	v_ashrrev_i32_e32 v99, 31, v98
	v_lshl_add_u64 v[98:99], v[98:99], 2, s[12:13]
	s_or_b64 exec, exec, s[0:1]
	v_ashrrev_i32_e32 v153, 31, v152
	v_lshlrev_b64 v[100:101], 11, v[152:153]
	v_lshl_add_u64 v[100:101], s[62:63], 0, v[100:101]
	s_waitcnt vmcnt(15)
	v_fmac_f32_e32 v195, 0.5, v122
	v_lshl_add_u64 v[100:101], v[130:131], 1, v[100:101]
	v_lshl_add_u64 v[98:99], v[98:99], 0, v[134:135]
	global_store_dword v[98:99], v195, off
	v_mul_f32_e32 v102, v195, v242
	v_cvt_pk_bf16_f32 v102, v102, s0
	global_store_short v[100:101], v102, off
.LBB0_793:
	s_waitcnt vmcnt(14)
	v_fmac_f32_e32 v196, 0.5, v106
	global_store_dword v[98:99], v196, off offset:128
	v_mul_f32_e32 v98, v196, v243
	v_cvt_pk_bf16_f32 v98, v98, s0
	global_store_short v[100:101], v98, off offset:64
.LBB0_795:
	v_cmp_gt_i32_e32 vcc, s34, v150
	s_nop 1
	v_cndmask_b32_e32 v98, v179, v150, vcc
	v_mul_hi_i32 v99, v98, s30
	v_lshrrev_b32_e32 v100, 31, v99
	v_ashrrev_i32_e32 v99, 11, v99
	v_add_u32_e32 v100, v99, v100
	v_mad_i32_i24 v101, v100, s31, v98
	v_cmp_lt_i32_e64 s[0:1], 15, v101
	s_and_saveexec_b64 s[2:3], s[0:1]
	s_xor_b64 s[0:1], exec, s[2:3]
	v_lshlrev_b32_e32 v98, 12, v100
	v_add3_u32 v98, v98, v101, -16
	v_ashrrev_i32_e32 v99, 31, v98
	v_lshlrev_b64 v[98:99], 12, v[98:99]
	v_lshl_add_u64 v[98:99], s[88:89], 0, v[98:99]
	s_andn2_saveexec_b64 s[0:1], s[0:1]
	v_lshlrev_b32_e32 v98, 14, v100
	v_lshl_add_u32 v98, v101, 10, v98
	v_ashrrev_i32_e32 v99, 31, v98
	v_lshl_add_u64 v[98:99], v[98:99], 2, s[12:13]
	s_or_b64 exec, exec, s[0:1]
	v_ashrrev_i32_e32 v151, 31, v150
	v_lshlrev_b64 v[100:101], 11, v[150:151]
	v_lshl_add_u64 v[100:101], s[62:63], 0, v[100:101]
	s_waitcnt vmcnt(13)
	v_fmac_f32_e32 v197, 0.5, v123
	v_lshl_add_u64 v[100:101], v[130:131], 1, v[100:101]
	v_lshl_add_u64 v[98:99], v[98:99], 0, v[134:135]
	global_store_dword v[98:99], v197, off
	v_mul_f32_e32 v102, v197, v242
	v_cvt_pk_bf16_f32 v102, v102, s0
	global_store_short v[100:101], v102, off
.LBB0_801:
	s_waitcnt vmcnt(12)
	v_fmac_f32_e32 v198, 0.5, v107
	global_store_dword v[98:99], v198, off offset:128
	v_mul_f32_e32 v98, v198, v243
	v_cvt_pk_bf16_f32 v98, v98, s0
	global_store_short v[100:101], v98, off offset:64
.LBB0_803:
	v_cmp_gt_i32_e32 vcc, s34, v148
	s_nop 1
	v_cndmask_b32_e32 v98, v179, v148, vcc
	v_mul_hi_i32 v99, v98, s30
	v_lshrrev_b32_e32 v100, 31, v99
	v_ashrrev_i32_e32 v99, 11, v99
	v_add_u32_e32 v100, v99, v100
	v_mad_i32_i24 v101, v100, s31, v98
	v_cmp_lt_i32_e64 s[0:1], 15, v101
	s_and_saveexec_b64 s[2:3], s[0:1]
	s_xor_b64 s[0:1], exec, s[2:3]
	v_lshlrev_b32_e32 v98, 12, v100
	v_add3_u32 v98, v98, v101, -16
	v_ashrrev_i32_e32 v99, 31, v98
	v_lshlrev_b64 v[98:99], 12, v[98:99]
	v_lshl_add_u64 v[98:99], s[88:89], 0, v[98:99]
	s_andn2_saveexec_b64 s[0:1], s[0:1]
	v_lshlrev_b32_e32 v98, 14, v100
	v_lshl_add_u32 v98, v101, 10, v98
	v_ashrrev_i32_e32 v99, 31, v98
	v_lshl_add_u64 v[98:99], v[98:99], 2, s[12:13]
	s_or_b64 exec, exec, s[0:1]
	v_ashrrev_i32_e32 v149, 31, v148
	v_lshlrev_b64 v[100:101], 11, v[148:149]
	v_lshl_add_u64 v[100:101], s[62:63], 0, v[100:101]
	s_waitcnt vmcnt(11)
	v_fmac_f32_e32 v199, 0.5, v124
	v_lshl_add_u64 v[100:101], v[130:131], 1, v[100:101]
	v_lshl_add_u64 v[98:99], v[98:99], 0, v[134:135]
	global_store_dword v[98:99], v199, off
	v_mul_f32_e32 v102, v199, v242
	v_cvt_pk_bf16_f32 v102, v102, s0
	global_store_short v[100:101], v102, off
.LBB0_809:
	s_waitcnt vmcnt(10)
	v_fmac_f32_e32 v200, 0.5, v108
	global_store_dword v[98:99], v200, off offset:128
	v_mul_f32_e32 v98, v200, v243
	v_cvt_pk_bf16_f32 v98, v98, s0
	global_store_short v[100:101], v98, off offset:64
.LBB0_811:
	v_cmp_gt_i32_e32 vcc, s34, v146
	s_nop 1
	v_cndmask_b32_e32 v98, v179, v146, vcc
	v_mul_hi_i32 v99, v98, s30
	v_lshrrev_b32_e32 v100, 31, v99
	v_ashrrev_i32_e32 v99, 11, v99
	v_add_u32_e32 v100, v99, v100
	v_mad_i32_i24 v101, v100, s31, v98
	v_cmp_lt_i32_e64 s[0:1], 15, v101
	s_and_saveexec_b64 s[2:3], s[0:1]
	s_xor_b64 s[0:1], exec, s[2:3]
	v_lshlrev_b32_e32 v98, 12, v100
	v_add3_u32 v98, v98, v101, -16
	v_ashrrev_i32_e32 v99, 31, v98
	v_lshlrev_b64 v[98:99], 12, v[98:99]
	v_lshl_add_u64 v[98:99], s[88:89], 0, v[98:99]
	s_andn2_saveexec_b64 s[0:1], s[0:1]
	v_lshlrev_b32_e32 v98, 14, v100
	v_lshl_add_u32 v98, v101, 10, v98
	v_ashrrev_i32_e32 v99, 31, v98
	v_lshl_add_u64 v[98:99], v[98:99], 2, s[12:13]
	s_or_b64 exec, exec, s[0:1]
	v_ashrrev_i32_e32 v147, 31, v146
	v_lshlrev_b64 v[100:101], 11, v[146:147]
	v_lshl_add_u64 v[100:101], s[62:63], 0, v[100:101]
	s_waitcnt vmcnt(9)
	v_fmac_f32_e32 v201, 0.5, v125
	v_lshl_add_u64 v[100:101], v[130:131], 1, v[100:101]
	v_lshl_add_u64 v[98:99], v[98:99], 0, v[134:135]
	global_store_dword v[98:99], v201, off
	v_mul_f32_e32 v102, v201, v242
	v_cvt_pk_bf16_f32 v102, v102, s0
	global_store_short v[100:101], v102, off
.LBB0_817:
	s_waitcnt vmcnt(8)
	v_fmac_f32_e32 v202, 0.5, v109
	global_store_dword v[98:99], v202, off offset:128
	v_mul_f32_e32 v98, v202, v243
	v_cvt_pk_bf16_f32 v98, v98, s0
	global_store_short v[100:101], v98, off offset:64
.LBB0_819:
	v_cmp_gt_i32_e32 vcc, s34, v144
	s_nop 1
	v_cndmask_b32_e32 v98, v179, v144, vcc
	v_mul_hi_i32 v99, v98, s30
	v_lshrrev_b32_e32 v100, 31, v99
	v_ashrrev_i32_e32 v99, 11, v99
	v_add_u32_e32 v100, v99, v100
	v_mad_i32_i24 v101, v100, s31, v98
	v_cmp_lt_i32_e64 s[0:1], 15, v101
	s_and_saveexec_b64 s[2:3], s[0:1]
	s_xor_b64 s[0:1], exec, s[2:3]
	v_lshlrev_b32_e32 v98, 12, v100
	v_add3_u32 v98, v98, v101, -16
	v_ashrrev_i32_e32 v99, 31, v98
	v_lshlrev_b64 v[98:99], 12, v[98:99]
	v_lshl_add_u64 v[98:99], s[88:89], 0, v[98:99]
	s_andn2_saveexec_b64 s[0:1], s[0:1]
	v_lshlrev_b32_e32 v98, 14, v100
	v_lshl_add_u32 v98, v101, 10, v98
	v_ashrrev_i32_e32 v99, 31, v98
	v_lshl_add_u64 v[98:99], v[98:99], 2, s[12:13]
	s_or_b64 exec, exec, s[0:1]
	v_ashrrev_i32_e32 v145, 31, v144
	v_lshlrev_b64 v[100:101], 11, v[144:145]
	v_lshl_add_u64 v[100:101], s[62:63], 0, v[100:101]
	s_waitcnt vmcnt(7)
	v_fmac_f32_e32 v203, 0.5, v126
	v_lshl_add_u64 v[100:101], v[130:131], 1, v[100:101]
	v_lshl_add_u64 v[98:99], v[98:99], 0, v[134:135]
	global_store_dword v[98:99], v203, off
	v_mul_f32_e32 v102, v203, v242
	v_cvt_pk_bf16_f32 v102, v102, s0
	global_store_short v[100:101], v102, off
.LBB0_825:
	s_waitcnt vmcnt(6)
	v_fmac_f32_e32 v204, 0.5, v110
	global_store_dword v[98:99], v204, off offset:128
	v_mul_f32_e32 v98, v204, v243
	v_cvt_pk_bf16_f32 v98, v98, s0
	global_store_short v[100:101], v98, off offset:64
.LBB0_827:
	v_cmp_gt_i32_e32 vcc, s34, v142
	s_nop 1
	v_cndmask_b32_e32 v98, v179, v142, vcc
	v_mul_hi_i32 v99, v98, s30
	v_lshrrev_b32_e32 v100, 31, v99
	v_ashrrev_i32_e32 v99, 11, v99
	v_add_u32_e32 v100, v99, v100
	v_mad_i32_i24 v101, v100, s31, v98
	v_cmp_lt_i32_e64 s[0:1], 15, v101
	s_and_saveexec_b64 s[2:3], s[0:1]
	s_xor_b64 s[0:1], exec, s[2:3]
	v_lshlrev_b32_e32 v98, 12, v100
	v_add3_u32 v98, v98, v101, -16
	v_ashrrev_i32_e32 v99, 31, v98
	v_lshlrev_b64 v[98:99], 12, v[98:99]
	v_lshl_add_u64 v[98:99], s[88:89], 0, v[98:99]
	s_andn2_saveexec_b64 s[0:1], s[0:1]
	v_lshlrev_b32_e32 v98, 14, v100
	v_lshl_add_u32 v98, v101, 10, v98
	v_ashrrev_i32_e32 v99, 31, v98
	v_lshl_add_u64 v[98:99], v[98:99], 2, s[12:13]
	s_or_b64 exec, exec, s[0:1]
	v_ashrrev_i32_e32 v143, 31, v142
	v_lshlrev_b64 v[100:101], 11, v[142:143]
	v_lshl_add_u64 v[100:101], s[62:63], 0, v[100:101]
	s_waitcnt vmcnt(5)
	v_fmac_f32_e32 v205, 0.5, v127
	v_lshl_add_u64 v[100:101], v[130:131], 1, v[100:101]
	v_lshl_add_u64 v[98:99], v[98:99], 0, v[134:135]
	global_store_dword v[98:99], v205, off
	v_mul_f32_e32 v102, v205, v242
	v_cvt_pk_bf16_f32 v102, v102, s0
	global_store_short v[100:101], v102, off
.LBB0_833:
	s_waitcnt vmcnt(4)
	v_fmac_f32_e32 v206, 0.5, v111
	global_store_dword v[98:99], v206, off offset:128
	v_mul_f32_e32 v98, v206, v243
	v_cvt_pk_bf16_f32 v98, v98, s0
	global_store_short v[100:101], v98, off offset:64
.LBB0_835:
	v_cmp_gt_i32_e32 vcc, s34, v140
	s_nop 1
	v_cndmask_b32_e32 v98, v179, v140, vcc
	v_mul_hi_i32 v99, v98, s30
	v_lshrrev_b32_e32 v100, 31, v99
	v_ashrrev_i32_e32 v99, 11, v99
	v_add_u32_e32 v100, v99, v100
	v_mad_i32_i24 v101, v100, s31, v98
	v_cmp_lt_i32_e64 s[0:1], 15, v101
	s_and_saveexec_b64 s[2:3], s[0:1]
	s_xor_b64 s[0:1], exec, s[2:3]
	v_lshlrev_b32_e32 v98, 12, v100
	v_add3_u32 v98, v98, v101, -16
	v_ashrrev_i32_e32 v99, 31, v98
	v_lshlrev_b64 v[98:99], 12, v[98:99]
	v_lshl_add_u64 v[98:99], s[88:89], 0, v[98:99]
	s_andn2_saveexec_b64 s[0:1], s[0:1]
	v_lshlrev_b32_e32 v98, 14, v100
	v_lshl_add_u32 v98, v101, 10, v98
	v_ashrrev_i32_e32 v99, 31, v98
	v_lshl_add_u64 v[98:99], v[98:99], 2, s[12:13]
	s_or_b64 exec, exec, s[0:1]
	v_ashrrev_i32_e32 v141, 31, v140
	v_lshlrev_b64 v[100:101], 11, v[140:141]
	v_lshl_add_u64 v[100:101], s[62:63], 0, v[100:101]
	s_waitcnt vmcnt(3)
	v_fmac_f32_e32 v207, 0.5, v128
	v_lshl_add_u64 v[100:101], v[130:131], 1, v[100:101]
	v_lshl_add_u64 v[98:99], v[98:99], 0, v[134:135]
	global_store_dword v[98:99], v207, off
	v_mul_f32_e32 v102, v207, v242
	v_cvt_pk_bf16_f32 v102, v102, s0
	global_store_short v[100:101], v102, off
.LBB0_841:
	s_waitcnt vmcnt(2)
	v_fmac_f32_e32 v210, 0.5, v112
	global_store_dword v[98:99], v210, off offset:128
	v_mul_f32_e32 v98, v210, v243
	v_cvt_pk_bf16_f32 v98, v98, s0
	global_store_short v[100:101], v98, off offset:64
.LBB0_843:
	v_cmp_gt_i32_e32 vcc, s34, v138
	s_nop 1
	v_cndmask_b32_e32 v98, v179, v138, vcc
	v_mul_hi_i32 v99, v98, s30
	v_lshrrev_b32_e32 v100, 31, v99
	v_ashrrev_i32_e32 v99, 11, v99
	v_add_u32_e32 v100, v99, v100
	v_mad_i32_i24 v101, v100, s31, v98
	v_cmp_lt_i32_e64 s[0:1], 15, v101
	s_and_saveexec_b64 s[2:3], s[0:1]
	s_xor_b64 s[0:1], exec, s[2:3]
	v_lshlrev_b32_e32 v98, 12, v100
	v_add3_u32 v98, v98, v101, -16
	v_ashrrev_i32_e32 v99, 31, v98
	v_lshlrev_b64 v[98:99], 12, v[98:99]
	v_lshl_add_u64 v[98:99], s[88:89], 0, v[98:99]
	s_andn2_saveexec_b64 s[0:1], s[0:1]
	v_lshlrev_b32_e32 v98, 14, v100
	v_lshl_add_u32 v98, v101, 10, v98
	v_ashrrev_i32_e32 v99, 31, v98
	v_lshl_add_u64 v[98:99], v[98:99], 2, s[12:13]
	s_or_b64 exec, exec, s[0:1]
	v_ashrrev_i32_e32 v139, 31, v138
	v_lshlrev_b64 v[100:101], 11, v[138:139]
	v_lshl_add_u64 v[100:101], s[62:63], 0, v[100:101]
	s_waitcnt vmcnt(1)
	v_fmac_f32_e32 v211, 0.5, v129
	v_lshl_add_u64 v[100:101], v[130:131], 1, v[100:101]
	v_lshl_add_u64 v[98:99], v[98:99], 0, v[134:135]
	global_store_dword v[98:99], v211, off
	v_mul_f32_e32 v102, v211, v242
	v_cvt_pk_bf16_f32 v102, v102, s0
	global_store_short v[100:101], v102, off
.LBB0_849:
	s_waitcnt vmcnt(0)
	v_fmac_f32_e32 v212, 0.5, v113
	global_store_dword v[98:99], v212, off offset:128
	v_mul_f32_e32 v98, v212, v243
	v_cvt_pk_bf16_f32 v98, v98, s0
	global_store_short v[100:101], v98, off offset:64
.LBB0_851:
	v_or_b32_e32 v128, 32, v136
	v_min_i32_e32 v98, 0x403f, v128
	v_mul_hi_i32 v99, v98, s30
	v_lshrrev_b32_e32 v100, 31, v99
	v_ashrrev_i32_e32 v99, 11, v99
	v_add_u32_e32 v101, v99, v100
	v_mad_i32_i24 v100, v101, s31, v98
	v_cmp_lt_i32_e32 vcc, 15, v100
	s_and_saveexec_b64 s[0:1], vcc
	s_xor_b64 s[0:1], exec, s[0:1]
	v_lshlrev_b32_e32 v98, 12, v101
	v_add3_u32 v98, v98, v100, -16
	v_ashrrev_i32_e32 v99, 31, v98
	v_lshlrev_b64 v[98:99], 12, v[98:99]
	v_lshl_add_u64 v[98:99], s[56:57], 0, v[98:99]
	s_andn2_saveexec_b64 s[0:1], s[0:1]
	v_lshlrev_b32_e32 v98, 10, v100
	v_ashrrev_i32_e32 v99, 31, v98
	v_lshl_add_u64 v[98:99], v[98:99], 2, s[58:59]
	s_or_b64 exec, exec, s[0:1]
	v_lshl_add_u64 v[98:99], v[130:131], 2, v[98:99]
	global_load_dword v137, v[98:99], off
	global_load_dword v140, v[98:99], off offset:128
	v_or_b32_e32 v126, 33, v136
	v_min_i32_e32 v98, 0x403f, v126
	v_mul_hi_i32 v99, v98, s30
	v_lshrrev_b32_e32 v100, 31, v99
	v_ashrrev_i32_e32 v99, 11, v99
	v_add_u32_e32 v101, v99, v100
	v_mad_i32_i24 v100, v101, s31, v98
	v_cmp_lt_i32_e32 vcc, 15, v100
	s_and_saveexec_b64 s[0:1], vcc
	s_xor_b64 s[0:1], exec, s[0:1]
	v_lshlrev_b32_e32 v98, 12, v101
	v_add3_u32 v98, v98, v100, -16
	v_ashrrev_i32_e32 v99, 31, v98
	v_lshlrev_b64 v[98:99], 12, v[98:99]
	v_lshl_add_u64 v[98:99], s[56:57], 0, v[98:99]
	s_andn2_saveexec_b64 s[0:1], s[0:1]
	v_lshlrev_b32_e32 v98, 10, v100
	v_ashrrev_i32_e32 v99, 31, v98
	v_lshl_add_u64 v[98:99], v[98:99], 2, s[58:59]
	s_or_b64 exec, exec, s[0:1]
	v_lshl_add_u64 v[98:99], v[130:131], 2, v[98:99]
	global_load_dword v141, v[98:99], off
	global_load_dword v142, v[98:99], off offset:128
	v_or_b32_e32 v124, 34, v136
	v_min_i32_e32 v98, 0x403f, v124
	v_mul_hi_i32 v99, v98, s30
	v_lshrrev_b32_e32 v100, 31, v99
	v_ashrrev_i32_e32 v99, 11, v99
	v_add_u32_e32 v101, v99, v100
	v_mad_i32_i24 v100, v101, s31, v98
	v_cmp_lt_i32_e32 vcc, 15, v100
	s_and_saveexec_b64 s[0:1], vcc
	s_xor_b64 s[0:1], exec, s[0:1]
	v_lshlrev_b32_e32 v98, 12, v101
	v_add3_u32 v98, v98, v100, -16
	v_ashrrev_i32_e32 v99, 31, v98
	v_lshlrev_b64 v[98:99], 12, v[98:99]
	v_lshl_add_u64 v[98:99], s[56:57], 0, v[98:99]
	s_andn2_saveexec_b64 s[0:1], s[0:1]
	v_lshlrev_b32_e32 v98, 10, v100
	v_ashrrev_i32_e32 v99, 31, v98
	v_lshl_add_u64 v[98:99], v[98:99], 2, s[58:59]
	s_or_b64 exec, exec, s[0:1]
	v_lshl_add_u64 v[98:99], v[130:131], 2, v[98:99]
	global_load_dword v143, v[98:99], off
	global_load_dword v144, v[98:99], off offset:128
	v_or_b32_e32 v122, 35, v136
	v_min_i32_e32 v98, 0x403f, v122
	v_mul_hi_i32 v99, v98, s30
	v_lshrrev_b32_e32 v100, 31, v99
	v_ashrrev_i32_e32 v99, 11, v99
	v_add_u32_e32 v101, v99, v100
	v_mad_i32_i24 v100, v101, s31, v98
	v_cmp_lt_i32_e32 vcc, 15, v100
	s_and_saveexec_b64 s[0:1], vcc
	s_xor_b64 s[0:1], exec, s[0:1]
	v_lshlrev_b32_e32 v98, 12, v101
	v_add3_u32 v98, v98, v100, -16
	v_ashrrev_i32_e32 v99, 31, v98
	v_lshlrev_b64 v[98:99], 12, v[98:99]
	v_lshl_add_u64 v[98:99], s[56:57], 0, v[98:99]
	s_andn2_saveexec_b64 s[0:1], s[0:1]
	v_lshlrev_b32_e32 v98, 10, v100
	v_ashrrev_i32_e32 v99, 31, v98
	v_lshl_add_u64 v[98:99], v[98:99], 2, s[58:59]
	s_or_b64 exec, exec, s[0:1]
	v_lshl_add_u64 v[98:99], v[130:131], 2, v[98:99]
	global_load_dword v145, v[98:99], off
	global_load_dword v146, v[98:99], off offset:128
	v_or_b32_e32 v120, 40, v136
	v_min_i32_e32 v98, 0x403f, v120
	v_mul_hi_i32 v99, v98, s30
	v_lshrrev_b32_e32 v100, 31, v99
	v_ashrrev_i32_e32 v99, 11, v99
	v_add_u32_e32 v101, v99, v100
	v_mad_i32_i24 v100, v101, s31, v98
	v_cmp_lt_i32_e32 vcc, 15, v100
	s_and_saveexec_b64 s[0:1], vcc
	s_xor_b64 s[0:1], exec, s[0:1]
	v_lshlrev_b32_e32 v98, 12, v101
	v_add3_u32 v98, v98, v100, -16
	v_ashrrev_i32_e32 v99, 31, v98
	v_lshlrev_b64 v[98:99], 12, v[98:99]
	v_lshl_add_u64 v[98:99], s[56:57], 0, v[98:99]
	s_andn2_saveexec_b64 s[0:1], s[0:1]
	v_lshlrev_b32_e32 v98, 10, v100
	v_ashrrev_i32_e32 v99, 31, v98
	v_lshl_add_u64 v[98:99], v[98:99], 2, s[58:59]
	s_or_b64 exec, exec, s[0:1]
	v_lshl_add_u64 v[98:99], v[130:131], 2, v[98:99]
	global_load_dword v147, v[98:99], off
	global_load_dword v148, v[98:99], off offset:128
	v_or_b32_e32 v118, 41, v136
	v_min_i32_e32 v98, 0x403f, v118
	v_mul_hi_i32 v99, v98, s30
	v_lshrrev_b32_e32 v100, 31, v99
	v_ashrrev_i32_e32 v99, 11, v99
	v_add_u32_e32 v101, v99, v100
	v_mad_i32_i24 v100, v101, s31, v98
	v_cmp_lt_i32_e32 vcc, 15, v100
	s_and_saveexec_b64 s[0:1], vcc
	s_xor_b64 s[0:1], exec, s[0:1]
	v_lshlrev_b32_e32 v98, 12, v101
	v_add3_u32 v98, v98, v100, -16
	v_ashrrev_i32_e32 v99, 31, v98
	v_lshlrev_b64 v[98:99], 12, v[98:99]
	v_lshl_add_u64 v[98:99], s[56:57], 0, v[98:99]
	s_andn2_saveexec_b64 s[0:1], s[0:1]
	v_lshlrev_b32_e32 v98, 10, v100
	v_ashrrev_i32_e32 v99, 31, v98
	v_lshl_add_u64 v[98:99], v[98:99], 2, s[58:59]
	s_or_b64 exec, exec, s[0:1]
	v_lshl_add_u64 v[98:99], v[130:131], 2, v[98:99]
	global_load_dword v149, v[98:99], off
	global_load_dword v150, v[98:99], off offset:128
	v_or_b32_e32 v116, 42, v136
	v_min_i32_e32 v98, 0x403f, v116
	v_mul_hi_i32 v99, v98, s30
	v_lshrrev_b32_e32 v100, 31, v99
	v_ashrrev_i32_e32 v99, 11, v99
	v_add_u32_e32 v101, v99, v100
	v_mad_i32_i24 v100, v101, s31, v98
	v_cmp_lt_i32_e32 vcc, 15, v100
	s_and_saveexec_b64 s[0:1], vcc
	s_xor_b64 s[0:1], exec, s[0:1]
	v_lshlrev_b32_e32 v98, 12, v101
	v_add3_u32 v98, v98, v100, -16
	v_ashrrev_i32_e32 v99, 31, v98
	v_lshlrev_b64 v[98:99], 12, v[98:99]
	v_lshl_add_u64 v[98:99], s[56:57], 0, v[98:99]
	s_andn2_saveexec_b64 s[0:1], s[0:1]
	v_lshlrev_b32_e32 v98, 10, v100
	v_ashrrev_i32_e32 v99, 31, v98
	v_lshl_add_u64 v[98:99], v[98:99], 2, s[58:59]
	s_or_b64 exec, exec, s[0:1]
	v_lshl_add_u64 v[98:99], v[130:131], 2, v[98:99]
	global_load_dword v151, v[98:99], off
	global_load_dword v152, v[98:99], off offset:128
	v_or_b32_e32 v114, 43, v136
	v_min_i32_e32 v98, 0x403f, v114
	v_mul_hi_i32 v99, v98, s30
	v_lshrrev_b32_e32 v100, 31, v99
	v_ashrrev_i32_e32 v99, 11, v99
	v_add_u32_e32 v101, v99, v100
	v_mad_i32_i24 v100, v101, s31, v98
	v_cmp_lt_i32_e32 vcc, 15, v100
	s_and_saveexec_b64 s[0:1], vcc
	s_xor_b64 s[0:1], exec, s[0:1]
	v_lshlrev_b32_e32 v98, 12, v101
	v_add3_u32 v98, v98, v100, -16
	v_ashrrev_i32_e32 v99, 31, v98
	v_lshlrev_b64 v[98:99], 12, v[98:99]
	v_lshl_add_u64 v[98:99], s[56:57], 0, v[98:99]
	s_andn2_saveexec_b64 s[0:1], s[0:1]
	v_lshlrev_b32_e32 v98, 10, v100
	v_ashrrev_i32_e32 v99, 31, v98
	v_lshl_add_u64 v[98:99], v[98:99], 2, s[58:59]
	s_or_b64 exec, exec, s[0:1]
	v_lshl_add_u64 v[98:99], v[130:131], 2, v[98:99]
	global_load_dword v153, v[98:99], off
	global_load_dword v154, v[98:99], off offset:128
	v_or_b32_e32 v112, 48, v136
	v_min_i32_e32 v98, 0x403f, v112
	v_mul_hi_i32 v99, v98, s30
	v_lshrrev_b32_e32 v100, 31, v99
	v_ashrrev_i32_e32 v99, 11, v99
	v_add_u32_e32 v101, v99, v100
	v_mad_i32_i24 v100, v101, s31, v98
	v_cmp_lt_i32_e32 vcc, 15, v100
	s_and_saveexec_b64 s[0:1], vcc
	s_xor_b64 s[0:1], exec, s[0:1]
	v_lshlrev_b32_e32 v98, 12, v101
	v_add3_u32 v98, v98, v100, -16
	v_ashrrev_i32_e32 v99, 31, v98
	v_lshlrev_b64 v[98:99], 12, v[98:99]
	v_lshl_add_u64 v[98:99], s[56:57], 0, v[98:99]
	s_andn2_saveexec_b64 s[0:1], s[0:1]
	v_lshlrev_b32_e32 v98, 10, v100
	v_ashrrev_i32_e32 v99, 31, v98
	v_lshl_add_u64 v[98:99], v[98:99], 2, s[58:59]
	s_or_b64 exec, exec, s[0:1]
	v_lshl_add_u64 v[98:99], v[130:131], 2, v[98:99]
	global_load_dword v155, v[98:99], off
	global_load_dword v156, v[98:99], off offset:128
	v_or_b32_e32 v110, 49, v136
	v_min_i32_e32 v98, 0x403f, v110
	v_mul_hi_i32 v99, v98, s30
	v_lshrrev_b32_e32 v100, 31, v99
	v_ashrrev_i32_e32 v99, 11, v99
	v_add_u32_e32 v101, v99, v100
	v_mad_i32_i24 v100, v101, s31, v98
	v_cmp_lt_i32_e32 vcc, 15, v100
	s_and_saveexec_b64 s[0:1], vcc
	s_xor_b64 s[0:1], exec, s[0:1]
	v_lshlrev_b32_e32 v98, 12, v101
	v_add3_u32 v98, v98, v100, -16
	v_ashrrev_i32_e32 v99, 31, v98
	v_lshlrev_b64 v[98:99], 12, v[98:99]
	v_lshl_add_u64 v[98:99], s[56:57], 0, v[98:99]
	s_andn2_saveexec_b64 s[0:1], s[0:1]
	v_lshlrev_b32_e32 v98, 10, v100
	v_ashrrev_i32_e32 v99, 31, v98
	v_lshl_add_u64 v[98:99], v[98:99], 2, s[58:59]
	s_or_b64 exec, exec, s[0:1]
	v_lshl_add_u64 v[98:99], v[130:131], 2, v[98:99]
	global_load_dword v157, v[98:99], off
	global_load_dword v158, v[98:99], off offset:128
	v_or_b32_e32 v108, 50, v136
	v_min_i32_e32 v98, 0x403f, v108
	v_mul_hi_i32 v99, v98, s30
	v_lshrrev_b32_e32 v100, 31, v99
	v_ashrrev_i32_e32 v99, 11, v99
	v_add_u32_e32 v101, v99, v100
	v_mad_i32_i24 v100, v101, s31, v98
	v_cmp_lt_i32_e32 vcc, 15, v100
	s_and_saveexec_b64 s[0:1], vcc
	s_xor_b64 s[0:1], exec, s[0:1]
	v_lshlrev_b32_e32 v98, 12, v101
	v_add3_u32 v98, v98, v100, -16
	v_ashrrev_i32_e32 v99, 31, v98
	v_lshlrev_b64 v[98:99], 12, v[98:99]
	v_lshl_add_u64 v[98:99], s[56:57], 0, v[98:99]
	s_andn2_saveexec_b64 s[0:1], s[0:1]
	v_lshlrev_b32_e32 v98, 10, v100
	v_ashrrev_i32_e32 v99, 31, v98
	v_lshl_add_u64 v[98:99], v[98:99], 2, s[58:59]
	s_or_b64 exec, exec, s[0:1]
	v_lshl_add_u64 v[98:99], v[130:131], 2, v[98:99]
	global_load_dword v159, v[98:99], off
	global_load_dword v160, v[98:99], off offset:128
	v_or_b32_e32 v106, 51, v136
	v_min_i32_e32 v98, 0x403f, v106
	v_mul_hi_i32 v99, v98, s30
	v_lshrrev_b32_e32 v100, 31, v99
	v_ashrrev_i32_e32 v99, 11, v99
	v_add_u32_e32 v101, v99, v100
	v_mad_i32_i24 v100, v101, s31, v98
	v_cmp_lt_i32_e32 vcc, 15, v100
	s_and_saveexec_b64 s[0:1], vcc
	s_xor_b64 s[0:1], exec, s[0:1]
	v_lshlrev_b32_e32 v98, 12, v101
	v_add3_u32 v98, v98, v100, -16
	v_ashrrev_i32_e32 v99, 31, v98
	v_lshlrev_b64 v[98:99], 12, v[98:99]
	v_lshl_add_u64 v[98:99], s[56:57], 0, v[98:99]
	s_andn2_saveexec_b64 s[0:1], s[0:1]
	v_lshlrev_b32_e32 v98, 10, v100
	v_ashrrev_i32_e32 v99, 31, v98
	v_lshl_add_u64 v[98:99], v[98:99], 2, s[58:59]
	s_or_b64 exec, exec, s[0:1]
	v_lshl_add_u64 v[98:99], v[130:131], 2, v[98:99]
	global_load_dword v161, v[98:99], off
	global_load_dword v162, v[98:99], off offset:128
	v_or_b32_e32 v104, 56, v136
	v_min_i32_e32 v98, 0x403f, v104
	v_mul_hi_i32 v99, v98, s30
	v_lshrrev_b32_e32 v100, 31, v99
	v_ashrrev_i32_e32 v99, 11, v99
	v_add_u32_e32 v101, v99, v100
	v_mad_i32_i24 v100, v101, s31, v98
	v_cmp_lt_i32_e32 vcc, 15, v100
	s_and_saveexec_b64 s[0:1], vcc
	s_xor_b64 s[0:1], exec, s[0:1]
	v_lshlrev_b32_e32 v98, 12, v101
	v_add3_u32 v98, v98, v100, -16
	v_ashrrev_i32_e32 v99, 31, v98
	v_lshlrev_b64 v[98:99], 12, v[98:99]
	v_lshl_add_u64 v[98:99], s[56:57], 0, v[98:99]
	s_andn2_saveexec_b64 s[0:1], s[0:1]
	v_lshlrev_b32_e32 v98, 10, v100
	v_ashrrev_i32_e32 v99, 31, v98
	v_lshl_add_u64 v[98:99], v[98:99], 2, s[58:59]
	s_or_b64 exec, exec, s[0:1]
	v_lshl_add_u64 v[98:99], v[130:131], 2, v[98:99]
	global_load_dword v163, v[98:99], off
	global_load_dword v164, v[98:99], off offset:128
	v_or_b32_e32 v102, 57, v136
	v_min_i32_e32 v98, 0x403f, v102
	v_mul_hi_i32 v99, v98, s30
	v_lshrrev_b32_e32 v100, 31, v99
	v_ashrrev_i32_e32 v99, 11, v99
	v_add_u32_e32 v101, v99, v100
	v_mad_i32_i24 v100, v101, s31, v98
	v_cmp_lt_i32_e32 vcc, 15, v100
	s_and_saveexec_b64 s[0:1], vcc
	s_xor_b64 s[0:1], exec, s[0:1]
	v_lshlrev_b32_e32 v98, 12, v101
	v_add3_u32 v98, v98, v100, -16
	v_ashrrev_i32_e32 v99, 31, v98
	v_lshlrev_b64 v[98:99], 12, v[98:99]
	v_lshl_add_u64 v[98:99], s[56:57], 0, v[98:99]
	s_andn2_saveexec_b64 s[0:1], s[0:1]
	v_lshlrev_b32_e32 v98, 10, v100
	v_ashrrev_i32_e32 v99, 31, v98
	v_lshl_add_u64 v[98:99], v[98:99], 2, s[58:59]
	s_or_b64 exec, exec, s[0:1]
	v_lshl_add_u64 v[98:99], v[130:131], 2, v[98:99]
	global_load_dword v167, v[98:99], off
	global_load_dword v168, v[98:99], off offset:128
	v_or_b32_e32 v100, 58, v136
	v_min_i32_e32 v98, 0x403f, v100
	v_mul_hi_i32 v99, v98, s30
	v_lshrrev_b32_e32 v101, 31, v99
	v_ashrrev_i32_e32 v99, 11, v99
	v_add_u32_e32 v103, v99, v101
	v_mad_i32_i24 v101, v103, s31, v98
	v_cmp_lt_i32_e32 vcc, 15, v101
	s_and_saveexec_b64 s[0:1], vcc
	s_xor_b64 s[0:1], exec, s[0:1]
	v_lshlrev_b32_e32 v98, 12, v103
	v_add3_u32 v98, v98, v101, -16
	v_ashrrev_i32_e32 v99, 31, v98
	v_lshlrev_b64 v[98:99], 12, v[98:99]
	v_lshl_add_u64 v[98:99], s[56:57], 0, v[98:99]
	s_andn2_saveexec_b64 s[0:1], s[0:1]
	v_lshlrev_b32_e32 v98, 10, v101
	v_ashrrev_i32_e32 v99, 31, v98
	v_lshl_add_u64 v[98:99], v[98:99], 2, s[58:59]
	s_or_b64 exec, exec, s[0:1]
	v_lshl_add_u64 v[98:99], v[130:131], 2, v[98:99]
	global_load_dword v169, v[98:99], off
	global_load_dword v170, v[98:99], off offset:128
	v_or_b32_e32 v98, 59, v136
	v_min_i32_e32 v99, 0x403f, v98
	v_mul_hi_i32 v101, v99, s30
	v_lshrrev_b32_e32 v103, 31, v101
	v_ashrrev_i32_e32 v101, 11, v101
	v_add_u32_e32 v101, v101, v103
	v_mad_i32_i24 v99, v101, s31, v99
	v_cmp_lt_i32_e32 vcc, 15, v99
	s_and_saveexec_b64 s[0:1], vcc
	s_xor_b64 s[0:1], exec, s[0:1]
	v_lshlrev_b32_e32 v101, 12, v101
	v_add3_u32 v138, v101, v99, -16
	v_ashrrev_i32_e32 v139, 31, v138
	v_lshlrev_b64 v[138:139], 12, v[138:139]
	v_lshl_add_u64 v[138:139], s[56:57], 0, v[138:139]
	s_andn2_saveexec_b64 s[0:1], s[0:1]
	v_lshlrev_b32_e32 v138, 10, v99
	v_ashrrev_i32_e32 v139, 31, v138
	v_lshl_add_u64 v[138:139], v[138:139], 2, s[58:59]
	s_or_b64 exec, exec, s[0:1]
	v_lshl_add_u64 v[138:139], v[130:131], 2, v[138:139]
	global_load_dword v165, v[138:139], off
	global_load_dword v166, v[138:139], off offset:128
	v_cmp_gt_i32_e32 vcc, s34, v128
	s_nop 1
	v_cndmask_b32_e32 v101, v179, v128, vcc
	v_mul_hi_i32 v99, v101, s30
	v_lshrrev_b32_e32 v103, 31, v99
	v_ashrrev_i32_e32 v99, 11, v99
	v_add_u32_e32 v99, v99, v103
	v_mad_i32_i24 v101, v99, s31, v101
	v_cmp_lt_i32_e64 s[0:1], 15, v101
	s_and_saveexec_b64 s[2:3], s[0:1]
	s_xor_b64 s[0:1], exec, s[2:3]
	v_lshlrev_b32_e32 v99, 12, v99
	v_add3_u32 v138, v99, v101, -16
	v_ashrrev_i32_e32 v139, 31, v138
	v_lshlrev_b64 v[138:139], 12, v[138:139]
	v_lshl_add_u64 v[138:139], s[88:89], 0, v[138:139]
	s_andn2_saveexec_b64 s[0:1], s[0:1]
	v_lshlrev_b32_e32 v99, 14, v99
	v_lshl_add_u32 v138, v101, 10, v99
	v_ashrrev_i32_e32 v139, 31, v138
	v_lshl_add_u64 v[138:139], v[138:139], 2, s[12:13]
	s_or_b64 exec, exec, s[0:1]
	v_ashrrev_i32_e32 v129, 31, v128
	v_lshlrev_b64 v[128:129], 11, v[128:129]
	v_lshl_add_u64 v[128:129], s[62:63], 0, v[128:129]
	s_waitcnt vmcnt(31)
	v_fmac_f32_e32 v137, 0.5, v82
	v_lshl_add_u64 v[128:129], v[130:131], 1, v[128:129]
	v_lshl_add_u64 v[138:139], v[138:139], 0, v[134:135]
	global_store_dword v[138:139], v137, off
	v_mul_f32_e32 v82, v137, v242
	v_cvt_pk_bf16_f32 v82, v82, s0
	global_store_short v[128:129], v82, off
.LBB0_921:
	s_waitcnt vmcnt(30)
	v_fmac_f32_e32 v140, 0.5, v66
	global_store_dword v[138:139], v140, off offset:128
	v_mul_f32_e32 v66, v140, v243
	v_cvt_pk_bf16_f32 v66, v66, s0
	global_store_short v[128:129], v66, off offset:64
.LBB0_923:
	v_cmp_gt_i32_e32 vcc, s34, v126
	s_nop 1
	v_cndmask_b32_e32 v82, v179, v126, vcc
	v_mul_hi_i32 v66, v82, s30
	v_lshrrev_b32_e32 v99, 31, v66
	v_ashrrev_i32_e32 v66, 11, v66
	v_add_u32_e32 v66, v66, v99
	v_mad_i32_i24 v82, v66, s31, v82
	v_cmp_lt_i32_e64 s[0:1], 15, v82
	s_and_saveexec_b64 s[2:3], s[0:1]
	s_xor_b64 s[0:1], exec, s[2:3]
	v_lshlrev_b32_e32 v66, 12, v66
	v_add3_u32 v128, v66, v82, -16
	v_ashrrev_i32_e32 v129, 31, v128
	v_lshlrev_b64 v[128:129], 12, v[128:129]
	v_lshl_add_u64 v[128:129], s[88:89], 0, v[128:129]
	s_andn2_saveexec_b64 s[0:1], s[0:1]
	v_lshlrev_b32_e32 v66, 14, v66
	v_lshl_add_u32 v128, v82, 10, v66
	v_ashrrev_i32_e32 v129, 31, v128
	v_lshl_add_u64 v[128:129], v[128:129], 2, s[12:13]
	s_or_b64 exec, exec, s[0:1]
	v_ashrrev_i32_e32 v127, 31, v126
	v_lshlrev_b64 v[126:127], 11, v[126:127]
	v_lshl_add_u64 v[126:127], s[62:63], 0, v[126:127]
	s_waitcnt vmcnt(29)
	v_fmac_f32_e32 v141, 0.5, v83
	v_lshl_add_u64 v[82:83], v[130:131], 1, v[126:127]
	v_lshl_add_u64 v[126:127], v[128:129], 0, v[134:135]
	global_store_dword v[126:127], v141, off
	v_mul_f32_e32 v66, v141, v242
	v_cvt_pk_bf16_f32 v66, v66, s0
	global_store_short v[82:83], v66, off
.LBB0_929:
	s_waitcnt vmcnt(28)
	v_fmac_f32_e32 v142, 0.5, v67
	global_store_dword v[126:127], v142, off offset:128
	v_mul_f32_e32 v66, v142, v243
	v_cvt_pk_bf16_f32 v66, v66, s0
	global_store_short v[82:83], v66, off offset:64
.LBB0_931:
	v_cmp_gt_i32_e32 vcc, s34, v124
	s_nop 1
	v_cndmask_b32_e32 v66, v179, v124, vcc
	v_mul_hi_i32 v67, v66, s30
	v_lshrrev_b32_e32 v82, 31, v67
	v_ashrrev_i32_e32 v67, 11, v67
	v_add_u32_e32 v82, v67, v82
	v_mad_i32_i24 v83, v82, s31, v66
	v_cmp_lt_i32_e64 s[0:1], 15, v83
	s_and_saveexec_b64 s[2:3], s[0:1]
	s_xor_b64 s[0:1], exec, s[2:3]
	v_lshlrev_b32_e32 v66, 12, v82
	v_add3_u32 v66, v66, v83, -16
	v_ashrrev_i32_e32 v67, 31, v66
	v_lshlrev_b64 v[66:67], 12, v[66:67]
	v_lshl_add_u64 v[66:67], s[88:89], 0, v[66:67]
	s_andn2_saveexec_b64 s[0:1], s[0:1]
	v_lshlrev_b32_e32 v66, 14, v82
	v_lshl_add_u32 v66, v83, 10, v66
	v_ashrrev_i32_e32 v67, 31, v66
	v_lshl_add_u64 v[66:67], v[66:67], 2, s[12:13]
	s_or_b64 exec, exec, s[0:1]
	v_ashrrev_i32_e32 v125, 31, v124
	v_lshlrev_b64 v[82:83], 11, v[124:125]
	v_lshl_add_u64 v[82:83], s[62:63], 0, v[82:83]
	s_waitcnt vmcnt(27)
	v_fmac_f32_e32 v143, 0.5, v84
	v_lshl_add_u64 v[82:83], v[130:131], 1, v[82:83]
	v_lshl_add_u64 v[66:67], v[66:67], 0, v[134:135]
	global_store_dword v[66:67], v143, off
	v_mul_f32_e32 v84, v143, v242
	v_cvt_pk_bf16_f32 v84, v84, s0
	global_store_short v[82:83], v84, off
.LBB0_937:
	s_waitcnt vmcnt(26)
	v_fmac_f32_e32 v144, 0.5, v68
	global_store_dword v[66:67], v144, off offset:128
	v_mul_f32_e32 v66, v144, v243
	v_cvt_pk_bf16_f32 v66, v66, s0
	global_store_short v[82:83], v66, off offset:64
.LBB0_939:
	v_cmp_gt_i32_e32 vcc, s34, v122
	s_nop 1
	v_cndmask_b32_e32 v66, v179, v122, vcc
	v_mul_hi_i32 v67, v66, s30
	v_lshrrev_b32_e32 v68, 31, v67
	v_ashrrev_i32_e32 v67, 11, v67
	v_add_u32_e32 v68, v67, v68
	v_mad_i32_i24 v82, v68, s31, v66
	v_cmp_lt_i32_e64 s[0:1], 15, v82
	s_and_saveexec_b64 s[2:3], s[0:1]
	s_xor_b64 s[0:1], exec, s[2:3]
	v_lshlrev_b32_e32 v66, 12, v68
	v_add3_u32 v66, v66, v82, -16
	v_ashrrev_i32_e32 v67, 31, v66
	v_lshlrev_b64 v[66:67], 12, v[66:67]
	v_lshl_add_u64 v[66:67], s[88:89], 0, v[66:67]
	s_andn2_saveexec_b64 s[0:1], s[0:1]
	v_lshlrev_b32_e32 v66, 14, v68
	v_lshl_add_u32 v66, v82, 10, v66
	v_ashrrev_i32_e32 v67, 31, v66
	v_lshl_add_u64 v[66:67], v[66:67], 2, s[12:13]
	s_or_b64 exec, exec, s[0:1]
	v_ashrrev_i32_e32 v123, 31, v122
	v_lshlrev_b64 v[82:83], 11, v[122:123]
	v_lshl_add_u64 v[82:83], s[62:63], 0, v[82:83]
	s_waitcnt vmcnt(25)
	v_fmac_f32_e32 v145, 0.5, v85
	v_lshl_add_u64 v[82:83], v[130:131], 1, v[82:83]
	v_lshl_add_u64 v[66:67], v[66:67], 0, v[134:135]
	global_store_dword v[66:67], v145, off
	v_mul_f32_e32 v68, v145, v242
	v_cvt_pk_bf16_f32 v68, v68, s0
	global_store_short v[82:83], v68, off
.LBB0_945:
	s_waitcnt vmcnt(24)
	v_fmac_f32_e32 v146, 0.5, v69
	global_store_dword v[66:67], v146, off offset:128
	v_mul_f32_e32 v66, v146, v243
	v_cvt_pk_bf16_f32 v66, v66, s0
	global_store_short v[82:83], v66, off offset:64
.LBB0_947:
	v_cmp_gt_i32_e32 vcc, s34, v120
	s_nop 1
	v_cndmask_b32_e32 v66, v179, v120, vcc
	v_mul_hi_i32 v67, v66, s30
	v_lshrrev_b32_e32 v68, 31, v67
	v_ashrrev_i32_e32 v67, 11, v67
	v_add_u32_e32 v68, v67, v68
	v_mad_i32_i24 v69, v68, s31, v66
	v_cmp_lt_i32_e64 s[0:1], 15, v69
	s_and_saveexec_b64 s[2:3], s[0:1]
	s_xor_b64 s[0:1], exec, s[2:3]
	v_lshlrev_b32_e32 v66, 12, v68
	v_add3_u32 v66, v66, v69, -16
	v_ashrrev_i32_e32 v67, 31, v66
	v_lshlrev_b64 v[66:67], 12, v[66:67]
	v_lshl_add_u64 v[66:67], s[88:89], 0, v[66:67]
	s_andn2_saveexec_b64 s[0:1], s[0:1]
	v_lshlrev_b32_e32 v66, 14, v68
	v_lshl_add_u32 v66, v69, 10, v66
	v_ashrrev_i32_e32 v67, 31, v66
	v_lshl_add_u64 v[66:67], v[66:67], 2, s[12:13]
	s_or_b64 exec, exec, s[0:1]
	v_ashrrev_i32_e32 v121, 31, v120
	v_lshlrev_b64 v[68:69], 11, v[120:121]
	v_lshl_add_u64 v[68:69], s[62:63], 0, v[68:69]
	s_waitcnt vmcnt(23)
	v_fmac_f32_e32 v147, 0.5, v86
	v_lshl_add_u64 v[68:69], v[130:131], 1, v[68:69]
	v_lshl_add_u64 v[66:67], v[66:67], 0, v[134:135]
	global_store_dword v[66:67], v147, off
	v_mul_f32_e32 v82, v147, v242
	v_cvt_pk_bf16_f32 v82, v82, s0
	global_store_short v[68:69], v82, off
.LBB0_953:
	s_waitcnt vmcnt(22)
	v_fmac_f32_e32 v148, 0.5, v70
	global_store_dword v[66:67], v148, off offset:128
	v_mul_f32_e32 v66, v148, v243
	v_cvt_pk_bf16_f32 v66, v66, s0
	global_store_short v[68:69], v66, off offset:64
.LBB0_955:
	v_cmp_gt_i32_e32 vcc, s34, v118
	s_nop 1
	v_cndmask_b32_e32 v66, v179, v118, vcc
	v_mul_hi_i32 v67, v66, s30
	v_lshrrev_b32_e32 v68, 31, v67
	v_ashrrev_i32_e32 v67, 11, v67
	v_add_u32_e32 v68, v67, v68
	v_mad_i32_i24 v69, v68, s31, v66
	v_cmp_lt_i32_e64 s[0:1], 15, v69
	s_and_saveexec_b64 s[2:3], s[0:1]
	s_xor_b64 s[0:1], exec, s[2:3]
	v_lshlrev_b32_e32 v66, 12, v68
	v_add3_u32 v66, v66, v69, -16
	v_ashrrev_i32_e32 v67, 31, v66
	v_lshlrev_b64 v[66:67], 12, v[66:67]
	v_lshl_add_u64 v[66:67], s[88:89], 0, v[66:67]
	s_andn2_saveexec_b64 s[0:1], s[0:1]
	v_lshlrev_b32_e32 v66, 14, v68
	v_lshl_add_u32 v66, v69, 10, v66
	v_ashrrev_i32_e32 v67, 31, v66
	v_lshl_add_u64 v[66:67], v[66:67], 2, s[12:13]
	s_or_b64 exec, exec, s[0:1]
	v_ashrrev_i32_e32 v119, 31, v118
	v_lshlrev_b64 v[68:69], 11, v[118:119]
	v_lshl_add_u64 v[68:69], s[62:63], 0, v[68:69]
	s_waitcnt vmcnt(21)
	v_fmac_f32_e32 v149, 0.5, v87
	v_lshl_add_u64 v[68:69], v[130:131], 1, v[68:69]
	v_lshl_add_u64 v[66:67], v[66:67], 0, v[134:135]
	global_store_dword v[66:67], v149, off
	v_mul_f32_e32 v70, v149, v242
	v_cvt_pk_bf16_f32 v70, v70, s0
	global_store_short v[68:69], v70, off
.LBB0_961:
	s_waitcnt vmcnt(20)
	v_fmac_f32_e32 v150, 0.5, v71
	global_store_dword v[66:67], v150, off offset:128
	v_mul_f32_e32 v66, v150, v243
	v_cvt_pk_bf16_f32 v66, v66, s0
	global_store_short v[68:69], v66, off offset:64
.LBB0_963:
	v_cmp_gt_i32_e32 vcc, s34, v116
	s_nop 1
	v_cndmask_b32_e32 v66, v179, v116, vcc
	v_mul_hi_i32 v67, v66, s30
	v_lshrrev_b32_e32 v68, 31, v67
	v_ashrrev_i32_e32 v67, 11, v67
	v_add_u32_e32 v68, v67, v68
	v_mad_i32_i24 v69, v68, s31, v66
	v_cmp_lt_i32_e64 s[0:1], 15, v69
	s_and_saveexec_b64 s[2:3], s[0:1]
	s_xor_b64 s[0:1], exec, s[2:3]
	v_lshlrev_b32_e32 v66, 12, v68
	v_add3_u32 v66, v66, v69, -16
	v_ashrrev_i32_e32 v67, 31, v66
	v_lshlrev_b64 v[66:67], 12, v[66:67]
	v_lshl_add_u64 v[66:67], s[88:89], 0, v[66:67]
	s_andn2_saveexec_b64 s[0:1], s[0:1]
	v_lshlrev_b32_e32 v66, 14, v68
	v_lshl_add_u32 v66, v69, 10, v66
	v_ashrrev_i32_e32 v67, 31, v66
	v_lshl_add_u64 v[66:67], v[66:67], 2, s[12:13]
	s_or_b64 exec, exec, s[0:1]
	v_ashrrev_i32_e32 v117, 31, v116
	v_lshlrev_b64 v[68:69], 11, v[116:117]
	v_lshl_add_u64 v[68:69], s[62:63], 0, v[68:69]
	s_waitcnt vmcnt(19)
	v_fmac_f32_e32 v151, 0.5, v88
	v_lshl_add_u64 v[68:69], v[130:131], 1, v[68:69]
	v_lshl_add_u64 v[66:67], v[66:67], 0, v[134:135]
	global_store_dword v[66:67], v151, off
	v_mul_f32_e32 v70, v151, v242
	v_cvt_pk_bf16_f32 v70, v70, s0
	global_store_short v[68:69], v70, off
.LBB0_969:
	s_waitcnt vmcnt(18)
	v_fmac_f32_e32 v152, 0.5, v72
	global_store_dword v[66:67], v152, off offset:128
	v_mul_f32_e32 v66, v152, v243
	v_cvt_pk_bf16_f32 v66, v66, s0
	global_store_short v[68:69], v66, off offset:64
.LBB0_971:
	v_cmp_gt_i32_e32 vcc, s34, v114
	s_nop 1
	v_cndmask_b32_e32 v66, v179, v114, vcc
	v_mul_hi_i32 v67, v66, s30
	v_lshrrev_b32_e32 v68, 31, v67
	v_ashrrev_i32_e32 v67, 11, v67
	v_add_u32_e32 v68, v67, v68
	v_mad_i32_i24 v69, v68, s31, v66
	v_cmp_lt_i32_e64 s[0:1], 15, v69
	s_and_saveexec_b64 s[2:3], s[0:1]
	s_xor_b64 s[0:1], exec, s[2:3]
	v_lshlrev_b32_e32 v66, 12, v68
	v_add3_u32 v66, v66, v69, -16
	v_ashrrev_i32_e32 v67, 31, v66
	v_lshlrev_b64 v[66:67], 12, v[66:67]
	v_lshl_add_u64 v[66:67], s[88:89], 0, v[66:67]
	s_andn2_saveexec_b64 s[0:1], s[0:1]
	v_lshlrev_b32_e32 v66, 14, v68
	v_lshl_add_u32 v66, v69, 10, v66
	v_ashrrev_i32_e32 v67, 31, v66
	v_lshl_add_u64 v[66:67], v[66:67], 2, s[12:13]
	s_or_b64 exec, exec, s[0:1]
	v_ashrrev_i32_e32 v115, 31, v114
	v_lshlrev_b64 v[68:69], 11, v[114:115]
	v_lshl_add_u64 v[68:69], s[62:63], 0, v[68:69]
	s_waitcnt vmcnt(17)
	v_fmac_f32_e32 v153, 0.5, v89
	v_lshl_add_u64 v[68:69], v[130:131], 1, v[68:69]
	v_lshl_add_u64 v[66:67], v[66:67], 0, v[134:135]
	global_store_dword v[66:67], v153, off
	v_mul_f32_e32 v70, v153, v242
	v_cvt_pk_bf16_f32 v70, v70, s0
	global_store_short v[68:69], v70, off
.LBB0_977:
	s_waitcnt vmcnt(16)
	v_fmac_f32_e32 v154, 0.5, v73
	global_store_dword v[66:67], v154, off offset:128
	v_mul_f32_e32 v66, v154, v243
	v_cvt_pk_bf16_f32 v66, v66, s0
	global_store_short v[68:69], v66, off offset:64
.LBB0_979:
	v_cmp_gt_i32_e32 vcc, s34, v112
	s_nop 1
	v_cndmask_b32_e32 v66, v179, v112, vcc
	v_mul_hi_i32 v67, v66, s30
	v_lshrrev_b32_e32 v68, 31, v67
	v_ashrrev_i32_e32 v67, 11, v67
	v_add_u32_e32 v68, v67, v68
	v_mad_i32_i24 v69, v68, s31, v66
	v_cmp_lt_i32_e64 s[0:1], 15, v69
	s_and_saveexec_b64 s[2:3], s[0:1]
	s_xor_b64 s[0:1], exec, s[2:3]
	v_lshlrev_b32_e32 v66, 12, v68
	v_add3_u32 v66, v66, v69, -16
	v_ashrrev_i32_e32 v67, 31, v66
	v_lshlrev_b64 v[66:67], 12, v[66:67]
	v_lshl_add_u64 v[66:67], s[88:89], 0, v[66:67]
	s_andn2_saveexec_b64 s[0:1], s[0:1]
	v_lshlrev_b32_e32 v66, 14, v68
	v_lshl_add_u32 v66, v69, 10, v66
	v_ashrrev_i32_e32 v67, 31, v66
	v_lshl_add_u64 v[66:67], v[66:67], 2, s[12:13]
	s_or_b64 exec, exec, s[0:1]
	v_ashrrev_i32_e32 v113, 31, v112
	v_lshlrev_b64 v[68:69], 11, v[112:113]
	v_lshl_add_u64 v[68:69], s[62:63], 0, v[68:69]
	s_waitcnt vmcnt(15)
	v_fmac_f32_e32 v155, 0.5, v90
	v_lshl_add_u64 v[68:69], v[130:131], 1, v[68:69]
	v_lshl_add_u64 v[66:67], v[66:67], 0, v[134:135]
	global_store_dword v[66:67], v155, off
	v_mul_f32_e32 v70, v155, v242
	v_cvt_pk_bf16_f32 v70, v70, s0
	global_store_short v[68:69], v70, off
.LBB0_985:
	s_waitcnt vmcnt(14)
	v_fmac_f32_e32 v156, 0.5, v74
	global_store_dword v[66:67], v156, off offset:128
	v_mul_f32_e32 v66, v156, v243
	v_cvt_pk_bf16_f32 v66, v66, s0
	global_store_short v[68:69], v66, off offset:64
.LBB0_987:
	v_cmp_gt_i32_e32 vcc, s34, v110
	s_nop 1
	v_cndmask_b32_e32 v66, v179, v110, vcc
	v_mul_hi_i32 v67, v66, s30
	v_lshrrev_b32_e32 v68, 31, v67
	v_ashrrev_i32_e32 v67, 11, v67
	v_add_u32_e32 v68, v67, v68
	v_mad_i32_i24 v69, v68, s31, v66
	v_cmp_lt_i32_e64 s[0:1], 15, v69
	s_and_saveexec_b64 s[2:3], s[0:1]
	s_xor_b64 s[0:1], exec, s[2:3]
	v_lshlrev_b32_e32 v66, 12, v68
	v_add3_u32 v66, v66, v69, -16
	v_ashrrev_i32_e32 v67, 31, v66
	v_lshlrev_b64 v[66:67], 12, v[66:67]
	v_lshl_add_u64 v[66:67], s[88:89], 0, v[66:67]
	s_andn2_saveexec_b64 s[0:1], s[0:1]
	v_lshlrev_b32_e32 v66, 14, v68
	v_lshl_add_u32 v66, v69, 10, v66
	v_ashrrev_i32_e32 v67, 31, v66
	v_lshl_add_u64 v[66:67], v[66:67], 2, s[12:13]
	s_or_b64 exec, exec, s[0:1]
	v_ashrrev_i32_e32 v111, 31, v110
	v_lshlrev_b64 v[68:69], 11, v[110:111]
	v_lshl_add_u64 v[68:69], s[62:63], 0, v[68:69]
	s_waitcnt vmcnt(13)
	v_fmac_f32_e32 v157, 0.5, v91
	v_lshl_add_u64 v[68:69], v[130:131], 1, v[68:69]
	v_lshl_add_u64 v[66:67], v[66:67], 0, v[134:135]
	global_store_dword v[66:67], v157, off
	v_mul_f32_e32 v70, v157, v242
	v_cvt_pk_bf16_f32 v70, v70, s0
	global_store_short v[68:69], v70, off
.LBB0_993:
	s_waitcnt vmcnt(12)
	v_fmac_f32_e32 v158, 0.5, v75
	global_store_dword v[66:67], v158, off offset:128
	v_mul_f32_e32 v66, v158, v243
	v_cvt_pk_bf16_f32 v66, v66, s0
	global_store_short v[68:69], v66, off offset:64
.LBB0_995:
	v_cmp_gt_i32_e32 vcc, s34, v108
	s_nop 1
	v_cndmask_b32_e32 v66, v179, v108, vcc
	v_mul_hi_i32 v67, v66, s30
	v_lshrrev_b32_e32 v68, 31, v67
	v_ashrrev_i32_e32 v67, 11, v67
	v_add_u32_e32 v68, v67, v68
	v_mad_i32_i24 v69, v68, s31, v66
	v_cmp_lt_i32_e64 s[0:1], 15, v69
	s_and_saveexec_b64 s[2:3], s[0:1]
	s_xor_b64 s[0:1], exec, s[2:3]
	v_lshlrev_b32_e32 v66, 12, v68
	v_add3_u32 v66, v66, v69, -16
	v_ashrrev_i32_e32 v67, 31, v66
	v_lshlrev_b64 v[66:67], 12, v[66:67]
	v_lshl_add_u64 v[66:67], s[88:89], 0, v[66:67]
	s_andn2_saveexec_b64 s[0:1], s[0:1]
	v_lshlrev_b32_e32 v66, 14, v68
	v_lshl_add_u32 v66, v69, 10, v66
	v_ashrrev_i32_e32 v67, 31, v66
	v_lshl_add_u64 v[66:67], v[66:67], 2, s[12:13]
	s_or_b64 exec, exec, s[0:1]
	v_ashrrev_i32_e32 v109, 31, v108
	v_lshlrev_b64 v[68:69], 11, v[108:109]
	v_lshl_add_u64 v[68:69], s[62:63], 0, v[68:69]
	s_waitcnt vmcnt(11)
	v_fmac_f32_e32 v159, 0.5, v92
	v_lshl_add_u64 v[68:69], v[130:131], 1, v[68:69]
	v_lshl_add_u64 v[66:67], v[66:67], 0, v[134:135]
	global_store_dword v[66:67], v159, off
	v_mul_f32_e32 v70, v159, v242
	v_cvt_pk_bf16_f32 v70, v70, s0
	global_store_short v[68:69], v70, off
.LBB0_1001:
	s_waitcnt vmcnt(10)
	v_fmac_f32_e32 v160, 0.5, v76
	global_store_dword v[66:67], v160, off offset:128
	v_mul_f32_e32 v66, v160, v243
	v_cvt_pk_bf16_f32 v66, v66, s0
	global_store_short v[68:69], v66, off offset:64
.LBB0_1003:
	v_cmp_gt_i32_e32 vcc, s34, v106
	s_nop 1
	v_cndmask_b32_e32 v66, v179, v106, vcc
	v_mul_hi_i32 v67, v66, s30
	v_lshrrev_b32_e32 v68, 31, v67
	v_ashrrev_i32_e32 v67, 11, v67
	v_add_u32_e32 v68, v67, v68
	v_mad_i32_i24 v69, v68, s31, v66
	v_cmp_lt_i32_e64 s[0:1], 15, v69
	s_and_saveexec_b64 s[2:3], s[0:1]
	s_xor_b64 s[0:1], exec, s[2:3]
	v_lshlrev_b32_e32 v66, 12, v68
	v_add3_u32 v66, v66, v69, -16
	v_ashrrev_i32_e32 v67, 31, v66
	v_lshlrev_b64 v[66:67], 12, v[66:67]
	v_lshl_add_u64 v[66:67], s[88:89], 0, v[66:67]
	s_andn2_saveexec_b64 s[0:1], s[0:1]
	v_lshlrev_b32_e32 v66, 14, v68
	v_lshl_add_u32 v66, v69, 10, v66
	v_ashrrev_i32_e32 v67, 31, v66
	v_lshl_add_u64 v[66:67], v[66:67], 2, s[12:13]
	s_or_b64 exec, exec, s[0:1]
	v_ashrrev_i32_e32 v107, 31, v106
	v_lshlrev_b64 v[68:69], 11, v[106:107]
	v_lshl_add_u64 v[68:69], s[62:63], 0, v[68:69]
	s_waitcnt vmcnt(9)
	v_fmac_f32_e32 v161, 0.5, v93
	v_lshl_add_u64 v[68:69], v[130:131], 1, v[68:69]
	v_lshl_add_u64 v[66:67], v[66:67], 0, v[134:135]
	global_store_dword v[66:67], v161, off
	v_mul_f32_e32 v70, v161, v242
	v_cvt_pk_bf16_f32 v70, v70, s0
	global_store_short v[68:69], v70, off
.LBB0_1009:
	s_waitcnt vmcnt(8)
	v_fmac_f32_e32 v162, 0.5, v77
	global_store_dword v[66:67], v162, off offset:128
	v_mul_f32_e32 v66, v162, v243
	v_cvt_pk_bf16_f32 v66, v66, s0
	global_store_short v[68:69], v66, off offset:64
.LBB0_1011:
	v_cmp_gt_i32_e32 vcc, s34, v104
	s_nop 1
	v_cndmask_b32_e32 v66, v179, v104, vcc
	v_mul_hi_i32 v67, v66, s30
	v_lshrrev_b32_e32 v68, 31, v67
	v_ashrrev_i32_e32 v67, 11, v67
	v_add_u32_e32 v68, v67, v68
	v_mad_i32_i24 v69, v68, s31, v66
	v_cmp_lt_i32_e64 s[0:1], 15, v69
	s_and_saveexec_b64 s[2:3], s[0:1]
	s_xor_b64 s[0:1], exec, s[2:3]
	v_lshlrev_b32_e32 v66, 12, v68
	v_add3_u32 v66, v66, v69, -16
	v_ashrrev_i32_e32 v67, 31, v66
	v_lshlrev_b64 v[66:67], 12, v[66:67]
	v_lshl_add_u64 v[66:67], s[88:89], 0, v[66:67]
	s_andn2_saveexec_b64 s[0:1], s[0:1]
	v_lshlrev_b32_e32 v66, 14, v68
	v_lshl_add_u32 v66, v69, 10, v66
	v_ashrrev_i32_e32 v67, 31, v66
	v_lshl_add_u64 v[66:67], v[66:67], 2, s[12:13]
	s_or_b64 exec, exec, s[0:1]
	v_ashrrev_i32_e32 v105, 31, v104
	v_lshlrev_b64 v[68:69], 11, v[104:105]
	v_lshl_add_u64 v[68:69], s[62:63], 0, v[68:69]
	s_waitcnt vmcnt(7)
	v_fmac_f32_e32 v163, 0.5, v94
	v_lshl_add_u64 v[68:69], v[130:131], 1, v[68:69]
	v_lshl_add_u64 v[66:67], v[66:67], 0, v[134:135]
	global_store_dword v[66:67], v163, off
	v_mul_f32_e32 v70, v163, v242
	v_cvt_pk_bf16_f32 v70, v70, s0
	global_store_short v[68:69], v70, off
.LBB0_1017:
	s_waitcnt vmcnt(6)
	v_fmac_f32_e32 v164, 0.5, v78
	global_store_dword v[66:67], v164, off offset:128
	v_mul_f32_e32 v66, v164, v243
	v_cvt_pk_bf16_f32 v66, v66, s0
	global_store_short v[68:69], v66, off offset:64
.LBB0_1019:
	v_cmp_gt_i32_e32 vcc, s34, v102
	s_nop 1
	v_cndmask_b32_e32 v66, v179, v102, vcc
	v_mul_hi_i32 v67, v66, s30
	v_lshrrev_b32_e32 v68, 31, v67
	v_ashrrev_i32_e32 v67, 11, v67
	v_add_u32_e32 v68, v67, v68
	v_mad_i32_i24 v69, v68, s31, v66
	v_cmp_lt_i32_e64 s[0:1], 15, v69
	s_and_saveexec_b64 s[2:3], s[0:1]
	s_xor_b64 s[0:1], exec, s[2:3]
	v_lshlrev_b32_e32 v66, 12, v68
	v_add3_u32 v66, v66, v69, -16
	v_ashrrev_i32_e32 v67, 31, v66
	v_lshlrev_b64 v[66:67], 12, v[66:67]
	v_lshl_add_u64 v[66:67], s[88:89], 0, v[66:67]
	s_andn2_saveexec_b64 s[0:1], s[0:1]
	v_lshlrev_b32_e32 v66, 14, v68
	v_lshl_add_u32 v66, v69, 10, v66
	v_ashrrev_i32_e32 v67, 31, v66
	v_lshl_add_u64 v[66:67], v[66:67], 2, s[12:13]
	s_or_b64 exec, exec, s[0:1]
	v_ashrrev_i32_e32 v103, 31, v102
	v_lshlrev_b64 v[68:69], 11, v[102:103]
	v_lshl_add_u64 v[68:69], s[62:63], 0, v[68:69]
	s_waitcnt vmcnt(5)
	v_fmac_f32_e32 v167, 0.5, v95
	v_lshl_add_u64 v[68:69], v[130:131], 1, v[68:69]
	v_lshl_add_u64 v[66:67], v[66:67], 0, v[134:135]
	global_store_dword v[66:67], v167, off
	v_mul_f32_e32 v70, v167, v242
	v_cvt_pk_bf16_f32 v70, v70, s0
	global_store_short v[68:69], v70, off
.LBB0_1025:
	s_waitcnt vmcnt(4)
	v_fmac_f32_e32 v168, 0.5, v79
	global_store_dword v[66:67], v168, off offset:128
	v_mul_f32_e32 v66, v168, v243
	v_cvt_pk_bf16_f32 v66, v66, s0
	global_store_short v[68:69], v66, off offset:64
.LBB0_1027:
	v_cmp_gt_i32_e32 vcc, s34, v100
	s_nop 1
	v_cndmask_b32_e32 v66, v179, v100, vcc
	v_mul_hi_i32 v67, v66, s30
	v_lshrrev_b32_e32 v68, 31, v67
	v_ashrrev_i32_e32 v67, 11, v67
	v_add_u32_e32 v68, v67, v68
	v_mad_i32_i24 v69, v68, s31, v66
	v_cmp_lt_i32_e64 s[0:1], 15, v69
	s_and_saveexec_b64 s[2:3], s[0:1]
	s_xor_b64 s[0:1], exec, s[2:3]
	v_lshlrev_b32_e32 v66, 12, v68
	v_add3_u32 v66, v66, v69, -16
	v_ashrrev_i32_e32 v67, 31, v66
	v_lshlrev_b64 v[66:67], 12, v[66:67]
	v_lshl_add_u64 v[66:67], s[88:89], 0, v[66:67]
	s_andn2_saveexec_b64 s[0:1], s[0:1]
	v_lshlrev_b32_e32 v66, 14, v68
	v_lshl_add_u32 v66, v69, 10, v66
	v_ashrrev_i32_e32 v67, 31, v66
	v_lshl_add_u64 v[66:67], v[66:67], 2, s[12:13]
	s_or_b64 exec, exec, s[0:1]
	v_ashrrev_i32_e32 v101, 31, v100
	v_lshlrev_b64 v[68:69], 11, v[100:101]
	v_lshl_add_u64 v[68:69], s[62:63], 0, v[68:69]
	s_waitcnt vmcnt(3)
	v_fmac_f32_e32 v169, 0.5, v96
	v_lshl_add_u64 v[68:69], v[130:131], 1, v[68:69]
	v_lshl_add_u64 v[66:67], v[66:67], 0, v[134:135]
	global_store_dword v[66:67], v169, off
	v_mul_f32_e32 v70, v169, v242
	v_cvt_pk_bf16_f32 v70, v70, s0
	global_store_short v[68:69], v70, off
.LBB0_1033:
	s_waitcnt vmcnt(2)
	v_fmac_f32_e32 v170, 0.5, v80
	global_store_dword v[66:67], v170, off offset:128
	v_mul_f32_e32 v66, v170, v243
	v_cvt_pk_bf16_f32 v66, v66, s0
	global_store_short v[68:69], v66, off offset:64
.LBB0_1035:
	v_cmp_gt_i32_e32 vcc, s34, v98
	s_nop 1
	v_cndmask_b32_e32 v66, v179, v98, vcc
	v_mul_hi_i32 v67, v66, s30
	v_lshrrev_b32_e32 v68, 31, v67
	v_ashrrev_i32_e32 v67, 11, v67
	v_add_u32_e32 v68, v67, v68
	v_mad_i32_i24 v69, v68, s31, v66
	v_cmp_lt_i32_e64 s[0:1], 15, v69
	s_and_saveexec_b64 s[2:3], s[0:1]
	s_xor_b64 s[0:1], exec, s[2:3]
	v_lshlrev_b32_e32 v66, 12, v68
	v_add3_u32 v66, v66, v69, -16
	v_ashrrev_i32_e32 v67, 31, v66
	v_lshlrev_b64 v[66:67], 12, v[66:67]
	v_lshl_add_u64 v[66:67], s[88:89], 0, v[66:67]
	s_andn2_saveexec_b64 s[0:1], s[0:1]
	v_lshlrev_b32_e32 v66, 14, v68
	v_lshl_add_u32 v66, v69, 10, v66
	v_ashrrev_i32_e32 v67, 31, v66
	v_lshl_add_u64 v[66:67], v[66:67], 2, s[12:13]
	s_or_b64 exec, exec, s[0:1]
	v_ashrrev_i32_e32 v99, 31, v98
	v_lshlrev_b64 v[68:69], 11, v[98:99]
	v_lshl_add_u64 v[68:69], s[62:63], 0, v[68:69]
	s_waitcnt vmcnt(1)
	v_fmac_f32_e32 v165, 0.5, v97
	v_lshl_add_u64 v[68:69], v[130:131], 1, v[68:69]
	v_lshl_add_u64 v[66:67], v[66:67], 0, v[134:135]
	global_store_dword v[66:67], v165, off
	v_mul_f32_e32 v70, v165, v242
	v_cvt_pk_bf16_f32 v70, v70, s0
	global_store_short v[68:69], v70, off
.LBB0_1041:
	s_waitcnt vmcnt(0)
	v_fmac_f32_e32 v166, 0.5, v81
	global_store_dword v[66:67], v166, off offset:128
	v_mul_f32_e32 v66, v166, v243
	v_cvt_pk_bf16_f32 v66, v66, s0
	global_store_short v[68:69], v66, off offset:64
.LBB0_1043:
	v_lshlrev_b32_e32 v66, 1, v175
	v_lshlrev_b32_e32 v103, 1, v172
	v_and_b32_e32 v66, 32, v66
	v_and_b32_e32 v103, 24, v103
	v_and_b32_e32 v104, 3, v172
	v_or3_b32 v66, v104, v103, v66
	v_and_b32_e32 v104, 64, v180
	v_xor_b32_e32 v103, 16, v180
	v_add_u32_e32 v108, 64, v104
	v_mul_f32_e32 v81, v140, v140
	v_mul_f32_e32 v97, v177, v177
	v_and_b32_e32 v98, 16, v172
	v_cmp_lt_i32_e32 vcc, v103, v108
	v_fmac_f32_e32 v81, v137, v137
	v_fmac_f32_e32 v97, v176, v176
	v_cndmask_b32_e32 v103, v180, v103, vcc
	v_cmp_eq_u32_e32 vcc, 0, v98
	v_lshlrev_b32_e32 v104, 2, v103
	v_mul_f32_e32 v77, v148, v148
	v_cndmask_b32_e32 v98, v97, v81, vcc
	ds_bpermute_b32 v98, v104, v98
	v_mul_f32_e32 v78, v146, v146
	v_mul_f32_e32 v80, v142, v142
	v_mul_f32_e32 v93, v188, v188
	v_mul_f32_e32 v94, v186, v186
	v_mul_f32_e32 v96, v182, v182
	v_mul_f32_e32 v71, v160, v160
	v_mul_f32_e32 v72, v158, v158
	v_mul_f32_e32 v74, v154, v154
	v_mul_f32_e32 v75, v152, v152
	v_mul_f32_e32 v76, v150, v150
	v_fmac_f32_e32 v77, v147, v147
	v_fmac_f32_e32 v78, v145, v145
	v_mul_f32_e32 v79, v144, v144
	v_fmac_f32_e32 v80, v141, v141
	v_mul_f32_e32 v87, v200, v200
	v_mul_f32_e32 v88, v198, v198
	v_mul_f32_e32 v90, v194, v194
	v_mul_f32_e32 v91, v192, v192
	v_mul_f32_e32 v92, v190, v190
	v_fmac_f32_e32 v93, v187, v187
	v_fmac_f32_e32 v94, v185, v185
	v_mul_f32_e32 v95, v184, v184
	v_fmac_f32_e32 v96, v181, v181
	v_cndmask_b32_e32 v81, v81, v97, vcc
	v_mul_f32_e32 v68, v168, v168
	v_mul_f32_e32 v69, v164, v164
	v_mul_f32_e32 v70, v162, v162
	v_fmac_f32_e32 v71, v159, v159
	v_fmac_f32_e32 v72, v157, v157
	v_mul_f32_e32 v73, v156, v156
	v_fmac_f32_e32 v74, v153, v153
	v_fmac_f32_e32 v75, v151, v151
	v_fmac_f32_e32 v76, v149, v149
	v_fmac_f32_e32 v79, v143, v143
	v_mul_f32_e32 v84, v206, v206
	v_mul_f32_e32 v85, v204, v204
	v_mul_f32_e32 v86, v202, v202
	v_fmac_f32_e32 v87, v199, v199
	v_fmac_f32_e32 v88, v197, v197
	v_mul_f32_e32 v89, v196, v196
	v_fmac_f32_e32 v90, v193, v193
	v_fmac_f32_e32 v91, v191, v191
	v_fmac_f32_e32 v92, v189, v189
	v_fmac_f32_e32 v95, v183, v183
	s_waitcnt lgkmcnt(0)
	v_add_f32_e32 v81, v81, v98
	v_cndmask_b32_e32 v97, v96, v80, vcc
	v_cndmask_b32_e32 v98, v94, v78, vcc
	v_cndmask_b32_e32 v78, v78, v94, vcc
	v_cndmask_b32_e32 v94, v93, v77, vcc
	v_mul_f32_e32 v67, v170, v170
	v_fmac_f32_e32 v68, v167, v167
	v_fmac_f32_e32 v69, v163, v163
	v_fmac_f32_e32 v70, v161, v161
	v_fmac_f32_e32 v73, v155, v155
	v_mul_f32_e32 v83, v210, v210
	v_fmac_f32_e32 v84, v205, v205
	v_fmac_f32_e32 v85, v203, v203
	v_fmac_f32_e32 v86, v201, v201
	v_fmac_f32_e32 v89, v195, v195
	v_cndmask_b32_e32 v80, v80, v96, vcc
	ds_bpermute_b32 v96, v104, v97
	v_cndmask_b32_e32 v97, v95, v79, vcc
	v_cndmask_b32_e32 v79, v79, v95, vcc
	v_cndmask_b32_e32 v77, v77, v93, vcc
	ds_bpermute_b32 v93, v104, v94
	v_cndmask_b32_e32 v94, v92, v76, vcc
	v_cndmask_b32_e32 v95, v91, v75, vcc
	v_cndmask_b32_e32 v76, v76, v92, vcc
	v_cndmask_b32_e32 v75, v75, v91, vcc
	v_cndmask_b32_e32 v91, v90, v74, vcc
	v_cndmask_b32_e32 v92, v88, v72, vcc
	v_cndmask_b32_e32 v72, v72, v88, vcc
	v_cndmask_b32_e32 v88, v87, v71, vcc
	v_fmac_f32_e32 v67, v169, v169
	v_mul_f32_e32 v82, v212, v212
	v_fmac_f32_e32 v83, v207, v207
	v_mul_f32_e32 v103, v166, v166
	v_cndmask_b32_e32 v74, v74, v90, vcc
	ds_bpermute_b32 v90, v104, v91
	v_cndmask_b32_e32 v91, v89, v73, vcc
	v_cndmask_b32_e32 v73, v73, v89, vcc
	v_cndmask_b32_e32 v71, v71, v87, vcc
	ds_bpermute_b32 v87, v104, v88
	v_cndmask_b32_e32 v88, v86, v70, vcc
	v_cndmask_b32_e32 v89, v85, v69, vcc
	v_cndmask_b32_e32 v69, v69, v85, vcc
	v_cndmask_b32_e32 v85, v84, v68, vcc
	v_fmac_f32_e32 v82, v211, v211
	v_fmac_f32_e32 v103, v165, v165
	ds_bpermute_b32 v97, v104, v97
	ds_bpermute_b32 v98, v104, v98
	ds_bpermute_b32 v91, v104, v91
	ds_bpermute_b32 v88, v104, v88
	v_cndmask_b32_e32 v68, v68, v84, vcc
	ds_bpermute_b32 v84, v104, v85
	v_cndmask_b32_e32 v85, v83, v67, vcc
	ds_bpermute_b32 v94, v104, v94
	ds_bpermute_b32 v95, v104, v95
	ds_bpermute_b32 v92, v104, v92
	ds_bpermute_b32 v89, v104, v89
	v_cndmask_b32_e32 v70, v70, v86, vcc
	ds_bpermute_b32 v85, v104, v85
	v_cndmask_b32_e32 v86, v82, v103, vcc
	s_lshl_b32 s0, s4, 2
	ds_bpermute_b32 v86, v104, v86
	s_ashr_i32 s1, s0, 31
	v_cndmask_b32_e32 v67, v67, v83, vcc
	v_xor_b32_e32 v83, 8, v180
	v_and_b32_e32 v99, 8, v172
	s_lshl_b64 s[8:9], s[0:1], 2
	v_cmp_lt_i32_e64 s[0:1], v83, v108
	s_waitcnt lgkmcnt(10)
	v_add_f32_e32 v79, v79, v97
	s_waitcnt lgkmcnt(9)
	v_add_f32_e32 v78, v78, v98
	s_waitcnt lgkmcnt(8)
	v_add_f32_e32 v73, v73, v91
	v_add_f32_e32 v71, v71, v87
	s_waitcnt lgkmcnt(7)
	v_add_f32_e32 v70, v70, v88
	v_cndmask_b32_e64 v83, v180, v83, s[0:1]
	v_cmp_eq_u32_e64 s[2:3], 0, v99
	v_add_f32_e32 v80, v80, v96
	v_add_f32_e32 v77, v77, v93
	s_waitcnt lgkmcnt(5)
	v_add_f32_e32 v76, v76, v94
	s_waitcnt lgkmcnt(4)
	v_add_f32_e32 v75, v75, v95
	s_waitcnt lgkmcnt(3)
	v_add_f32_e32 v72, v72, v92
	s_waitcnt lgkmcnt(2)
	v_add_f32_e32 v69, v69, v89
	v_add_f32_e32 v68, v68, v84
	s_waitcnt lgkmcnt(1)
	v_add_f32_e32 v67, v67, v85
	v_cndmask_b32_e32 v82, v103, v82, vcc
	v_lshlrev_b32_e32 v105, 2, v83
	v_cndmask_b32_e64 v83, v81, v73, s[2:3]
	v_cndmask_b32_e64 v84, v79, v71, s[2:3]
	v_cndmask_b32_e64 v71, v71, v79, s[2:3]
	v_cndmask_b32_e64 v79, v78, v70, s[2:3]
	v_add_f32_e32 v74, v74, v90
	s_waitcnt lgkmcnt(0)
	v_add_f32_e32 v82, v82, v86
	v_cndmask_b32_e64 v73, v73, v81, s[2:3]
	ds_bpermute_b32 v81, v105, v83
	v_cndmask_b32_e64 v83, v80, v72, s[2:3]
	v_cndmask_b32_e64 v72, v72, v80, s[2:3]
	v_cndmask_b32_e64 v70, v70, v78, s[2:3]
	ds_bpermute_b32 v78, v105, v79
	v_cndmask_b32_e64 v79, v77, v69, s[2:3]
	v_cndmask_b32_e64 v80, v76, v68, s[2:3]
	v_cndmask_b32_e64 v68, v68, v76, s[2:3]
	v_cndmask_b32_e64 v76, v75, v67, s[2:3]
	ds_bpermute_b32 v83, v105, v83
	ds_bpermute_b32 v79, v105, v79
	ds_bpermute_b32 v80, v105, v80
	v_cndmask_b32_e64 v67, v67, v75, s[2:3]
	ds_bpermute_b32 v75, v105, v76
	v_cndmask_b32_e64 v76, v74, v82, s[2:3]
	ds_bpermute_b32 v84, v105, v84
	ds_bpermute_b32 v76, v105, v76
	v_cndmask_b32_e64 v69, v69, v77, s[2:3]
	v_xor_b32_e32 v77, 4, v180
	v_and_b32_e32 v100, 4, v172
	v_cmp_lt_i32_e64 s[0:1], v77, v108
	s_waitcnt lgkmcnt(7)
	v_add_f32_e32 v73, v73, v81
	s_waitcnt lgkmcnt(5)
	v_add_f32_e32 v72, v72, v83
	s_waitcnt lgkmcnt(4)
	v_add_f32_e32 v69, v69, v79
	s_waitcnt lgkmcnt(3)
	v_add_f32_e32 v68, v68, v80
	v_cndmask_b32_e64 v77, v180, v77, s[0:1]
	v_cmp_eq_u32_e64 s[4:5], 0, v100
	v_cndmask_b32_e64 v74, v82, v74, s[2:3]
	s_waitcnt lgkmcnt(1)
	v_add_f32_e32 v71, v71, v84
	v_add_f32_e32 v70, v70, v78
	v_lshlrev_b32_e32 v106, 2, v77
	v_cndmask_b32_e64 v77, v73, v69, s[4:5]
	v_add_f32_e32 v67, v67, v75
	s_waitcnt lgkmcnt(0)
	v_add_f32_e32 v74, v74, v76
	v_cndmask_b32_e64 v69, v69, v73, s[4:5]
	v_cndmask_b32_e64 v73, v72, v68, s[4:5]
	v_cndmask_b32_e64 v68, v68, v72, s[4:5]
	ds_bpermute_b32 v72, v106, v73
	v_cndmask_b32_e64 v73, v71, v67, s[4:5]
	v_cndmask_b32_e64 v75, v70, v74, s[4:5]
	ds_bpermute_b32 v77, v106, v77
	ds_bpermute_b32 v73, v106, v73
	ds_bpermute_b32 v75, v106, v75
	v_cndmask_b32_e64 v67, v67, v71, s[4:5]
	v_xor_b32_e32 v71, 2, v180
	v_and_b32_e32 v101, 2, v172
	v_cndmask_b32_e64 v70, v74, v70, s[4:5]
	v_cmp_lt_i32_e64 s[0:1], v71, v108
	s_waitcnt lgkmcnt(2)
	v_add_f32_e32 v69, v69, v77
	v_add_f32_e32 v68, v68, v72
	s_waitcnt lgkmcnt(1)
	v_add_f32_e32 v67, v67, v73
	s_waitcnt lgkmcnt(0)
	v_add_f32_e32 v70, v70, v75
	v_cndmask_b32_e64 v71, v180, v71, s[0:1]
	v_cmp_eq_u32_e64 s[6:7], 0, v101
	v_lshlrev_b32_e32 v107, 2, v71
	v_and_b32_e32 v102, 1, v172
	v_cndmask_b32_e64 v71, v69, v67, s[6:7]
	v_cndmask_b32_e64 v72, v68, v70, s[6:7]
	ds_bpermute_b32 v71, v107, v71
	ds_bpermute_b32 v72, v107, v72
	v_cndmask_b32_e64 v67, v67, v69, s[6:7]
	v_xor_b32_e32 v69, 1, v180
	s_add_u32 s10, s70, s8
	v_cndmask_b32_e64 v68, v70, v68, s[6:7]
	v_cmp_lt_i32_e64 s[0:1], v69, v108
	s_addc_u32 s11, s71, s9
	s_waitcnt lgkmcnt(1)
	v_add_f32_e32 v67, v67, v71
	s_waitcnt lgkmcnt(0)
	v_add_f32_e32 v70, v68, v72
	v_cmp_eq_u32_e64 s[8:9], 0, v102
	v_cndmask_b32_e64 v69, v180, v69, s[0:1]
	v_lshlrev_b32_e32 v108, 2, v69
	v_cndmask_b32_e64 v68, v67, v70, s[8:9]
	ds_bpermute_b32 v71, v108, v68
	v_or3_b32 v66, v66, v173, v174
	v_lshlrev_b32_e32 v0, 2, v0
	v_lshl_add_u64 v[68:69], s[10:11], 0, v[0:1]
	v_cndmask_b32_e64 v0, v70, v67, s[8:9]
	v_ashrrev_i32_e32 v67, 31, v66
	s_waitcnt lgkmcnt(0)
	v_add_f32_e32 v0, v0, v71
	v_lshlrev_b64 v[70:71], 6, v[66:67]
	v_lshl_add_u64 v[70:71], v[68:69], 0, v[70:71]
	v_or_b32_e32 v100, 64, v136
	global_store_dword v[70:71], v0, off
	s_cmp_lg_u32 s32, 0
	s_cbranch_scc0 .Lrt0_c
	s_branch .LBB0_596
.Lrt0_c:
	v_min_i32_e32 v0, 0x403f, v100
	v_mul_hi_i32 v67, v0, s30
	v_lshrrev_b32_e32 v70, 31, v67
	v_ashrrev_i32_e32 v67, 11, v67
	v_add_u32_e32 v67, v67, v70
	v_mad_i32_i24 v0, v67, s31, v0
	v_cmp_lt_i32_e64 s[0:1], 15, v0
	s_and_saveexec_b64 s[10:11], s[0:1]
	s_xor_b64 s[0:1], exec, s[10:11]
	v_lshlrev_b32_e32 v67, 12, v67
	v_add3_u32 v70, v67, v0, -16
	v_ashrrev_i32_e32 v71, 31, v70
	v_lshlrev_b64 v[70:71], 12, v[70:71]
	v_lshl_add_u64 v[70:71], s[56:57], 0, v[70:71]
	s_andn2_saveexec_b64 s[0:1], s[0:1]
	v_lshlrev_b32_e32 v70, 10, v0
	v_ashrrev_i32_e32 v71, 31, v70
	v_lshl_add_u64 v[70:71], v[70:71], 2, s[58:59]
	s_or_b64 exec, exec, s[0:1]
	v_lshl_add_u64 v[70:71], v[130:131], 2, v[70:71]
	global_load_dword v0, v[70:71], off
	global_load_dword v67, v[70:71], off offset:128
	v_or_b32_e32 v98, 0x41, v136
	v_min_i32_e32 v70, 0x403f, v98
	v_mul_hi_i32 v71, v70, s30
	v_lshrrev_b32_e32 v72, 31, v71
	v_ashrrev_i32_e32 v71, 11, v71
	v_add_u32_e32 v73, v71, v72
	v_mad_i32_i24 v72, v73, s31, v70
	v_cmp_lt_i32_e64 s[0:1], 15, v72
	s_and_saveexec_b64 s[10:11], s[0:1]
	s_xor_b64 s[0:1], exec, s[10:11]
	v_lshlrev_b32_e32 v70, 12, v73
	v_add3_u32 v70, v70, v72, -16
	v_ashrrev_i32_e32 v71, 31, v70
	v_lshlrev_b64 v[70:71], 12, v[70:71]
	v_lshl_add_u64 v[70:71], s[56:57], 0, v[70:71]
	s_andn2_saveexec_b64 s[0:1], s[0:1]
	v_lshlrev_b32_e32 v70, 10, v72
	v_ashrrev_i32_e32 v71, 31, v70
	v_lshl_add_u64 v[70:71], v[70:71], 2, s[58:59]
	s_or_b64 exec, exec, s[0:1]
	v_lshl_add_u64 v[70:71], v[130:131], 2, v[70:71]
	global_load_dword v109, v[70:71], off
	global_load_dword v110, v[70:71], off offset:128
	v_or_b32_e32 v96, 0x42, v136
	v_min_i32_e32 v70, 0x403f, v96
	v_mul_hi_i32 v71, v70, s30
	v_lshrrev_b32_e32 v72, 31, v71
	v_ashrrev_i32_e32 v71, 11, v71
	v_add_u32_e32 v73, v71, v72
	v_mad_i32_i24 v72, v73, s31, v70
	v_cmp_lt_i32_e64 s[0:1], 15, v72
	s_and_saveexec_b64 s[10:11], s[0:1]
	s_xor_b64 s[0:1], exec, s[10:11]
	v_lshlrev_b32_e32 v70, 12, v73
	v_add3_u32 v70, v70, v72, -16
	v_ashrrev_i32_e32 v71, 31, v70
	v_lshlrev_b64 v[70:71], 12, v[70:71]
	v_lshl_add_u64 v[70:71], s[56:57], 0, v[70:71]
	s_andn2_saveexec_b64 s[0:1], s[0:1]
	v_lshlrev_b32_e32 v70, 10, v72
	v_ashrrev_i32_e32 v71, 31, v70
	v_lshl_add_u64 v[70:71], v[70:71], 2, s[58:59]
	s_or_b64 exec, exec, s[0:1]
	v_lshl_add_u64 v[70:71], v[130:131], 2, v[70:71]
	global_load_dword v111, v[70:71], off
	global_load_dword v112, v[70:71], off offset:128
	v_or_b32_e32 v94, 0x43, v136
	v_min_i32_e32 v70, 0x403f, v94
	v_mul_hi_i32 v71, v70, s30
	v_lshrrev_b32_e32 v72, 31, v71
	v_ashrrev_i32_e32 v71, 11, v71
	v_add_u32_e32 v73, v71, v72
	v_mad_i32_i24 v72, v73, s31, v70
	v_cmp_lt_i32_e64 s[0:1], 15, v72
	s_and_saveexec_b64 s[10:11], s[0:1]
	s_xor_b64 s[0:1], exec, s[10:11]
	v_lshlrev_b32_e32 v70, 12, v73
	v_add3_u32 v70, v70, v72, -16
	v_ashrrev_i32_e32 v71, 31, v70
	v_lshlrev_b64 v[70:71], 12, v[70:71]
	v_lshl_add_u64 v[70:71], s[56:57], 0, v[70:71]
	s_andn2_saveexec_b64 s[0:1], s[0:1]
	v_lshlrev_b32_e32 v70, 10, v72
	v_ashrrev_i32_e32 v71, 31, v70
	v_lshl_add_u64 v[70:71], v[70:71], 2, s[58:59]
	s_or_b64 exec, exec, s[0:1]
	v_lshl_add_u64 v[70:71], v[130:131], 2, v[70:71]
	global_load_dword v113, v[70:71], off
	global_load_dword v114, v[70:71], off offset:128
	v_or_b32_e32 v92, 0x48, v136
	v_min_i32_e32 v70, 0x403f, v92
	v_mul_hi_i32 v71, v70, s30
	v_lshrrev_b32_e32 v72, 31, v71
	v_ashrrev_i32_e32 v71, 11, v71
	v_add_u32_e32 v73, v71, v72
	v_mad_i32_i24 v72, v73, s31, v70
	v_cmp_lt_i32_e64 s[0:1], 15, v72
	s_and_saveexec_b64 s[10:11], s[0:1]
	s_xor_b64 s[0:1], exec, s[10:11]
	v_lshlrev_b32_e32 v70, 12, v73
	v_add3_u32 v70, v70, v72, -16
	v_ashrrev_i32_e32 v71, 31, v70
	v_lshlrev_b64 v[70:71], 12, v[70:71]
	v_lshl_add_u64 v[70:71], s[56:57], 0, v[70:71]
	s_andn2_saveexec_b64 s[0:1], s[0:1]
	v_lshlrev_b32_e32 v70, 10, v72
	v_ashrrev_i32_e32 v71, 31, v70
	v_lshl_add_u64 v[70:71], v[70:71], 2, s[58:59]
	s_or_b64 exec, exec, s[0:1]
	v_lshl_add_u64 v[70:71], v[130:131], 2, v[70:71]
	global_load_dword v115, v[70:71], off
	global_load_dword v116, v[70:71], off offset:128
	v_or_b32_e32 v90, 0x49, v136
	v_min_i32_e32 v70, 0x403f, v90
	v_mul_hi_i32 v71, v70, s30
	v_lshrrev_b32_e32 v72, 31, v71
	v_ashrrev_i32_e32 v71, 11, v71
	v_add_u32_e32 v73, v71, v72
	v_mad_i32_i24 v72, v73, s31, v70
	v_cmp_lt_i32_e64 s[0:1], 15, v72
	s_and_saveexec_b64 s[10:11], s[0:1]
	s_xor_b64 s[0:1], exec, s[10:11]
	v_lshlrev_b32_e32 v70, 12, v73
	v_add3_u32 v70, v70, v72, -16
	v_ashrrev_i32_e32 v71, 31, v70
	v_lshlrev_b64 v[70:71], 12, v[70:71]
	v_lshl_add_u64 v[70:71], s[56:57], 0, v[70:71]
	s_andn2_saveexec_b64 s[0:1], s[0:1]
	v_lshlrev_b32_e32 v70, 10, v72
	v_ashrrev_i32_e32 v71, 31, v70
	v_lshl_add_u64 v[70:71], v[70:71], 2, s[58:59]
	s_or_b64 exec, exec, s[0:1]
	v_lshl_add_u64 v[70:71], v[130:131], 2, v[70:71]
	global_load_dword v117, v[70:71], off
	global_load_dword v118, v[70:71], off offset:128
	v_or_b32_e32 v88, 0x4a, v136
	v_min_i32_e32 v70, 0x403f, v88
	v_mul_hi_i32 v71, v70, s30
	v_lshrrev_b32_e32 v72, 31, v71
	v_ashrrev_i32_e32 v71, 11, v71
	v_add_u32_e32 v73, v71, v72
	v_mad_i32_i24 v72, v73, s31, v70
	v_cmp_lt_i32_e64 s[0:1], 15, v72
	s_and_saveexec_b64 s[10:11], s[0:1]
	s_xor_b64 s[0:1], exec, s[10:11]
	v_lshlrev_b32_e32 v70, 12, v73
	v_add3_u32 v70, v70, v72, -16
	v_ashrrev_i32_e32 v71, 31, v70
	v_lshlrev_b64 v[70:71], 12, v[70:71]
	v_lshl_add_u64 v[70:71], s[56:57], 0, v[70:71]
	s_andn2_saveexec_b64 s[0:1], s[0:1]
	v_lshlrev_b32_e32 v70, 10, v72
	v_ashrrev_i32_e32 v71, 31, v70
	v_lshl_add_u64 v[70:71], v[70:71], 2, s[58:59]
	s_or_b64 exec, exec, s[0:1]
	v_lshl_add_u64 v[70:71], v[130:131], 2, v[70:71]
	global_load_dword v119, v[70:71], off
	global_load_dword v120, v[70:71], off offset:128
	v_or_b32_e32 v86, 0x4b, v136
	v_min_i32_e32 v70, 0x403f, v86
	v_mul_hi_i32 v71, v70, s30
	v_lshrrev_b32_e32 v72, 31, v71
	v_ashrrev_i32_e32 v71, 11, v71
	v_add_u32_e32 v73, v71, v72
	v_mad_i32_i24 v72, v73, s31, v70
	v_cmp_lt_i32_e64 s[0:1], 15, v72
	s_and_saveexec_b64 s[10:11], s[0:1]
	s_xor_b64 s[0:1], exec, s[10:11]
	v_lshlrev_b32_e32 v70, 12, v73
	v_add3_u32 v70, v70, v72, -16
	v_ashrrev_i32_e32 v71, 31, v70
	v_lshlrev_b64 v[70:71], 12, v[70:71]
	v_lshl_add_u64 v[70:71], s[56:57], 0, v[70:71]
	s_andn2_saveexec_b64 s[0:1], s[0:1]
	v_lshlrev_b32_e32 v70, 10, v72
	v_ashrrev_i32_e32 v71, 31, v70
	v_lshl_add_u64 v[70:71], v[70:71], 2, s[58:59]
	s_or_b64 exec, exec, s[0:1]
	v_lshl_add_u64 v[70:71], v[130:131], 2, v[70:71]
	global_load_dword v121, v[70:71], off
	global_load_dword v122, v[70:71], off offset:128
	v_or_b32_e32 v84, 0x50, v136
	v_min_i32_e32 v70, 0x403f, v84
	v_mul_hi_i32 v71, v70, s30
	v_lshrrev_b32_e32 v72, 31, v71
	v_ashrrev_i32_e32 v71, 11, v71
	v_add_u32_e32 v73, v71, v72
	v_mad_i32_i24 v72, v73, s31, v70
	v_cmp_lt_i32_e64 s[0:1], 15, v72
	s_and_saveexec_b64 s[10:11], s[0:1]
	s_xor_b64 s[0:1], exec, s[10:11]
	v_lshlrev_b32_e32 v70, 12, v73
	v_add3_u32 v70, v70, v72, -16
	v_ashrrev_i32_e32 v71, 31, v70
	v_lshlrev_b64 v[70:71], 12, v[70:71]
	v_lshl_add_u64 v[70:71], s[56:57], 0, v[70:71]
	s_andn2_saveexec_b64 s[0:1], s[0:1]
	v_lshlrev_b32_e32 v70, 10, v72
	v_ashrrev_i32_e32 v71, 31, v70
	v_lshl_add_u64 v[70:71], v[70:71], 2, s[58:59]
	s_or_b64 exec, exec, s[0:1]
	v_lshl_add_u64 v[70:71], v[130:131], 2, v[70:71]
	global_load_dword v123, v[70:71], off
	global_load_dword v124, v[70:71], off offset:128
	v_or_b32_e32 v82, 0x51, v136
	v_min_i32_e32 v70, 0x403f, v82
	v_mul_hi_i32 v71, v70, s30
	v_lshrrev_b32_e32 v72, 31, v71
	v_ashrrev_i32_e32 v71, 11, v71
	v_add_u32_e32 v73, v71, v72
	v_mad_i32_i24 v72, v73, s31, v70
	v_cmp_lt_i32_e64 s[0:1], 15, v72
	s_and_saveexec_b64 s[10:11], s[0:1]
	s_xor_b64 s[0:1], exec, s[10:11]
	v_lshlrev_b32_e32 v70, 12, v73
	v_add3_u32 v70, v70, v72, -16
	v_ashrrev_i32_e32 v71, 31, v70
	v_lshlrev_b64 v[70:71], 12, v[70:71]
	v_lshl_add_u64 v[70:71], s[56:57], 0, v[70:71]
	s_andn2_saveexec_b64 s[0:1], s[0:1]
	v_lshlrev_b32_e32 v70, 10, v72
	v_ashrrev_i32_e32 v71, 31, v70
	v_lshl_add_u64 v[70:71], v[70:71], 2, s[58:59]
	s_or_b64 exec, exec, s[0:1]
	v_lshl_add_u64 v[70:71], v[130:131], 2, v[70:71]
	global_load_dword v125, v[70:71], off
	global_load_dword v126, v[70:71], off offset:128
	v_or_b32_e32 v80, 0x52, v136
	v_min_i32_e32 v70, 0x403f, v80
	v_mul_hi_i32 v71, v70, s30
	v_lshrrev_b32_e32 v72, 31, v71
	v_ashrrev_i32_e32 v71, 11, v71
	v_add_u32_e32 v73, v71, v72
	v_mad_i32_i24 v72, v73, s31, v70
	v_cmp_lt_i32_e64 s[0:1], 15, v72
	s_and_saveexec_b64 s[10:11], s[0:1]
	s_xor_b64 s[0:1], exec, s[10:11]
	v_lshlrev_b32_e32 v70, 12, v73
	v_add3_u32 v70, v70, v72, -16
	v_ashrrev_i32_e32 v71, 31, v70
	v_lshlrev_b64 v[70:71], 12, v[70:71]
	v_lshl_add_u64 v[70:71], s[56:57], 0, v[70:71]
	s_andn2_saveexec_b64 s[0:1], s[0:1]
	v_lshlrev_b32_e32 v70, 10, v72
	v_ashrrev_i32_e32 v71, 31, v70
	v_lshl_add_u64 v[70:71], v[70:71], 2, s[58:59]
	s_or_b64 exec, exec, s[0:1]
	v_lshl_add_u64 v[70:71], v[130:131], 2, v[70:71]
	global_load_dword v127, v[70:71], off
	global_load_dword v128, v[70:71], off offset:128
	v_or_b32_e32 v78, 0x53, v136
	v_min_i32_e32 v70, 0x403f, v78
	v_mul_hi_i32 v71, v70, s30
	v_lshrrev_b32_e32 v72, 31, v71
	v_ashrrev_i32_e32 v71, 11, v71
	v_add_u32_e32 v73, v71, v72
	v_mad_i32_i24 v72, v73, s31, v70
	v_cmp_lt_i32_e64 s[0:1], 15, v72
	s_and_saveexec_b64 s[10:11], s[0:1]
	s_xor_b64 s[0:1], exec, s[10:11]
	v_lshlrev_b32_e32 v70, 12, v73
	v_add3_u32 v70, v70, v72, -16
	v_ashrrev_i32_e32 v71, 31, v70
	v_lshlrev_b64 v[70:71], 12, v[70:71]
	v_lshl_add_u64 v[70:71], s[56:57], 0, v[70:71]
	s_andn2_saveexec_b64 s[0:1], s[0:1]
	v_lshlrev_b32_e32 v70, 10, v72
	v_ashrrev_i32_e32 v71, 31, v70
	v_lshl_add_u64 v[70:71], v[70:71], 2, s[58:59]
	s_or_b64 exec, exec, s[0:1]
	v_lshl_add_u64 v[70:71], v[130:131], 2, v[70:71]
	global_load_dword v129, v[70:71], off
	global_load_dword v137, v[70:71], off offset:128
	v_or_b32_e32 v76, 0x58, v136
	v_min_i32_e32 v70, 0x403f, v76
	v_mul_hi_i32 v71, v70, s30
	v_lshrrev_b32_e32 v72, 31, v71
	v_ashrrev_i32_e32 v71, 11, v71
	v_add_u32_e32 v73, v71, v72
	v_mad_i32_i24 v72, v73, s31, v70
	v_cmp_lt_i32_e64 s[0:1], 15, v72
	s_and_saveexec_b64 s[10:11], s[0:1]
	s_xor_b64 s[0:1], exec, s[10:11]
	v_lshlrev_b32_e32 v70, 12, v73
	v_add3_u32 v70, v70, v72, -16
	v_ashrrev_i32_e32 v71, 31, v70
	v_lshlrev_b64 v[70:71], 12, v[70:71]
	v_lshl_add_u64 v[70:71], s[56:57], 0, v[70:71]
	s_andn2_saveexec_b64 s[0:1], s[0:1]
	v_lshlrev_b32_e32 v70, 10, v72
	v_ashrrev_i32_e32 v71, 31, v70
	v_lshl_add_u64 v[70:71], v[70:71], 2, s[58:59]
	s_or_b64 exec, exec, s[0:1]
	v_lshl_add_u64 v[70:71], v[130:131], 2, v[70:71]
	global_load_dword v138, v[70:71], off
	global_load_dword v139, v[70:71], off offset:128
	v_or_b32_e32 v74, 0x59, v136
	v_min_i32_e32 v70, 0x403f, v74
	v_mul_hi_i32 v71, v70, s30
	v_lshrrev_b32_e32 v72, 31, v71
	v_ashrrev_i32_e32 v71, 11, v71
	v_add_u32_e32 v73, v71, v72
	v_mad_i32_i24 v72, v73, s31, v70
	v_cmp_lt_i32_e64 s[0:1], 15, v72
	s_and_saveexec_b64 s[10:11], s[0:1]
	s_xor_b64 s[0:1], exec, s[10:11]
	v_lshlrev_b32_e32 v70, 12, v73
	v_add3_u32 v70, v70, v72, -16
	v_ashrrev_i32_e32 v71, 31, v70
	v_lshlrev_b64 v[70:71], 12, v[70:71]
	v_lshl_add_u64 v[70:71], s[56:57], 0, v[70:71]
	s_andn2_saveexec_b64 s[0:1], s[0:1]
	v_lshlrev_b32_e32 v70, 10, v72
	v_ashrrev_i32_e32 v71, 31, v70
	v_lshl_add_u64 v[70:71], v[70:71], 2, s[58:59]
	s_or_b64 exec, exec, s[0:1]
	v_lshl_add_u64 v[70:71], v[130:131], 2, v[70:71]
	global_load_dword v140, v[70:71], off
	global_load_dword v141, v[70:71], off offset:128
	v_or_b32_e32 v72, 0x5a, v136
	v_min_i32_e32 v70, 0x403f, v72
	v_mul_hi_i32 v71, v70, s30
	v_lshrrev_b32_e32 v73, 31, v71
	v_ashrrev_i32_e32 v71, 11, v71
	v_add_u32_e32 v75, v71, v73
	v_mad_i32_i24 v73, v75, s31, v70
	v_cmp_lt_i32_e64 s[0:1], 15, v73
	s_and_saveexec_b64 s[10:11], s[0:1]
	s_xor_b64 s[0:1], exec, s[10:11]
	v_lshlrev_b32_e32 v70, 12, v75
	v_add3_u32 v70, v70, v73, -16
	v_ashrrev_i32_e32 v71, 31, v70
	v_lshlrev_b64 v[70:71], 12, v[70:71]
	v_lshl_add_u64 v[70:71], s[56:57], 0, v[70:71]
	s_andn2_saveexec_b64 s[0:1], s[0:1]
	v_lshlrev_b32_e32 v70, 10, v73
	v_ashrrev_i32_e32 v71, 31, v70
	v_lshl_add_u64 v[70:71], v[70:71], 2, s[58:59]
	s_or_b64 exec, exec, s[0:1]
	v_lshl_add_u64 v[70:71], v[130:131], 2, v[70:71]
	global_load_dword v142, v[70:71], off
	global_load_dword v143, v[70:71], off offset:128
	v_or_b32_e32 v70, 0x5b, v136
	v_min_i32_e32 v71, 0x403f, v70
	v_mul_hi_i32 v73, v71, s30
	v_lshrrev_b32_e32 v75, 31, v73
	v_ashrrev_i32_e32 v73, 11, v73
	v_add_u32_e32 v73, v73, v75
	v_mad_i32_i24 v71, v73, s31, v71
	v_cmp_lt_i32_e64 s[0:1], 15, v71
	s_and_saveexec_b64 s[10:11], s[0:1]
	s_xor_b64 s[0:1], exec, s[10:11]
	v_lshlrev_b32_e32 v73, 12, v73
	v_add3_u32 v102, v73, v71, -16
	v_ashrrev_i32_e32 v103, 31, v102
	v_lshlrev_b64 v[102:103], 12, v[102:103]
	v_lshl_add_u64 v[102:103], s[56:57], 0, v[102:103]
	s_andn2_saveexec_b64 s[0:1], s[0:1]
	v_lshlrev_b32_e32 v102, 10, v71
	v_ashrrev_i32_e32 v103, 31, v102
	v_lshl_add_u64 v[102:103], v[102:103], 2, s[58:59]
	s_or_b64 exec, exec, s[0:1]
	v_lshl_add_u64 v[102:103], v[130:131], 2, v[102:103]
	global_load_dword v144, v[102:103], off
	global_load_dword v145, v[102:103], off offset:128
	v_cmp_gt_i32_e64 s[10:11], s34, v100
	s_nop 1
	v_cndmask_b32_e64 v73, v179, v100, s[10:11]
	v_mul_hi_i32 v71, v73, s30
	v_lshrrev_b32_e32 v75, 31, v71
	v_ashrrev_i32_e32 v71, 11, v71
	v_add_u32_e32 v71, v71, v75
	v_mad_i32_i24 v73, v71, s31, v73
	v_cmp_lt_i32_e64 s[0:1], 15, v73
	s_and_saveexec_b64 s[36:37], s[0:1]
	s_xor_b64 s[0:1], exec, s[36:37]
	v_lshlrev_b32_e32 v71, 12, v71
	v_add3_u32 v102, v71, v73, -16
	v_ashrrev_i32_e32 v103, 31, v102
	v_lshlrev_b64 v[102:103], 12, v[102:103]
	v_lshl_add_u64 v[102:103], s[88:89], 0, v[102:103]
	s_andn2_saveexec_b64 s[0:1], s[0:1]
	v_lshlrev_b32_e32 v71, 14, v71
	v_lshl_add_u32 v102, v73, 10, v71
	v_ashrrev_i32_e32 v103, 31, v102
	v_lshl_add_u64 v[102:103], v[102:103], 2, s[12:13]
	s_or_b64 exec, exec, s[0:1]
	v_ashrrev_i32_e32 v101, 31, v100
	v_lshlrev_b64 v[100:101], 11, v[100:101]
	v_lshl_add_u64 v[100:101], s[62:63], 0, v[100:101]
	s_waitcnt vmcnt(31)
	v_fmac_f32_e32 v0, 0.5, v50
	v_lshl_add_u64 v[100:101], v[130:131], 1, v[100:101]
	v_lshl_add_u64 v[102:103], v[102:103], 0, v[134:135]
	global_store_dword v[102:103], v0, off
	v_mul_f32_e32 v50, v0, v242
	v_cvt_pk_bf16_f32 v50, v50, s0
	global_store_short v[100:101], v50, off
.LBB0_1113:
	s_waitcnt vmcnt(30)
	v_fmac_f32_e32 v67, 0.5, v34
	global_store_dword v[102:103], v67, off offset:128
	v_mul_f32_e32 v34, v67, v243
	v_cvt_pk_bf16_f32 v34, v34, s0
	global_store_short v[100:101], v34, off offset:64
.LBB0_1115:
	v_cmp_gt_i32_e64 s[10:11], s34, v98
	s_nop 1
	v_cndmask_b32_e64 v50, v179, v98, s[10:11]
	v_mul_hi_i32 v34, v50, s30
	v_lshrrev_b32_e32 v71, 31, v34
	v_ashrrev_i32_e32 v34, 11, v34
	v_add_u32_e32 v34, v34, v71
	v_mad_i32_i24 v50, v34, s31, v50
	v_cmp_lt_i32_e64 s[0:1], 15, v50
	s_and_saveexec_b64 s[36:37], s[0:1]
	s_xor_b64 s[0:1], exec, s[36:37]
	v_lshlrev_b32_e32 v34, 12, v34
	v_add3_u32 v100, v34, v50, -16
	v_ashrrev_i32_e32 v101, 31, v100
	v_lshlrev_b64 v[100:101], 12, v[100:101]
	v_lshl_add_u64 v[100:101], s[88:89], 0, v[100:101]
	s_andn2_saveexec_b64 s[0:1], s[0:1]
	v_lshlrev_b32_e32 v34, 14, v34
	v_lshl_add_u32 v100, v50, 10, v34
	v_ashrrev_i32_e32 v101, 31, v100
	v_lshl_add_u64 v[100:101], v[100:101], 2, s[12:13]
	s_or_b64 exec, exec, s[0:1]
	v_ashrrev_i32_e32 v99, 31, v98
	v_lshlrev_b64 v[98:99], 11, v[98:99]
	v_lshl_add_u64 v[98:99], s[62:63], 0, v[98:99]
	s_waitcnt vmcnt(29)
	v_fmac_f32_e32 v109, 0.5, v51
	v_lshl_add_u64 v[50:51], v[130:131], 1, v[98:99]
	v_lshl_add_u64 v[98:99], v[100:101], 0, v[134:135]
	global_store_dword v[98:99], v109, off
	v_mul_f32_e32 v34, v109, v242
	v_cvt_pk_bf16_f32 v34, v34, s0
	global_store_short v[50:51], v34, off
.LBB0_1121:
	s_waitcnt vmcnt(28)
	v_fmac_f32_e32 v110, 0.5, v35
	global_store_dword v[98:99], v110, off offset:128
	v_mul_f32_e32 v34, v110, v243
	v_cvt_pk_bf16_f32 v34, v34, s0
	global_store_short v[50:51], v34, off offset:64
.LBB0_1123:
	v_cmp_gt_i32_e64 s[10:11], s34, v96
	s_nop 1
	v_cndmask_b32_e64 v34, v179, v96, s[10:11]
	v_mul_hi_i32 v35, v34, s30
	v_lshrrev_b32_e32 v50, 31, v35
	v_ashrrev_i32_e32 v35, 11, v35
	v_add_u32_e32 v50, v35, v50
	v_mad_i32_i24 v51, v50, s31, v34
	v_cmp_lt_i32_e64 s[0:1], 15, v51
	s_and_saveexec_b64 s[36:37], s[0:1]
	s_xor_b64 s[0:1], exec, s[36:37]
	v_lshlrev_b32_e32 v34, 12, v50
	v_add3_u32 v34, v34, v51, -16
	v_ashrrev_i32_e32 v35, 31, v34
	v_lshlrev_b64 v[34:35], 12, v[34:35]
	v_lshl_add_u64 v[34:35], s[88:89], 0, v[34:35]
	s_andn2_saveexec_b64 s[0:1], s[0:1]
	v_lshlrev_b32_e32 v34, 14, v50
	v_lshl_add_u32 v34, v51, 10, v34
	v_ashrrev_i32_e32 v35, 31, v34
	v_lshl_add_u64 v[34:35], v[34:35], 2, s[12:13]
	s_or_b64 exec, exec, s[0:1]
	v_ashrrev_i32_e32 v97, 31, v96
	v_lshlrev_b64 v[50:51], 11, v[96:97]
	v_lshl_add_u64 v[50:51], s[62:63], 0, v[50:51]
	s_waitcnt vmcnt(27)
	v_fmac_f32_e32 v111, 0.5, v52
	v_lshl_add_u64 v[50:51], v[130:131], 1, v[50:51]
	v_lshl_add_u64 v[34:35], v[34:35], 0, v[134:135]
	global_store_dword v[34:35], v111, off
	v_mul_f32_e32 v52, v111, v242
	v_cvt_pk_bf16_f32 v52, v52, s0
	global_store_short v[50:51], v52, off
.LBB0_1129:
	s_waitcnt vmcnt(26)
	v_fmac_f32_e32 v112, 0.5, v36
	global_store_dword v[34:35], v112, off offset:128
	v_mul_f32_e32 v34, v112, v243
	v_cvt_pk_bf16_f32 v34, v34, s0
	global_store_short v[50:51], v34, off offset:64
.LBB0_1131:
	v_cmp_gt_i32_e64 s[10:11], s34, v94
	s_nop 1
	v_cndmask_b32_e64 v34, v179, v94, s[10:11]
	v_mul_hi_i32 v35, v34, s30
	v_lshrrev_b32_e32 v36, 31, v35
	v_ashrrev_i32_e32 v35, 11, v35
	v_add_u32_e32 v36, v35, v36
	v_mad_i32_i24 v50, v36, s31, v34
	v_cmp_lt_i32_e64 s[0:1], 15, v50
	s_and_saveexec_b64 s[36:37], s[0:1]
	s_xor_b64 s[0:1], exec, s[36:37]
	v_lshlrev_b32_e32 v34, 12, v36
	v_add3_u32 v34, v34, v50, -16
	v_ashrrev_i32_e32 v35, 31, v34
	v_lshlrev_b64 v[34:35], 12, v[34:35]
	v_lshl_add_u64 v[34:35], s[88:89], 0, v[34:35]
	s_andn2_saveexec_b64 s[0:1], s[0:1]
	v_lshlrev_b32_e32 v34, 14, v36
	v_lshl_add_u32 v34, v50, 10, v34
	v_ashrrev_i32_e32 v35, 31, v34
	v_lshl_add_u64 v[34:35], v[34:35], 2, s[12:13]
	s_or_b64 exec, exec, s[0:1]
	v_ashrrev_i32_e32 v95, 31, v94
	v_lshlrev_b64 v[50:51], 11, v[94:95]
	v_lshl_add_u64 v[50:51], s[62:63], 0, v[50:51]
	s_waitcnt vmcnt(25)
	v_fmac_f32_e32 v113, 0.5, v53
	v_lshl_add_u64 v[50:51], v[130:131], 1, v[50:51]
	v_lshl_add_u64 v[34:35], v[34:35], 0, v[134:135]
	global_store_dword v[34:35], v113, off
	v_mul_f32_e32 v36, v113, v242
	v_cvt_pk_bf16_f32 v36, v36, s0
	global_store_short v[50:51], v36, off
.LBB0_1137:
	s_waitcnt vmcnt(24)
	v_fmac_f32_e32 v114, 0.5, v37
	global_store_dword v[34:35], v114, off offset:128
	v_mul_f32_e32 v34, v114, v243
	v_cvt_pk_bf16_f32 v34, v34, s0
	global_store_short v[50:51], v34, off offset:64
.LBB0_1139:
	v_cmp_gt_i32_e64 s[10:11], s34, v92
	s_nop 1
	v_cndmask_b32_e64 v34, v179, v92, s[10:11]
	v_mul_hi_i32 v35, v34, s30
	v_lshrrev_b32_e32 v36, 31, v35
	v_ashrrev_i32_e32 v35, 11, v35
	v_add_u32_e32 v36, v35, v36
	v_mad_i32_i24 v37, v36, s31, v34
	v_cmp_lt_i32_e64 s[0:1], 15, v37
	s_and_saveexec_b64 s[36:37], s[0:1]
	s_xor_b64 s[0:1], exec, s[36:37]
	v_lshlrev_b32_e32 v34, 12, v36
	v_add3_u32 v34, v34, v37, -16
	v_ashrrev_i32_e32 v35, 31, v34
	v_lshlrev_b64 v[34:35], 12, v[34:35]
	v_lshl_add_u64 v[34:35], s[88:89], 0, v[34:35]
	s_andn2_saveexec_b64 s[0:1], s[0:1]
	v_lshlrev_b32_e32 v34, 14, v36
	v_lshl_add_u32 v34, v37, 10, v34
	v_ashrrev_i32_e32 v35, 31, v34
	v_lshl_add_u64 v[34:35], v[34:35], 2, s[12:13]
	s_or_b64 exec, exec, s[0:1]
	v_ashrrev_i32_e32 v93, 31, v92
	v_lshlrev_b64 v[36:37], 11, v[92:93]
	v_lshl_add_u64 v[36:37], s[62:63], 0, v[36:37]
	s_waitcnt vmcnt(23)
	v_fmac_f32_e32 v115, 0.5, v54
	v_lshl_add_u64 v[36:37], v[130:131], 1, v[36:37]
	v_lshl_add_u64 v[34:35], v[34:35], 0, v[134:135]
	global_store_dword v[34:35], v115, off
	v_mul_f32_e32 v50, v115, v242
	v_cvt_pk_bf16_f32 v50, v50, s0
	global_store_short v[36:37], v50, off
.LBB0_1145:
	s_waitcnt vmcnt(22)
	v_fmac_f32_e32 v116, 0.5, v38
	global_store_dword v[34:35], v116, off offset:128
	v_mul_f32_e32 v34, v116, v243
	v_cvt_pk_bf16_f32 v34, v34, s0
	global_store_short v[36:37], v34, off offset:64
.LBB0_1147:
	v_cmp_gt_i32_e64 s[10:11], s34, v90
	s_nop 1
	v_cndmask_b32_e64 v34, v179, v90, s[10:11]
	v_mul_hi_i32 v35, v34, s30
	v_lshrrev_b32_e32 v36, 31, v35
	v_ashrrev_i32_e32 v35, 11, v35
	v_add_u32_e32 v36, v35, v36
	v_mad_i32_i24 v37, v36, s31, v34
	v_cmp_lt_i32_e64 s[0:1], 15, v37
	s_and_saveexec_b64 s[36:37], s[0:1]
	s_xor_b64 s[0:1], exec, s[36:37]
	v_lshlrev_b32_e32 v34, 12, v36
	v_add3_u32 v34, v34, v37, -16
	v_ashrrev_i32_e32 v35, 31, v34
	v_lshlrev_b64 v[34:35], 12, v[34:35]
	v_lshl_add_u64 v[34:35], s[88:89], 0, v[34:35]
	s_andn2_saveexec_b64 s[0:1], s[0:1]
	v_lshlrev_b32_e32 v34, 14, v36
	v_lshl_add_u32 v34, v37, 10, v34
	v_ashrrev_i32_e32 v35, 31, v34
	v_lshl_add_u64 v[34:35], v[34:35], 2, s[12:13]
	s_or_b64 exec, exec, s[0:1]
	v_ashrrev_i32_e32 v91, 31, v90
	v_lshlrev_b64 v[36:37], 11, v[90:91]
	v_lshl_add_u64 v[36:37], s[62:63], 0, v[36:37]
	s_waitcnt vmcnt(21)
	v_fmac_f32_e32 v117, 0.5, v55
	v_lshl_add_u64 v[36:37], v[130:131], 1, v[36:37]
	v_lshl_add_u64 v[34:35], v[34:35], 0, v[134:135]
	global_store_dword v[34:35], v117, off
	v_mul_f32_e32 v38, v117, v242
	v_cvt_pk_bf16_f32 v38, v38, s0
	global_store_short v[36:37], v38, off
.LBB0_1153:
	s_waitcnt vmcnt(20)
	v_fmac_f32_e32 v118, 0.5, v39
	global_store_dword v[34:35], v118, off offset:128
	v_mul_f32_e32 v34, v118, v243
	v_cvt_pk_bf16_f32 v34, v34, s0
	global_store_short v[36:37], v34, off offset:64
.LBB0_1155:
	v_cmp_gt_i32_e64 s[10:11], s34, v88
	s_nop 1
	v_cndmask_b32_e64 v34, v179, v88, s[10:11]
	v_mul_hi_i32 v35, v34, s30
	v_lshrrev_b32_e32 v36, 31, v35
	v_ashrrev_i32_e32 v35, 11, v35
	v_add_u32_e32 v36, v35, v36
	v_mad_i32_i24 v37, v36, s31, v34
	v_cmp_lt_i32_e64 s[0:1], 15, v37
	s_and_saveexec_b64 s[36:37], s[0:1]
	s_xor_b64 s[0:1], exec, s[36:37]
	v_lshlrev_b32_e32 v34, 12, v36
	v_add3_u32 v34, v34, v37, -16
	v_ashrrev_i32_e32 v35, 31, v34
	v_lshlrev_b64 v[34:35], 12, v[34:35]
	v_lshl_add_u64 v[34:35], s[88:89], 0, v[34:35]
	s_andn2_saveexec_b64 s[0:1], s[0:1]
	v_lshlrev_b32_e32 v34, 14, v36
	v_lshl_add_u32 v34, v37, 10, v34
	v_ashrrev_i32_e32 v35, 31, v34
	v_lshl_add_u64 v[34:35], v[34:35], 2, s[12:13]
	s_or_b64 exec, exec, s[0:1]
	v_ashrrev_i32_e32 v89, 31, v88
	v_lshlrev_b64 v[36:37], 11, v[88:89]
	v_lshl_add_u64 v[36:37], s[62:63], 0, v[36:37]
	s_waitcnt vmcnt(19)
	v_fmac_f32_e32 v119, 0.5, v56
	v_lshl_add_u64 v[36:37], v[130:131], 1, v[36:37]
	v_lshl_add_u64 v[34:35], v[34:35], 0, v[134:135]
	global_store_dword v[34:35], v119, off
	v_mul_f32_e32 v38, v119, v242
	v_cvt_pk_bf16_f32 v38, v38, s0
	global_store_short v[36:37], v38, off
.LBB0_1161:
	s_waitcnt vmcnt(18)
	v_fmac_f32_e32 v120, 0.5, v40
	global_store_dword v[34:35], v120, off offset:128
	v_mul_f32_e32 v34, v120, v243
	v_cvt_pk_bf16_f32 v34, v34, s0
	global_store_short v[36:37], v34, off offset:64
.LBB0_1163:
	v_cmp_gt_i32_e64 s[10:11], s34, v86
	s_nop 1
	v_cndmask_b32_e64 v34, v179, v86, s[10:11]
	v_mul_hi_i32 v35, v34, s30
	v_lshrrev_b32_e32 v36, 31, v35
	v_ashrrev_i32_e32 v35, 11, v35
	v_add_u32_e32 v36, v35, v36
	v_mad_i32_i24 v37, v36, s31, v34
	v_cmp_lt_i32_e64 s[0:1], 15, v37
	s_and_saveexec_b64 s[36:37], s[0:1]
	s_xor_b64 s[0:1], exec, s[36:37]
	v_lshlrev_b32_e32 v34, 12, v36
	v_add3_u32 v34, v34, v37, -16
	v_ashrrev_i32_e32 v35, 31, v34
	v_lshlrev_b64 v[34:35], 12, v[34:35]
	v_lshl_add_u64 v[34:35], s[88:89], 0, v[34:35]
	s_andn2_saveexec_b64 s[0:1], s[0:1]
	v_lshlrev_b32_e32 v34, 14, v36
	v_lshl_add_u32 v34, v37, 10, v34
	v_ashrrev_i32_e32 v35, 31, v34
	v_lshl_add_u64 v[34:35], v[34:35], 2, s[12:13]
	s_or_b64 exec, exec, s[0:1]
	v_ashrrev_i32_e32 v87, 31, v86
	v_lshlrev_b64 v[36:37], 11, v[86:87]
	v_lshl_add_u64 v[36:37], s[62:63], 0, v[36:37]
	s_waitcnt vmcnt(17)
	v_fmac_f32_e32 v121, 0.5, v57
	v_lshl_add_u64 v[36:37], v[130:131], 1, v[36:37]
	v_lshl_add_u64 v[34:35], v[34:35], 0, v[134:135]
	global_store_dword v[34:35], v121, off
	v_mul_f32_e32 v38, v121, v242
	v_cvt_pk_bf16_f32 v38, v38, s0
	global_store_short v[36:37], v38, off
.LBB0_1169:
	s_waitcnt vmcnt(16)
	v_fmac_f32_e32 v122, 0.5, v41
	global_store_dword v[34:35], v122, off offset:128
	v_mul_f32_e32 v34, v122, v243
	v_cvt_pk_bf16_f32 v34, v34, s0
	global_store_short v[36:37], v34, off offset:64
.LBB0_1171:
	v_cmp_gt_i32_e64 s[10:11], s34, v84
	s_nop 1
	v_cndmask_b32_e64 v34, v179, v84, s[10:11]
	v_mul_hi_i32 v35, v34, s30
	v_lshrrev_b32_e32 v36, 31, v35
	v_ashrrev_i32_e32 v35, 11, v35
	v_add_u32_e32 v36, v35, v36
	v_mad_i32_i24 v37, v36, s31, v34
	v_cmp_lt_i32_e64 s[0:1], 15, v37
	s_and_saveexec_b64 s[36:37], s[0:1]
	s_xor_b64 s[0:1], exec, s[36:37]
	v_lshlrev_b32_e32 v34, 12, v36
	v_add3_u32 v34, v34, v37, -16
	v_ashrrev_i32_e32 v35, 31, v34
	v_lshlrev_b64 v[34:35], 12, v[34:35]
	v_lshl_add_u64 v[34:35], s[88:89], 0, v[34:35]
	s_andn2_saveexec_b64 s[0:1], s[0:1]
	v_lshlrev_b32_e32 v34, 14, v36
	v_lshl_add_u32 v34, v37, 10, v34
	v_ashrrev_i32_e32 v35, 31, v34
	v_lshl_add_u64 v[34:35], v[34:35], 2, s[12:13]
	s_or_b64 exec, exec, s[0:1]
	v_ashrrev_i32_e32 v85, 31, v84
	v_lshlrev_b64 v[36:37], 11, v[84:85]
	v_lshl_add_u64 v[36:37], s[62:63], 0, v[36:37]
	s_waitcnt vmcnt(15)
	v_fmac_f32_e32 v123, 0.5, v58
	v_lshl_add_u64 v[36:37], v[130:131], 1, v[36:37]
	v_lshl_add_u64 v[34:35], v[34:35], 0, v[134:135]
	global_store_dword v[34:35], v123, off
	v_mul_f32_e32 v38, v123, v242
	v_cvt_pk_bf16_f32 v38, v38, s0
	global_store_short v[36:37], v38, off
.LBB0_1177:
	s_waitcnt vmcnt(14)
	v_fmac_f32_e32 v124, 0.5, v42
	global_store_dword v[34:35], v124, off offset:128
	v_mul_f32_e32 v34, v124, v243
	v_cvt_pk_bf16_f32 v34, v34, s0
	global_store_short v[36:37], v34, off offset:64
.LBB0_1179:
	v_cmp_gt_i32_e64 s[10:11], s34, v82
	s_nop 1
	v_cndmask_b32_e64 v34, v179, v82, s[10:11]
	v_mul_hi_i32 v35, v34, s30
	v_lshrrev_b32_e32 v36, 31, v35
	v_ashrrev_i32_e32 v35, 11, v35
	v_add_u32_e32 v36, v35, v36
	v_mad_i32_i24 v37, v36, s31, v34
	v_cmp_lt_i32_e64 s[0:1], 15, v37
	s_and_saveexec_b64 s[36:37], s[0:1]
	s_xor_b64 s[0:1], exec, s[36:37]
	v_lshlrev_b32_e32 v34, 12, v36
	v_add3_u32 v34, v34, v37, -16
	v_ashrrev_i32_e32 v35, 31, v34
	v_lshlrev_b64 v[34:35], 12, v[34:35]
	v_lshl_add_u64 v[34:35], s[88:89], 0, v[34:35]
	s_andn2_saveexec_b64 s[0:1], s[0:1]
	v_lshlrev_b32_e32 v34, 14, v36
	v_lshl_add_u32 v34, v37, 10, v34
	v_ashrrev_i32_e32 v35, 31, v34
	v_lshl_add_u64 v[34:35], v[34:35], 2, s[12:13]
	s_or_b64 exec, exec, s[0:1]
	v_ashrrev_i32_e32 v83, 31, v82
	v_lshlrev_b64 v[36:37], 11, v[82:83]
	v_lshl_add_u64 v[36:37], s[62:63], 0, v[36:37]
	s_waitcnt vmcnt(13)
	v_fmac_f32_e32 v125, 0.5, v59
	v_lshl_add_u64 v[36:37], v[130:131], 1, v[36:37]
	v_lshl_add_u64 v[34:35], v[34:35], 0, v[134:135]
	global_store_dword v[34:35], v125, off
	v_mul_f32_e32 v38, v125, v242
	v_cvt_pk_bf16_f32 v38, v38, s0
	global_store_short v[36:37], v38, off
.LBB0_1185:
	s_waitcnt vmcnt(12)
	v_fmac_f32_e32 v126, 0.5, v43
	global_store_dword v[34:35], v126, off offset:128
	v_mul_f32_e32 v34, v126, v243
	v_cvt_pk_bf16_f32 v34, v34, s0
	global_store_short v[36:37], v34, off offset:64
.LBB0_1187:
	v_cmp_gt_i32_e64 s[10:11], s34, v80
	s_nop 1
	v_cndmask_b32_e64 v34, v179, v80, s[10:11]
	v_mul_hi_i32 v35, v34, s30
	v_lshrrev_b32_e32 v36, 31, v35
	v_ashrrev_i32_e32 v35, 11, v35
	v_add_u32_e32 v36, v35, v36
	v_mad_i32_i24 v37, v36, s31, v34
	v_cmp_lt_i32_e64 s[0:1], 15, v37
	s_and_saveexec_b64 s[36:37], s[0:1]
	s_xor_b64 s[0:1], exec, s[36:37]
	v_lshlrev_b32_e32 v34, 12, v36
	v_add3_u32 v34, v34, v37, -16
	v_ashrrev_i32_e32 v35, 31, v34
	v_lshlrev_b64 v[34:35], 12, v[34:35]
	v_lshl_add_u64 v[34:35], s[88:89], 0, v[34:35]
	s_andn2_saveexec_b64 s[0:1], s[0:1]
	v_lshlrev_b32_e32 v34, 14, v36
	v_lshl_add_u32 v34, v37, 10, v34
	v_ashrrev_i32_e32 v35, 31, v34
	v_lshl_add_u64 v[34:35], v[34:35], 2, s[12:13]
	s_or_b64 exec, exec, s[0:1]
	v_ashrrev_i32_e32 v81, 31, v80
	v_lshlrev_b64 v[36:37], 11, v[80:81]
	v_lshl_add_u64 v[36:37], s[62:63], 0, v[36:37]
	s_waitcnt vmcnt(11)
	v_fmac_f32_e32 v127, 0.5, v60
	v_lshl_add_u64 v[36:37], v[130:131], 1, v[36:37]
	v_lshl_add_u64 v[34:35], v[34:35], 0, v[134:135]
	global_store_dword v[34:35], v127, off
	v_mul_f32_e32 v38, v127, v242
	v_cvt_pk_bf16_f32 v38, v38, s0
	global_store_short v[36:37], v38, off
.LBB0_1193:
	s_waitcnt vmcnt(10)
	v_fmac_f32_e32 v128, 0.5, v44
	global_store_dword v[34:35], v128, off offset:128
	v_mul_f32_e32 v34, v128, v243
	v_cvt_pk_bf16_f32 v34, v34, s0
	global_store_short v[36:37], v34, off offset:64
.LBB0_1195:
	v_cmp_gt_i32_e64 s[10:11], s34, v78
	s_nop 1
	v_cndmask_b32_e64 v34, v179, v78, s[10:11]
	v_mul_hi_i32 v35, v34, s30
	v_lshrrev_b32_e32 v36, 31, v35
	v_ashrrev_i32_e32 v35, 11, v35
	v_add_u32_e32 v36, v35, v36
	v_mad_i32_i24 v37, v36, s31, v34
	v_cmp_lt_i32_e64 s[0:1], 15, v37
	s_and_saveexec_b64 s[36:37], s[0:1]
	s_xor_b64 s[0:1], exec, s[36:37]
	v_lshlrev_b32_e32 v34, 12, v36
	v_add3_u32 v34, v34, v37, -16
	v_ashrrev_i32_e32 v35, 31, v34
	v_lshlrev_b64 v[34:35], 12, v[34:35]
	v_lshl_add_u64 v[34:35], s[88:89], 0, v[34:35]
	s_andn2_saveexec_b64 s[0:1], s[0:1]
	v_lshlrev_b32_e32 v34, 14, v36
	v_lshl_add_u32 v34, v37, 10, v34
	v_ashrrev_i32_e32 v35, 31, v34
	v_lshl_add_u64 v[34:35], v[34:35], 2, s[12:13]
	s_or_b64 exec, exec, s[0:1]
	v_ashrrev_i32_e32 v79, 31, v78
	v_lshlrev_b64 v[36:37], 11, v[78:79]
	v_lshl_add_u64 v[36:37], s[62:63], 0, v[36:37]
	s_waitcnt vmcnt(9)
	v_fmac_f32_e32 v129, 0.5, v61
	v_lshl_add_u64 v[36:37], v[130:131], 1, v[36:37]
	v_lshl_add_u64 v[34:35], v[34:35], 0, v[134:135]
	global_store_dword v[34:35], v129, off
	v_mul_f32_e32 v38, v129, v242
	v_cvt_pk_bf16_f32 v38, v38, s0
	global_store_short v[36:37], v38, off
.LBB0_1201:
	s_waitcnt vmcnt(8)
	v_fmac_f32_e32 v137, 0.5, v45
	global_store_dword v[34:35], v137, off offset:128
	v_mul_f32_e32 v34, v137, v243
	v_cvt_pk_bf16_f32 v34, v34, s0
	global_store_short v[36:37], v34, off offset:64
.LBB0_1203:
	v_cmp_gt_i32_e64 s[10:11], s34, v76
	s_nop 1
	v_cndmask_b32_e64 v34, v179, v76, s[10:11]
	v_mul_hi_i32 v35, v34, s30
	v_lshrrev_b32_e32 v36, 31, v35
	v_ashrrev_i32_e32 v35, 11, v35
	v_add_u32_e32 v36, v35, v36
	v_mad_i32_i24 v37, v36, s31, v34
	v_cmp_lt_i32_e64 s[0:1], 15, v37
	s_and_saveexec_b64 s[36:37], s[0:1]
	s_xor_b64 s[0:1], exec, s[36:37]
	v_lshlrev_b32_e32 v34, 12, v36
	v_add3_u32 v34, v34, v37, -16
	v_ashrrev_i32_e32 v35, 31, v34
	v_lshlrev_b64 v[34:35], 12, v[34:35]
	v_lshl_add_u64 v[34:35], s[88:89], 0, v[34:35]
	s_andn2_saveexec_b64 s[0:1], s[0:1]
	v_lshlrev_b32_e32 v34, 14, v36
	v_lshl_add_u32 v34, v37, 10, v34
	v_ashrrev_i32_e32 v35, 31, v34
	v_lshl_add_u64 v[34:35], v[34:35], 2, s[12:13]
	s_or_b64 exec, exec, s[0:1]
	v_ashrrev_i32_e32 v77, 31, v76
	v_lshlrev_b64 v[36:37], 11, v[76:77]
	v_lshl_add_u64 v[36:37], s[62:63], 0, v[36:37]
	s_waitcnt vmcnt(7)
	v_fmac_f32_e32 v138, 0.5, v62
	v_lshl_add_u64 v[36:37], v[130:131], 1, v[36:37]
	v_lshl_add_u64 v[34:35], v[34:35], 0, v[134:135]
	global_store_dword v[34:35], v138, off
	v_mul_f32_e32 v38, v138, v242
	v_cvt_pk_bf16_f32 v38, v38, s0
	global_store_short v[36:37], v38, off
.LBB0_1209:
	s_waitcnt vmcnt(6)
	v_fmac_f32_e32 v139, 0.5, v46
	global_store_dword v[34:35], v139, off offset:128
	v_mul_f32_e32 v34, v139, v243
	v_cvt_pk_bf16_f32 v34, v34, s0
	global_store_short v[36:37], v34, off offset:64
.LBB0_1211:
	v_cmp_gt_i32_e64 s[10:11], s34, v74
	s_nop 1
	v_cndmask_b32_e64 v34, v179, v74, s[10:11]
	v_mul_hi_i32 v35, v34, s30
	v_lshrrev_b32_e32 v36, 31, v35
	v_ashrrev_i32_e32 v35, 11, v35
	v_add_u32_e32 v36, v35, v36
	v_mad_i32_i24 v37, v36, s31, v34
	v_cmp_lt_i32_e64 s[0:1], 15, v37
	s_and_saveexec_b64 s[36:37], s[0:1]
	s_xor_b64 s[0:1], exec, s[36:37]
	v_lshlrev_b32_e32 v34, 12, v36
	v_add3_u32 v34, v34, v37, -16
	v_ashrrev_i32_e32 v35, 31, v34
	v_lshlrev_b64 v[34:35], 12, v[34:35]
	v_lshl_add_u64 v[34:35], s[88:89], 0, v[34:35]
	s_andn2_saveexec_b64 s[0:1], s[0:1]
	v_lshlrev_b32_e32 v34, 14, v36
	v_lshl_add_u32 v34, v37, 10, v34
	v_ashrrev_i32_e32 v35, 31, v34
	v_lshl_add_u64 v[34:35], v[34:35], 2, s[12:13]
	s_or_b64 exec, exec, s[0:1]
	v_ashrrev_i32_e32 v75, 31, v74
	v_lshlrev_b64 v[36:37], 11, v[74:75]
	v_lshl_add_u64 v[36:37], s[62:63], 0, v[36:37]
	s_waitcnt vmcnt(5)
	v_fmac_f32_e32 v140, 0.5, v63
	v_lshl_add_u64 v[36:37], v[130:131], 1, v[36:37]
	v_lshl_add_u64 v[34:35], v[34:35], 0, v[134:135]
	global_store_dword v[34:35], v140, off
	v_mul_f32_e32 v38, v140, v242
	v_cvt_pk_bf16_f32 v38, v38, s0
	global_store_short v[36:37], v38, off
.LBB0_1217:
	s_waitcnt vmcnt(4)
	v_fmac_f32_e32 v141, 0.5, v47
	global_store_dword v[34:35], v141, off offset:128
	v_mul_f32_e32 v34, v141, v243
	v_cvt_pk_bf16_f32 v34, v34, s0
	global_store_short v[36:37], v34, off offset:64
.LBB0_1219:
	v_cmp_gt_i32_e64 s[10:11], s34, v72
	s_nop 1
	v_cndmask_b32_e64 v34, v179, v72, s[10:11]
	v_mul_hi_i32 v35, v34, s30
	v_lshrrev_b32_e32 v36, 31, v35
	v_ashrrev_i32_e32 v35, 11, v35
	v_add_u32_e32 v36, v35, v36
	v_mad_i32_i24 v37, v36, s31, v34
	v_cmp_lt_i32_e64 s[0:1], 15, v37
	s_and_saveexec_b64 s[36:37], s[0:1]
	s_xor_b64 s[0:1], exec, s[36:37]
	v_lshlrev_b32_e32 v34, 12, v36
	v_add3_u32 v34, v34, v37, -16
	v_ashrrev_i32_e32 v35, 31, v34
	v_lshlrev_b64 v[34:35], 12, v[34:35]
	v_lshl_add_u64 v[34:35], s[88:89], 0, v[34:35]
	s_andn2_saveexec_b64 s[0:1], s[0:1]
	v_lshlrev_b32_e32 v34, 14, v36
	v_lshl_add_u32 v34, v37, 10, v34
	v_ashrrev_i32_e32 v35, 31, v34
	v_lshl_add_u64 v[34:35], v[34:35], 2, s[12:13]
	s_or_b64 exec, exec, s[0:1]
	v_ashrrev_i32_e32 v73, 31, v72
	v_lshlrev_b64 v[36:37], 11, v[72:73]
	v_lshl_add_u64 v[36:37], s[62:63], 0, v[36:37]
	s_waitcnt vmcnt(3)
	v_fmac_f32_e32 v142, 0.5, v64
	v_lshl_add_u64 v[36:37], v[130:131], 1, v[36:37]
	v_lshl_add_u64 v[34:35], v[34:35], 0, v[134:135]
	global_store_dword v[34:35], v142, off
	v_mul_f32_e32 v38, v142, v242
	v_cvt_pk_bf16_f32 v38, v38, s0
	global_store_short v[36:37], v38, off
.LBB0_1225:
	s_waitcnt vmcnt(2)
	v_fmac_f32_e32 v143, 0.5, v48
	global_store_dword v[34:35], v143, off offset:128
	v_mul_f32_e32 v34, v143, v243
	v_cvt_pk_bf16_f32 v34, v34, s0
	global_store_short v[36:37], v34, off offset:64
.LBB0_1227:
	v_cmp_gt_i32_e64 s[10:11], s34, v70
	s_nop 1
	v_cndmask_b32_e64 v34, v179, v70, s[10:11]
	v_mul_hi_i32 v35, v34, s30
	v_lshrrev_b32_e32 v36, 31, v35
	v_ashrrev_i32_e32 v35, 11, v35
	v_add_u32_e32 v36, v35, v36
	v_mad_i32_i24 v37, v36, s31, v34
	v_cmp_lt_i32_e64 s[0:1], 15, v37
	s_and_saveexec_b64 s[36:37], s[0:1]
	s_xor_b64 s[0:1], exec, s[36:37]
	v_lshlrev_b32_e32 v34, 12, v36
	v_add3_u32 v34, v34, v37, -16
	v_ashrrev_i32_e32 v35, 31, v34
	v_lshlrev_b64 v[34:35], 12, v[34:35]
	v_lshl_add_u64 v[34:35], s[88:89], 0, v[34:35]
	s_andn2_saveexec_b64 s[0:1], s[0:1]
	v_lshlrev_b32_e32 v34, 14, v36
	v_lshl_add_u32 v34, v37, 10, v34
	v_ashrrev_i32_e32 v35, 31, v34
	v_lshl_add_u64 v[34:35], v[34:35], 2, s[12:13]
	s_or_b64 exec, exec, s[0:1]
	v_ashrrev_i32_e32 v71, 31, v70
	v_lshlrev_b64 v[36:37], 11, v[70:71]
	v_lshl_add_u64 v[36:37], s[62:63], 0, v[36:37]
	s_waitcnt vmcnt(1)
	v_fmac_f32_e32 v144, 0.5, v65
	v_lshl_add_u64 v[36:37], v[130:131], 1, v[36:37]
	v_lshl_add_u64 v[34:35], v[34:35], 0, v[134:135]
	global_store_dword v[34:35], v144, off
	v_mul_f32_e32 v38, v144, v242
	v_cvt_pk_bf16_f32 v38, v38, s0
	global_store_short v[36:37], v38, off
.LBB0_1233:
	s_waitcnt vmcnt(0)
	v_fmac_f32_e32 v145, 0.5, v49
	global_store_dword v[34:35], v145, off offset:128
	v_mul_f32_e32 v34, v145, v243
	v_cvt_pk_bf16_f32 v34, v34, s0
	global_store_short v[36:37], v34, off offset:64
.LBB0_1235:
	v_or_b32_e32 v64, 0x60, v136
	v_min_i32_e32 v34, 0x403f, v64
	v_mul_hi_i32 v35, v34, s30
	v_lshrrev_b32_e32 v36, 31, v35
	v_ashrrev_i32_e32 v35, 11, v35
	v_add_u32_e32 v37, v35, v36
	v_mad_i32_i24 v36, v37, s31, v34
	v_cmp_lt_i32_e64 s[0:1], 15, v36
	s_and_saveexec_b64 s[10:11], s[0:1]
	s_xor_b64 s[0:1], exec, s[10:11]
	v_lshlrev_b32_e32 v34, 12, v37
	v_add3_u32 v34, v34, v36, -16
	v_ashrrev_i32_e32 v35, 31, v34
	v_lshlrev_b64 v[34:35], 12, v[34:35]
	v_lshl_add_u64 v[34:35], s[56:57], 0, v[34:35]
	s_andn2_saveexec_b64 s[0:1], s[0:1]
	v_lshlrev_b32_e32 v34, 10, v36
	v_ashrrev_i32_e32 v35, 31, v34
	v_lshl_add_u64 v[34:35], v[34:35], 2, s[58:59]
	s_or_b64 exec, exec, s[0:1]
	v_lshl_add_u64 v[34:35], v[130:131], 2, v[34:35]
	global_load_dword v72, v[34:35], off
	global_load_dword v73, v[34:35], off offset:128
	v_or_b32_e32 v62, 0x61, v136
	v_min_i32_e32 v34, 0x403f, v62
	v_mul_hi_i32 v35, v34, s30
	v_lshrrev_b32_e32 v36, 31, v35
	v_ashrrev_i32_e32 v35, 11, v35
	v_add_u32_e32 v37, v35, v36
	v_mad_i32_i24 v36, v37, s31, v34
	v_cmp_lt_i32_e64 s[0:1], 15, v36
	s_and_saveexec_b64 s[10:11], s[0:1]
	s_xor_b64 s[0:1], exec, s[10:11]
	v_lshlrev_b32_e32 v34, 12, v37
	v_add3_u32 v34, v34, v36, -16
	v_ashrrev_i32_e32 v35, 31, v34
	v_lshlrev_b64 v[34:35], 12, v[34:35]
	v_lshl_add_u64 v[34:35], s[56:57], 0, v[34:35]
	s_andn2_saveexec_b64 s[0:1], s[0:1]
	v_lshlrev_b32_e32 v34, 10, v36
	v_ashrrev_i32_e32 v35, 31, v34
	v_lshl_add_u64 v[34:35], v[34:35], 2, s[58:59]
	s_or_b64 exec, exec, s[0:1]
	v_lshl_add_u64 v[34:35], v[130:131], 2, v[34:35]
	global_load_dword v74, v[34:35], off
	global_load_dword v75, v[34:35], off offset:128
	v_or_b32_e32 v60, 0x62, v136
	v_min_i32_e32 v34, 0x403f, v60
	v_mul_hi_i32 v35, v34, s30
	v_lshrrev_b32_e32 v36, 31, v35
	v_ashrrev_i32_e32 v35, 11, v35
	v_add_u32_e32 v37, v35, v36
	v_mad_i32_i24 v36, v37, s31, v34
	v_cmp_lt_i32_e64 s[0:1], 15, v36
	s_and_saveexec_b64 s[10:11], s[0:1]
	s_xor_b64 s[0:1], exec, s[10:11]
	v_lshlrev_b32_e32 v34, 12, v37
	v_add3_u32 v34, v34, v36, -16
	v_ashrrev_i32_e32 v35, 31, v34
	v_lshlrev_b64 v[34:35], 12, v[34:35]
	v_lshl_add_u64 v[34:35], s[56:57], 0, v[34:35]
	s_andn2_saveexec_b64 s[0:1], s[0:1]
	v_lshlrev_b32_e32 v34, 10, v36
	v_ashrrev_i32_e32 v35, 31, v34
	v_lshl_add_u64 v[34:35], v[34:35], 2, s[58:59]
	s_or_b64 exec, exec, s[0:1]
	v_lshl_add_u64 v[34:35], v[130:131], 2, v[34:35]
	global_load_dword v76, v[34:35], off
	global_load_dword v77, v[34:35], off offset:128
	v_or_b32_e32 v58, 0x63, v136
	v_min_i32_e32 v34, 0x403f, v58
	v_mul_hi_i32 v35, v34, s30
	v_lshrrev_b32_e32 v36, 31, v35
	v_ashrrev_i32_e32 v35, 11, v35
	v_add_u32_e32 v37, v35, v36
	v_mad_i32_i24 v36, v37, s31, v34
	v_cmp_lt_i32_e64 s[0:1], 15, v36
	s_and_saveexec_b64 s[10:11], s[0:1]
	s_xor_b64 s[0:1], exec, s[10:11]
	v_lshlrev_b32_e32 v34, 12, v37
	v_add3_u32 v34, v34, v36, -16
	v_ashrrev_i32_e32 v35, 31, v34
	v_lshlrev_b64 v[34:35], 12, v[34:35]
	v_lshl_add_u64 v[34:35], s[56:57], 0, v[34:35]
	s_andn2_saveexec_b64 s[0:1], s[0:1]
	v_lshlrev_b32_e32 v34, 10, v36
	v_ashrrev_i32_e32 v35, 31, v34
	v_lshl_add_u64 v[34:35], v[34:35], 2, s[58:59]
	s_or_b64 exec, exec, s[0:1]
	v_lshl_add_u64 v[34:35], v[130:131], 2, v[34:35]
	global_load_dword v78, v[34:35], off
	global_load_dword v79, v[34:35], off offset:128
	v_or_b32_e32 v56, 0x68, v136
	v_min_i32_e32 v34, 0x403f, v56
	v_mul_hi_i32 v35, v34, s30
	v_lshrrev_b32_e32 v36, 31, v35
	v_ashrrev_i32_e32 v35, 11, v35
	v_add_u32_e32 v37, v35, v36
	v_mad_i32_i24 v36, v37, s31, v34
	v_cmp_lt_i32_e64 s[0:1], 15, v36
	s_and_saveexec_b64 s[10:11], s[0:1]
	s_xor_b64 s[0:1], exec, s[10:11]
	v_lshlrev_b32_e32 v34, 12, v37
	v_add3_u32 v34, v34, v36, -16
	v_ashrrev_i32_e32 v35, 31, v34
	v_lshlrev_b64 v[34:35], 12, v[34:35]
	v_lshl_add_u64 v[34:35], s[56:57], 0, v[34:35]
	s_andn2_saveexec_b64 s[0:1], s[0:1]
	v_lshlrev_b32_e32 v34, 10, v36
	v_ashrrev_i32_e32 v35, 31, v34
	v_lshl_add_u64 v[34:35], v[34:35], 2, s[58:59]
	s_or_b64 exec, exec, s[0:1]
	v_lshl_add_u64 v[34:35], v[130:131], 2, v[34:35]
	global_load_dword v80, v[34:35], off
	global_load_dword v81, v[34:35], off offset:128
	v_or_b32_e32 v54, 0x69, v136
	v_min_i32_e32 v34, 0x403f, v54
	v_mul_hi_i32 v35, v34, s30
	v_lshrrev_b32_e32 v36, 31, v35
	v_ashrrev_i32_e32 v35, 11, v35
	v_add_u32_e32 v37, v35, v36
	v_mad_i32_i24 v36, v37, s31, v34
	v_cmp_lt_i32_e64 s[0:1], 15, v36
	s_and_saveexec_b64 s[10:11], s[0:1]
	s_xor_b64 s[0:1], exec, s[10:11]
	v_lshlrev_b32_e32 v34, 12, v37
	v_add3_u32 v34, v34, v36, -16
	v_ashrrev_i32_e32 v35, 31, v34
	v_lshlrev_b64 v[34:35], 12, v[34:35]
	v_lshl_add_u64 v[34:35], s[56:57], 0, v[34:35]
	s_andn2_saveexec_b64 s[0:1], s[0:1]
	v_lshlrev_b32_e32 v34, 10, v36
	v_ashrrev_i32_e32 v35, 31, v34
	v_lshl_add_u64 v[34:35], v[34:35], 2, s[58:59]
	s_or_b64 exec, exec, s[0:1]
	v_lshl_add_u64 v[34:35], v[130:131], 2, v[34:35]
	global_load_dword v82, v[34:35], off
	global_load_dword v83, v[34:35], off offset:128
	v_or_b32_e32 v52, 0x6a, v136
	v_min_i32_e32 v34, 0x403f, v52
	v_mul_hi_i32 v35, v34, s30
	v_lshrrev_b32_e32 v36, 31, v35
	v_ashrrev_i32_e32 v35, 11, v35
	v_add_u32_e32 v37, v35, v36
	v_mad_i32_i24 v36, v37, s31, v34
	v_cmp_lt_i32_e64 s[0:1], 15, v36
	s_and_saveexec_b64 s[10:11], s[0:1]
	s_xor_b64 s[0:1], exec, s[10:11]
	v_lshlrev_b32_e32 v34, 12, v37
	v_add3_u32 v34, v34, v36, -16
	v_ashrrev_i32_e32 v35, 31, v34
	v_lshlrev_b64 v[34:35], 12, v[34:35]
	v_lshl_add_u64 v[34:35], s[56:57], 0, v[34:35]
	s_andn2_saveexec_b64 s[0:1], s[0:1]
	v_lshlrev_b32_e32 v34, 10, v36
	v_ashrrev_i32_e32 v35, 31, v34
	v_lshl_add_u64 v[34:35], v[34:35], 2, s[58:59]
	s_or_b64 exec, exec, s[0:1]
	v_lshl_add_u64 v[34:35], v[130:131], 2, v[34:35]
	global_load_dword v84, v[34:35], off
	global_load_dword v85, v[34:35], off offset:128
	v_or_b32_e32 v50, 0x6b, v136
	v_min_i32_e32 v34, 0x403f, v50
	v_mul_hi_i32 v35, v34, s30
	v_lshrrev_b32_e32 v36, 31, v35
	v_ashrrev_i32_e32 v35, 11, v35
	v_add_u32_e32 v37, v35, v36
	v_mad_i32_i24 v36, v37, s31, v34
	v_cmp_lt_i32_e64 s[0:1], 15, v36
	s_and_saveexec_b64 s[10:11], s[0:1]
	s_xor_b64 s[0:1], exec, s[10:11]
	v_lshlrev_b32_e32 v34, 12, v37
	v_add3_u32 v34, v34, v36, -16
	v_ashrrev_i32_e32 v35, 31, v34
	v_lshlrev_b64 v[34:35], 12, v[34:35]
	v_lshl_add_u64 v[34:35], s[56:57], 0, v[34:35]
	s_andn2_saveexec_b64 s[0:1], s[0:1]
	v_lshlrev_b32_e32 v34, 10, v36
	v_ashrrev_i32_e32 v35, 31, v34
	v_lshl_add_u64 v[34:35], v[34:35], 2, s[58:59]
	s_or_b64 exec, exec, s[0:1]
	v_lshl_add_u64 v[34:35], v[130:131], 2, v[34:35]
	global_load_dword v86, v[34:35], off
	global_load_dword v87, v[34:35], off offset:128
	v_or_b32_e32 v48, 0x70, v136
	v_min_i32_e32 v34, 0x403f, v48
	v_mul_hi_i32 v35, v34, s30
	v_lshrrev_b32_e32 v36, 31, v35
	v_ashrrev_i32_e32 v35, 11, v35
	v_add_u32_e32 v37, v35, v36
	v_mad_i32_i24 v36, v37, s31, v34
	v_cmp_lt_i32_e64 s[0:1], 15, v36
	s_and_saveexec_b64 s[10:11], s[0:1]
	s_xor_b64 s[0:1], exec, s[10:11]
	v_lshlrev_b32_e32 v34, 12, v37
	v_add3_u32 v34, v34, v36, -16
	v_ashrrev_i32_e32 v35, 31, v34
	v_lshlrev_b64 v[34:35], 12, v[34:35]
	v_lshl_add_u64 v[34:35], s[56:57], 0, v[34:35]
	s_andn2_saveexec_b64 s[0:1], s[0:1]
	v_lshlrev_b32_e32 v34, 10, v36
	v_ashrrev_i32_e32 v35, 31, v34
	v_lshl_add_u64 v[34:35], v[34:35], 2, s[58:59]
	s_or_b64 exec, exec, s[0:1]
	v_lshl_add_u64 v[34:35], v[130:131], 2, v[34:35]
	global_load_dword v88, v[34:35], off
	global_load_dword v89, v[34:35], off offset:128
	v_or_b32_e32 v46, 0x71, v136
	v_min_i32_e32 v34, 0x403f, v46
	v_mul_hi_i32 v35, v34, s30
	v_lshrrev_b32_e32 v36, 31, v35
	v_ashrrev_i32_e32 v35, 11, v35
	v_add_u32_e32 v37, v35, v36
	v_mad_i32_i24 v36, v37, s31, v34
	v_cmp_lt_i32_e64 s[0:1], 15, v36
	s_and_saveexec_b64 s[10:11], s[0:1]
	s_xor_b64 s[0:1], exec, s[10:11]
	v_lshlrev_b32_e32 v34, 12, v37
	v_add3_u32 v34, v34, v36, -16
	v_ashrrev_i32_e32 v35, 31, v34
	v_lshlrev_b64 v[34:35], 12, v[34:35]
	v_lshl_add_u64 v[34:35], s[56:57], 0, v[34:35]
	s_andn2_saveexec_b64 s[0:1], s[0:1]
	v_lshlrev_b32_e32 v34, 10, v36
	v_ashrrev_i32_e32 v35, 31, v34
	v_lshl_add_u64 v[34:35], v[34:35], 2, s[58:59]
	s_or_b64 exec, exec, s[0:1]
	v_lshl_add_u64 v[34:35], v[130:131], 2, v[34:35]
	global_load_dword v90, v[34:35], off
	global_load_dword v91, v[34:35], off offset:128
	v_or_b32_e32 v44, 0x72, v136
	v_min_i32_e32 v34, 0x403f, v44
	v_mul_hi_i32 v35, v34, s30
	v_lshrrev_b32_e32 v36, 31, v35
	v_ashrrev_i32_e32 v35, 11, v35
	v_add_u32_e32 v37, v35, v36
	v_mad_i32_i24 v36, v37, s31, v34
	v_cmp_lt_i32_e64 s[0:1], 15, v36
	s_and_saveexec_b64 s[10:11], s[0:1]
	s_xor_b64 s[0:1], exec, s[10:11]
	v_lshlrev_b32_e32 v34, 12, v37
	v_add3_u32 v34, v34, v36, -16
	v_ashrrev_i32_e32 v35, 31, v34
	v_lshlrev_b64 v[34:35], 12, v[34:35]
	v_lshl_add_u64 v[34:35], s[56:57], 0, v[34:35]
	s_andn2_saveexec_b64 s[0:1], s[0:1]
	v_lshlrev_b32_e32 v34, 10, v36
	v_ashrrev_i32_e32 v35, 31, v34
	v_lshl_add_u64 v[34:35], v[34:35], 2, s[58:59]
	s_or_b64 exec, exec, s[0:1]
	v_lshl_add_u64 v[34:35], v[130:131], 2, v[34:35]
	global_load_dword v92, v[34:35], off
	global_load_dword v93, v[34:35], off offset:128
	v_or_b32_e32 v42, 0x73, v136
	v_min_i32_e32 v34, 0x403f, v42
	v_mul_hi_i32 v35, v34, s30
	v_lshrrev_b32_e32 v36, 31, v35
	v_ashrrev_i32_e32 v35, 11, v35
	v_add_u32_e32 v37, v35, v36
	v_mad_i32_i24 v36, v37, s31, v34
	v_cmp_lt_i32_e64 s[0:1], 15, v36
	s_and_saveexec_b64 s[10:11], s[0:1]
	s_xor_b64 s[0:1], exec, s[10:11]
	v_lshlrev_b32_e32 v34, 12, v37
	v_add3_u32 v34, v34, v36, -16
	v_ashrrev_i32_e32 v35, 31, v34
	v_lshlrev_b64 v[34:35], 12, v[34:35]
	v_lshl_add_u64 v[34:35], s[56:57], 0, v[34:35]
	s_andn2_saveexec_b64 s[0:1], s[0:1]
	v_lshlrev_b32_e32 v34, 10, v36
	v_ashrrev_i32_e32 v35, 31, v34
	v_lshl_add_u64 v[34:35], v[34:35], 2, s[58:59]
	s_or_b64 exec, exec, s[0:1]
	v_lshl_add_u64 v[34:35], v[130:131], 2, v[34:35]
	global_load_dword v94, v[34:35], off
	global_load_dword v95, v[34:35], off offset:128
	v_or_b32_e32 v40, 0x78, v136
	v_min_i32_e32 v34, 0x403f, v40
	v_mul_hi_i32 v35, v34, s30
	v_lshrrev_b32_e32 v36, 31, v35
	v_ashrrev_i32_e32 v35, 11, v35
	v_add_u32_e32 v37, v35, v36
	v_mad_i32_i24 v36, v37, s31, v34
	v_cmp_lt_i32_e64 s[0:1], 15, v36
	s_and_saveexec_b64 s[10:11], s[0:1]
	s_xor_b64 s[0:1], exec, s[10:11]
	v_lshlrev_b32_e32 v34, 12, v37
	v_add3_u32 v34, v34, v36, -16
	v_ashrrev_i32_e32 v35, 31, v34
	v_lshlrev_b64 v[34:35], 12, v[34:35]
	v_lshl_add_u64 v[34:35], s[56:57], 0, v[34:35]
	s_andn2_saveexec_b64 s[0:1], s[0:1]
	v_lshlrev_b32_e32 v34, 10, v36
	v_ashrrev_i32_e32 v35, 31, v34
	v_lshl_add_u64 v[34:35], v[34:35], 2, s[58:59]
	s_or_b64 exec, exec, s[0:1]
	v_lshl_add_u64 v[34:35], v[130:131], 2, v[34:35]
	global_load_dword v96, v[34:35], off
	global_load_dword v97, v[34:35], off offset:128
	v_or_b32_e32 v38, 0x79, v136
	v_min_i32_e32 v34, 0x403f, v38
	v_mul_hi_i32 v35, v34, s30
	v_lshrrev_b32_e32 v36, 31, v35
	v_ashrrev_i32_e32 v35, 11, v35
	v_add_u32_e32 v37, v35, v36
	v_mad_i32_i24 v36, v37, s31, v34
	v_cmp_lt_i32_e64 s[0:1], 15, v36
	s_and_saveexec_b64 s[10:11], s[0:1]
	s_xor_b64 s[0:1], exec, s[10:11]
	v_lshlrev_b32_e32 v34, 12, v37
	v_add3_u32 v34, v34, v36, -16
	v_ashrrev_i32_e32 v35, 31, v34
	v_lshlrev_b64 v[34:35], 12, v[34:35]
	v_lshl_add_u64 v[34:35], s[56:57], 0, v[34:35]
	s_andn2_saveexec_b64 s[0:1], s[0:1]
	v_lshlrev_b32_e32 v34, 10, v36
	v_ashrrev_i32_e32 v35, 31, v34
	v_lshl_add_u64 v[34:35], v[34:35], 2, s[58:59]
	s_or_b64 exec, exec, s[0:1]
	v_lshl_add_u64 v[34:35], v[130:131], 2, v[34:35]
	global_load_dword v99, v[34:35], off
	global_load_dword v101, v[34:35], off offset:128
	v_or_b32_e32 v36, 0x7a, v136
	v_min_i32_e32 v34, 0x403f, v36
	v_mul_hi_i32 v35, v34, s30
	v_lshrrev_b32_e32 v37, 31, v35
	v_ashrrev_i32_e32 v35, 11, v35
	v_add_u32_e32 v39, v35, v37
	v_mad_i32_i24 v37, v39, s31, v34
	v_cmp_lt_i32_e64 s[0:1], 15, v37
	s_and_saveexec_b64 s[10:11], s[0:1]
	s_xor_b64 s[0:1], exec, s[10:11]
	v_lshlrev_b32_e32 v34, 12, v39
	v_add3_u32 v34, v34, v37, -16
	v_ashrrev_i32_e32 v35, 31, v34
	v_lshlrev_b64 v[34:35], 12, v[34:35]
	v_lshl_add_u64 v[34:35], s[56:57], 0, v[34:35]
	s_andn2_saveexec_b64 s[0:1], s[0:1]
	v_lshlrev_b32_e32 v34, 10, v37
	v_ashrrev_i32_e32 v35, 31, v34
	v_lshl_add_u64 v[34:35], v[34:35], 2, s[58:59]
	s_or_b64 exec, exec, s[0:1]
	v_lshl_add_u64 v[34:35], v[130:131], 2, v[34:35]
	global_load_dword v102, v[34:35], off
	global_load_dword v103, v[34:35], off offset:128
	v_or_b32_e32 v34, 0x7b, v136
	v_min_i32_e32 v35, 0x403f, v34
	v_mul_hi_i32 v37, v35, s30
	v_lshrrev_b32_e32 v39, 31, v37
	v_ashrrev_i32_e32 v37, 11, v37
	v_add_u32_e32 v37, v37, v39
	v_mad_i32_i24 v35, v37, s31, v35
	v_cmp_lt_i32_e64 s[0:1], 15, v35
	s_and_saveexec_b64 s[10:11], s[0:1]
	s_xor_b64 s[0:1], exec, s[10:11]
	v_lshlrev_b32_e32 v37, 12, v37
	v_add3_u32 v70, v37, v35, -16
	v_ashrrev_i32_e32 v71, 31, v70
	v_lshlrev_b64 v[70:71], 12, v[70:71]
	v_lshl_add_u64 v[70:71], s[56:57], 0, v[70:71]
	s_andn2_saveexec_b64 s[0:1], s[0:1]
	v_lshlrev_b32_e32 v70, 10, v35
	v_ashrrev_i32_e32 v71, 31, v70
	v_lshl_add_u64 v[70:71], v[70:71], 2, s[58:59]
	s_or_b64 exec, exec, s[0:1]
	v_lshl_add_u64 v[70:71], v[130:131], 2, v[70:71]
	global_load_dword v98, v[70:71], off
	global_load_dword v100, v[70:71], off offset:128
	v_cmp_gt_i32_e64 s[10:11], s34, v64
	s_nop 1
	v_cndmask_b32_e64 v37, v179, v64, s[10:11]
	v_mul_hi_i32 v35, v37, s30
	v_lshrrev_b32_e32 v39, 31, v35
	v_ashrrev_i32_e32 v35, 11, v35
	v_add_u32_e32 v35, v35, v39
	v_mad_i32_i24 v37, v35, s31, v37
	v_cmp_lt_i32_e64 s[0:1], 15, v37
	s_and_saveexec_b64 s[36:37], s[0:1]
	s_xor_b64 s[0:1], exec, s[36:37]
	v_lshlrev_b32_e32 v35, 12, v35
	v_add3_u32 v70, v35, v37, -16
	v_ashrrev_i32_e32 v71, 31, v70
	v_lshlrev_b64 v[70:71], 12, v[70:71]
	v_lshl_add_u64 v[70:71], s[88:89], 0, v[70:71]
	s_andn2_saveexec_b64 s[0:1], s[0:1]
	v_lshlrev_b32_e32 v35, 14, v35
	v_lshl_add_u32 v70, v37, 10, v35
	v_ashrrev_i32_e32 v71, 31, v70
	v_lshl_add_u64 v[70:71], v[70:71], 2, s[12:13]
	s_or_b64 exec, exec, s[0:1]
	v_ashrrev_i32_e32 v65, 31, v64
	v_lshlrev_b64 v[64:65], 11, v[64:65]
	v_lshl_add_u64 v[64:65], s[62:63], 0, v[64:65]
	s_waitcnt vmcnt(31)
	v_fmac_f32_e32 v72, 0.5, v18
	v_lshl_add_u64 v[64:65], v[130:131], 1, v[64:65]
	v_lshl_add_u64 v[70:71], v[70:71], 0, v[134:135]
	global_store_dword v[70:71], v72, off
	v_mul_f32_e32 v18, v72, v242
	v_cvt_pk_bf16_f32 v18, v18, s0
	global_store_short v[64:65], v18, off
.LBB0_1305:
	s_waitcnt vmcnt(30)
	v_fmac_f32_e32 v73, 0.5, v2
	global_store_dword v[70:71], v73, off offset:128
	v_mul_f32_e32 v2, v73, v243
	v_cvt_pk_bf16_f32 v2, v2, s0
	global_store_short v[64:65], v2, off offset:64
.LBB0_1307:
	v_cmp_gt_i32_e64 s[10:11], s34, v62
	s_nop 1
	v_cndmask_b32_e64 v18, v179, v62, s[10:11]
	v_mul_hi_i32 v2, v18, s30
	v_lshrrev_b32_e32 v35, 31, v2
	v_ashrrev_i32_e32 v2, 11, v2
	v_add_u32_e32 v2, v2, v35
	v_mad_i32_i24 v18, v2, s31, v18
	v_cmp_lt_i32_e64 s[0:1], 15, v18
	s_and_saveexec_b64 s[36:37], s[0:1]
	s_xor_b64 s[0:1], exec, s[36:37]
	v_lshlrev_b32_e32 v2, 12, v2
	v_add3_u32 v64, v2, v18, -16
	v_ashrrev_i32_e32 v65, 31, v64
	v_lshlrev_b64 v[64:65], 12, v[64:65]
	v_lshl_add_u64 v[64:65], s[88:89], 0, v[64:65]
	s_andn2_saveexec_b64 s[0:1], s[0:1]
	v_lshlrev_b32_e32 v2, 14, v2
	v_lshl_add_u32 v64, v18, 10, v2
	v_ashrrev_i32_e32 v65, 31, v64
	v_lshl_add_u64 v[64:65], v[64:65], 2, s[12:13]
	s_or_b64 exec, exec, s[0:1]
	v_ashrrev_i32_e32 v63, 31, v62
	v_lshlrev_b64 v[62:63], 11, v[62:63]
	v_lshl_add_u64 v[62:63], s[62:63], 0, v[62:63]
	s_waitcnt vmcnt(29)
	v_fmac_f32_e32 v74, 0.5, v19
	v_lshl_add_u64 v[18:19], v[130:131], 1, v[62:63]
	v_lshl_add_u64 v[62:63], v[64:65], 0, v[134:135]
	global_store_dword v[62:63], v74, off
	v_mul_f32_e32 v2, v74, v242
	v_cvt_pk_bf16_f32 v2, v2, s0
	global_store_short v[18:19], v2, off
.LBB0_1313:
	s_waitcnt vmcnt(28)
	v_fmac_f32_e32 v75, 0.5, v3
	global_store_dword v[62:63], v75, off offset:128
	v_mul_f32_e32 v2, v75, v243
	v_cvt_pk_bf16_f32 v2, v2, s0
	global_store_short v[18:19], v2, off offset:64
.LBB0_1315:
	v_cmp_gt_i32_e64 s[10:11], s34, v60
	s_nop 1
	v_cndmask_b32_e64 v2, v179, v60, s[10:11]
	v_mul_hi_i32 v3, v2, s30
	v_lshrrev_b32_e32 v18, 31, v3
	v_ashrrev_i32_e32 v3, 11, v3
	v_add_u32_e32 v18, v3, v18
	v_mad_i32_i24 v19, v18, s31, v2
	v_cmp_lt_i32_e64 s[0:1], 15, v19
	s_and_saveexec_b64 s[36:37], s[0:1]
	s_xor_b64 s[0:1], exec, s[36:37]
	v_lshlrev_b32_e32 v2, 12, v18
	v_add3_u32 v2, v2, v19, -16
	v_ashrrev_i32_e32 v3, 31, v2
	v_lshlrev_b64 v[2:3], 12, v[2:3]
	v_lshl_add_u64 v[2:3], s[88:89], 0, v[2:3]
	s_andn2_saveexec_b64 s[0:1], s[0:1]
	v_lshlrev_b32_e32 v2, 14, v18
	v_lshl_add_u32 v2, v19, 10, v2
	v_ashrrev_i32_e32 v3, 31, v2
	v_lshl_add_u64 v[2:3], v[2:3], 2, s[12:13]
	s_or_b64 exec, exec, s[0:1]
	v_ashrrev_i32_e32 v61, 31, v60
	v_lshlrev_b64 v[18:19], 11, v[60:61]
	v_lshl_add_u64 v[18:19], s[62:63], 0, v[18:19]
	s_waitcnt vmcnt(27)
	v_fmac_f32_e32 v76, 0.5, v20
	v_lshl_add_u64 v[18:19], v[130:131], 1, v[18:19]
	v_lshl_add_u64 v[2:3], v[2:3], 0, v[134:135]
	global_store_dword v[2:3], v76, off
	v_mul_f32_e32 v20, v76, v242
	v_cvt_pk_bf16_f32 v20, v20, s0
	global_store_short v[18:19], v20, off
.LBB0_1321:
	s_waitcnt vmcnt(26)
	v_fmac_f32_e32 v77, 0.5, v4
	global_store_dword v[2:3], v77, off offset:128
	v_mul_f32_e32 v2, v77, v243
	v_cvt_pk_bf16_f32 v2, v2, s0
	global_store_short v[18:19], v2, off offset:64
.LBB0_1323:
	v_cmp_gt_i32_e64 s[10:11], s34, v58
	s_nop 1
	v_cndmask_b32_e64 v2, v179, v58, s[10:11]
	v_mul_hi_i32 v3, v2, s30
	v_lshrrev_b32_e32 v4, 31, v3
	v_ashrrev_i32_e32 v3, 11, v3
	v_add_u32_e32 v4, v3, v4
	v_mad_i32_i24 v18, v4, s31, v2
	v_cmp_lt_i32_e64 s[0:1], 15, v18
	s_and_saveexec_b64 s[36:37], s[0:1]
	s_xor_b64 s[0:1], exec, s[36:37]
	v_lshlrev_b32_e32 v2, 12, v4
	v_add3_u32 v2, v2, v18, -16
	v_ashrrev_i32_e32 v3, 31, v2
	v_lshlrev_b64 v[2:3], 12, v[2:3]
	v_lshl_add_u64 v[2:3], s[88:89], 0, v[2:3]
	s_andn2_saveexec_b64 s[0:1], s[0:1]
	v_lshlrev_b32_e32 v2, 14, v4
	v_lshl_add_u32 v2, v18, 10, v2
	v_ashrrev_i32_e32 v3, 31, v2
	v_lshl_add_u64 v[2:3], v[2:3], 2, s[12:13]
	s_or_b64 exec, exec, s[0:1]
	v_ashrrev_i32_e32 v59, 31, v58
	v_lshlrev_b64 v[18:19], 11, v[58:59]
	v_lshl_add_u64 v[18:19], s[62:63], 0, v[18:19]
	s_waitcnt vmcnt(25)
	v_fmac_f32_e32 v78, 0.5, v21
	v_lshl_add_u64 v[18:19], v[130:131], 1, v[18:19]
	v_lshl_add_u64 v[2:3], v[2:3], 0, v[134:135]
	global_store_dword v[2:3], v78, off
	v_mul_f32_e32 v4, v78, v242
	v_cvt_pk_bf16_f32 v4, v4, s0
	global_store_short v[18:19], v4, off
.LBB0_1329:
	s_waitcnt vmcnt(24)
	v_fmac_f32_e32 v79, 0.5, v5
	global_store_dword v[2:3], v79, off offset:128
	v_mul_f32_e32 v2, v79, v243
	v_cvt_pk_bf16_f32 v2, v2, s0
	global_store_short v[18:19], v2, off offset:64
.LBB0_1331:
	v_cmp_gt_i32_e64 s[10:11], s34, v56
	s_nop 1
	v_cndmask_b32_e64 v2, v179, v56, s[10:11]
	v_mul_hi_i32 v3, v2, s30
	v_lshrrev_b32_e32 v4, 31, v3
	v_ashrrev_i32_e32 v3, 11, v3
	v_add_u32_e32 v4, v3, v4
	v_mad_i32_i24 v5, v4, s31, v2
	v_cmp_lt_i32_e64 s[0:1], 15, v5
	s_and_saveexec_b64 s[36:37], s[0:1]
	s_xor_b64 s[0:1], exec, s[36:37]
	v_lshlrev_b32_e32 v2, 12, v4
	v_add3_u32 v2, v2, v5, -16
	v_ashrrev_i32_e32 v3, 31, v2
	v_lshlrev_b64 v[2:3], 12, v[2:3]
	v_lshl_add_u64 v[2:3], s[88:89], 0, v[2:3]
	s_andn2_saveexec_b64 s[0:1], s[0:1]
	v_lshlrev_b32_e32 v2, 14, v4
	v_lshl_add_u32 v2, v5, 10, v2
	v_ashrrev_i32_e32 v3, 31, v2
	v_lshl_add_u64 v[2:3], v[2:3], 2, s[12:13]
	s_or_b64 exec, exec, s[0:1]
	v_ashrrev_i32_e32 v57, 31, v56
	v_lshlrev_b64 v[4:5], 11, v[56:57]
	v_lshl_add_u64 v[4:5], s[62:63], 0, v[4:5]
	s_waitcnt vmcnt(23)
	v_fmac_f32_e32 v80, 0.5, v22
	v_lshl_add_u64 v[4:5], v[130:131], 1, v[4:5]
	v_lshl_add_u64 v[2:3], v[2:3], 0, v[134:135]
	global_store_dword v[2:3], v80, off
	v_mul_f32_e32 v18, v80, v242
	v_cvt_pk_bf16_f32 v18, v18, s0
	global_store_short v[4:5], v18, off
.LBB0_1337:
	s_waitcnt vmcnt(22)
	v_fmac_f32_e32 v81, 0.5, v6
	global_store_dword v[2:3], v81, off offset:128
	v_mul_f32_e32 v2, v81, v243
	v_cvt_pk_bf16_f32 v2, v2, s0
	global_store_short v[4:5], v2, off offset:64
.LBB0_1339:
	v_cmp_gt_i32_e64 s[10:11], s34, v54
	s_nop 1
	v_cndmask_b32_e64 v2, v179, v54, s[10:11]
	v_mul_hi_i32 v3, v2, s30
	v_lshrrev_b32_e32 v4, 31, v3
	v_ashrrev_i32_e32 v3, 11, v3
	v_add_u32_e32 v4, v3, v4
	v_mad_i32_i24 v5, v4, s31, v2
	v_cmp_lt_i32_e64 s[0:1], 15, v5
	s_and_saveexec_b64 s[36:37], s[0:1]
	s_xor_b64 s[0:1], exec, s[36:37]
	v_lshlrev_b32_e32 v2, 12, v4
	v_add3_u32 v2, v2, v5, -16
	v_ashrrev_i32_e32 v3, 31, v2
	v_lshlrev_b64 v[2:3], 12, v[2:3]
	v_lshl_add_u64 v[2:3], s[88:89], 0, v[2:3]
	s_andn2_saveexec_b64 s[0:1], s[0:1]
	v_lshlrev_b32_e32 v2, 14, v4
	v_lshl_add_u32 v2, v5, 10, v2
	v_ashrrev_i32_e32 v3, 31, v2
	v_lshl_add_u64 v[2:3], v[2:3], 2, s[12:13]
	s_or_b64 exec, exec, s[0:1]
	v_ashrrev_i32_e32 v55, 31, v54
	v_lshlrev_b64 v[4:5], 11, v[54:55]
	v_lshl_add_u64 v[4:5], s[62:63], 0, v[4:5]
	s_waitcnt vmcnt(21)
	v_fmac_f32_e32 v82, 0.5, v23
	v_lshl_add_u64 v[4:5], v[130:131], 1, v[4:5]
	v_lshl_add_u64 v[2:3], v[2:3], 0, v[134:135]
	global_store_dword v[2:3], v82, off
	v_mul_f32_e32 v6, v82, v242
	v_cvt_pk_bf16_f32 v6, v6, s0
	global_store_short v[4:5], v6, off
.LBB0_1345:
	s_waitcnt vmcnt(20)
	v_fmac_f32_e32 v83, 0.5, v7
	global_store_dword v[2:3], v83, off offset:128
	v_mul_f32_e32 v2, v83, v243
	v_cvt_pk_bf16_f32 v2, v2, s0
	global_store_short v[4:5], v2, off offset:64
.LBB0_1347:
	v_cmp_gt_i32_e64 s[10:11], s34, v52
	s_nop 1
	v_cndmask_b32_e64 v2, v179, v52, s[10:11]
	v_mul_hi_i32 v3, v2, s30
	v_lshrrev_b32_e32 v4, 31, v3
	v_ashrrev_i32_e32 v3, 11, v3
	v_add_u32_e32 v4, v3, v4
	v_mad_i32_i24 v5, v4, s31, v2
	v_cmp_lt_i32_e64 s[0:1], 15, v5
	s_and_saveexec_b64 s[36:37], s[0:1]
	s_xor_b64 s[0:1], exec, s[36:37]
	v_lshlrev_b32_e32 v2, 12, v4
	v_add3_u32 v2, v2, v5, -16
	v_ashrrev_i32_e32 v3, 31, v2
	v_lshlrev_b64 v[2:3], 12, v[2:3]
	v_lshl_add_u64 v[2:3], s[88:89], 0, v[2:3]
	s_andn2_saveexec_b64 s[0:1], s[0:1]
	v_lshlrev_b32_e32 v2, 14, v4
	v_lshl_add_u32 v2, v5, 10, v2
	v_ashrrev_i32_e32 v3, 31, v2
	v_lshl_add_u64 v[2:3], v[2:3], 2, s[12:13]
	s_or_b64 exec, exec, s[0:1]
	v_ashrrev_i32_e32 v53, 31, v52
	v_lshlrev_b64 v[4:5], 11, v[52:53]
	v_lshl_add_u64 v[4:5], s[62:63], 0, v[4:5]
	s_waitcnt vmcnt(19)
	v_fmac_f32_e32 v84, 0.5, v24
	v_lshl_add_u64 v[4:5], v[130:131], 1, v[4:5]
	v_lshl_add_u64 v[2:3], v[2:3], 0, v[134:135]
	global_store_dword v[2:3], v84, off
	v_mul_f32_e32 v6, v84, v242
	v_cvt_pk_bf16_f32 v6, v6, s0
	global_store_short v[4:5], v6, off
.LBB0_1353:
	s_waitcnt vmcnt(18)
	v_fmac_f32_e32 v85, 0.5, v8
	global_store_dword v[2:3], v85, off offset:128
	v_mul_f32_e32 v2, v85, v243
	v_cvt_pk_bf16_f32 v2, v2, s0
	global_store_short v[4:5], v2, off offset:64
.LBB0_1355:
	v_cmp_gt_i32_e64 s[10:11], s34, v50
	s_nop 1
	v_cndmask_b32_e64 v2, v179, v50, s[10:11]
	v_mul_hi_i32 v3, v2, s30
	v_lshrrev_b32_e32 v4, 31, v3
	v_ashrrev_i32_e32 v3, 11, v3
	v_add_u32_e32 v4, v3, v4
	v_mad_i32_i24 v5, v4, s31, v2
	v_cmp_lt_i32_e64 s[0:1], 15, v5
	s_and_saveexec_b64 s[36:37], s[0:1]
	s_xor_b64 s[0:1], exec, s[36:37]
	v_lshlrev_b32_e32 v2, 12, v4
	v_add3_u32 v2, v2, v5, -16
	v_ashrrev_i32_e32 v3, 31, v2
	v_lshlrev_b64 v[2:3], 12, v[2:3]
	v_lshl_add_u64 v[2:3], s[88:89], 0, v[2:3]
	s_andn2_saveexec_b64 s[0:1], s[0:1]
	v_lshlrev_b32_e32 v2, 14, v4
	v_lshl_add_u32 v2, v5, 10, v2
	v_ashrrev_i32_e32 v3, 31, v2
	v_lshl_add_u64 v[2:3], v[2:3], 2, s[12:13]
	s_or_b64 exec, exec, s[0:1]
	v_ashrrev_i32_e32 v51, 31, v50
	v_lshlrev_b64 v[4:5], 11, v[50:51]
	v_lshl_add_u64 v[4:5], s[62:63], 0, v[4:5]
	s_waitcnt vmcnt(17)
	v_fmac_f32_e32 v86, 0.5, v25
	v_lshl_add_u64 v[4:5], v[130:131], 1, v[4:5]
	v_lshl_add_u64 v[2:3], v[2:3], 0, v[134:135]
	global_store_dword v[2:3], v86, off
	v_mul_f32_e32 v6, v86, v242
	v_cvt_pk_bf16_f32 v6, v6, s0
	global_store_short v[4:5], v6, off
.LBB0_1361:
	s_waitcnt vmcnt(16)
	v_fmac_f32_e32 v87, 0.5, v9
	global_store_dword v[2:3], v87, off offset:128
	v_mul_f32_e32 v2, v87, v243
	v_cvt_pk_bf16_f32 v2, v2, s0
	global_store_short v[4:5], v2, off offset:64
.LBB0_1363:
	v_cmp_gt_i32_e64 s[10:11], s34, v48
	s_nop 1
	v_cndmask_b32_e64 v2, v179, v48, s[10:11]
	v_mul_hi_i32 v3, v2, s30
	v_lshrrev_b32_e32 v4, 31, v3
	v_ashrrev_i32_e32 v3, 11, v3
	v_add_u32_e32 v4, v3, v4
	v_mad_i32_i24 v5, v4, s31, v2
	v_cmp_lt_i32_e64 s[0:1], 15, v5
	s_and_saveexec_b64 s[36:37], s[0:1]
	s_xor_b64 s[0:1], exec, s[36:37]
	v_lshlrev_b32_e32 v2, 12, v4
	v_add3_u32 v2, v2, v5, -16
	v_ashrrev_i32_e32 v3, 31, v2
	v_lshlrev_b64 v[2:3], 12, v[2:3]
	v_lshl_add_u64 v[2:3], s[88:89], 0, v[2:3]
	s_andn2_saveexec_b64 s[0:1], s[0:1]
	v_lshlrev_b32_e32 v2, 14, v4
	v_lshl_add_u32 v2, v5, 10, v2
	v_ashrrev_i32_e32 v3, 31, v2
	v_lshl_add_u64 v[2:3], v[2:3], 2, s[12:13]
	s_or_b64 exec, exec, s[0:1]
	v_ashrrev_i32_e32 v49, 31, v48
	v_lshlrev_b64 v[4:5], 11, v[48:49]
	v_lshl_add_u64 v[4:5], s[62:63], 0, v[4:5]
	s_waitcnt vmcnt(15)
	v_fmac_f32_e32 v88, 0.5, v26
	v_lshl_add_u64 v[4:5], v[130:131], 1, v[4:5]
	v_lshl_add_u64 v[2:3], v[2:3], 0, v[134:135]
	global_store_dword v[2:3], v88, off
	v_mul_f32_e32 v6, v88, v242
	v_cvt_pk_bf16_f32 v6, v6, s0
	global_store_short v[4:5], v6, off
.LBB0_1369:
	s_waitcnt vmcnt(14)
	v_fmac_f32_e32 v89, 0.5, v10
	global_store_dword v[2:3], v89, off offset:128
	v_mul_f32_e32 v2, v89, v243
	v_cvt_pk_bf16_f32 v2, v2, s0
	global_store_short v[4:5], v2, off offset:64
.LBB0_1371:
	v_cmp_gt_i32_e64 s[10:11], s34, v46
	s_nop 1
	v_cndmask_b32_e64 v2, v179, v46, s[10:11]
	v_mul_hi_i32 v3, v2, s30
	v_lshrrev_b32_e32 v4, 31, v3
	v_ashrrev_i32_e32 v3, 11, v3
	v_add_u32_e32 v4, v3, v4
	v_mad_i32_i24 v5, v4, s31, v2
	v_cmp_lt_i32_e64 s[0:1], 15, v5
	s_and_saveexec_b64 s[36:37], s[0:1]
	s_xor_b64 s[0:1], exec, s[36:37]
	v_lshlrev_b32_e32 v2, 12, v4
	v_add3_u32 v2, v2, v5, -16
	v_ashrrev_i32_e32 v3, 31, v2
	v_lshlrev_b64 v[2:3], 12, v[2:3]
	v_lshl_add_u64 v[2:3], s[88:89], 0, v[2:3]
	s_andn2_saveexec_b64 s[0:1], s[0:1]
	v_lshlrev_b32_e32 v2, 14, v4
	v_lshl_add_u32 v2, v5, 10, v2
	v_ashrrev_i32_e32 v3, 31, v2
	v_lshl_add_u64 v[2:3], v[2:3], 2, s[12:13]
	s_or_b64 exec, exec, s[0:1]
	v_ashrrev_i32_e32 v47, 31, v46
	v_lshlrev_b64 v[4:5], 11, v[46:47]
	v_lshl_add_u64 v[4:5], s[62:63], 0, v[4:5]
	s_waitcnt vmcnt(13)
	v_fmac_f32_e32 v90, 0.5, v27
	v_lshl_add_u64 v[4:5], v[130:131], 1, v[4:5]
	v_lshl_add_u64 v[2:3], v[2:3], 0, v[134:135]
	global_store_dword v[2:3], v90, off
	v_mul_f32_e32 v6, v90, v242
	v_cvt_pk_bf16_f32 v6, v6, s0
	global_store_short v[4:5], v6, off
.LBB0_1377:
	s_waitcnt vmcnt(12)
	v_fmac_f32_e32 v91, 0.5, v11
	global_store_dword v[2:3], v91, off offset:128
	v_mul_f32_e32 v2, v91, v243
	v_cvt_pk_bf16_f32 v2, v2, s0
	global_store_short v[4:5], v2, off offset:64
.LBB0_1379:
	v_cmp_gt_i32_e64 s[10:11], s34, v44
	s_nop 1
	v_cndmask_b32_e64 v2, v179, v44, s[10:11]
	v_mul_hi_i32 v3, v2, s30
	v_lshrrev_b32_e32 v4, 31, v3
	v_ashrrev_i32_e32 v3, 11, v3
	v_add_u32_e32 v4, v3, v4
	v_mad_i32_i24 v5, v4, s31, v2
	v_cmp_lt_i32_e64 s[0:1], 15, v5
	s_and_saveexec_b64 s[36:37], s[0:1]
	s_xor_b64 s[0:1], exec, s[36:37]
	v_lshlrev_b32_e32 v2, 12, v4
	v_add3_u32 v2, v2, v5, -16
	v_ashrrev_i32_e32 v3, 31, v2
	v_lshlrev_b64 v[2:3], 12, v[2:3]
	v_lshl_add_u64 v[2:3], s[88:89], 0, v[2:3]
	s_andn2_saveexec_b64 s[0:1], s[0:1]
	v_lshlrev_b32_e32 v2, 14, v4
	v_lshl_add_u32 v2, v5, 10, v2
	v_ashrrev_i32_e32 v3, 31, v2
	v_lshl_add_u64 v[2:3], v[2:3], 2, s[12:13]
	s_or_b64 exec, exec, s[0:1]
	v_ashrrev_i32_e32 v45, 31, v44
	v_lshlrev_b64 v[4:5], 11, v[44:45]
	v_lshl_add_u64 v[4:5], s[62:63], 0, v[4:5]
	s_waitcnt vmcnt(11)
	v_fmac_f32_e32 v92, 0.5, v28
	v_lshl_add_u64 v[4:5], v[130:131], 1, v[4:5]
	v_lshl_add_u64 v[2:3], v[2:3], 0, v[134:135]
	global_store_dword v[2:3], v92, off
	v_mul_f32_e32 v6, v92, v242
	v_cvt_pk_bf16_f32 v6, v6, s0
	global_store_short v[4:5], v6, off
.LBB0_1385:
	s_waitcnt vmcnt(10)
	v_fmac_f32_e32 v93, 0.5, v12
	global_store_dword v[2:3], v93, off offset:128
	v_mul_f32_e32 v2, v93, v243
	v_cvt_pk_bf16_f32 v2, v2, s0
	global_store_short v[4:5], v2, off offset:64
.LBB0_1387:
	v_cmp_gt_i32_e64 s[10:11], s34, v42
	s_nop 1
	v_cndmask_b32_e64 v2, v179, v42, s[10:11]
	v_mul_hi_i32 v3, v2, s30
	v_lshrrev_b32_e32 v4, 31, v3
	v_ashrrev_i32_e32 v3, 11, v3
	v_add_u32_e32 v4, v3, v4
	v_mad_i32_i24 v5, v4, s31, v2
	v_cmp_lt_i32_e64 s[0:1], 15, v5
	s_and_saveexec_b64 s[36:37], s[0:1]
	s_xor_b64 s[0:1], exec, s[36:37]
	v_lshlrev_b32_e32 v2, 12, v4
	v_add3_u32 v2, v2, v5, -16
	v_ashrrev_i32_e32 v3, 31, v2
	v_lshlrev_b64 v[2:3], 12, v[2:3]
	v_lshl_add_u64 v[2:3], s[88:89], 0, v[2:3]
	s_andn2_saveexec_b64 s[0:1], s[0:1]
	v_lshlrev_b32_e32 v2, 14, v4
	v_lshl_add_u32 v2, v5, 10, v2
	v_ashrrev_i32_e32 v3, 31, v2
	v_lshl_add_u64 v[2:3], v[2:3], 2, s[12:13]
	s_or_b64 exec, exec, s[0:1]
	v_ashrrev_i32_e32 v43, 31, v42
	v_lshlrev_b64 v[4:5], 11, v[42:43]
	v_lshl_add_u64 v[4:5], s[62:63], 0, v[4:5]
	s_waitcnt vmcnt(9)
	v_fmac_f32_e32 v94, 0.5, v29
	v_lshl_add_u64 v[4:5], v[130:131], 1, v[4:5]
	v_lshl_add_u64 v[2:3], v[2:3], 0, v[134:135]
	global_store_dword v[2:3], v94, off
	v_mul_f32_e32 v6, v94, v242
	v_cvt_pk_bf16_f32 v6, v6, s0
	global_store_short v[4:5], v6, off
.LBB0_1393:
	s_waitcnt vmcnt(8)
	v_fmac_f32_e32 v95, 0.5, v13
	global_store_dword v[2:3], v95, off offset:128
	v_mul_f32_e32 v2, v95, v243
	v_cvt_pk_bf16_f32 v2, v2, s0
	global_store_short v[4:5], v2, off offset:64
.LBB0_1395:
	v_cmp_gt_i32_e64 s[10:11], s34, v40
	s_nop 1
	v_cndmask_b32_e64 v2, v179, v40, s[10:11]
	v_mul_hi_i32 v3, v2, s30
	v_lshrrev_b32_e32 v4, 31, v3
	v_ashrrev_i32_e32 v3, 11, v3
	v_add_u32_e32 v4, v3, v4
	v_mad_i32_i24 v5, v4, s31, v2
	v_cmp_lt_i32_e64 s[0:1], 15, v5
	s_and_saveexec_b64 s[36:37], s[0:1]
	s_xor_b64 s[0:1], exec, s[36:37]
	v_lshlrev_b32_e32 v2, 12, v4
	v_add3_u32 v2, v2, v5, -16
	v_ashrrev_i32_e32 v3, 31, v2
	v_lshlrev_b64 v[2:3], 12, v[2:3]
	v_lshl_add_u64 v[2:3], s[88:89], 0, v[2:3]
	s_andn2_saveexec_b64 s[0:1], s[0:1]
	v_lshlrev_b32_e32 v2, 14, v4
	v_lshl_add_u32 v2, v5, 10, v2
	v_ashrrev_i32_e32 v3, 31, v2
	v_lshl_add_u64 v[2:3], v[2:3], 2, s[12:13]
	s_or_b64 exec, exec, s[0:1]
	v_ashrrev_i32_e32 v41, 31, v40
	v_lshlrev_b64 v[4:5], 11, v[40:41]
	v_lshl_add_u64 v[4:5], s[62:63], 0, v[4:5]
	s_waitcnt vmcnt(7)
	v_fmac_f32_e32 v96, 0.5, v30
	v_lshl_add_u64 v[4:5], v[130:131], 1, v[4:5]
	v_lshl_add_u64 v[2:3], v[2:3], 0, v[134:135]
	global_store_dword v[2:3], v96, off
	v_mul_f32_e32 v6, v96, v242
	v_cvt_pk_bf16_f32 v6, v6, s0
	global_store_short v[4:5], v6, off
.LBB0_1401:
	s_waitcnt vmcnt(6)
	v_fmac_f32_e32 v97, 0.5, v14
	global_store_dword v[2:3], v97, off offset:128
	v_mul_f32_e32 v2, v97, v243
	v_cvt_pk_bf16_f32 v2, v2, s0
	global_store_short v[4:5], v2, off offset:64
.LBB0_1403:
	v_cmp_gt_i32_e64 s[10:11], s34, v38
	s_nop 1
	v_cndmask_b32_e64 v2, v179, v38, s[10:11]
	v_mul_hi_i32 v3, v2, s30
	v_lshrrev_b32_e32 v4, 31, v3
	v_ashrrev_i32_e32 v3, 11, v3
	v_add_u32_e32 v4, v3, v4
	v_mad_i32_i24 v5, v4, s31, v2
	v_cmp_lt_i32_e64 s[0:1], 15, v5
	s_and_saveexec_b64 s[36:37], s[0:1]
	s_xor_b64 s[0:1], exec, s[36:37]
	v_lshlrev_b32_e32 v2, 12, v4
	v_add3_u32 v2, v2, v5, -16
	v_ashrrev_i32_e32 v3, 31, v2
	v_lshlrev_b64 v[2:3], 12, v[2:3]
	v_lshl_add_u64 v[2:3], s[88:89], 0, v[2:3]
	s_andn2_saveexec_b64 s[0:1], s[0:1]
	v_lshlrev_b32_e32 v2, 14, v4
	v_lshl_add_u32 v2, v5, 10, v2
	v_ashrrev_i32_e32 v3, 31, v2
	v_lshl_add_u64 v[2:3], v[2:3], 2, s[12:13]
	s_or_b64 exec, exec, s[0:1]
	v_ashrrev_i32_e32 v39, 31, v38
	v_lshlrev_b64 v[4:5], 11, v[38:39]
	v_lshl_add_u64 v[4:5], s[62:63], 0, v[4:5]
	s_waitcnt vmcnt(5)
	v_fmac_f32_e32 v99, 0.5, v31
	v_lshl_add_u64 v[4:5], v[130:131], 1, v[4:5]
	v_lshl_add_u64 v[2:3], v[2:3], 0, v[134:135]
	global_store_dword v[2:3], v99, off
	v_mul_f32_e32 v6, v99, v242
	v_cvt_pk_bf16_f32 v6, v6, s0
	global_store_short v[4:5], v6, off
.LBB0_1409:
	s_waitcnt vmcnt(4)
	v_fmac_f32_e32 v101, 0.5, v15
	global_store_dword v[2:3], v101, off offset:128
	v_mul_f32_e32 v2, v101, v243
	v_cvt_pk_bf16_f32 v2, v2, s0
	global_store_short v[4:5], v2, off offset:64
.LBB0_1411:
	v_cmp_gt_i32_e64 s[10:11], s34, v36
	s_nop 1
	v_cndmask_b32_e64 v2, v179, v36, s[10:11]
	v_mul_hi_i32 v3, v2, s30
	v_lshrrev_b32_e32 v4, 31, v3
	v_ashrrev_i32_e32 v3, 11, v3
	v_add_u32_e32 v4, v3, v4
	v_mad_i32_i24 v5, v4, s31, v2
	v_cmp_lt_i32_e64 s[0:1], 15, v5
	s_and_saveexec_b64 s[36:37], s[0:1]
	s_xor_b64 s[0:1], exec, s[36:37]
	v_lshlrev_b32_e32 v2, 12, v4
	v_add3_u32 v2, v2, v5, -16
	v_ashrrev_i32_e32 v3, 31, v2
	v_lshlrev_b64 v[2:3], 12, v[2:3]
	v_lshl_add_u64 v[2:3], s[88:89], 0, v[2:3]
	s_andn2_saveexec_b64 s[0:1], s[0:1]
	v_lshlrev_b32_e32 v2, 14, v4
	v_lshl_add_u32 v2, v5, 10, v2
	v_ashrrev_i32_e32 v3, 31, v2
	v_lshl_add_u64 v[2:3], v[2:3], 2, s[12:13]
	s_or_b64 exec, exec, s[0:1]
	v_ashrrev_i32_e32 v37, 31, v36
	v_lshlrev_b64 v[4:5], 11, v[36:37]
	v_lshl_add_u64 v[4:5], s[62:63], 0, v[4:5]
	s_waitcnt vmcnt(3)
	v_fmac_f32_e32 v102, 0.5, v32
	v_lshl_add_u64 v[4:5], v[130:131], 1, v[4:5]
	v_lshl_add_u64 v[2:3], v[2:3], 0, v[134:135]
	global_store_dword v[2:3], v102, off
	v_mul_f32_e32 v6, v102, v242
	v_cvt_pk_bf16_f32 v6, v6, s0
	global_store_short v[4:5], v6, off
.LBB0_1417:
	s_waitcnt vmcnt(2)
	v_fmac_f32_e32 v103, 0.5, v16
	global_store_dword v[2:3], v103, off offset:128
	v_mul_f32_e32 v2, v103, v243
	v_cvt_pk_bf16_f32 v2, v2, s0
	global_store_short v[4:5], v2, off offset:64
.LBB0_1419:
	v_cmp_gt_i32_e64 s[10:11], s34, v34
	s_nop 1
	v_cndmask_b32_e64 v2, v179, v34, s[10:11]
	v_mul_hi_i32 v3, v2, s30
	v_lshrrev_b32_e32 v4, 31, v3
	v_ashrrev_i32_e32 v3, 11, v3
	v_add_u32_e32 v4, v3, v4
	v_mad_i32_i24 v5, v4, s31, v2
	v_cmp_lt_i32_e64 s[0:1], 15, v5
	s_and_saveexec_b64 s[36:37], s[0:1]
	s_xor_b64 s[0:1], exec, s[36:37]
	v_lshlrev_b32_e32 v2, 12, v4
	v_add3_u32 v2, v2, v5, -16
	v_ashrrev_i32_e32 v3, 31, v2
	v_lshlrev_b64 v[2:3], 12, v[2:3]
	v_lshl_add_u64 v[2:3], s[88:89], 0, v[2:3]
	s_andn2_saveexec_b64 s[0:1], s[0:1]
	v_lshlrev_b32_e32 v2, 14, v4
	v_lshl_add_u32 v2, v5, 10, v2
	v_ashrrev_i32_e32 v3, 31, v2
	v_lshl_add_u64 v[2:3], v[2:3], 2, s[12:13]
	s_or_b64 exec, exec, s[0:1]
	v_ashrrev_i32_e32 v35, 31, v34
	v_lshlrev_b64 v[4:5], 11, v[34:35]
	v_lshl_add_u64 v[4:5], s[62:63], 0, v[4:5]
	s_waitcnt vmcnt(1)
	v_fmac_f32_e32 v98, 0.5, v33
	v_lshl_add_u64 v[4:5], v[130:131], 1, v[4:5]
	v_lshl_add_u64 v[2:3], v[2:3], 0, v[134:135]
	global_store_dword v[2:3], v98, off
	v_mul_f32_e32 v6, v98, v242
	v_cvt_pk_bf16_f32 v6, v6, s0
	global_store_short v[4:5], v6, off
.LBB0_1425:
	s_waitcnt vmcnt(0)
	v_fmac_f32_e32 v100, 0.5, v17
	s_and_saveexec_b64 s[0:1], s[10:11]
	s_cbranch_execz .LBB0_595
	global_store_dword v[2:3], v100, off offset:128
	global_load_dword v2, v[132:133], off offset:128
	s_waitcnt vmcnt(0)
	v_mul_f32_e32 v2, v100, v2
	v_cvt_pk_bf16_f32 v2, v2, s0
	global_store_short v[4:5], v2, off offset:64
	s_branch .LBB0_595

.Lrt1_f:
	v_mov_b32_e32 v172, v208
	s_nop 0
	v_ashrrev_i32_e32 v0, 1, v172
	v_and_b32_e32 v0, 0xffffff80, v0
	s_waitcnt vmcnt(7)
	v_lshrrev_b32_e32 v130, 3, v172
	v_and_b32_e32 v173, 4, v130
	v_add_u32_e32 v174, s6, v0
	s_waitcnt vmcnt(6)
	v_or_b32_e32 v136, v174, v173
	v_min_i32_e32 v130, 0x403f, v136
	v_mul_hi_i32 v0, v130, s83
	v_lshrrev_b32_e32 v131, 31, v0
	v_ashrrev_i32_e32 v0, 11, v0
	v_add_u32_e32 v0, v0, v131
	v_mad_i32_i24 v130, v0, s84, v130
	v_cmp_lt_i32_e32 vcc, 15, v130
	s_and_saveexec_b64 s[2:3], vcc
	s_xor_b64 s[2:3], exec, s[2:3]
	v_lshlrev_b32_e32 v0, 12, v0
	v_add3_u32 v130, v0, v130, -16
	v_ashrrev_i32_e32 v131, 31, v130
	v_lshlrev_b64 v[130:131], 12, v[130:131]
	v_lshl_add_u64 v[132:133], s[88:89], 0, v[130:131]
	s_andn2_saveexec_b64 s[2:3], s[2:3]
	v_lshlrev_b32_e32 v0, 14, v0
	v_lshl_add_u32 v130, v130, 10, v0
	v_ashrrev_i32_e32 v131, 31, v130
	v_lshl_add_u64 v[132:133], v[130:131], 2, s[16:17]
	s_or_b64 exec, exec, s[2:3]
	v_bfe_u32 v0, v172, 6, 2
	v_and_b32_e32 v175, 31, v172
	v_lshlrev_b32_e32 v130, 6, v0
	v_or3_b32 v130, v130, s0, v175
	v_ashrrev_i32_e32 v131, 31, v130
	v_lshl_add_u64 v[132:133], v[130:131], 2, v[132:133]
	global_load_dword v134, v[132:133], off
	global_load_dword v167, v[132:133], off offset:128
	v_or_b32_e32 v166, 1, v136
	v_min_i32_e32 v132, 0x403f, v166
	v_mul_hi_i32 v133, v132, s83
	v_lshrrev_b32_e32 v135, 31, v133
	v_ashrrev_i32_e32 v133, 11, v133
	v_add_u32_e32 v135, v133, v135
	v_mad_i32_i24 v137, v135, s84, v132
	v_cmp_lt_i32_e32 vcc, 15, v137
	s_and_saveexec_b64 s[0:1], vcc
	s_xor_b64 s[0:1], exec, s[0:1]
	v_lshlrev_b32_e32 v132, 12, v135
	v_add3_u32 v132, v132, v137, -16
	v_ashrrev_i32_e32 v133, 31, v132
	v_lshlrev_b64 v[132:133], 12, v[132:133]
	v_lshl_add_u64 v[132:133], s[88:89], 0, v[132:133]
	s_andn2_saveexec_b64 s[0:1], s[0:1]
	v_lshlrev_b32_e32 v132, 14, v135
	v_lshl_add_u32 v132, v137, 10, v132
	v_ashrrev_i32_e32 v133, 31, v132
	v_lshl_add_u64 v[132:133], v[132:133], 2, s[16:17]
	s_or_b64 exec, exec, s[0:1]
	v_lshl_add_u64 v[132:133], v[130:131], 2, v[132:133]
	global_load_dword v194, v[132:133], off
	global_load_dword v165, v[132:133], off offset:128
	v_or_b32_e32 v164, 2, v136
	v_min_i32_e32 v132, 0x403f, v164
	v_mul_hi_i32 v133, v132, s83
	v_lshrrev_b32_e32 v135, 31, v133
	v_ashrrev_i32_e32 v133, 11, v133
	v_add_u32_e32 v135, v133, v135
	v_mad_i32_i24 v137, v135, s84, v132
	v_cmp_lt_i32_e32 vcc, 15, v137
	s_and_saveexec_b64 s[0:1], vcc
	s_xor_b64 s[0:1], exec, s[0:1]
	v_lshlrev_b32_e32 v132, 12, v135
	v_add3_u32 v132, v132, v137, -16
	v_ashrrev_i32_e32 v133, 31, v132
	v_lshlrev_b64 v[132:133], 12, v[132:133]
	v_lshl_add_u64 v[132:133], s[88:89], 0, v[132:133]
	s_andn2_saveexec_b64 s[0:1], s[0:1]
	v_lshlrev_b32_e32 v132, 14, v135
	v_lshl_add_u32 v132, v137, 10, v132
	v_ashrrev_i32_e32 v133, 31, v132
	v_lshl_add_u64 v[132:133], v[132:133], 2, s[16:17]
	s_or_b64 exec, exec, s[0:1]
	v_lshl_add_u64 v[132:133], v[130:131], 2, v[132:133]
	global_load_dword v193, v[132:133], off
	global_load_dword v163, v[132:133], off offset:128
	v_or_b32_e32 v162, 3, v136
	v_min_i32_e32 v132, 0x403f, v162
	v_mul_hi_i32 v133, v132, s83
	v_lshrrev_b32_e32 v135, 31, v133
	v_ashrrev_i32_e32 v133, 11, v133
	v_add_u32_e32 v135, v133, v135
	v_mad_i32_i24 v137, v135, s84, v132
	v_cmp_lt_i32_e32 vcc, 15, v137
	s_and_saveexec_b64 s[0:1], vcc
	s_xor_b64 s[0:1], exec, s[0:1]
	v_lshlrev_b32_e32 v132, 12, v135
	v_add3_u32 v132, v132, v137, -16
	v_ashrrev_i32_e32 v133, 31, v132
	v_lshlrev_b64 v[132:133], 12, v[132:133]
	v_lshl_add_u64 v[132:133], s[88:89], 0, v[132:133]
	s_andn2_saveexec_b64 s[0:1], s[0:1]
	v_lshlrev_b32_e32 v132, 14, v135
	v_lshl_add_u32 v132, v137, 10, v132
	v_ashrrev_i32_e32 v133, 31, v132
	v_lshl_add_u64 v[132:133], v[132:133], 2, s[16:17]
	s_or_b64 exec, exec, s[0:1]
	v_lshl_add_u64 v[132:133], v[130:131], 2, v[132:133]
	global_load_dword v192, v[132:133], off
	global_load_dword v161, v[132:133], off offset:128
	s_waitcnt vmcnt(13)
	v_or_b32_e32 v160, 8, v136
	v_min_i32_e32 v132, 0x403f, v160
	v_mul_hi_i32 v133, v132, s83
	v_lshrrev_b32_e32 v135, 31, v133
	v_ashrrev_i32_e32 v133, 11, v133
	v_add_u32_e32 v135, v133, v135
	v_mad_i32_i24 v137, v135, s84, v132
	v_cmp_lt_i32_e32 vcc, 15, v137
	s_and_saveexec_b64 s[0:1], vcc
	s_xor_b64 s[0:1], exec, s[0:1]
	v_lshlrev_b32_e32 v132, 12, v135
	v_add3_u32 v132, v132, v137, -16
	v_ashrrev_i32_e32 v133, 31, v132
	v_lshlrev_b64 v[132:133], 12, v[132:133]
	v_lshl_add_u64 v[132:133], s[88:89], 0, v[132:133]
	s_andn2_saveexec_b64 s[0:1], s[0:1]
	v_lshlrev_b32_e32 v132, 14, v135
	v_lshl_add_u32 v132, v137, 10, v132
	v_ashrrev_i32_e32 v133, 31, v132
	v_lshl_add_u64 v[132:133], v[132:133], 2, s[16:17]
	s_or_b64 exec, exec, s[0:1]
	v_lshl_add_u64 v[132:133], v[130:131], 2, v[132:133]
	global_load_dword v191, v[132:133], off
	global_load_dword v159, v[132:133], off offset:128
	v_or_b32_e32 v158, 9, v136
	v_min_i32_e32 v132, 0x403f, v158
	v_mul_hi_i32 v133, v132, s83
	v_lshrrev_b32_e32 v135, 31, v133
	v_ashrrev_i32_e32 v133, 11, v133
	v_add_u32_e32 v135, v133, v135
	v_mad_i32_i24 v137, v135, s84, v132
	v_cmp_lt_i32_e32 vcc, 15, v137
	s_and_saveexec_b64 s[0:1], vcc
	s_xor_b64 s[0:1], exec, s[0:1]
	v_lshlrev_b32_e32 v132, 12, v135
	v_add3_u32 v132, v132, v137, -16
	v_ashrrev_i32_e32 v133, 31, v132
	v_lshlrev_b64 v[132:133], 12, v[132:133]
	v_lshl_add_u64 v[132:133], s[88:89], 0, v[132:133]
	s_andn2_saveexec_b64 s[0:1], s[0:1]
	v_lshlrev_b32_e32 v132, 14, v135
	v_lshl_add_u32 v132, v137, 10, v132
	v_ashrrev_i32_e32 v133, 31, v132
	v_lshl_add_u64 v[132:133], v[132:133], 2, s[16:17]
	s_or_b64 exec, exec, s[0:1]
	v_lshl_add_u64 v[132:133], v[130:131], 2, v[132:133]
	global_load_dword v190, v[132:133], off
	global_load_dword v157, v[132:133], off offset:128
	s_waitcnt vmcnt(12)
	v_or_b32_e32 v156, 10, v136
	v_min_i32_e32 v132, 0x403f, v156
	v_mul_hi_i32 v133, v132, s83
	v_lshrrev_b32_e32 v135, 31, v133
	v_ashrrev_i32_e32 v133, 11, v133
	v_add_u32_e32 v135, v133, v135
	v_mad_i32_i24 v137, v135, s84, v132
	v_cmp_lt_i32_e32 vcc, 15, v137
	s_and_saveexec_b64 s[0:1], vcc
	s_xor_b64 s[0:1], exec, s[0:1]
	v_lshlrev_b32_e32 v132, 12, v135
	v_add3_u32 v132, v132, v137, -16
	v_ashrrev_i32_e32 v133, 31, v132
	v_lshlrev_b64 v[132:133], 12, v[132:133]
	v_lshl_add_u64 v[132:133], s[88:89], 0, v[132:133]
	s_andn2_saveexec_b64 s[0:1], s[0:1]
	v_lshlrev_b32_e32 v132, 14, v135
	v_lshl_add_u32 v132, v137, 10, v132
	v_ashrrev_i32_e32 v133, 31, v132
	v_lshl_add_u64 v[132:133], v[132:133], 2, s[16:17]
	s_or_b64 exec, exec, s[0:1]
	v_lshl_add_u64 v[132:133], v[130:131], 2, v[132:133]
	global_load_dword v189, v[132:133], off
	global_load_dword v155, v[132:133], off offset:128
	v_or_b32_e32 v154, 11, v136
	v_min_i32_e32 v132, 0x403f, v154
	v_mul_hi_i32 v133, v132, s83
	v_lshrrev_b32_e32 v135, 31, v133
	v_ashrrev_i32_e32 v133, 11, v133
	v_add_u32_e32 v135, v133, v135
	v_mad_i32_i24 v137, v135, s84, v132
	v_cmp_lt_i32_e32 vcc, 15, v137
	s_and_saveexec_b64 s[0:1], vcc
	s_xor_b64 s[0:1], exec, s[0:1]
	v_lshlrev_b32_e32 v132, 12, v135
	v_add3_u32 v132, v132, v137, -16
	v_ashrrev_i32_e32 v133, 31, v132
	v_lshlrev_b64 v[132:133], 12, v[132:133]
	v_lshl_add_u64 v[132:133], s[88:89], 0, v[132:133]
	s_andn2_saveexec_b64 s[0:1], s[0:1]
	v_lshlrev_b32_e32 v132, 14, v135
	v_lshl_add_u32 v132, v137, 10, v132
	v_ashrrev_i32_e32 v133, 31, v132
	v_lshl_add_u64 v[132:133], v[132:133], 2, s[16:17]
	s_or_b64 exec, exec, s[0:1]
	v_lshl_add_u64 v[132:133], v[130:131], 2, v[132:133]
	global_load_dword v188, v[132:133], off
	global_load_dword v153, v[132:133], off offset:128
	v_or_b32_e32 v152, 16, v136
	v_min_i32_e32 v132, 0x403f, v152
	v_mul_hi_i32 v133, v132, s83
	v_lshrrev_b32_e32 v135, 31, v133
	v_ashrrev_i32_e32 v133, 11, v133
	v_add_u32_e32 v135, v133, v135
	v_mad_i32_i24 v137, v135, s84, v132
	v_cmp_lt_i32_e32 vcc, 15, v137
	s_and_saveexec_b64 s[0:1], vcc
	s_xor_b64 s[0:1], exec, s[0:1]
	v_lshlrev_b32_e32 v132, 12, v135
	v_add3_u32 v132, v132, v137, -16
	v_ashrrev_i32_e32 v133, 31, v132
	v_lshlrev_b64 v[132:133], 12, v[132:133]
	v_lshl_add_u64 v[132:133], s[88:89], 0, v[132:133]
	s_andn2_saveexec_b64 s[0:1], s[0:1]
	v_lshlrev_b32_e32 v132, 14, v135
	v_lshl_add_u32 v132, v137, 10, v132
	v_ashrrev_i32_e32 v133, 31, v132
	v_lshl_add_u64 v[132:133], v[132:133], 2, s[16:17]
	s_or_b64 exec, exec, s[0:1]
	v_lshl_add_u64 v[132:133], v[130:131], 2, v[132:133]
	global_load_dword v187, v[132:133], off
	global_load_dword v151, v[132:133], off offset:128
	v_or_b32_e32 v150, 17, v136
	v_min_i32_e32 v132, 0x403f, v150
	v_mul_hi_i32 v133, v132, s83
	v_lshrrev_b32_e32 v135, 31, v133
	v_ashrrev_i32_e32 v133, 11, v133
	v_add_u32_e32 v135, v133, v135
	v_mad_i32_i24 v137, v135, s84, v132
	v_cmp_lt_i32_e32 vcc, 15, v137
	s_and_saveexec_b64 s[0:1], vcc
	s_xor_b64 s[0:1], exec, s[0:1]
	v_lshlrev_b32_e32 v132, 12, v135
	v_add3_u32 v132, v132, v137, -16
	v_ashrrev_i32_e32 v133, 31, v132
	v_lshlrev_b64 v[132:133], 12, v[132:133]
	v_lshl_add_u64 v[132:133], s[88:89], 0, v[132:133]
	s_andn2_saveexec_b64 s[0:1], s[0:1]
	v_lshlrev_b32_e32 v132, 14, v135
	v_lshl_add_u32 v132, v137, 10, v132
	v_ashrrev_i32_e32 v133, 31, v132
	v_lshl_add_u64 v[132:133], v[132:133], 2, s[16:17]
	s_or_b64 exec, exec, s[0:1]
	v_lshl_add_u64 v[132:133], v[130:131], 2, v[132:133]
	global_load_dword v186, v[132:133], off
	global_load_dword v149, v[132:133], off offset:128
	v_or_b32_e32 v148, 18, v136
	v_min_i32_e32 v132, 0x403f, v148
	v_mul_hi_i32 v133, v132, s83
	v_lshrrev_b32_e32 v135, 31, v133
	v_ashrrev_i32_e32 v133, 11, v133
	v_add_u32_e32 v135, v133, v135
	v_mad_i32_i24 v137, v135, s84, v132
	v_cmp_lt_i32_e32 vcc, 15, v137
	s_and_saveexec_b64 s[0:1], vcc
	s_xor_b64 s[0:1], exec, s[0:1]
	v_lshlrev_b32_e32 v132, 12, v135
	v_add3_u32 v132, v132, v137, -16
	v_ashrrev_i32_e32 v133, 31, v132
	v_lshlrev_b64 v[132:133], 12, v[132:133]
	v_lshl_add_u64 v[132:133], s[88:89], 0, v[132:133]
	s_andn2_saveexec_b64 s[0:1], s[0:1]
	v_lshlrev_b32_e32 v132, 14, v135
	v_lshl_add_u32 v132, v137, 10, v132
	v_ashrrev_i32_e32 v133, 31, v132
	v_lshl_add_u64 v[132:133], v[132:133], 2, s[16:17]
	s_or_b64 exec, exec, s[0:1]
	v_lshl_add_u64 v[132:133], v[130:131], 2, v[132:133]
	global_load_dword v185, v[132:133], off
	global_load_dword v147, v[132:133], off offset:128
	v_or_b32_e32 v146, 19, v136
	v_min_i32_e32 v132, 0x403f, v146
	v_mul_hi_i32 v133, v132, s83
	v_lshrrev_b32_e32 v135, 31, v133
	v_ashrrev_i32_e32 v133, 11, v133
	v_add_u32_e32 v135, v133, v135
	v_mad_i32_i24 v137, v135, s84, v132
	v_cmp_lt_i32_e32 vcc, 15, v137
	s_and_saveexec_b64 s[0:1], vcc
	s_xor_b64 s[0:1], exec, s[0:1]
	v_lshlrev_b32_e32 v132, 12, v135
	v_add3_u32 v132, v132, v137, -16
	v_ashrrev_i32_e32 v133, 31, v132
	v_lshlrev_b64 v[132:133], 12, v[132:133]
	v_lshl_add_u64 v[132:133], s[88:89], 0, v[132:133]
	s_andn2_saveexec_b64 s[0:1], s[0:1]
	v_lshlrev_b32_e32 v132, 14, v135
	v_lshl_add_u32 v132, v137, 10, v132
	v_ashrrev_i32_e32 v133, 31, v132
	v_lshl_add_u64 v[132:133], v[132:133], 2, s[16:17]
	s_or_b64 exec, exec, s[0:1]
	v_lshl_add_u64 v[132:133], v[130:131], 2, v[132:133]
	global_load_dword v184, v[132:133], off
	global_load_dword v145, v[132:133], off offset:128
	v_or_b32_e32 v144, 24, v136
	v_min_i32_e32 v132, 0x403f, v144
	v_mul_hi_i32 v133, v132, s83
	v_lshrrev_b32_e32 v135, 31, v133
	v_ashrrev_i32_e32 v133, 11, v133
	v_add_u32_e32 v135, v133, v135
	v_mad_i32_i24 v137, v135, s84, v132
	v_cmp_lt_i32_e32 vcc, 15, v137
	s_and_saveexec_b64 s[0:1], vcc
	s_xor_b64 s[0:1], exec, s[0:1]
	v_lshlrev_b32_e32 v132, 12, v135
	v_add3_u32 v132, v132, v137, -16
	v_ashrrev_i32_e32 v133, 31, v132
	v_lshlrev_b64 v[132:133], 12, v[132:133]
	v_lshl_add_u64 v[132:133], s[88:89], 0, v[132:133]
	s_andn2_saveexec_b64 s[0:1], s[0:1]
	v_lshlrev_b32_e32 v132, 14, v135
	v_lshl_add_u32 v132, v137, 10, v132
	v_ashrrev_i32_e32 v133, 31, v132
	v_lshl_add_u64 v[132:133], v[132:133], 2, s[16:17]
	s_or_b64 exec, exec, s[0:1]
	v_lshl_add_u64 v[132:133], v[130:131], 2, v[132:133]
	global_load_dword v183, v[132:133], off
	global_load_dword v143, v[132:133], off offset:128
	v_or_b32_e32 v142, 25, v136
	v_min_i32_e32 v132, 0x403f, v142
	v_mul_hi_i32 v133, v132, s83
	v_lshrrev_b32_e32 v135, 31, v133
	v_ashrrev_i32_e32 v133, 11, v133
	v_add_u32_e32 v135, v133, v135
	v_mad_i32_i24 v137, v135, s84, v132
	v_cmp_lt_i32_e32 vcc, 15, v137
	s_and_saveexec_b64 s[0:1], vcc
	s_xor_b64 s[0:1], exec, s[0:1]
	v_lshlrev_b32_e32 v132, 12, v135
	v_add3_u32 v132, v132, v137, -16
	v_ashrrev_i32_e32 v133, 31, v132
	v_lshlrev_b64 v[132:133], 12, v[132:133]
	v_lshl_add_u64 v[132:133], s[88:89], 0, v[132:133]
	s_andn2_saveexec_b64 s[0:1], s[0:1]
	v_lshlrev_b32_e32 v132, 14, v135
	v_lshl_add_u32 v132, v137, 10, v132
	v_ashrrev_i32_e32 v133, 31, v132
	v_lshl_add_u64 v[132:133], v[132:133], 2, s[16:17]
	s_or_b64 exec, exec, s[0:1]
	v_lshl_add_u64 v[132:133], v[130:131], 2, v[132:133]
	global_load_dword v182, v[132:133], off
	global_load_dword v141, v[132:133], off offset:128
	v_or_b32_e32 v140, 26, v136
	v_min_i32_e32 v132, 0x403f, v140
	v_mul_hi_i32 v133, v132, s83
	v_lshrrev_b32_e32 v135, 31, v133
	v_ashrrev_i32_e32 v133, 11, v133
	v_add_u32_e32 v135, v133, v135
	v_mad_i32_i24 v137, v135, s84, v132
	v_cmp_lt_i32_e32 vcc, 15, v137
	s_and_saveexec_b64 s[0:1], vcc
	s_xor_b64 s[0:1], exec, s[0:1]
	v_lshlrev_b32_e32 v132, 12, v135
	v_add3_u32 v132, v132, v137, -16
	v_ashrrev_i32_e32 v133, 31, v132
	v_lshlrev_b64 v[132:133], 12, v[132:133]
	v_lshl_add_u64 v[132:133], s[88:89], 0, v[132:133]
	s_andn2_saveexec_b64 s[0:1], s[0:1]
	v_lshlrev_b32_e32 v132, 14, v135
	v_lshl_add_u32 v132, v137, 10, v132
	v_ashrrev_i32_e32 v133, 31, v132
	v_lshl_add_u64 v[132:133], v[132:133], 2, s[16:17]
	s_or_b64 exec, exec, s[0:1]
	v_lshl_add_u64 v[132:133], v[130:131], 2, v[132:133]
	global_load_dword v179, v[132:133], off
	global_load_dword v139, v[132:133], off offset:128
	v_or_b32_e32 v138, 27, v136
	v_min_i32_e32 v132, 0x403f, v138
	v_mul_hi_i32 v133, v132, s83
	v_lshrrev_b32_e32 v135, 31, v133
	v_ashrrev_i32_e32 v133, 11, v133
	v_add_u32_e32 v135, v133, v135
	v_mad_i32_i24 v137, v135, s84, v132
	v_cmp_lt_i32_e32 vcc, 15, v137
	s_and_saveexec_b64 s[0:1], vcc
	s_xor_b64 s[0:1], exec, s[0:1]
	v_lshlrev_b32_e32 v132, 12, v135
	v_add3_u32 v132, v132, v137, -16
	v_ashrrev_i32_e32 v133, 31, v132
	v_lshlrev_b64 v[132:133], 12, v[132:133]
	v_lshl_add_u64 v[132:133], s[88:89], 0, v[132:133]
	s_andn2_saveexec_b64 s[0:1], s[0:1]
	v_lshlrev_b32_e32 v132, 14, v135
	v_lshl_add_u32 v132, v137, 10, v132
	v_ashrrev_i32_e32 v133, 31, v132
	v_lshl_add_u64 v[132:133], v[132:133], 2, s[16:17]
	s_or_b64 exec, exec, s[0:1]
	v_lshl_add_u64 v[132:133], v[130:131], 2, v[132:133]
	global_load_dword v178, v[132:133], off
	global_load_dword v177, v[132:133], off offset:128
	v_cmp_gt_i32_e32 vcc, s85, v136
	s_nop 1
	v_cndmask_b32_e32 v132, v181, v136, vcc
	v_mul_hi_i32 v133, v132, s83
	v_lshrrev_b32_e32 v135, 31, v133
	v_ashrrev_i32_e32 v133, 11, v133
	v_add_u32_e32 v135, v133, v135
	v_mad_i32_i24 v137, v135, s84, v132
	v_cmp_lt_i32_e64 s[0:1], 15, v137
	s_and_saveexec_b64 s[2:3], s[0:1]
	s_xor_b64 s[0:1], exec, s[2:3]
	v_lshlrev_b32_e32 v132, 12, v135
	v_add3_u32 v132, v132, v137, -16
	v_ashrrev_i32_e32 v133, 31, v132
	v_lshlrev_b64 v[132:133], 12, v[132:133]
	v_lshl_add_u64 v[132:133], s[88:89], 0, v[132:133]
	s_andn2_saveexec_b64 s[0:1], s[0:1]
	v_lshlrev_b32_e32 v132, 14, v135
	v_lshl_add_u32 v132, v137, 10, v132
	v_ashrrev_i32_e32 v133, 31, v132
	v_lshl_add_u64 v[132:133], v[132:133], 2, s[16:17]
	s_or_b64 exec, exec, s[0:1]
	v_ashrrev_i32_e32 v137, 31, v136
	v_lshlrev_b64 v[168:169], 11, v[136:137]
	v_readlane_b32 s44, v239, 4
	v_lshl_add_u64 v[168:169], s[62:63], 0, v[168:169]
	s_waitcnt vmcnt(31)
	v_add_f32_e32 v137, v114, v134
	v_lshlrev_b64 v[134:135], 2, v[130:131]
	v_readlane_b32 s50, v239, 10
	v_readlane_b32 s51, v239, 11
	v_lshl_add_u64 v[168:169], v[130:131], 1, v[168:169]
	v_lshl_add_u64 v[170:171], v[132:133], 0, v[134:135]
	v_lshl_add_u64 v[132:133], s[50:51], 0, v[134:135]
	global_load_dword v242, v[132:133], off
	global_load_dword v243, v[132:133], off offset:128
	s_waitcnt vmcnt(0)
	v_readlane_b32 s45, v239, 5
	v_readlane_b32 s46, v239, 6
	v_readlane_b32 s47, v239, 7
	v_readlane_b32 s48, v239, 8
	v_readlane_b32 s49, v239, 9
	v_readlane_b32 s52, v239, 12
	v_readlane_b32 s53, v239, 13
	v_readlane_b32 s54, v239, 14
	v_readlane_b32 s55, v239, 15
	v_readlane_b32 s56, v239, 16
	v_readlane_b32 s57, v239, 17
	v_readlane_b32 s58, v239, 18
	v_readlane_b32 s59, v239, 19
	global_store_dword v[170:171], v137, off
	v_mul_f32_e32 v114, v137, v242
	v_cvt_pk_bf16_f32 v114, v114, s0
	global_store_short v[168:169], v114, off
.LBB0_3711:
	s_waitcnt vmcnt(30)
	v_add_f32_e32 v176, v98, v167
	global_store_dword v[170:171], v176, off offset:128
	v_mul_f32_e32 v98, v176, v243
	v_cvt_pk_bf16_f32 v98, v98, s0
	global_store_short v[168:169], v98, off offset:64
.LBB0_3713:
	v_cmp_gt_i32_e32 vcc, s85, v166
	s_nop 1
	v_cndmask_b32_e32 v114, v181, v166, vcc
	v_mul_hi_i32 v98, v114, s83
	v_lshrrev_b32_e32 v167, 31, v98
	v_ashrrev_i32_e32 v98, 11, v98
	v_add_u32_e32 v98, v98, v167
	v_mad_i32_i24 v114, v98, s84, v114
	v_cmp_lt_i32_e64 s[0:1], 15, v114
	s_and_saveexec_b64 s[2:3], s[0:1]
	s_xor_b64 s[0:1], exec, s[2:3]
	v_lshlrev_b32_e32 v98, 12, v98
	v_add3_u32 v168, v98, v114, -16
	v_ashrrev_i32_e32 v169, 31, v168
	v_lshlrev_b64 v[168:169], 12, v[168:169]
	v_lshl_add_u64 v[168:169], s[88:89], 0, v[168:169]
	s_andn2_saveexec_b64 s[0:1], s[0:1]
	v_lshlrev_b32_e32 v98, 14, v98
	v_lshl_add_u32 v168, v114, 10, v98
	v_ashrrev_i32_e32 v169, 31, v168
	v_lshl_add_u64 v[168:169], v[168:169], 2, s[16:17]
	s_or_b64 exec, exec, s[0:1]
	v_ashrrev_i32_e32 v167, 31, v166
	v_lshlrev_b64 v[166:167], 11, v[166:167]
	v_lshl_add_u64 v[166:167], s[62:63], 0, v[166:167]
	s_waitcnt vmcnt(29)
	v_add_f32_e32 v170, v115, v194
	v_lshl_add_u64 v[114:115], v[130:131], 1, v[166:167]
	v_lshl_add_u64 v[166:167], v[168:169], 0, v[134:135]
	global_store_dword v[166:167], v170, off
	v_mul_f32_e32 v98, v170, v242
	v_cvt_pk_bf16_f32 v98, v98, s0
	global_store_short v[114:115], v98, off
.LBB0_3719:
	s_waitcnt vmcnt(28)
	v_add_f32_e32 v168, v99, v165
	global_store_dword v[166:167], v168, off offset:128
	v_mul_f32_e32 v98, v168, v243
	v_cvt_pk_bf16_f32 v98, v98, s0
	global_store_short v[114:115], v98, off offset:64
.LBB0_3721:
	v_cmp_gt_i32_e32 vcc, s85, v164
	s_nop 1
	v_cndmask_b32_e32 v98, v181, v164, vcc
	v_mul_hi_i32 v99, v98, s83
	v_lshrrev_b32_e32 v114, 31, v99
	v_ashrrev_i32_e32 v99, 11, v99
	v_add_u32_e32 v114, v99, v114
	v_mad_i32_i24 v115, v114, s84, v98
	v_cmp_lt_i32_e64 s[0:1], 15, v115
	s_and_saveexec_b64 s[2:3], s[0:1]
	s_xor_b64 s[0:1], exec, s[2:3]
	v_lshlrev_b32_e32 v98, 12, v114
	v_add3_u32 v98, v98, v115, -16
	v_ashrrev_i32_e32 v99, 31, v98
	v_lshlrev_b64 v[98:99], 12, v[98:99]
	v_lshl_add_u64 v[98:99], s[88:89], 0, v[98:99]
	s_andn2_saveexec_b64 s[0:1], s[0:1]
	v_lshlrev_b32_e32 v98, 14, v114
	v_lshl_add_u32 v98, v115, 10, v98
	v_ashrrev_i32_e32 v99, 31, v98
	v_lshl_add_u64 v[98:99], v[98:99], 2, s[16:17]
	s_or_b64 exec, exec, s[0:1]
	v_ashrrev_i32_e32 v165, 31, v164
	v_lshlrev_b64 v[114:115], 11, v[164:165]
	v_lshl_add_u64 v[114:115], s[62:63], 0, v[114:115]
	s_waitcnt vmcnt(27)
	v_add_f32_e32 v164, v116, v193
	v_lshl_add_u64 v[114:115], v[130:131], 1, v[114:115]
	v_lshl_add_u64 v[98:99], v[98:99], 0, v[134:135]
	global_store_dword v[98:99], v164, off
	v_mul_f32_e32 v116, v164, v242
	v_cvt_pk_bf16_f32 v116, v116, s0
	global_store_short v[114:115], v116, off
.LBB0_3727:
	s_waitcnt vmcnt(26)
	v_add_f32_e32 v165, v100, v163
	global_store_dword v[98:99], v165, off offset:128
	v_mul_f32_e32 v98, v165, v243
	v_cvt_pk_bf16_f32 v98, v98, s0
	global_store_short v[114:115], v98, off offset:64
.LBB0_3729:
	v_cmp_gt_i32_e32 vcc, s85, v162
	s_nop 1
	v_cndmask_b32_e32 v98, v181, v162, vcc
	v_mul_hi_i32 v99, v98, s83
	v_lshrrev_b32_e32 v100, 31, v99
	v_ashrrev_i32_e32 v99, 11, v99
	v_add_u32_e32 v100, v99, v100
	v_mad_i32_i24 v114, v100, s84, v98
	v_cmp_lt_i32_e64 s[0:1], 15, v114
	s_and_saveexec_b64 s[2:3], s[0:1]
	s_xor_b64 s[0:1], exec, s[2:3]
	v_lshlrev_b32_e32 v98, 12, v100
	v_add3_u32 v98, v98, v114, -16
	v_ashrrev_i32_e32 v99, 31, v98
	v_lshlrev_b64 v[98:99], 12, v[98:99]
	v_lshl_add_u64 v[98:99], s[88:89], 0, v[98:99]
	s_andn2_saveexec_b64 s[0:1], s[0:1]
	v_lshlrev_b32_e32 v98, 14, v100
	v_lshl_add_u32 v98, v114, 10, v98
	v_ashrrev_i32_e32 v99, 31, v98
	v_lshl_add_u64 v[98:99], v[98:99], 2, s[16:17]
	s_or_b64 exec, exec, s[0:1]
	v_ashrrev_i32_e32 v163, 31, v162
	v_lshlrev_b64 v[114:115], 11, v[162:163]
	v_lshl_add_u64 v[114:115], s[62:63], 0, v[114:115]
	s_waitcnt vmcnt(25)
	v_add_f32_e32 v162, v117, v192
	v_lshl_add_u64 v[114:115], v[130:131], 1, v[114:115]
	v_lshl_add_u64 v[98:99], v[98:99], 0, v[134:135]
	global_store_dword v[98:99], v162, off
	v_mul_f32_e32 v100, v162, v242
	v_cvt_pk_bf16_f32 v100, v100, s0
	global_store_short v[114:115], v100, off
.LBB0_3735:
	s_waitcnt vmcnt(24)
	v_add_f32_e32 v163, v101, v161
	global_store_dword v[98:99], v163, off offset:128
	v_mul_f32_e32 v98, v163, v243
	v_cvt_pk_bf16_f32 v98, v98, s0
	global_store_short v[114:115], v98, off offset:64
.LBB0_3737:
	v_cmp_gt_i32_e32 vcc, s85, v160
	s_nop 1
	v_cndmask_b32_e32 v98, v181, v160, vcc
	v_mul_hi_i32 v99, v98, s83
	v_lshrrev_b32_e32 v100, 31, v99
	v_ashrrev_i32_e32 v99, 11, v99
	v_add_u32_e32 v100, v99, v100
	v_mad_i32_i24 v101, v100, s84, v98
	v_cmp_lt_i32_e64 s[0:1], 15, v101
	s_and_saveexec_b64 s[2:3], s[0:1]
	s_xor_b64 s[0:1], exec, s[2:3]
	v_lshlrev_b32_e32 v98, 12, v100
	v_add3_u32 v98, v98, v101, -16
	v_ashrrev_i32_e32 v99, 31, v98
	v_lshlrev_b64 v[98:99], 12, v[98:99]
	v_lshl_add_u64 v[98:99], s[88:89], 0, v[98:99]
	s_andn2_saveexec_b64 s[0:1], s[0:1]
	v_lshlrev_b32_e32 v98, 14, v100
	v_lshl_add_u32 v98, v101, 10, v98
	v_ashrrev_i32_e32 v99, 31, v98
	v_lshl_add_u64 v[98:99], v[98:99], 2, s[16:17]
	s_or_b64 exec, exec, s[0:1]
	v_ashrrev_i32_e32 v161, 31, v160
	v_lshlrev_b64 v[100:101], 11, v[160:161]
	v_lshl_add_u64 v[100:101], s[62:63], 0, v[100:101]
	s_waitcnt vmcnt(23)
	v_add_f32_e32 v160, v118, v191
	v_lshl_add_u64 v[100:101], v[130:131], 1, v[100:101]
	v_lshl_add_u64 v[98:99], v[98:99], 0, v[134:135]
	global_store_dword v[98:99], v160, off
	v_mul_f32_e32 v114, v160, v242
	v_cvt_pk_bf16_f32 v114, v114, s0
	global_store_short v[100:101], v114, off
.LBB0_3743:
	s_waitcnt vmcnt(22)
	v_add_f32_e32 v161, v102, v159
	global_store_dword v[98:99], v161, off offset:128
	v_mul_f32_e32 v98, v161, v243
	v_cvt_pk_bf16_f32 v98, v98, s0
	global_store_short v[100:101], v98, off offset:64
.LBB0_3745:
	v_cmp_gt_i32_e32 vcc, s85, v158
	s_nop 1
	v_cndmask_b32_e32 v98, v181, v158, vcc
	v_mul_hi_i32 v99, v98, s83
	v_lshrrev_b32_e32 v100, 31, v99
	v_ashrrev_i32_e32 v99, 11, v99
	v_add_u32_e32 v100, v99, v100
	v_mad_i32_i24 v101, v100, s84, v98
	v_cmp_lt_i32_e64 s[0:1], 15, v101
	s_and_saveexec_b64 s[2:3], s[0:1]
	s_xor_b64 s[0:1], exec, s[2:3]
	v_lshlrev_b32_e32 v98, 12, v100
	v_add3_u32 v98, v98, v101, -16
	v_ashrrev_i32_e32 v99, 31, v98
	v_lshlrev_b64 v[98:99], 12, v[98:99]
	v_lshl_add_u64 v[98:99], s[88:89], 0, v[98:99]
	s_andn2_saveexec_b64 s[0:1], s[0:1]
	v_lshlrev_b32_e32 v98, 14, v100
	v_lshl_add_u32 v98, v101, 10, v98
	v_ashrrev_i32_e32 v99, 31, v98
	v_lshl_add_u64 v[98:99], v[98:99], 2, s[16:17]
	s_or_b64 exec, exec, s[0:1]
	v_ashrrev_i32_e32 v159, 31, v158
	v_lshlrev_b64 v[100:101], 11, v[158:159]
	v_lshl_add_u64 v[100:101], s[62:63], 0, v[100:101]
	s_waitcnt vmcnt(21)
	v_add_f32_e32 v158, v119, v190
	v_lshl_add_u64 v[100:101], v[130:131], 1, v[100:101]
	v_lshl_add_u64 v[98:99], v[98:99], 0, v[134:135]
	global_store_dword v[98:99], v158, off
	v_mul_f32_e32 v102, v158, v242
	v_cvt_pk_bf16_f32 v102, v102, s0
	global_store_short v[100:101], v102, off
.LBB0_3751:
	s_waitcnt vmcnt(20)
	v_add_f32_e32 v159, v103, v157
	global_store_dword v[98:99], v159, off offset:128
	v_mul_f32_e32 v98, v159, v243
	v_cvt_pk_bf16_f32 v98, v98, s0
	global_store_short v[100:101], v98, off offset:64
.LBB0_3753:
	v_cmp_gt_i32_e32 vcc, s85, v156
	s_nop 1
	v_cndmask_b32_e32 v98, v181, v156, vcc
	v_mul_hi_i32 v99, v98, s83
	v_lshrrev_b32_e32 v100, 31, v99
	v_ashrrev_i32_e32 v99, 11, v99
	v_add_u32_e32 v100, v99, v100
	v_mad_i32_i24 v101, v100, s84, v98
	v_cmp_lt_i32_e64 s[0:1], 15, v101
	s_and_saveexec_b64 s[2:3], s[0:1]
	s_xor_b64 s[0:1], exec, s[2:3]
	v_lshlrev_b32_e32 v98, 12, v100
	v_add3_u32 v98, v98, v101, -16
	v_ashrrev_i32_e32 v99, 31, v98
	v_lshlrev_b64 v[98:99], 12, v[98:99]
	v_lshl_add_u64 v[98:99], s[88:89], 0, v[98:99]
	s_andn2_saveexec_b64 s[0:1], s[0:1]
	v_lshlrev_b32_e32 v98, 14, v100
	v_lshl_add_u32 v98, v101, 10, v98
	v_ashrrev_i32_e32 v99, 31, v98
	v_lshl_add_u64 v[98:99], v[98:99], 2, s[16:17]
	s_or_b64 exec, exec, s[0:1]
	v_ashrrev_i32_e32 v157, 31, v156
	v_lshlrev_b64 v[100:101], 11, v[156:157]
	v_lshl_add_u64 v[100:101], s[62:63], 0, v[100:101]
	s_waitcnt vmcnt(19)
	v_add_f32_e32 v156, v120, v189
	v_lshl_add_u64 v[100:101], v[130:131], 1, v[100:101]
	v_lshl_add_u64 v[98:99], v[98:99], 0, v[134:135]
	global_store_dword v[98:99], v156, off
	v_mul_f32_e32 v102, v156, v242
	v_cvt_pk_bf16_f32 v102, v102, s0
	global_store_short v[100:101], v102, off
.LBB0_3759:
	s_waitcnt vmcnt(18)
	v_add_f32_e32 v157, v104, v155
	global_store_dword v[98:99], v157, off offset:128
	v_mul_f32_e32 v98, v157, v243
	v_cvt_pk_bf16_f32 v98, v98, s0
	global_store_short v[100:101], v98, off offset:64
.LBB0_3761:
	v_cmp_gt_i32_e32 vcc, s85, v154
	s_nop 1
	v_cndmask_b32_e32 v98, v181, v154, vcc
	v_mul_hi_i32 v99, v98, s83
	v_lshrrev_b32_e32 v100, 31, v99
	v_ashrrev_i32_e32 v99, 11, v99
	v_add_u32_e32 v100, v99, v100
	v_mad_i32_i24 v101, v100, s84, v98
	v_cmp_lt_i32_e64 s[0:1], 15, v101
	s_and_saveexec_b64 s[2:3], s[0:1]
	s_xor_b64 s[0:1], exec, s[2:3]
	v_lshlrev_b32_e32 v98, 12, v100
	v_add3_u32 v98, v98, v101, -16
	v_ashrrev_i32_e32 v99, 31, v98
	v_lshlrev_b64 v[98:99], 12, v[98:99]
	v_lshl_add_u64 v[98:99], s[88:89], 0, v[98:99]
	s_andn2_saveexec_b64 s[0:1], s[0:1]
	v_lshlrev_b32_e32 v98, 14, v100
	v_lshl_add_u32 v98, v101, 10, v98
	v_ashrrev_i32_e32 v99, 31, v98
	v_lshl_add_u64 v[98:99], v[98:99], 2, s[16:17]
	s_or_b64 exec, exec, s[0:1]
	v_ashrrev_i32_e32 v155, 31, v154
	v_lshlrev_b64 v[100:101], 11, v[154:155]
	v_lshl_add_u64 v[100:101], s[62:63], 0, v[100:101]
	s_waitcnt vmcnt(17)
	v_add_f32_e32 v154, v121, v188
	v_lshl_add_u64 v[100:101], v[130:131], 1, v[100:101]
	v_lshl_add_u64 v[98:99], v[98:99], 0, v[134:135]
	global_store_dword v[98:99], v154, off
	v_mul_f32_e32 v102, v154, v242
	v_cvt_pk_bf16_f32 v102, v102, s0
	global_store_short v[100:101], v102, off
.LBB0_3767:
	s_waitcnt vmcnt(16)
	v_add_f32_e32 v155, v105, v153
	global_store_dword v[98:99], v155, off offset:128
	v_mul_f32_e32 v98, v155, v243
	v_cvt_pk_bf16_f32 v98, v98, s0
	global_store_short v[100:101], v98, off offset:64
.LBB0_3769:
	v_cmp_gt_i32_e32 vcc, s85, v152
	s_nop 1
	v_cndmask_b32_e32 v98, v181, v152, vcc
	v_mul_hi_i32 v99, v98, s83
	v_lshrrev_b32_e32 v100, 31, v99
	v_ashrrev_i32_e32 v99, 11, v99
	v_add_u32_e32 v100, v99, v100
	v_mad_i32_i24 v101, v100, s84, v98
	v_cmp_lt_i32_e64 s[0:1], 15, v101
	s_and_saveexec_b64 s[2:3], s[0:1]
	s_xor_b64 s[0:1], exec, s[2:3]
	v_lshlrev_b32_e32 v98, 12, v100
	v_add3_u32 v98, v98, v101, -16
	v_ashrrev_i32_e32 v99, 31, v98
	v_lshlrev_b64 v[98:99], 12, v[98:99]
	v_lshl_add_u64 v[98:99], s[88:89], 0, v[98:99]
	s_andn2_saveexec_b64 s[0:1], s[0:1]
	v_lshlrev_b32_e32 v98, 14, v100
	v_lshl_add_u32 v98, v101, 10, v98
	v_ashrrev_i32_e32 v99, 31, v98
	v_lshl_add_u64 v[98:99], v[98:99], 2, s[16:17]
	s_or_b64 exec, exec, s[0:1]
	v_ashrrev_i32_e32 v153, 31, v152
	v_lshlrev_b64 v[100:101], 11, v[152:153]
	v_lshl_add_u64 v[100:101], s[62:63], 0, v[100:101]
	s_waitcnt vmcnt(15)
	v_add_f32_e32 v152, v122, v187
	v_lshl_add_u64 v[100:101], v[130:131], 1, v[100:101]
	v_lshl_add_u64 v[98:99], v[98:99], 0, v[134:135]
	global_store_dword v[98:99], v152, off
	v_mul_f32_e32 v102, v152, v242
	v_cvt_pk_bf16_f32 v102, v102, s0
	global_store_short v[100:101], v102, off
.LBB0_3775:
	s_waitcnt vmcnt(14)
	v_add_f32_e32 v153, v106, v151
	global_store_dword v[98:99], v153, off offset:128
	v_mul_f32_e32 v98, v153, v243
	v_cvt_pk_bf16_f32 v98, v98, s0
	global_store_short v[100:101], v98, off offset:64
.LBB0_3777:
	v_cmp_gt_i32_e32 vcc, s85, v150
	s_nop 1
	v_cndmask_b32_e32 v98, v181, v150, vcc
	v_mul_hi_i32 v99, v98, s83
	v_lshrrev_b32_e32 v100, 31, v99
	v_ashrrev_i32_e32 v99, 11, v99
	v_add_u32_e32 v100, v99, v100
	v_mad_i32_i24 v101, v100, s84, v98
	v_cmp_lt_i32_e64 s[0:1], 15, v101
	s_and_saveexec_b64 s[2:3], s[0:1]
	s_xor_b64 s[0:1], exec, s[2:3]
	v_lshlrev_b32_e32 v98, 12, v100
	v_add3_u32 v98, v98, v101, -16
	v_ashrrev_i32_e32 v99, 31, v98
	v_lshlrev_b64 v[98:99], 12, v[98:99]
	v_lshl_add_u64 v[98:99], s[88:89], 0, v[98:99]
	s_andn2_saveexec_b64 s[0:1], s[0:1]
	v_lshlrev_b32_e32 v98, 14, v100
	v_lshl_add_u32 v98, v101, 10, v98
	v_ashrrev_i32_e32 v99, 31, v98
	v_lshl_add_u64 v[98:99], v[98:99], 2, s[16:17]
	s_or_b64 exec, exec, s[0:1]
	v_ashrrev_i32_e32 v151, 31, v150
	v_lshlrev_b64 v[100:101], 11, v[150:151]
	v_lshl_add_u64 v[100:101], s[62:63], 0, v[100:101]
	s_waitcnt vmcnt(13)
	v_add_f32_e32 v150, v123, v186
	v_lshl_add_u64 v[100:101], v[130:131], 1, v[100:101]
	v_lshl_add_u64 v[98:99], v[98:99], 0, v[134:135]
	global_store_dword v[98:99], v150, off
	v_mul_f32_e32 v102, v150, v242
	v_cvt_pk_bf16_f32 v102, v102, s0
	global_store_short v[100:101], v102, off
.LBB0_3783:
	s_waitcnt vmcnt(12)
	v_add_f32_e32 v151, v107, v149
	global_store_dword v[98:99], v151, off offset:128
	v_mul_f32_e32 v98, v151, v243
	v_cvt_pk_bf16_f32 v98, v98, s0
	global_store_short v[100:101], v98, off offset:64
.LBB0_3785:
	v_cmp_gt_i32_e32 vcc, s85, v148
	s_nop 1
	v_cndmask_b32_e32 v98, v181, v148, vcc
	v_mul_hi_i32 v99, v98, s83
	v_lshrrev_b32_e32 v100, 31, v99
	v_ashrrev_i32_e32 v99, 11, v99
	v_add_u32_e32 v100, v99, v100
	v_mad_i32_i24 v101, v100, s84, v98
	v_cmp_lt_i32_e64 s[0:1], 15, v101
	s_and_saveexec_b64 s[2:3], s[0:1]
	s_xor_b64 s[0:1], exec, s[2:3]
	v_lshlrev_b32_e32 v98, 12, v100
	v_add3_u32 v98, v98, v101, -16
	v_ashrrev_i32_e32 v99, 31, v98
	v_lshlrev_b64 v[98:99], 12, v[98:99]
	v_lshl_add_u64 v[98:99], s[88:89], 0, v[98:99]
	s_andn2_saveexec_b64 s[0:1], s[0:1]
	v_lshlrev_b32_e32 v98, 14, v100
	v_lshl_add_u32 v98, v101, 10, v98
	v_ashrrev_i32_e32 v99, 31, v98
	v_lshl_add_u64 v[98:99], v[98:99], 2, s[16:17]
	s_or_b64 exec, exec, s[0:1]
	v_ashrrev_i32_e32 v149, 31, v148
	v_lshlrev_b64 v[100:101], 11, v[148:149]
	v_lshl_add_u64 v[100:101], s[62:63], 0, v[100:101]
	s_waitcnt vmcnt(11)
	v_add_f32_e32 v148, v124, v185
	v_lshl_add_u64 v[100:101], v[130:131], 1, v[100:101]
	v_lshl_add_u64 v[98:99], v[98:99], 0, v[134:135]
	global_store_dword v[98:99], v148, off
	v_mul_f32_e32 v102, v148, v242
	v_cvt_pk_bf16_f32 v102, v102, s0
	global_store_short v[100:101], v102, off
.LBB0_3791:
	s_waitcnt vmcnt(10)
	v_add_f32_e32 v149, v108, v147
	global_store_dword v[98:99], v149, off offset:128
	v_mul_f32_e32 v98, v149, v243
	v_cvt_pk_bf16_f32 v98, v98, s0
	global_store_short v[100:101], v98, off offset:64
.LBB0_3793:
	v_cmp_gt_i32_e32 vcc, s85, v146
	s_nop 1
	v_cndmask_b32_e32 v98, v181, v146, vcc
	v_mul_hi_i32 v99, v98, s83
	v_lshrrev_b32_e32 v100, 31, v99
	v_ashrrev_i32_e32 v99, 11, v99
	v_add_u32_e32 v100, v99, v100
	v_mad_i32_i24 v101, v100, s84, v98
	v_cmp_lt_i32_e64 s[0:1], 15, v101
	s_and_saveexec_b64 s[2:3], s[0:1]
	s_xor_b64 s[0:1], exec, s[2:3]
	v_lshlrev_b32_e32 v98, 12, v100
	v_add3_u32 v98, v98, v101, -16
	v_ashrrev_i32_e32 v99, 31, v98
	v_lshlrev_b64 v[98:99], 12, v[98:99]
	v_lshl_add_u64 v[98:99], s[88:89], 0, v[98:99]
	s_andn2_saveexec_b64 s[0:1], s[0:1]
	v_lshlrev_b32_e32 v98, 14, v100
	v_lshl_add_u32 v98, v101, 10, v98
	v_ashrrev_i32_e32 v99, 31, v98
	v_lshl_add_u64 v[98:99], v[98:99], 2, s[16:17]
	s_or_b64 exec, exec, s[0:1]
	v_ashrrev_i32_e32 v147, 31, v146
	v_lshlrev_b64 v[100:101], 11, v[146:147]
	v_lshl_add_u64 v[100:101], s[62:63], 0, v[100:101]
	s_waitcnt vmcnt(9)
	v_add_f32_e32 v146, v125, v184
	v_lshl_add_u64 v[100:101], v[130:131], 1, v[100:101]
	v_lshl_add_u64 v[98:99], v[98:99], 0, v[134:135]
	global_store_dword v[98:99], v146, off
	v_mul_f32_e32 v102, v146, v242
	v_cvt_pk_bf16_f32 v102, v102, s0
	global_store_short v[100:101], v102, off
.LBB0_3799:
	s_waitcnt vmcnt(8)
	v_add_f32_e32 v147, v109, v145
	global_store_dword v[98:99], v147, off offset:128
	v_mul_f32_e32 v98, v147, v243
	v_cvt_pk_bf16_f32 v98, v98, s0
	global_store_short v[100:101], v98, off offset:64
.LBB0_3801:
	v_cmp_gt_i32_e32 vcc, s85, v144
	s_nop 1
	v_cndmask_b32_e32 v98, v181, v144, vcc
	v_mul_hi_i32 v99, v98, s83
	v_lshrrev_b32_e32 v100, 31, v99
	v_ashrrev_i32_e32 v99, 11, v99
	v_add_u32_e32 v100, v99, v100
	v_mad_i32_i24 v101, v100, s84, v98
	v_cmp_lt_i32_e64 s[0:1], 15, v101
	s_and_saveexec_b64 s[2:3], s[0:1]
	s_xor_b64 s[0:1], exec, s[2:3]
	v_lshlrev_b32_e32 v98, 12, v100
	v_add3_u32 v98, v98, v101, -16
	v_ashrrev_i32_e32 v99, 31, v98
	v_lshlrev_b64 v[98:99], 12, v[98:99]
	v_lshl_add_u64 v[98:99], s[88:89], 0, v[98:99]
	s_andn2_saveexec_b64 s[0:1], s[0:1]
	v_lshlrev_b32_e32 v98, 14, v100
	v_lshl_add_u32 v98, v101, 10, v98
	v_ashrrev_i32_e32 v99, 31, v98
	v_lshl_add_u64 v[98:99], v[98:99], 2, s[16:17]
	s_or_b64 exec, exec, s[0:1]
	v_ashrrev_i32_e32 v145, 31, v144
	v_lshlrev_b64 v[100:101], 11, v[144:145]
	v_lshl_add_u64 v[100:101], s[62:63], 0, v[100:101]
	s_waitcnt vmcnt(7)
	v_add_f32_e32 v144, v126, v183
	v_lshl_add_u64 v[100:101], v[130:131], 1, v[100:101]
	v_lshl_add_u64 v[98:99], v[98:99], 0, v[134:135]
	global_store_dword v[98:99], v144, off
	v_mul_f32_e32 v102, v144, v242
	v_cvt_pk_bf16_f32 v102, v102, s0
	global_store_short v[100:101], v102, off
.LBB0_3807:
	s_waitcnt vmcnt(6)
	v_add_f32_e32 v145, v110, v143
	global_store_dword v[98:99], v145, off offset:128
	v_mul_f32_e32 v98, v145, v243
	v_cvt_pk_bf16_f32 v98, v98, s0
	global_store_short v[100:101], v98, off offset:64
.LBB0_3809:
	v_cmp_gt_i32_e32 vcc, s85, v142
	s_nop 1
	v_cndmask_b32_e32 v98, v181, v142, vcc
	v_mul_hi_i32 v99, v98, s83
	v_lshrrev_b32_e32 v100, 31, v99
	v_ashrrev_i32_e32 v99, 11, v99
	v_add_u32_e32 v100, v99, v100
	v_mad_i32_i24 v101, v100, s84, v98
	v_cmp_lt_i32_e64 s[0:1], 15, v101
	s_and_saveexec_b64 s[2:3], s[0:1]
	s_xor_b64 s[0:1], exec, s[2:3]
	v_lshlrev_b32_e32 v98, 12, v100
	v_add3_u32 v98, v98, v101, -16
	v_ashrrev_i32_e32 v99, 31, v98
	v_lshlrev_b64 v[98:99], 12, v[98:99]
	v_lshl_add_u64 v[98:99], s[88:89], 0, v[98:99]
	s_andn2_saveexec_b64 s[0:1], s[0:1]
	v_lshlrev_b32_e32 v98, 14, v100
	v_lshl_add_u32 v98, v101, 10, v98
	v_ashrrev_i32_e32 v99, 31, v98
	v_lshl_add_u64 v[98:99], v[98:99], 2, s[16:17]
	s_or_b64 exec, exec, s[0:1]
	v_ashrrev_i32_e32 v143, 31, v142
	v_lshlrev_b64 v[100:101], 11, v[142:143]
	v_lshl_add_u64 v[100:101], s[62:63], 0, v[100:101]
	s_waitcnt vmcnt(5)
	v_add_f32_e32 v142, v127, v182
	v_lshl_add_u64 v[100:101], v[130:131], 1, v[100:101]
	v_lshl_add_u64 v[98:99], v[98:99], 0, v[134:135]
	global_store_dword v[98:99], v142, off
	v_mul_f32_e32 v102, v142, v242
	v_cvt_pk_bf16_f32 v102, v102, s0
	global_store_short v[100:101], v102, off
.LBB0_3815:
	s_waitcnt vmcnt(4)
	v_add_f32_e32 v143, v111, v141
	global_store_dword v[98:99], v143, off offset:128
	v_mul_f32_e32 v98, v143, v243
	v_cvt_pk_bf16_f32 v98, v98, s0
	global_store_short v[100:101], v98, off offset:64
.LBB0_3817:
	v_cmp_gt_i32_e32 vcc, s85, v140
	s_nop 1
	v_cndmask_b32_e32 v98, v181, v140, vcc
	v_mul_hi_i32 v99, v98, s83
	v_lshrrev_b32_e32 v100, 31, v99
	v_ashrrev_i32_e32 v99, 11, v99
	v_add_u32_e32 v100, v99, v100
	v_mad_i32_i24 v101, v100, s84, v98
	v_cmp_lt_i32_e64 s[0:1], 15, v101
	s_and_saveexec_b64 s[2:3], s[0:1]
	s_xor_b64 s[0:1], exec, s[2:3]
	v_lshlrev_b32_e32 v98, 12, v100
	v_add3_u32 v98, v98, v101, -16
	v_ashrrev_i32_e32 v99, 31, v98
	v_lshlrev_b64 v[98:99], 12, v[98:99]
	v_lshl_add_u64 v[98:99], s[88:89], 0, v[98:99]
	s_andn2_saveexec_b64 s[0:1], s[0:1]
	v_lshlrev_b32_e32 v98, 14, v100
	v_lshl_add_u32 v98, v101, 10, v98
	v_ashrrev_i32_e32 v99, 31, v98
	v_lshl_add_u64 v[98:99], v[98:99], 2, s[16:17]
	s_or_b64 exec, exec, s[0:1]
	v_ashrrev_i32_e32 v141, 31, v140
	v_lshlrev_b64 v[100:101], 11, v[140:141]
	v_lshl_add_u64 v[100:101], s[62:63], 0, v[100:101]
	s_waitcnt vmcnt(3)
	v_add_f32_e32 v140, v128, v179
	v_lshl_add_u64 v[100:101], v[130:131], 1, v[100:101]
	v_lshl_add_u64 v[98:99], v[98:99], 0, v[134:135]
	global_store_dword v[98:99], v140, off
	v_mul_f32_e32 v102, v140, v242
	v_cvt_pk_bf16_f32 v102, v102, s0
	global_store_short v[100:101], v102, off
.LBB0_3823:
	s_waitcnt vmcnt(2)
	v_add_f32_e32 v141, v112, v139
	global_store_dword v[98:99], v141, off offset:128
	v_mul_f32_e32 v98, v141, v243
	v_cvt_pk_bf16_f32 v98, v98, s0
	global_store_short v[100:101], v98, off offset:64
.LBB0_3825:
	v_cmp_gt_i32_e32 vcc, s85, v138
	s_nop 1
	v_cndmask_b32_e32 v98, v181, v138, vcc
	v_mul_hi_i32 v99, v98, s83
	v_lshrrev_b32_e32 v100, 31, v99
	v_ashrrev_i32_e32 v99, 11, v99
	v_add_u32_e32 v100, v99, v100
	v_mad_i32_i24 v101, v100, s84, v98
	v_cmp_lt_i32_e64 s[0:1], 15, v101
	s_and_saveexec_b64 s[2:3], s[0:1]
	s_xor_b64 s[0:1], exec, s[2:3]
	v_lshlrev_b32_e32 v98, 12, v100
	v_add3_u32 v98, v98, v101, -16
	v_ashrrev_i32_e32 v99, 31, v98
	v_lshlrev_b64 v[98:99], 12, v[98:99]
	v_lshl_add_u64 v[98:99], s[88:89], 0, v[98:99]
	s_andn2_saveexec_b64 s[0:1], s[0:1]
	v_lshlrev_b32_e32 v98, 14, v100
	v_lshl_add_u32 v98, v101, 10, v98
	v_ashrrev_i32_e32 v99, 31, v98
	v_lshl_add_u64 v[98:99], v[98:99], 2, s[16:17]
	s_or_b64 exec, exec, s[0:1]
	v_ashrrev_i32_e32 v139, 31, v138
	v_lshlrev_b64 v[100:101], 11, v[138:139]
	v_lshl_add_u64 v[100:101], s[62:63], 0, v[100:101]
	s_waitcnt vmcnt(1)
	v_add_f32_e32 v166, v129, v178
	v_lshl_add_u64 v[100:101], v[130:131], 1, v[100:101]
	v_lshl_add_u64 v[98:99], v[98:99], 0, v[134:135]
	global_store_dword v[98:99], v166, off
	v_mul_f32_e32 v102, v166, v242
	v_cvt_pk_bf16_f32 v102, v102, s0
	global_store_short v[100:101], v102, off
.LBB0_3831:
	s_waitcnt vmcnt(0)
	v_add_f32_e32 v167, v113, v177
	global_store_dword v[98:99], v167, off offset:128
	v_mul_f32_e32 v98, v167, v243
	v_cvt_pk_bf16_f32 v98, v98, s0
	global_store_short v[100:101], v98, off offset:64
.LBB0_3833:
	v_or_b32_e32 v128, 32, v136
	v_min_i32_e32 v98, 0x403f, v128
	v_mul_hi_i32 v99, v98, s83
	v_lshrrev_b32_e32 v100, 31, v99
	v_ashrrev_i32_e32 v99, 11, v99
	v_add_u32_e32 v100, v99, v100
	v_mad_i32_i24 v101, v100, s84, v98
	v_cmp_lt_i32_e32 vcc, 15, v101
	s_and_saveexec_b64 s[0:1], vcc
	s_xor_b64 s[0:1], exec, s[0:1]
	v_lshlrev_b32_e32 v98, 12, v100
	v_add3_u32 v98, v98, v101, -16
	v_ashrrev_i32_e32 v99, 31, v98
	v_lshlrev_b64 v[98:99], 12, v[98:99]
	v_lshl_add_u64 v[98:99], s[88:89], 0, v[98:99]
	s_andn2_saveexec_b64 s[0:1], s[0:1]
	v_lshlrev_b32_e32 v98, 14, v100
	v_lshl_add_u32 v98, v101, 10, v98
	v_ashrrev_i32_e32 v99, 31, v98
	v_lshl_add_u64 v[98:99], v[98:99], 2, s[16:17]
	s_or_b64 exec, exec, s[0:1]
	v_lshl_add_u64 v[98:99], v[130:131], 2, v[98:99]
	global_load_dword v169, v[98:99], off
	global_load_dword v127, v[98:99], off offset:128
	v_or_b32_e32 v126, 33, v136
	v_min_i32_e32 v98, 0x403f, v126
	v_mul_hi_i32 v99, v98, s83
	v_lshrrev_b32_e32 v100, 31, v99
	v_ashrrev_i32_e32 v99, 11, v99
	v_add_u32_e32 v100, v99, v100
	v_mad_i32_i24 v101, v100, s84, v98
	v_cmp_lt_i32_e32 vcc, 15, v101
	s_and_saveexec_b64 s[0:1], vcc
	s_xor_b64 s[0:1], exec, s[0:1]
	v_lshlrev_b32_e32 v98, 12, v100
	v_add3_u32 v98, v98, v101, -16
	v_ashrrev_i32_e32 v99, 31, v98
	v_lshlrev_b64 v[98:99], 12, v[98:99]
	v_lshl_add_u64 v[98:99], s[88:89], 0, v[98:99]
	s_andn2_saveexec_b64 s[0:1], s[0:1]
	v_lshlrev_b32_e32 v98, 14, v100
	v_lshl_add_u32 v98, v101, 10, v98
	v_ashrrev_i32_e32 v99, 31, v98
	v_lshl_add_u64 v[98:99], v[98:99], 2, s[16:17]
	s_or_b64 exec, exec, s[0:1]
	v_lshl_add_u64 v[98:99], v[130:131], 2, v[98:99]
	global_load_dword v194, v[98:99], off
	global_load_dword v125, v[98:99], off offset:128
	v_or_b32_e32 v124, 34, v136
	v_min_i32_e32 v98, 0x403f, v124
	v_mul_hi_i32 v99, v98, s83
	v_lshrrev_b32_e32 v100, 31, v99
	v_ashrrev_i32_e32 v99, 11, v99
	v_add_u32_e32 v100, v99, v100
	v_mad_i32_i24 v101, v100, s84, v98
	v_cmp_lt_i32_e32 vcc, 15, v101
	s_and_saveexec_b64 s[0:1], vcc
	s_xor_b64 s[0:1], exec, s[0:1]
	v_lshlrev_b32_e32 v98, 12, v100
	v_add3_u32 v98, v98, v101, -16
	v_ashrrev_i32_e32 v99, 31, v98
	v_lshlrev_b64 v[98:99], 12, v[98:99]
	v_lshl_add_u64 v[98:99], s[88:89], 0, v[98:99]
	s_andn2_saveexec_b64 s[0:1], s[0:1]
	v_lshlrev_b32_e32 v98, 14, v100
	v_lshl_add_u32 v98, v101, 10, v98
	v_ashrrev_i32_e32 v99, 31, v98
	v_lshl_add_u64 v[98:99], v[98:99], 2, s[16:17]
	s_or_b64 exec, exec, s[0:1]
	v_lshl_add_u64 v[98:99], v[130:131], 2, v[98:99]
	global_load_dword v193, v[98:99], off
	global_load_dword v123, v[98:99], off offset:128
	v_or_b32_e32 v122, 35, v136
	v_min_i32_e32 v98, 0x403f, v122
	v_mul_hi_i32 v99, v98, s83
	v_lshrrev_b32_e32 v100, 31, v99
	v_ashrrev_i32_e32 v99, 11, v99
	v_add_u32_e32 v100, v99, v100
	v_mad_i32_i24 v101, v100, s84, v98
	v_cmp_lt_i32_e32 vcc, 15, v101
	s_and_saveexec_b64 s[0:1], vcc
	s_xor_b64 s[0:1], exec, s[0:1]
	v_lshlrev_b32_e32 v98, 12, v100
	v_add3_u32 v98, v98, v101, -16
	v_ashrrev_i32_e32 v99, 31, v98
	v_lshlrev_b64 v[98:99], 12, v[98:99]
	v_lshl_add_u64 v[98:99], s[88:89], 0, v[98:99]
	s_andn2_saveexec_b64 s[0:1], s[0:1]
	v_lshlrev_b32_e32 v98, 14, v100
	v_lshl_add_u32 v98, v101, 10, v98
	v_ashrrev_i32_e32 v99, 31, v98
	v_lshl_add_u64 v[98:99], v[98:99], 2, s[16:17]
	s_or_b64 exec, exec, s[0:1]
	v_lshl_add_u64 v[98:99], v[130:131], 2, v[98:99]
	global_load_dword v192, v[98:99], off
	global_load_dword v121, v[98:99], off offset:128
	v_or_b32_e32 v120, 40, v136
	v_min_i32_e32 v98, 0x403f, v120
	v_mul_hi_i32 v99, v98, s83
	v_lshrrev_b32_e32 v100, 31, v99
	v_ashrrev_i32_e32 v99, 11, v99
	v_add_u32_e32 v100, v99, v100
	v_mad_i32_i24 v101, v100, s84, v98
	v_cmp_lt_i32_e32 vcc, 15, v101
	s_and_saveexec_b64 s[0:1], vcc
	s_xor_b64 s[0:1], exec, s[0:1]
	v_lshlrev_b32_e32 v98, 12, v100
	v_add3_u32 v98, v98, v101, -16
	v_ashrrev_i32_e32 v99, 31, v98
	v_lshlrev_b64 v[98:99], 12, v[98:99]
	v_lshl_add_u64 v[98:99], s[88:89], 0, v[98:99]
	s_andn2_saveexec_b64 s[0:1], s[0:1]
	v_lshlrev_b32_e32 v98, 14, v100
	v_lshl_add_u32 v98, v101, 10, v98
	v_ashrrev_i32_e32 v99, 31, v98
	v_lshl_add_u64 v[98:99], v[98:99], 2, s[16:17]
	s_or_b64 exec, exec, s[0:1]
	v_lshl_add_u64 v[98:99], v[130:131], 2, v[98:99]
	global_load_dword v191, v[98:99], off
	global_load_dword v119, v[98:99], off offset:128
	v_or_b32_e32 v118, 41, v136
	v_min_i32_e32 v98, 0x403f, v118
	v_mul_hi_i32 v99, v98, s83
	v_lshrrev_b32_e32 v100, 31, v99
	v_ashrrev_i32_e32 v99, 11, v99
	v_add_u32_e32 v100, v99, v100
	v_mad_i32_i24 v101, v100, s84, v98
	v_cmp_lt_i32_e32 vcc, 15, v101
	s_and_saveexec_b64 s[0:1], vcc
	s_xor_b64 s[0:1], exec, s[0:1]
	v_lshlrev_b32_e32 v98, 12, v100
	v_add3_u32 v98, v98, v101, -16
	v_ashrrev_i32_e32 v99, 31, v98
	v_lshlrev_b64 v[98:99], 12, v[98:99]
	v_lshl_add_u64 v[98:99], s[88:89], 0, v[98:99]
	s_andn2_saveexec_b64 s[0:1], s[0:1]
	v_lshlrev_b32_e32 v98, 14, v100
	v_lshl_add_u32 v98, v101, 10, v98
	v_ashrrev_i32_e32 v99, 31, v98
	v_lshl_add_u64 v[98:99], v[98:99], 2, s[16:17]
	s_or_b64 exec, exec, s[0:1]
	v_lshl_add_u64 v[98:99], v[130:131], 2, v[98:99]
	global_load_dword v190, v[98:99], off
	global_load_dword v117, v[98:99], off offset:128
	v_or_b32_e32 v116, 42, v136
	v_min_i32_e32 v98, 0x403f, v116
	v_mul_hi_i32 v99, v98, s83
	v_lshrrev_b32_e32 v100, 31, v99
	v_ashrrev_i32_e32 v99, 11, v99
	v_add_u32_e32 v100, v99, v100
	v_mad_i32_i24 v101, v100, s84, v98
	v_cmp_lt_i32_e32 vcc, 15, v101
	s_and_saveexec_b64 s[0:1], vcc
	s_xor_b64 s[0:1], exec, s[0:1]
	v_lshlrev_b32_e32 v98, 12, v100
	v_add3_u32 v98, v98, v101, -16
	v_ashrrev_i32_e32 v99, 31, v98
	v_lshlrev_b64 v[98:99], 12, v[98:99]
	v_lshl_add_u64 v[98:99], s[88:89], 0, v[98:99]
	s_andn2_saveexec_b64 s[0:1], s[0:1]
	v_lshlrev_b32_e32 v98, 14, v100
	v_lshl_add_u32 v98, v101, 10, v98
	v_ashrrev_i32_e32 v99, 31, v98
	v_lshl_add_u64 v[98:99], v[98:99], 2, s[16:17]
	s_or_b64 exec, exec, s[0:1]
	v_lshl_add_u64 v[98:99], v[130:131], 2, v[98:99]
	global_load_dword v189, v[98:99], off
	global_load_dword v115, v[98:99], off offset:128
	v_or_b32_e32 v114, 43, v136
	v_min_i32_e32 v98, 0x403f, v114
	v_mul_hi_i32 v99, v98, s83
	v_lshrrev_b32_e32 v100, 31, v99
	v_ashrrev_i32_e32 v99, 11, v99
	v_add_u32_e32 v100, v99, v100
	v_mad_i32_i24 v101, v100, s84, v98
	v_cmp_lt_i32_e32 vcc, 15, v101
	s_and_saveexec_b64 s[0:1], vcc
	s_xor_b64 s[0:1], exec, s[0:1]
	v_lshlrev_b32_e32 v98, 12, v100
	v_add3_u32 v98, v98, v101, -16
	v_ashrrev_i32_e32 v99, 31, v98
	v_lshlrev_b64 v[98:99], 12, v[98:99]
	v_lshl_add_u64 v[98:99], s[88:89], 0, v[98:99]
	s_andn2_saveexec_b64 s[0:1], s[0:1]
	v_lshlrev_b32_e32 v98, 14, v100
	v_lshl_add_u32 v98, v101, 10, v98
	v_ashrrev_i32_e32 v99, 31, v98
	v_lshl_add_u64 v[98:99], v[98:99], 2, s[16:17]
	s_or_b64 exec, exec, s[0:1]
	v_lshl_add_u64 v[98:99], v[130:131], 2, v[98:99]
	global_load_dword v188, v[98:99], off
	global_load_dword v113, v[98:99], off offset:128
	v_or_b32_e32 v112, 48, v136
	v_min_i32_e32 v98, 0x403f, v112
	v_mul_hi_i32 v99, v98, s83
	v_lshrrev_b32_e32 v100, 31, v99
	v_ashrrev_i32_e32 v99, 11, v99
	v_add_u32_e32 v100, v99, v100
	v_mad_i32_i24 v101, v100, s84, v98
	v_cmp_lt_i32_e32 vcc, 15, v101
	s_and_saveexec_b64 s[0:1], vcc
	s_xor_b64 s[0:1], exec, s[0:1]
	v_lshlrev_b32_e32 v98, 12, v100
	v_add3_u32 v98, v98, v101, -16
	v_ashrrev_i32_e32 v99, 31, v98
	v_lshlrev_b64 v[98:99], 12, v[98:99]
	v_lshl_add_u64 v[98:99], s[88:89], 0, v[98:99]
	s_andn2_saveexec_b64 s[0:1], s[0:1]
	v_lshlrev_b32_e32 v98, 14, v100
	v_lshl_add_u32 v98, v101, 10, v98
	v_ashrrev_i32_e32 v99, 31, v98
	v_lshl_add_u64 v[98:99], v[98:99], 2, s[16:17]
	s_or_b64 exec, exec, s[0:1]
	v_lshl_add_u64 v[98:99], v[130:131], 2, v[98:99]
	global_load_dword v187, v[98:99], off
	global_load_dword v111, v[98:99], off offset:128
	v_or_b32_e32 v110, 49, v136
	v_min_i32_e32 v98, 0x403f, v110
	v_mul_hi_i32 v99, v98, s83
	v_lshrrev_b32_e32 v100, 31, v99
	v_ashrrev_i32_e32 v99, 11, v99
	v_add_u32_e32 v100, v99, v100
	v_mad_i32_i24 v101, v100, s84, v98
	v_cmp_lt_i32_e32 vcc, 15, v101
	s_and_saveexec_b64 s[0:1], vcc
	s_xor_b64 s[0:1], exec, s[0:1]
	v_lshlrev_b32_e32 v98, 12, v100
	v_add3_u32 v98, v98, v101, -16
	v_ashrrev_i32_e32 v99, 31, v98
	v_lshlrev_b64 v[98:99], 12, v[98:99]
	v_lshl_add_u64 v[98:99], s[88:89], 0, v[98:99]
	s_andn2_saveexec_b64 s[0:1], s[0:1]
	v_lshlrev_b32_e32 v98, 14, v100
	v_lshl_add_u32 v98, v101, 10, v98
	v_ashrrev_i32_e32 v99, 31, v98
	v_lshl_add_u64 v[98:99], v[98:99], 2, s[16:17]
	s_or_b64 exec, exec, s[0:1]
	v_lshl_add_u64 v[98:99], v[130:131], 2, v[98:99]
	global_load_dword v186, v[98:99], off
	global_load_dword v109, v[98:99], off offset:128
	v_or_b32_e32 v108, 50, v136
	v_min_i32_e32 v98, 0x403f, v108
	v_mul_hi_i32 v99, v98, s83
	v_lshrrev_b32_e32 v100, 31, v99
	v_ashrrev_i32_e32 v99, 11, v99
	v_add_u32_e32 v100, v99, v100
	v_mad_i32_i24 v101, v100, s84, v98
	v_cmp_lt_i32_e32 vcc, 15, v101
	s_and_saveexec_b64 s[0:1], vcc
	s_xor_b64 s[0:1], exec, s[0:1]
	v_lshlrev_b32_e32 v98, 12, v100
	v_add3_u32 v98, v98, v101, -16
	v_ashrrev_i32_e32 v99, 31, v98
	v_lshlrev_b64 v[98:99], 12, v[98:99]
	v_lshl_add_u64 v[98:99], s[88:89], 0, v[98:99]
	s_andn2_saveexec_b64 s[0:1], s[0:1]
	v_lshlrev_b32_e32 v98, 14, v100
	v_lshl_add_u32 v98, v101, 10, v98
	v_ashrrev_i32_e32 v99, 31, v98
	v_lshl_add_u64 v[98:99], v[98:99], 2, s[16:17]
	s_or_b64 exec, exec, s[0:1]
	v_lshl_add_u64 v[98:99], v[130:131], 2, v[98:99]
	global_load_dword v185, v[98:99], off
	global_load_dword v107, v[98:99], off offset:128
	v_or_b32_e32 v106, 51, v136
	v_min_i32_e32 v98, 0x403f, v106
	v_mul_hi_i32 v99, v98, s83
	v_lshrrev_b32_e32 v100, 31, v99
	v_ashrrev_i32_e32 v99, 11, v99
	v_add_u32_e32 v100, v99, v100
	v_mad_i32_i24 v101, v100, s84, v98
	v_cmp_lt_i32_e32 vcc, 15, v101
	s_and_saveexec_b64 s[0:1], vcc
	s_xor_b64 s[0:1], exec, s[0:1]
	v_lshlrev_b32_e32 v98, 12, v100
	v_add3_u32 v98, v98, v101, -16
	v_ashrrev_i32_e32 v99, 31, v98
	v_lshlrev_b64 v[98:99], 12, v[98:99]
	v_lshl_add_u64 v[98:99], s[88:89], 0, v[98:99]
	s_andn2_saveexec_b64 s[0:1], s[0:1]
	v_lshlrev_b32_e32 v98, 14, v100
	v_lshl_add_u32 v98, v101, 10, v98
	v_ashrrev_i32_e32 v99, 31, v98
	v_lshl_add_u64 v[98:99], v[98:99], 2, s[16:17]
	s_or_b64 exec, exec, s[0:1]
	v_lshl_add_u64 v[98:99], v[130:131], 2, v[98:99]
	global_load_dword v184, v[98:99], off
	global_load_dword v105, v[98:99], off offset:128
	v_or_b32_e32 v104, 56, v136
	v_min_i32_e32 v98, 0x403f, v104
	v_mul_hi_i32 v99, v98, s83
	v_lshrrev_b32_e32 v100, 31, v99
	v_ashrrev_i32_e32 v99, 11, v99
	v_add_u32_e32 v100, v99, v100
	v_mad_i32_i24 v101, v100, s84, v98
	v_cmp_lt_i32_e32 vcc, 15, v101
	s_and_saveexec_b64 s[0:1], vcc
	s_xor_b64 s[0:1], exec, s[0:1]
	v_lshlrev_b32_e32 v98, 12, v100
	v_add3_u32 v98, v98, v101, -16
	v_ashrrev_i32_e32 v99, 31, v98
	v_lshlrev_b64 v[98:99], 12, v[98:99]
	v_lshl_add_u64 v[98:99], s[88:89], 0, v[98:99]
	s_andn2_saveexec_b64 s[0:1], s[0:1]
	v_lshlrev_b32_e32 v98, 14, v100
	v_lshl_add_u32 v98, v101, 10, v98
	v_ashrrev_i32_e32 v99, 31, v98
	v_lshl_add_u64 v[98:99], v[98:99], 2, s[16:17]
	s_or_b64 exec, exec, s[0:1]
	v_lshl_add_u64 v[98:99], v[130:131], 2, v[98:99]
	global_load_dword v183, v[98:99], off
	global_load_dword v103, v[98:99], off offset:128
	v_or_b32_e32 v102, 57, v136
	v_min_i32_e32 v98, 0x403f, v102
	v_mul_hi_i32 v99, v98, s83
	v_lshrrev_b32_e32 v100, 31, v99
	v_ashrrev_i32_e32 v99, 11, v99
	v_add_u32_e32 v100, v99, v100
	v_mad_i32_i24 v101, v100, s84, v98
	v_cmp_lt_i32_e32 vcc, 15, v101
	s_and_saveexec_b64 s[0:1], vcc
	s_xor_b64 s[0:1], exec, s[0:1]
	v_lshlrev_b32_e32 v98, 12, v100
	v_add3_u32 v98, v98, v101, -16
	v_ashrrev_i32_e32 v99, 31, v98
	v_lshlrev_b64 v[98:99], 12, v[98:99]
	v_lshl_add_u64 v[98:99], s[88:89], 0, v[98:99]
	s_andn2_saveexec_b64 s[0:1], s[0:1]
	v_lshlrev_b32_e32 v98, 14, v100
	v_lshl_add_u32 v98, v101, 10, v98
	v_ashrrev_i32_e32 v99, 31, v98
	v_lshl_add_u64 v[98:99], v[98:99], 2, s[16:17]
	s_or_b64 exec, exec, s[0:1]
	v_lshl_add_u64 v[98:99], v[130:131], 2, v[98:99]
	global_load_dword v182, v[98:99], off
	global_load_dword v101, v[98:99], off offset:128
	v_or_b32_e32 v100, 58, v136
	v_min_i32_e32 v98, 0x403f, v100
	v_mul_hi_i32 v99, v98, s83
	v_lshrrev_b32_e32 v129, 31, v99
	v_ashrrev_i32_e32 v99, 11, v99
	v_add_u32_e32 v129, v99, v129
	v_mad_i32_i24 v138, v129, s84, v98
	v_cmp_lt_i32_e32 vcc, 15, v138
	s_and_saveexec_b64 s[0:1], vcc
	s_xor_b64 s[0:1], exec, s[0:1]
	v_lshlrev_b32_e32 v98, 12, v129
	v_add3_u32 v98, v98, v138, -16
	v_ashrrev_i32_e32 v99, 31, v98
	v_lshlrev_b64 v[98:99], 12, v[98:99]
	v_lshl_add_u64 v[98:99], s[88:89], 0, v[98:99]
	s_andn2_saveexec_b64 s[0:1], s[0:1]
	v_lshlrev_b32_e32 v98, 14, v129
	v_lshl_add_u32 v98, v138, 10, v98
	v_ashrrev_i32_e32 v99, 31, v98
	v_lshl_add_u64 v[98:99], v[98:99], 2, s[16:17]
	s_or_b64 exec, exec, s[0:1]
	v_lshl_add_u64 v[98:99], v[130:131], 2, v[98:99]
	global_load_dword v179, v[98:99], off
	s_nop 0
	global_load_dword v99, v[98:99], off offset:128
	v_or_b32_e32 v98, 59, v136
	v_min_i32_e32 v138, 0x403f, v98
	v_mul_hi_i32 v129, v138, s83
	v_lshrrev_b32_e32 v139, 31, v129
	v_ashrrev_i32_e32 v129, 11, v129
	v_add_u32_e32 v129, v129, v139
	v_mad_i32_i24 v171, v129, s84, v138
	v_cmp_lt_i32_e32 vcc, 15, v171
	s_and_saveexec_b64 s[0:1], vcc
	s_xor_b64 s[0:1], exec, s[0:1]
	v_lshlrev_b32_e32 v129, 12, v129
	v_add3_u32 v138, v129, v171, -16
	v_ashrrev_i32_e32 v139, 31, v138
	v_lshlrev_b64 v[138:139], 12, v[138:139]
	v_lshl_add_u64 v[138:139], s[88:89], 0, v[138:139]
	s_andn2_saveexec_b64 s[0:1], s[0:1]
	v_lshlrev_b32_e32 v129, 14, v129
	v_lshl_add_u32 v138, v171, 10, v129
	v_ashrrev_i32_e32 v139, 31, v138
	v_lshl_add_u64 v[138:139], v[138:139], 2, s[16:17]
	s_or_b64 exec, exec, s[0:1]
	v_lshl_add_u64 v[138:139], v[130:131], 2, v[138:139]
	global_load_dword v177, v[138:139], off
	global_load_dword v171, v[138:139], off offset:128
	v_cmp_gt_i32_e32 vcc, s85, v128
	s_nop 1
	v_cndmask_b32_e32 v138, v181, v128, vcc
	v_mul_hi_i32 v129, v138, s83
	v_lshrrev_b32_e32 v139, 31, v129
	v_ashrrev_i32_e32 v129, 11, v129
	v_add_u32_e32 v129, v129, v139
	v_mad_i32_i24 v178, v129, s84, v138
	v_cmp_lt_i32_e64 s[0:1], 15, v178
	s_and_saveexec_b64 s[2:3], s[0:1]
	s_xor_b64 s[0:1], exec, s[2:3]
	v_lshlrev_b32_e32 v129, 12, v129
	v_add3_u32 v138, v129, v178, -16
	v_ashrrev_i32_e32 v139, 31, v138
	v_lshlrev_b64 v[138:139], 12, v[138:139]
	v_lshl_add_u64 v[138:139], s[88:89], 0, v[138:139]
	s_andn2_saveexec_b64 s[0:1], s[0:1]
	v_lshlrev_b32_e32 v129, 14, v129
	v_lshl_add_u32 v138, v178, 10, v129
	v_ashrrev_i32_e32 v139, 31, v138
	v_lshl_add_u64 v[138:139], v[138:139], 2, s[16:17]
	s_or_b64 exec, exec, s[0:1]
	v_ashrrev_i32_e32 v129, 31, v128
	v_lshlrev_b64 v[128:129], 11, v[128:129]
	v_lshl_add_u64 v[128:129], s[62:63], 0, v[128:129]
	s_waitcnt vmcnt(31)
	v_add_f32_e32 v169, v82, v169
	v_lshl_add_u64 v[128:129], v[130:131], 1, v[128:129]
	v_lshl_add_u64 v[138:139], v[138:139], 0, v[134:135]
	global_store_dword v[138:139], v169, off
	v_mul_f32_e32 v82, v169, v242
	v_cvt_pk_bf16_f32 v82, v82, s0
	global_store_short v[128:129], v82, off
.LBB0_3903:
	s_waitcnt vmcnt(30)
	v_add_f32_e32 v178, v66, v127
	global_store_dword v[138:139], v178, off offset:128
	v_mul_f32_e32 v66, v178, v243
	v_cvt_pk_bf16_f32 v66, v66, s0
	global_store_short v[128:129], v66, off offset:64
.LBB0_3905:
	v_cmp_gt_i32_e32 vcc, s85, v126
	s_nop 1
	v_cndmask_b32_e32 v82, v181, v126, vcc
	v_mul_hi_i32 v66, v82, s83
	v_lshrrev_b32_e32 v127, 31, v66
	v_ashrrev_i32_e32 v66, 11, v66
	v_add_u32_e32 v66, v66, v127
	v_mad_i32_i24 v82, v66, s84, v82
	v_cmp_lt_i32_e64 s[0:1], 15, v82
	s_and_saveexec_b64 s[2:3], s[0:1]
	s_xor_b64 s[0:1], exec, s[2:3]
	v_lshlrev_b32_e32 v66, 12, v66
	v_add3_u32 v128, v66, v82, -16
	v_ashrrev_i32_e32 v129, 31, v128
	v_lshlrev_b64 v[128:129], 12, v[128:129]
	v_lshl_add_u64 v[128:129], s[88:89], 0, v[128:129]
	s_andn2_saveexec_b64 s[0:1], s[0:1]
	v_lshlrev_b32_e32 v66, 14, v66
	v_lshl_add_u32 v128, v82, 10, v66
	v_ashrrev_i32_e32 v129, 31, v128
	v_lshl_add_u64 v[128:129], v[128:129], 2, s[16:17]
	s_or_b64 exec, exec, s[0:1]
	v_ashrrev_i32_e32 v127, 31, v126
	v_lshlrev_b64 v[126:127], 11, v[126:127]
	v_lshl_add_u64 v[126:127], s[62:63], 0, v[126:127]
	s_waitcnt vmcnt(29)
	v_add_f32_e32 v138, v83, v194
	v_lshl_add_u64 v[82:83], v[130:131], 1, v[126:127]
	v_lshl_add_u64 v[126:127], v[128:129], 0, v[134:135]
	global_store_dword v[126:127], v138, off
	v_mul_f32_e32 v66, v138, v242
	v_cvt_pk_bf16_f32 v66, v66, s0
	global_store_short v[82:83], v66, off
.LBB0_3911:
	s_waitcnt vmcnt(28)
	v_add_f32_e32 v128, v67, v125
	global_store_dword v[126:127], v128, off offset:128
	v_mul_f32_e32 v66, v128, v243
	v_cvt_pk_bf16_f32 v66, v66, s0
	global_store_short v[82:83], v66, off offset:64
.LBB0_3913:
	v_cmp_gt_i32_e32 vcc, s85, v124
	s_nop 1
	v_cndmask_b32_e32 v66, v181, v124, vcc
	v_mul_hi_i32 v67, v66, s83
	v_lshrrev_b32_e32 v82, 31, v67
	v_ashrrev_i32_e32 v67, 11, v67
	v_add_u32_e32 v82, v67, v82
	v_mad_i32_i24 v83, v82, s84, v66
	v_cmp_lt_i32_e64 s[0:1], 15, v83
	s_and_saveexec_b64 s[2:3], s[0:1]
	s_xor_b64 s[0:1], exec, s[2:3]
	v_lshlrev_b32_e32 v66, 12, v82
	v_add3_u32 v66, v66, v83, -16
	v_ashrrev_i32_e32 v67, 31, v66
	v_lshlrev_b64 v[66:67], 12, v[66:67]
	v_lshl_add_u64 v[66:67], s[88:89], 0, v[66:67]
	s_andn2_saveexec_b64 s[0:1], s[0:1]
	v_lshlrev_b32_e32 v66, 14, v82
	v_lshl_add_u32 v66, v83, 10, v66
	v_ashrrev_i32_e32 v67, 31, v66
	v_lshl_add_u64 v[66:67], v[66:67], 2, s[16:17]
	s_or_b64 exec, exec, s[0:1]
	v_ashrrev_i32_e32 v125, 31, v124
	v_lshlrev_b64 v[82:83], 11, v[124:125]
	v_lshl_add_u64 v[82:83], s[62:63], 0, v[82:83]
	s_waitcnt vmcnt(27)
	v_add_f32_e32 v84, v84, v193
	v_lshl_add_u64 v[82:83], v[130:131], 1, v[82:83]
	v_lshl_add_u64 v[66:67], v[66:67], 0, v[134:135]
	global_store_dword v[66:67], v84, off
	v_mul_f32_e32 v124, v84, v242
	v_cvt_pk_bf16_f32 v124, v124, s0
	global_store_short v[82:83], v124, off
.LBB0_3919:
	s_waitcnt vmcnt(26)
	v_add_f32_e32 v124, v68, v123
	global_store_dword v[66:67], v124, off offset:128
	v_mul_f32_e32 v66, v124, v243
	v_cvt_pk_bf16_f32 v66, v66, s0
	global_store_short v[82:83], v66, off offset:64
.LBB0_3921:
	v_cmp_gt_i32_e32 vcc, s85, v122
	s_nop 1
	v_cndmask_b32_e32 v66, v181, v122, vcc
	v_mul_hi_i32 v67, v66, s83
	v_lshrrev_b32_e32 v68, 31, v67
	v_ashrrev_i32_e32 v67, 11, v67
	v_add_u32_e32 v68, v67, v68
	v_mad_i32_i24 v82, v68, s84, v66
	v_cmp_lt_i32_e64 s[0:1], 15, v82
	s_and_saveexec_b64 s[2:3], s[0:1]
	s_xor_b64 s[0:1], exec, s[2:3]
	v_lshlrev_b32_e32 v66, 12, v68
	v_add3_u32 v66, v66, v82, -16
	v_ashrrev_i32_e32 v67, 31, v66
	v_lshlrev_b64 v[66:67], 12, v[66:67]
	v_lshl_add_u64 v[66:67], s[88:89], 0, v[66:67]
	s_andn2_saveexec_b64 s[0:1], s[0:1]
	v_lshlrev_b32_e32 v66, 14, v68
	v_lshl_add_u32 v66, v82, 10, v66
	v_ashrrev_i32_e32 v67, 31, v66
	v_lshl_add_u64 v[66:67], v[66:67], 2, s[16:17]
	s_or_b64 exec, exec, s[0:1]
	v_ashrrev_i32_e32 v123, 31, v122
	v_lshlrev_b64 v[82:83], 11, v[122:123]
	v_lshl_add_u64 v[82:83], s[62:63], 0, v[82:83]
	s_waitcnt vmcnt(25)
	v_add_f32_e32 v85, v85, v192
	v_lshl_add_u64 v[82:83], v[130:131], 1, v[82:83]
	v_lshl_add_u64 v[66:67], v[66:67], 0, v[134:135]
	global_store_dword v[66:67], v85, off
	v_mul_f32_e32 v68, v85, v242
	v_cvt_pk_bf16_f32 v68, v68, s0
	global_store_short v[82:83], v68, off
.LBB0_3927:
	s_waitcnt vmcnt(24)
	v_add_f32_e32 v122, v69, v121
	global_store_dword v[66:67], v122, off offset:128
	v_mul_f32_e32 v66, v122, v243
	v_cvt_pk_bf16_f32 v66, v66, s0
	global_store_short v[82:83], v66, off offset:64
.LBB0_3929:
	v_cmp_gt_i32_e32 vcc, s85, v120
	s_nop 1
	v_cndmask_b32_e32 v66, v181, v120, vcc
	v_mul_hi_i32 v67, v66, s83
	v_lshrrev_b32_e32 v68, 31, v67
	v_ashrrev_i32_e32 v67, 11, v67
	v_add_u32_e32 v68, v67, v68
	v_mad_i32_i24 v69, v68, s84, v66
	v_cmp_lt_i32_e64 s[0:1], 15, v69
	s_and_saveexec_b64 s[2:3], s[0:1]
	s_xor_b64 s[0:1], exec, s[2:3]
	v_lshlrev_b32_e32 v66, 12, v68
	v_add3_u32 v66, v66, v69, -16
	v_ashrrev_i32_e32 v67, 31, v66
	v_lshlrev_b64 v[66:67], 12, v[66:67]
	v_lshl_add_u64 v[66:67], s[88:89], 0, v[66:67]
	s_andn2_saveexec_b64 s[0:1], s[0:1]
	v_lshlrev_b32_e32 v66, 14, v68
	v_lshl_add_u32 v66, v69, 10, v66
	v_ashrrev_i32_e32 v67, 31, v66
	v_lshl_add_u64 v[66:67], v[66:67], 2, s[16:17]
	s_or_b64 exec, exec, s[0:1]
	v_ashrrev_i32_e32 v121, 31, v120
	v_lshlrev_b64 v[68:69], 11, v[120:121]
	v_lshl_add_u64 v[68:69], s[62:63], 0, v[68:69]
	s_waitcnt vmcnt(23)
	v_add_f32_e32 v82, v86, v191
	v_lshl_add_u64 v[68:69], v[130:131], 1, v[68:69]
	v_lshl_add_u64 v[66:67], v[66:67], 0, v[134:135]
	global_store_dword v[66:67], v82, off
	v_mul_f32_e32 v83, v82, v242
	v_cvt_pk_bf16_f32 v83, v83, s0
	global_store_short v[68:69], v83, off
.LBB0_3935:
	s_waitcnt vmcnt(22)
	v_add_f32_e32 v70, v70, v119
	global_store_dword v[66:67], v70, off offset:128
	v_mul_f32_e32 v66, v70, v243
	v_cvt_pk_bf16_f32 v66, v66, s0
	global_store_short v[68:69], v66, off offset:64
.LBB0_3937:
	v_cmp_gt_i32_e32 vcc, s85, v118
	s_nop 1
	v_cndmask_b32_e32 v66, v181, v118, vcc
	v_mul_hi_i32 v67, v66, s83
	v_lshrrev_b32_e32 v68, 31, v67
	v_ashrrev_i32_e32 v67, 11, v67
	v_add_u32_e32 v68, v67, v68
	v_mad_i32_i24 v69, v68, s84, v66
	v_cmp_lt_i32_e64 s[0:1], 15, v69
	s_and_saveexec_b64 s[2:3], s[0:1]
	s_xor_b64 s[0:1], exec, s[2:3]
	v_lshlrev_b32_e32 v66, 12, v68
	v_add3_u32 v66, v66, v69, -16
	v_ashrrev_i32_e32 v67, 31, v66
	v_lshlrev_b64 v[66:67], 12, v[66:67]
	v_lshl_add_u64 v[66:67], s[88:89], 0, v[66:67]
	s_andn2_saveexec_b64 s[0:1], s[0:1]
	v_lshlrev_b32_e32 v66, 14, v68
	v_lshl_add_u32 v66, v69, 10, v66
	v_ashrrev_i32_e32 v67, 31, v66
	v_lshl_add_u64 v[66:67], v[66:67], 2, s[16:17]
	s_or_b64 exec, exec, s[0:1]
	v_ashrrev_i32_e32 v119, 31, v118
	v_lshlrev_b64 v[68:69], 11, v[118:119]
	v_lshl_add_u64 v[68:69], s[62:63], 0, v[68:69]
	s_waitcnt vmcnt(21)
	v_add_f32_e32 v83, v87, v190
	v_lshl_add_u64 v[68:69], v[130:131], 1, v[68:69]
	v_lshl_add_u64 v[66:67], v[66:67], 0, v[134:135]
	global_store_dword v[66:67], v83, off
	v_mul_f32_e32 v86, v83, v242
	v_cvt_pk_bf16_f32 v86, v86, s0
	global_store_short v[68:69], v86, off
.LBB0_3943:
	s_waitcnt vmcnt(20)
	v_add_f32_e32 v71, v71, v117
	global_store_dword v[66:67], v71, off offset:128
	v_mul_f32_e32 v66, v71, v243
	v_cvt_pk_bf16_f32 v66, v66, s0
	global_store_short v[68:69], v66, off offset:64
.LBB0_3945:
	v_cmp_gt_i32_e32 vcc, s85, v116
	s_nop 1
	v_cndmask_b32_e32 v66, v181, v116, vcc
	v_mul_hi_i32 v67, v66, s83
	v_lshrrev_b32_e32 v68, 31, v67
	v_ashrrev_i32_e32 v67, 11, v67
	v_add_u32_e32 v68, v67, v68
	v_mad_i32_i24 v69, v68, s84, v66
	v_cmp_lt_i32_e64 s[0:1], 15, v69
	s_and_saveexec_b64 s[2:3], s[0:1]
	s_xor_b64 s[0:1], exec, s[2:3]
	v_lshlrev_b32_e32 v66, 12, v68
	v_add3_u32 v66, v66, v69, -16
	v_ashrrev_i32_e32 v67, 31, v66
	v_lshlrev_b64 v[66:67], 12, v[66:67]
	v_lshl_add_u64 v[66:67], s[88:89], 0, v[66:67]
	s_andn2_saveexec_b64 s[0:1], s[0:1]
	v_lshlrev_b32_e32 v66, 14, v68
	v_lshl_add_u32 v66, v69, 10, v66
	v_ashrrev_i32_e32 v67, 31, v66
	v_lshl_add_u64 v[66:67], v[66:67], 2, s[16:17]
	s_or_b64 exec, exec, s[0:1]
	v_ashrrev_i32_e32 v117, 31, v116
	v_lshlrev_b64 v[68:69], 11, v[116:117]
	v_lshl_add_u64 v[68:69], s[62:63], 0, v[68:69]
	s_waitcnt vmcnt(19)
	v_add_f32_e32 v86, v88, v189
	v_lshl_add_u64 v[68:69], v[130:131], 1, v[68:69]
	v_lshl_add_u64 v[66:67], v[66:67], 0, v[134:135]
	global_store_dword v[66:67], v86, off
	v_mul_f32_e32 v87, v86, v242
	v_cvt_pk_bf16_f32 v87, v87, s0
	global_store_short v[68:69], v87, off
.LBB0_3951:
	s_waitcnt vmcnt(18)
	v_add_f32_e32 v72, v72, v115
	global_store_dword v[66:67], v72, off offset:128
	v_mul_f32_e32 v66, v72, v243
	v_cvt_pk_bf16_f32 v66, v66, s0
	global_store_short v[68:69], v66, off offset:64
.LBB0_3953:
	v_cmp_gt_i32_e32 vcc, s85, v114
	s_nop 1
	v_cndmask_b32_e32 v66, v181, v114, vcc
	v_mul_hi_i32 v67, v66, s83
	v_lshrrev_b32_e32 v68, 31, v67
	v_ashrrev_i32_e32 v67, 11, v67
	v_add_u32_e32 v68, v67, v68
	v_mad_i32_i24 v69, v68, s84, v66
	v_cmp_lt_i32_e64 s[0:1], 15, v69
	s_and_saveexec_b64 s[2:3], s[0:1]
	s_xor_b64 s[0:1], exec, s[2:3]
	v_lshlrev_b32_e32 v66, 12, v68
	v_add3_u32 v66, v66, v69, -16
	v_ashrrev_i32_e32 v67, 31, v66
	v_lshlrev_b64 v[66:67], 12, v[66:67]
	v_lshl_add_u64 v[66:67], s[88:89], 0, v[66:67]
	s_andn2_saveexec_b64 s[0:1], s[0:1]
	v_lshlrev_b32_e32 v66, 14, v68
	v_lshl_add_u32 v66, v69, 10, v66
	v_ashrrev_i32_e32 v67, 31, v66
	v_lshl_add_u64 v[66:67], v[66:67], 2, s[16:17]
	s_or_b64 exec, exec, s[0:1]
	v_ashrrev_i32_e32 v115, 31, v114
	v_lshlrev_b64 v[68:69], 11, v[114:115]
	v_lshl_add_u64 v[68:69], s[62:63], 0, v[68:69]
	s_waitcnt vmcnt(17)
	v_add_f32_e32 v87, v89, v188
	v_lshl_add_u64 v[68:69], v[130:131], 1, v[68:69]
	v_lshl_add_u64 v[66:67], v[66:67], 0, v[134:135]
	global_store_dword v[66:67], v87, off
	v_mul_f32_e32 v88, v87, v242
	v_cvt_pk_bf16_f32 v88, v88, s0
	global_store_short v[68:69], v88, off
.LBB0_3959:
	s_waitcnt vmcnt(16)
	v_add_f32_e32 v73, v73, v113
	global_store_dword v[66:67], v73, off offset:128
	v_mul_f32_e32 v66, v73, v243
	v_cvt_pk_bf16_f32 v66, v66, s0
	global_store_short v[68:69], v66, off offset:64
.LBB0_3961:
	v_cmp_gt_i32_e32 vcc, s85, v112
	s_nop 1
	v_cndmask_b32_e32 v66, v181, v112, vcc
	v_mul_hi_i32 v67, v66, s83
	v_lshrrev_b32_e32 v68, 31, v67
	v_ashrrev_i32_e32 v67, 11, v67
	v_add_u32_e32 v68, v67, v68
	v_mad_i32_i24 v69, v68, s84, v66
	v_cmp_lt_i32_e64 s[0:1], 15, v69
	s_and_saveexec_b64 s[2:3], s[0:1]
	s_xor_b64 s[0:1], exec, s[2:3]
	v_lshlrev_b32_e32 v66, 12, v68
	v_add3_u32 v66, v66, v69, -16
	v_ashrrev_i32_e32 v67, 31, v66
	v_lshlrev_b64 v[66:67], 12, v[66:67]
	v_lshl_add_u64 v[66:67], s[88:89], 0, v[66:67]
	s_andn2_saveexec_b64 s[0:1], s[0:1]
	v_lshlrev_b32_e32 v66, 14, v68
	v_lshl_add_u32 v66, v69, 10, v66
	v_ashrrev_i32_e32 v67, 31, v66
	v_lshl_add_u64 v[66:67], v[66:67], 2, s[16:17]
	s_or_b64 exec, exec, s[0:1]
	v_ashrrev_i32_e32 v113, 31, v112
	v_lshlrev_b64 v[68:69], 11, v[112:113]
	v_lshl_add_u64 v[68:69], s[62:63], 0, v[68:69]
	s_waitcnt vmcnt(15)
	v_add_f32_e32 v88, v90, v187
	v_lshl_add_u64 v[68:69], v[130:131], 1, v[68:69]
	v_lshl_add_u64 v[66:67], v[66:67], 0, v[134:135]
	global_store_dword v[66:67], v88, off
	v_mul_f32_e32 v89, v88, v242
	v_cvt_pk_bf16_f32 v89, v89, s0
	global_store_short v[68:69], v89, off
.LBB0_3967:
	s_waitcnt vmcnt(14)
	v_add_f32_e32 v74, v74, v111
	global_store_dword v[66:67], v74, off offset:128
	v_mul_f32_e32 v66, v74, v243
	v_cvt_pk_bf16_f32 v66, v66, s0
	global_store_short v[68:69], v66, off offset:64
.LBB0_3969:
	v_cmp_gt_i32_e32 vcc, s85, v110
	s_nop 1
	v_cndmask_b32_e32 v66, v181, v110, vcc
	v_mul_hi_i32 v67, v66, s83
	v_lshrrev_b32_e32 v68, 31, v67
	v_ashrrev_i32_e32 v67, 11, v67
	v_add_u32_e32 v68, v67, v68
	v_mad_i32_i24 v69, v68, s84, v66
	v_cmp_lt_i32_e64 s[0:1], 15, v69
	s_and_saveexec_b64 s[2:3], s[0:1]
	s_xor_b64 s[0:1], exec, s[2:3]
	v_lshlrev_b32_e32 v66, 12, v68
	v_add3_u32 v66, v66, v69, -16
	v_ashrrev_i32_e32 v67, 31, v66
	v_lshlrev_b64 v[66:67], 12, v[66:67]
	v_lshl_add_u64 v[66:67], s[88:89], 0, v[66:67]
	s_andn2_saveexec_b64 s[0:1], s[0:1]
	v_lshlrev_b32_e32 v66, 14, v68
	v_lshl_add_u32 v66, v69, 10, v66
	v_ashrrev_i32_e32 v67, 31, v66
	v_lshl_add_u64 v[66:67], v[66:67], 2, s[16:17]
	s_or_b64 exec, exec, s[0:1]
	v_ashrrev_i32_e32 v111, 31, v110
	v_lshlrev_b64 v[68:69], 11, v[110:111]
	v_lshl_add_u64 v[68:69], s[62:63], 0, v[68:69]
	s_waitcnt vmcnt(13)
	v_add_f32_e32 v89, v91, v186
	v_lshl_add_u64 v[68:69], v[130:131], 1, v[68:69]
	v_lshl_add_u64 v[66:67], v[66:67], 0, v[134:135]
	global_store_dword v[66:67], v89, off
	v_mul_f32_e32 v90, v89, v242
	v_cvt_pk_bf16_f32 v90, v90, s0
	global_store_short v[68:69], v90, off
.LBB0_3975:
	s_waitcnt vmcnt(12)
	v_add_f32_e32 v75, v75, v109
	global_store_dword v[66:67], v75, off offset:128
	v_mul_f32_e32 v66, v75, v243
	v_cvt_pk_bf16_f32 v66, v66, s0
	global_store_short v[68:69], v66, off offset:64
.LBB0_3977:
	v_cmp_gt_i32_e32 vcc, s85, v108
	s_nop 1
	v_cndmask_b32_e32 v66, v181, v108, vcc
	v_mul_hi_i32 v67, v66, s83
	v_lshrrev_b32_e32 v68, 31, v67
	v_ashrrev_i32_e32 v67, 11, v67
	v_add_u32_e32 v68, v67, v68
	v_mad_i32_i24 v69, v68, s84, v66
	v_cmp_lt_i32_e64 s[0:1], 15, v69
	s_and_saveexec_b64 s[2:3], s[0:1]
	s_xor_b64 s[0:1], exec, s[2:3]
	v_lshlrev_b32_e32 v66, 12, v68
	v_add3_u32 v66, v66, v69, -16
	v_ashrrev_i32_e32 v67, 31, v66
	v_lshlrev_b64 v[66:67], 12, v[66:67]
	v_lshl_add_u64 v[66:67], s[88:89], 0, v[66:67]
	s_andn2_saveexec_b64 s[0:1], s[0:1]
	v_lshlrev_b32_e32 v66, 14, v68
	v_lshl_add_u32 v66, v69, 10, v66
	v_ashrrev_i32_e32 v67, 31, v66
	v_lshl_add_u64 v[66:67], v[66:67], 2, s[16:17]
	s_or_b64 exec, exec, s[0:1]
	v_ashrrev_i32_e32 v109, 31, v108
	v_lshlrev_b64 v[68:69], 11, v[108:109]
	v_lshl_add_u64 v[68:69], s[62:63], 0, v[68:69]
	s_waitcnt vmcnt(11)
	v_add_f32_e32 v90, v92, v185
	v_lshl_add_u64 v[68:69], v[130:131], 1, v[68:69]
	v_lshl_add_u64 v[66:67], v[66:67], 0, v[134:135]
	global_store_dword v[66:67], v90, off
	v_mul_f32_e32 v91, v90, v242
	v_cvt_pk_bf16_f32 v91, v91, s0
	global_store_short v[68:69], v91, off
.LBB0_3983:
	s_waitcnt vmcnt(10)
	v_add_f32_e32 v76, v76, v107
	global_store_dword v[66:67], v76, off offset:128
	v_mul_f32_e32 v66, v76, v243
	v_cvt_pk_bf16_f32 v66, v66, s0
	global_store_short v[68:69], v66, off offset:64
.LBB0_3985:
	v_cmp_gt_i32_e32 vcc, s85, v106
	s_nop 1
	v_cndmask_b32_e32 v66, v181, v106, vcc
	v_mul_hi_i32 v67, v66, s83
	v_lshrrev_b32_e32 v68, 31, v67
	v_ashrrev_i32_e32 v67, 11, v67
	v_add_u32_e32 v68, v67, v68
	v_mad_i32_i24 v69, v68, s84, v66
	v_cmp_lt_i32_e64 s[0:1], 15, v69
	s_and_saveexec_b64 s[2:3], s[0:1]
	s_xor_b64 s[0:1], exec, s[2:3]
	v_lshlrev_b32_e32 v66, 12, v68
	v_add3_u32 v66, v66, v69, -16
	v_ashrrev_i32_e32 v67, 31, v66
	v_lshlrev_b64 v[66:67], 12, v[66:67]
	v_lshl_add_u64 v[66:67], s[88:89], 0, v[66:67]
	s_andn2_saveexec_b64 s[0:1], s[0:1]
	v_lshlrev_b32_e32 v66, 14, v68
	v_lshl_add_u32 v66, v69, 10, v66
	v_ashrrev_i32_e32 v67, 31, v66
	v_lshl_add_u64 v[66:67], v[66:67], 2, s[16:17]
	s_or_b64 exec, exec, s[0:1]
	v_ashrrev_i32_e32 v107, 31, v106
	v_lshlrev_b64 v[68:69], 11, v[106:107]
	v_lshl_add_u64 v[68:69], s[62:63], 0, v[68:69]
	s_waitcnt vmcnt(9)
	v_add_f32_e32 v91, v93, v184
	v_lshl_add_u64 v[68:69], v[130:131], 1, v[68:69]
	v_lshl_add_u64 v[66:67], v[66:67], 0, v[134:135]
	global_store_dword v[66:67], v91, off
	v_mul_f32_e32 v92, v91, v242
	v_cvt_pk_bf16_f32 v92, v92, s0
	global_store_short v[68:69], v92, off
.LBB0_3991:
	s_waitcnt vmcnt(8)
	v_add_f32_e32 v77, v77, v105
	global_store_dword v[66:67], v77, off offset:128
	v_mul_f32_e32 v66, v77, v243
	v_cvt_pk_bf16_f32 v66, v66, s0
	global_store_short v[68:69], v66, off offset:64
.LBB0_3993:
	v_cmp_gt_i32_e32 vcc, s85, v104
	s_nop 1
	v_cndmask_b32_e32 v66, v181, v104, vcc
	v_mul_hi_i32 v67, v66, s83
	v_lshrrev_b32_e32 v68, 31, v67
	v_ashrrev_i32_e32 v67, 11, v67
	v_add_u32_e32 v68, v67, v68
	v_mad_i32_i24 v69, v68, s84, v66
	v_cmp_lt_i32_e64 s[0:1], 15, v69
	s_and_saveexec_b64 s[2:3], s[0:1]
	s_xor_b64 s[0:1], exec, s[2:3]
	v_lshlrev_b32_e32 v66, 12, v68
	v_add3_u32 v66, v66, v69, -16
	v_ashrrev_i32_e32 v67, 31, v66
	v_lshlrev_b64 v[66:67], 12, v[66:67]
	v_lshl_add_u64 v[66:67], s[88:89], 0, v[66:67]
	s_andn2_saveexec_b64 s[0:1], s[0:1]
	v_lshlrev_b32_e32 v66, 14, v68
	v_lshl_add_u32 v66, v69, 10, v66
	v_ashrrev_i32_e32 v67, 31, v66
	v_lshl_add_u64 v[66:67], v[66:67], 2, s[16:17]
	s_or_b64 exec, exec, s[0:1]
	v_ashrrev_i32_e32 v105, 31, v104
	v_lshlrev_b64 v[68:69], 11, v[104:105]
	v_lshl_add_u64 v[68:69], s[62:63], 0, v[68:69]
	s_waitcnt vmcnt(7)
	v_add_f32_e32 v92, v94, v183
	v_lshl_add_u64 v[68:69], v[130:131], 1, v[68:69]
	v_lshl_add_u64 v[66:67], v[66:67], 0, v[134:135]
	global_store_dword v[66:67], v92, off
	v_mul_f32_e32 v93, v92, v242
	v_cvt_pk_bf16_f32 v93, v93, s0
	global_store_short v[68:69], v93, off
.LBB0_3999:
	s_waitcnt vmcnt(6)
	v_add_f32_e32 v78, v78, v103
	global_store_dword v[66:67], v78, off offset:128
	v_mul_f32_e32 v66, v78, v243
	v_cvt_pk_bf16_f32 v66, v66, s0
	global_store_short v[68:69], v66, off offset:64
.LBB0_4001:
	v_cmp_gt_i32_e32 vcc, s85, v102
	s_nop 1
	v_cndmask_b32_e32 v66, v181, v102, vcc
	v_mul_hi_i32 v67, v66, s83
	v_lshrrev_b32_e32 v68, 31, v67
	v_ashrrev_i32_e32 v67, 11, v67
	v_add_u32_e32 v68, v67, v68
	v_mad_i32_i24 v69, v68, s84, v66
	v_cmp_lt_i32_e64 s[0:1], 15, v69
	s_and_saveexec_b64 s[2:3], s[0:1]
	s_xor_b64 s[0:1], exec, s[2:3]
	v_lshlrev_b32_e32 v66, 12, v68
	v_add3_u32 v66, v66, v69, -16
	v_ashrrev_i32_e32 v67, 31, v66
	v_lshlrev_b64 v[66:67], 12, v[66:67]
	v_lshl_add_u64 v[66:67], s[88:89], 0, v[66:67]
	s_andn2_saveexec_b64 s[0:1], s[0:1]
	v_lshlrev_b32_e32 v66, 14, v68
	v_lshl_add_u32 v66, v69, 10, v66
	v_ashrrev_i32_e32 v67, 31, v66
	v_lshl_add_u64 v[66:67], v[66:67], 2, s[16:17]
	s_or_b64 exec, exec, s[0:1]
	v_ashrrev_i32_e32 v103, 31, v102
	v_lshlrev_b64 v[68:69], 11, v[102:103]
	v_lshl_add_u64 v[68:69], s[62:63], 0, v[68:69]
	s_waitcnt vmcnt(5)
	v_add_f32_e32 v93, v95, v182
	v_lshl_add_u64 v[68:69], v[130:131], 1, v[68:69]
	v_lshl_add_u64 v[66:67], v[66:67], 0, v[134:135]
	global_store_dword v[66:67], v93, off
	v_mul_f32_e32 v94, v93, v242
	v_cvt_pk_bf16_f32 v94, v94, s0
	global_store_short v[68:69], v94, off
.LBB0_4007:
	s_waitcnt vmcnt(4)
	v_add_f32_e32 v79, v79, v101
	global_store_dword v[66:67], v79, off offset:128
	v_mul_f32_e32 v66, v79, v243
	v_cvt_pk_bf16_f32 v66, v66, s0
	global_store_short v[68:69], v66, off offset:64
.LBB0_4009:
	v_cmp_gt_i32_e32 vcc, s85, v100
	s_nop 1
	v_cndmask_b32_e32 v66, v181, v100, vcc
	v_mul_hi_i32 v67, v66, s83
	v_lshrrev_b32_e32 v68, 31, v67
	v_ashrrev_i32_e32 v67, 11, v67
	v_add_u32_e32 v68, v67, v68
	v_mad_i32_i24 v69, v68, s84, v66
	v_cmp_lt_i32_e64 s[0:1], 15, v69
	s_and_saveexec_b64 s[2:3], s[0:1]
	s_xor_b64 s[0:1], exec, s[2:3]
	v_lshlrev_b32_e32 v66, 12, v68
	v_add3_u32 v66, v66, v69, -16
	v_ashrrev_i32_e32 v67, 31, v66
	v_lshlrev_b64 v[66:67], 12, v[66:67]
	v_lshl_add_u64 v[66:67], s[88:89], 0, v[66:67]
	s_andn2_saveexec_b64 s[0:1], s[0:1]
	v_lshlrev_b32_e32 v66, 14, v68
	v_lshl_add_u32 v66, v69, 10, v66
	v_ashrrev_i32_e32 v67, 31, v66
	v_lshl_add_u64 v[66:67], v[66:67], 2, s[16:17]
	s_or_b64 exec, exec, s[0:1]
	v_ashrrev_i32_e32 v101, 31, v100
	v_lshlrev_b64 v[68:69], 11, v[100:101]
	v_lshl_add_u64 v[68:69], s[62:63], 0, v[68:69]
	s_waitcnt vmcnt(3)
	v_add_f32_e32 v94, v96, v179
	v_lshl_add_u64 v[68:69], v[130:131], 1, v[68:69]
	v_lshl_add_u64 v[66:67], v[66:67], 0, v[134:135]
	global_store_dword v[66:67], v94, off
	v_mul_f32_e32 v95, v94, v242
	v_cvt_pk_bf16_f32 v95, v95, s0
	global_store_short v[68:69], v95, off
.LBB0_4015:
	s_waitcnt vmcnt(2)
	v_add_f32_e32 v95, v80, v99
	global_store_dword v[66:67], v95, off offset:128
	v_mul_f32_e32 v66, v95, v243
	v_cvt_pk_bf16_f32 v66, v66, s0
	global_store_short v[68:69], v66, off offset:64
.LBB0_4017:
	v_cmp_gt_i32_e32 vcc, s85, v98
	s_nop 1
	v_cndmask_b32_e32 v66, v181, v98, vcc
	v_mul_hi_i32 v67, v66, s83
	v_lshrrev_b32_e32 v68, 31, v67
	v_ashrrev_i32_e32 v67, 11, v67
	v_add_u32_e32 v68, v67, v68
	v_mad_i32_i24 v69, v68, s84, v66
	v_cmp_lt_i32_e64 s[0:1], 15, v69
	s_and_saveexec_b64 s[2:3], s[0:1]
	s_xor_b64 s[0:1], exec, s[2:3]
	v_lshlrev_b32_e32 v66, 12, v68
	v_add3_u32 v66, v66, v69, -16
	v_ashrrev_i32_e32 v67, 31, v66
	v_lshlrev_b64 v[66:67], 12, v[66:67]
	v_lshl_add_u64 v[66:67], s[88:89], 0, v[66:67]
	s_andn2_saveexec_b64 s[0:1], s[0:1]
	v_lshlrev_b32_e32 v66, 14, v68
	v_lshl_add_u32 v66, v69, 10, v66
	v_ashrrev_i32_e32 v67, 31, v66
	v_lshl_add_u64 v[66:67], v[66:67], 2, s[16:17]
	s_or_b64 exec, exec, s[0:1]
	v_ashrrev_i32_e32 v99, 31, v98
	v_lshlrev_b64 v[68:69], 11, v[98:99]
	v_lshl_add_u64 v[68:69], s[62:63], 0, v[68:69]
	s_waitcnt vmcnt(1)
	v_add_f32_e32 v80, v97, v177
	v_lshl_add_u64 v[68:69], v[130:131], 1, v[68:69]
	v_lshl_add_u64 v[66:67], v[66:67], 0, v[134:135]
	global_store_dword v[66:67], v80, off
	v_mul_f32_e32 v96, v80, v242
	v_cvt_pk_bf16_f32 v96, v96, s0
	global_store_short v[68:69], v96, off
.LBB0_4023:
	s_waitcnt vmcnt(0)
	v_add_f32_e32 v81, v81, v171
	global_store_dword v[66:67], v81, off offset:128
	v_mul_f32_e32 v66, v81, v243
	v_cvt_pk_bf16_f32 v66, v66, s0
	global_store_short v[68:69], v66, off offset:64
.LBB0_4025:
	v_lshlrev_b32_e32 v66, 1, v175
	v_lshlrev_b32_e32 v104, 1, v172
	v_and_b32_e32 v66, 32, v66
	v_and_b32_e32 v104, 24, v104
	v_and_b32_e32 v105, 3, v172
	v_or3_b32 v66, v105, v104, v66
	v_and_b32_e32 v105, 64, v200
	v_mul_f32_e32 v71, v71, v71
	v_mul_f32_e32 v70, v70, v70
	v_xor_b32_e32 v104, 16, v200
	v_add_u32_e32 v109, 64, v105
	v_fmac_f32_e32 v71, v83, v83
	v_fmac_f32_e32 v70, v82, v82
	v_mul_f32_e32 v82, v128, v128
	v_mul_f32_e32 v83, v178, v178
	v_mul_f32_e32 v98, v168, v168
	v_mul_f32_e32 v99, v176, v176
	v_and_b32_e32 v100, 16, v172
	v_cmp_lt_i32_e32 vcc, v104, v109
	v_fmac_f32_e32 v82, v138, v138
	v_fmac_f32_e32 v83, v169, v169
	v_fmac_f32_e32 v98, v170, v170
	v_fmac_f32_e32 v99, v137, v137
	v_cndmask_b32_e32 v104, v200, v104, vcc
	v_cmp_eq_u32_e32 vcc, 0, v100
	v_mul_f32_e32 v81, v81, v81
	v_lshlrev_b32_e32 v104, 2, v104
	v_cndmask_b32_e32 v100, v99, v83, vcc
	v_fmac_f32_e32 v81, v80, v80
	v_cndmask_b32_e32 v80, v83, v99, vcc
	v_cndmask_b32_e32 v83, v98, v82, vcc
	ds_bpermute_b32 v83, v104, v83
	v_mul_f32_e32 v67, v95, v95
	v_mul_f32_e32 v95, v161, v161
	v_fmac_f32_e32 v95, v160, v160
	v_cndmask_b32_e32 v82, v82, v98, vcc
	s_waitcnt lgkmcnt(0)
	v_add_f32_e32 v82, v82, v83
	v_cndmask_b32_e32 v83, v95, v70, vcc
	ds_bpermute_b32 v83, v104, v83
	v_mul_f32_e32 v69, v78, v78
	v_fmac_f32_e32 v69, v92, v92
	v_mul_f32_e32 v73, v73, v73
	v_mul_f32_e32 v92, v155, v155
	v_fmac_f32_e32 v73, v87, v87
	v_fmac_f32_e32 v92, v154, v154
	v_cndmask_b32_e32 v70, v70, v95, vcc
	s_waitcnt lgkmcnt(0)
	v_add_f32_e32 v70, v70, v83
	v_cndmask_b32_e32 v83, v92, v73, vcc
	ds_bpermute_b32 v83, v104, v83
	v_mul_f32_e32 v75, v75, v75
	v_mul_f32_e32 v76, v76, v76
	v_fmac_f32_e32 v75, v89, v89
	v_mul_f32_e32 v89, v149, v149
	v_fmac_f32_e32 v76, v90, v90
	v_fmac_f32_e32 v89, v148, v148
	v_cndmask_b32_e32 v73, v73, v92, vcc
	s_waitcnt lgkmcnt(0)
	v_add_f32_e32 v73, v73, v83
	v_cndmask_b32_e32 v83, v89, v76, vcc
	ds_bpermute_b32 v83, v104, v83
	v_mul_f32_e32 v72, v72, v72
	v_mul_f32_e32 v68, v79, v79
	v_fmac_f32_e32 v72, v86, v86
	v_mul_f32_e32 v86, v143, v143
	v_fmac_f32_e32 v68, v93, v93
	v_mul_f32_e32 v77, v77, v77
	v_fmac_f32_e32 v86, v142, v142
	v_cndmask_b32_e32 v76, v76, v89, vcc
	v_fmac_f32_e32 v77, v91, v91
	v_mul_f32_e32 v74, v74, v74
	v_mul_f32_e32 v91, v153, v153
	s_waitcnt lgkmcnt(0)
	v_add_f32_e32 v76, v76, v83
	v_cndmask_b32_e32 v83, v86, v68, vcc
	v_fmac_f32_e32 v74, v88, v88
	v_mul_f32_e32 v78, v122, v122
	v_mul_f32_e32 v79, v124, v124
	v_mul_f32_e32 v88, v147, v147
	v_fmac_f32_e32 v91, v152, v152
	v_mul_f32_e32 v96, v163, v163
	v_mul_f32_e32 v97, v165, v165
	ds_bpermute_b32 v83, v104, v83
	v_fmac_f32_e32 v78, v85, v85
	v_fmac_f32_e32 v79, v84, v84
	v_mul_f32_e32 v87, v145, v145
	v_fmac_f32_e32 v88, v146, v146
	v_mul_f32_e32 v90, v151, v151
	v_mul_f32_e32 v93, v157, v157
	v_fmac_f32_e32 v96, v162, v162
	v_fmac_f32_e32 v97, v164, v164
	v_cndmask_b32_e32 v92, v91, v74, vcc
	v_fmac_f32_e32 v87, v144, v144
	v_fmac_f32_e32 v90, v150, v150
	v_fmac_f32_e32 v93, v156, v156
	ds_bpermute_b32 v100, v104, v100
	v_cndmask_b32_e32 v98, v97, v79, vcc
	v_cndmask_b32_e32 v99, v96, v78, vcc
	ds_bpermute_b32 v92, v104, v92
	v_cndmask_b32_e32 v89, v88, v77, vcc
	ds_bpermute_b32 v98, v104, v98
	ds_bpermute_b32 v99, v104, v99
	v_cndmask_b32_e32 v78, v78, v96, vcc
	v_cndmask_b32_e32 v96, v93, v72, vcc
	v_cndmask_b32_e32 v72, v72, v93, vcc
	v_cndmask_b32_e32 v93, v90, v75, vcc
	v_cndmask_b32_e32 v75, v75, v90, vcc
	ds_bpermute_b32 v89, v104, v89
	v_cndmask_b32_e32 v90, v87, v69, vcc
	s_lshl_b32 s0, s4, 2
	ds_bpermute_b32 v90, v104, v90
	v_cndmask_b32_e32 v68, v68, v86, vcc
	v_fmac_f32_e32 v67, v94, v94
	v_mul_f32_e32 v85, v141, v141
	v_mul_f32_e32 v94, v159, v159
	s_ashr_i32 s1, s0, 31
	s_waitcnt lgkmcnt(6)
	v_add_f32_e32 v68, v68, v83
	v_xor_b32_e32 v83, 8, v200
	v_mul_f32_e32 v84, v167, v167
	v_fmac_f32_e32 v85, v140, v140
	v_fmac_f32_e32 v94, v158, v158
	v_and_b32_e32 v101, 8, v172
	s_lshl_b64 s[8:9], s[0:1], 2
	v_cndmask_b32_e32 v74, v74, v91, vcc
	v_cmp_lt_i32_e64 s[0:1], v83, v109
	v_fmac_f32_e32 v84, v166, v166
	s_waitcnt lgkmcnt(5)
	v_add_f32_e32 v80, v80, v100
	v_cndmask_b32_e32 v79, v79, v97, vcc
	v_cndmask_b32_e32 v95, v94, v71, vcc
	s_waitcnt lgkmcnt(4)
	v_add_f32_e32 v74, v74, v92
	v_cndmask_b32_e32 v77, v77, v88, vcc
	v_cndmask_b32_e32 v86, v85, v67, vcc
	v_cndmask_b32_e64 v83, v200, v83, s[0:1]
	v_cmp_eq_u32_e64 s[2:3], 0, v101
	s_waitcnt lgkmcnt(3)
	v_add_f32_e32 v79, v79, v98
	s_waitcnt lgkmcnt(2)
	v_add_f32_e32 v78, v78, v99
	ds_bpermute_b32 v95, v104, v95
	ds_bpermute_b32 v96, v104, v96
	ds_bpermute_b32 v93, v104, v93
	s_waitcnt lgkmcnt(4)
	v_add_f32_e32 v77, v77, v89
	v_cndmask_b32_e32 v69, v69, v87, vcc
	ds_bpermute_b32 v86, v104, v86
	v_cndmask_b32_e32 v87, v84, v81, vcc
	v_lshlrev_b32_e32 v105, 2, v83
	v_cndmask_b32_e64 v83, v80, v74, s[2:3]
	s_waitcnt lgkmcnt(4)
	v_add_f32_e32 v69, v69, v90
	ds_bpermute_b32 v87, v104, v87
	v_cndmask_b32_e32 v81, v81, v84, vcc
	v_cndmask_b32_e64 v74, v74, v80, s[2:3]
	ds_bpermute_b32 v80, v105, v83
	v_cndmask_b32_e64 v84, v79, v76, s[2:3]
	v_cndmask_b32_e64 v76, v76, v79, s[2:3]
	v_cndmask_b32_e64 v79, v78, v77, s[2:3]
	v_cndmask_b32_e64 v77, v77, v78, s[2:3]
	ds_bpermute_b32 v78, v105, v79
	v_cndmask_b32_e64 v79, v70, v69, s[2:3]
	ds_bpermute_b32 v79, v105, v79
	v_cndmask_b32_e32 v71, v71, v94, vcc
	v_cndmask_b32_e32 v67, v67, v85, vcc
	s_waitcnt lgkmcnt(7)
	v_add_f32_e32 v71, v71, v95
	s_waitcnt lgkmcnt(6)
	v_add_f32_e32 v72, v72, v96
	s_waitcnt lgkmcnt(5)
	v_add_f32_e32 v75, v75, v93
	s_waitcnt lgkmcnt(4)
	v_add_f32_e32 v67, v67, v86
	s_waitcnt lgkmcnt(3)
	v_add_f32_e32 v81, v81, v87
	v_cndmask_b32_e64 v83, v82, v75, s[2:3]
	s_waitcnt lgkmcnt(2)
	v_add_f32_e32 v74, v74, v80
	v_cndmask_b32_e64 v80, v71, v68, s[2:3]
	v_cndmask_b32_e64 v69, v69, v70, s[2:3]
	v_cndmask_b32_e64 v70, v72, v67, s[2:3]
	v_cndmask_b32_e64 v67, v67, v72, s[2:3]
	v_xor_b32_e32 v72, 4, v200
	v_and_b32_e32 v102, 4, v172
	ds_bpermute_b32 v83, v105, v83
	ds_bpermute_b32 v80, v105, v80
	v_cndmask_b32_e64 v68, v68, v71, s[2:3]
	ds_bpermute_b32 v70, v105, v70
	v_cndmask_b32_e64 v71, v73, v81, s[2:3]
	v_cmp_lt_i32_e64 s[0:1], v72, v109
	s_waitcnt lgkmcnt(3)
	v_add_f32_e32 v69, v69, v79
	ds_bpermute_b32 v71, v105, v71
	v_cndmask_b32_e64 v72, v200, v72, s[0:1]
	v_cmp_eq_u32_e64 s[4:5], 0, v102
	ds_bpermute_b32 v84, v105, v84
	v_lshlrev_b32_e32 v106, 2, v72
	v_cndmask_b32_e64 v72, v74, v69, s[4:5]
	ds_bpermute_b32 v72, v106, v72
	v_cndmask_b32_e64 v75, v75, v82, s[2:3]
	s_waitcnt lgkmcnt(5)
	v_add_f32_e32 v75, v75, v83
	s_waitcnt lgkmcnt(4)
	v_add_f32_e32 v68, v68, v80
	s_waitcnt lgkmcnt(3)
	v_add_f32_e32 v67, v67, v70
	v_cndmask_b32_e64 v70, v81, v73, s[2:3]
	s_waitcnt lgkmcnt(2)
	v_add_f32_e32 v70, v70, v71
	v_cndmask_b32_e64 v71, v75, v68, s[4:5]
	s_waitcnt lgkmcnt(1)
	v_add_f32_e32 v76, v76, v84
	v_add_f32_e32 v77, v77, v78
	v_cndmask_b32_e64 v69, v69, v74, s[4:5]
	ds_bpermute_b32 v71, v106, v71
	s_waitcnt lgkmcnt(1)
	v_add_f32_e32 v69, v69, v72
	v_cndmask_b32_e64 v72, v76, v67, s[4:5]
	v_cndmask_b32_e64 v73, v77, v70, s[4:5]
	ds_bpermute_b32 v72, v106, v72
	ds_bpermute_b32 v73, v106, v73
	v_cndmask_b32_e64 v68, v68, v75, s[4:5]
	s_waitcnt lgkmcnt(2)
	v_add_f32_e32 v68, v68, v71
	v_xor_b32_e32 v71, 2, v200
	v_and_b32_e32 v103, 2, v172
	v_cndmask_b32_e64 v67, v67, v76, s[4:5]
	v_cndmask_b32_e64 v70, v70, v77, s[4:5]
	v_cmp_lt_i32_e64 s[0:1], v71, v109
	s_waitcnt lgkmcnt(1)
	v_add_f32_e32 v67, v67, v72
	s_waitcnt lgkmcnt(0)
	v_add_f32_e32 v70, v70, v73
	v_cndmask_b32_e64 v71, v200, v71, s[0:1]
	v_cmp_eq_u32_e64 s[6:7], 0, v103
	v_lshlrev_b32_e32 v107, 2, v71
	v_and_b32_e32 v108, 1, v172
	v_cndmask_b32_e64 v71, v69, v67, s[6:7]
	v_cndmask_b32_e64 v72, v68, v70, s[6:7]
	ds_bpermute_b32 v71, v107, v71
	ds_bpermute_b32 v72, v107, v72
	v_cndmask_b32_e64 v67, v67, v69, s[6:7]
	v_xor_b32_e32 v69, 1, v200
	s_add_u32 s10, s12, s8
	v_cndmask_b32_e64 v68, v70, v68, s[6:7]
	v_cmp_lt_i32_e64 s[0:1], v69, v109
	s_addc_u32 s11, s13, s9
	s_waitcnt lgkmcnt(1)
	v_add_f32_e32 v67, v67, v71
	s_waitcnt lgkmcnt(0)
	v_add_f32_e32 v70, v68, v72
	v_cmp_eq_u32_e64 s[8:9], 0, v108
	v_cndmask_b32_e64 v69, v200, v69, s[0:1]
	v_lshlrev_b32_e32 v108, 2, v69
	v_cndmask_b32_e64 v68, v67, v70, s[8:9]
	ds_bpermute_b32 v71, v108, v68
	v_or3_b32 v66, v66, v173, v174
	v_lshlrev_b32_e32 v0, 2, v0
	v_lshl_add_u64 v[68:69], s[10:11], 0, v[0:1]
	v_cndmask_b32_e64 v0, v70, v67, s[8:9]
	v_ashrrev_i32_e32 v67, 31, v66
	s_waitcnt lgkmcnt(0)
	v_add_f32_e32 v0, v0, v71
	v_lshlrev_b64 v[70:71], 6, v[66:67]
	v_or_b32_e32 v100, 64, v136
	v_lshl_add_u64 v[70:71], v[68:69], 0, v[70:71]
	v_min_i32_e32 v67, 0x403f, v100
	global_store_dword v[70:71], v0, off
	s_cmp_lg_u32 s32, 0
	s_cbranch_scc0 .Lrt1_c
	s_branch .LBB0_3578
.Lrt1_c:
	v_mul_hi_i32 v0, v67, s83
	v_lshrrev_b32_e32 v70, 31, v0
	v_ashrrev_i32_e32 v0, 11, v0
	v_add_u32_e32 v0, v0, v70
	v_mad_i32_i24 v67, v0, s84, v67
	v_cmp_lt_i32_e64 s[0:1], 15, v67
	s_and_saveexec_b64 s[10:11], s[0:1]
	s_xor_b64 s[0:1], exec, s[10:11]
	v_lshlrev_b32_e32 v0, 12, v0
	v_add3_u32 v70, v0, v67, -16
	v_ashrrev_i32_e32 v71, 31, v70
	v_lshlrev_b64 v[70:71], 12, v[70:71]
	v_lshl_add_u64 v[70:71], s[88:89], 0, v[70:71]
	s_andn2_saveexec_b64 s[0:1], s[0:1]
	v_lshlrev_b32_e32 v0, 14, v0
	v_lshl_add_u32 v70, v67, 10, v0
	v_ashrrev_i32_e32 v71, 31, v70
	v_lshl_add_u64 v[70:71], v[70:71], 2, s[16:17]
	s_or_b64 exec, exec, s[0:1]
	v_lshl_add_u64 v[70:71], v[130:131], 2, v[70:71]
	global_load_dword v0, v[70:71], off
	global_load_dword v67, v[70:71], off offset:128
	v_or_b32_e32 v98, 0x41, v136
	v_min_i32_e32 v70, 0x403f, v98
	v_mul_hi_i32 v71, v70, s83
	v_lshrrev_b32_e32 v72, 31, v71
	v_ashrrev_i32_e32 v71, 11, v71
	v_add_u32_e32 v72, v71, v72
	v_mad_i32_i24 v73, v72, s84, v70
	v_cmp_lt_i32_e64 s[0:1], 15, v73
	s_and_saveexec_b64 s[10:11], s[0:1]
	s_xor_b64 s[0:1], exec, s[10:11]
	v_lshlrev_b32_e32 v70, 12, v72
	v_add3_u32 v70, v70, v73, -16
	v_ashrrev_i32_e32 v71, 31, v70
	v_lshlrev_b64 v[70:71], 12, v[70:71]
	v_lshl_add_u64 v[70:71], s[88:89], 0, v[70:71]
	s_andn2_saveexec_b64 s[0:1], s[0:1]
	v_lshlrev_b32_e32 v70, 14, v72
	v_lshl_add_u32 v70, v73, 10, v70
	v_ashrrev_i32_e32 v71, 31, v70
	v_lshl_add_u64 v[70:71], v[70:71], 2, s[16:17]
	s_or_b64 exec, exec, s[0:1]
	v_lshl_add_u64 v[70:71], v[130:131], 2, v[70:71]
	global_load_dword v124, v[70:71], off
	global_load_dword v97, v[70:71], off offset:128
	v_or_b32_e32 v96, 0x42, v136
	v_min_i32_e32 v70, 0x403f, v96
	v_mul_hi_i32 v71, v70, s83
	v_lshrrev_b32_e32 v72, 31, v71
	v_ashrrev_i32_e32 v71, 11, v71
	v_add_u32_e32 v72, v71, v72
	v_mad_i32_i24 v73, v72, s84, v70
	v_cmp_lt_i32_e64 s[0:1], 15, v73
	s_and_saveexec_b64 s[10:11], s[0:1]
	s_xor_b64 s[0:1], exec, s[10:11]
	v_lshlrev_b32_e32 v70, 12, v72
	v_add3_u32 v70, v70, v73, -16
	v_ashrrev_i32_e32 v71, 31, v70
	v_lshlrev_b64 v[70:71], 12, v[70:71]
	v_lshl_add_u64 v[70:71], s[88:89], 0, v[70:71]
	s_andn2_saveexec_b64 s[0:1], s[0:1]
	v_lshlrev_b32_e32 v70, 14, v72
	v_lshl_add_u32 v70, v73, 10, v70
	v_ashrrev_i32_e32 v71, 31, v70
	v_lshl_add_u64 v[70:71], v[70:71], 2, s[16:17]
	s_or_b64 exec, exec, s[0:1]
	v_lshl_add_u64 v[70:71], v[130:131], 2, v[70:71]
	global_load_dword v123, v[70:71], off
	global_load_dword v95, v[70:71], off offset:128
	v_or_b32_e32 v94, 0x43, v136
	v_min_i32_e32 v70, 0x403f, v94
	v_mul_hi_i32 v71, v70, s83
	v_lshrrev_b32_e32 v72, 31, v71
	v_ashrrev_i32_e32 v71, 11, v71
	v_add_u32_e32 v72, v71, v72
	v_mad_i32_i24 v73, v72, s84, v70
	v_cmp_lt_i32_e64 s[0:1], 15, v73
	s_and_saveexec_b64 s[10:11], s[0:1]
	s_xor_b64 s[0:1], exec, s[10:11]
	v_lshlrev_b32_e32 v70, 12, v72
	v_add3_u32 v70, v70, v73, -16
	v_ashrrev_i32_e32 v71, 31, v70
	v_lshlrev_b64 v[70:71], 12, v[70:71]
	v_lshl_add_u64 v[70:71], s[88:89], 0, v[70:71]
	s_andn2_saveexec_b64 s[0:1], s[0:1]
	v_lshlrev_b32_e32 v70, 14, v72
	v_lshl_add_u32 v70, v73, 10, v70
	v_ashrrev_i32_e32 v71, 31, v70
	v_lshl_add_u64 v[70:71], v[70:71], 2, s[16:17]
	s_or_b64 exec, exec, s[0:1]
	v_lshl_add_u64 v[70:71], v[130:131], 2, v[70:71]
	global_load_dword v122, v[70:71], off
	global_load_dword v93, v[70:71], off offset:128
	v_or_b32_e32 v92, 0x48, v136
	v_min_i32_e32 v70, 0x403f, v92
	v_mul_hi_i32 v71, v70, s83
	v_lshrrev_b32_e32 v72, 31, v71
	v_ashrrev_i32_e32 v71, 11, v71
	v_add_u32_e32 v72, v71, v72
	v_mad_i32_i24 v73, v72, s84, v70
	v_cmp_lt_i32_e64 s[0:1], 15, v73
	s_and_saveexec_b64 s[10:11], s[0:1]
	s_xor_b64 s[0:1], exec, s[10:11]
	v_lshlrev_b32_e32 v70, 12, v72
	v_add3_u32 v70, v70, v73, -16
	v_ashrrev_i32_e32 v71, 31, v70
	v_lshlrev_b64 v[70:71], 12, v[70:71]
	v_lshl_add_u64 v[70:71], s[88:89], 0, v[70:71]
	s_andn2_saveexec_b64 s[0:1], s[0:1]
	v_lshlrev_b32_e32 v70, 14, v72
	v_lshl_add_u32 v70, v73, 10, v70
	v_ashrrev_i32_e32 v71, 31, v70
	v_lshl_add_u64 v[70:71], v[70:71], 2, s[16:17]
	s_or_b64 exec, exec, s[0:1]
	v_lshl_add_u64 v[70:71], v[130:131], 2, v[70:71]
	global_load_dword v121, v[70:71], off
	global_load_dword v91, v[70:71], off offset:128
	v_or_b32_e32 v90, 0x49, v136
	v_min_i32_e32 v70, 0x403f, v90
	v_mul_hi_i32 v71, v70, s83
	v_lshrrev_b32_e32 v72, 31, v71
	v_ashrrev_i32_e32 v71, 11, v71
	v_add_u32_e32 v72, v71, v72
	v_mad_i32_i24 v73, v72, s84, v70
	v_cmp_lt_i32_e64 s[0:1], 15, v73
	s_and_saveexec_b64 s[10:11], s[0:1]
	s_xor_b64 s[0:1], exec, s[10:11]
	v_lshlrev_b32_e32 v70, 12, v72
	v_add3_u32 v70, v70, v73, -16
	v_ashrrev_i32_e32 v71, 31, v70
	v_lshlrev_b64 v[70:71], 12, v[70:71]
	v_lshl_add_u64 v[70:71], s[88:89], 0, v[70:71]
	s_andn2_saveexec_b64 s[0:1], s[0:1]
	v_lshlrev_b32_e32 v70, 14, v72
	v_lshl_add_u32 v70, v73, 10, v70
	v_ashrrev_i32_e32 v71, 31, v70
	v_lshl_add_u64 v[70:71], v[70:71], 2, s[16:17]
	s_or_b64 exec, exec, s[0:1]
	v_lshl_add_u64 v[70:71], v[130:131], 2, v[70:71]
	global_load_dword v120, v[70:71], off
	global_load_dword v89, v[70:71], off offset:128
	v_or_b32_e32 v88, 0x4a, v136
	v_min_i32_e32 v70, 0x403f, v88
	v_mul_hi_i32 v71, v70, s83
	v_lshrrev_b32_e32 v72, 31, v71
	v_ashrrev_i32_e32 v71, 11, v71
	v_add_u32_e32 v72, v71, v72
	v_mad_i32_i24 v73, v72, s84, v70
	v_cmp_lt_i32_e64 s[0:1], 15, v73
	s_and_saveexec_b64 s[10:11], s[0:1]
	s_xor_b64 s[0:1], exec, s[10:11]
	v_lshlrev_b32_e32 v70, 12, v72
	v_add3_u32 v70, v70, v73, -16
	v_ashrrev_i32_e32 v71, 31, v70
	v_lshlrev_b64 v[70:71], 12, v[70:71]
	v_lshl_add_u64 v[70:71], s[88:89], 0, v[70:71]
	s_andn2_saveexec_b64 s[0:1], s[0:1]
	v_lshlrev_b32_e32 v70, 14, v72
	v_lshl_add_u32 v70, v73, 10, v70
	v_ashrrev_i32_e32 v71, 31, v70
	v_lshl_add_u64 v[70:71], v[70:71], 2, s[16:17]
	s_or_b64 exec, exec, s[0:1]
	v_lshl_add_u64 v[70:71], v[130:131], 2, v[70:71]
	global_load_dword v119, v[70:71], off
	global_load_dword v87, v[70:71], off offset:128
	v_or_b32_e32 v86, 0x4b, v136
	v_min_i32_e32 v70, 0x403f, v86
	v_mul_hi_i32 v71, v70, s83
	v_lshrrev_b32_e32 v72, 31, v71
	v_ashrrev_i32_e32 v71, 11, v71
	v_add_u32_e32 v72, v71, v72
	v_mad_i32_i24 v73, v72, s84, v70
	v_cmp_lt_i32_e64 s[0:1], 15, v73
	s_and_saveexec_b64 s[10:11], s[0:1]
	s_xor_b64 s[0:1], exec, s[10:11]
	v_lshlrev_b32_e32 v70, 12, v72
	v_add3_u32 v70, v70, v73, -16
	v_ashrrev_i32_e32 v71, 31, v70
	v_lshlrev_b64 v[70:71], 12, v[70:71]
	v_lshl_add_u64 v[70:71], s[88:89], 0, v[70:71]
	s_andn2_saveexec_b64 s[0:1], s[0:1]
	v_lshlrev_b32_e32 v70, 14, v72
	v_lshl_add_u32 v70, v73, 10, v70
	v_ashrrev_i32_e32 v71, 31, v70
	v_lshl_add_u64 v[70:71], v[70:71], 2, s[16:17]
	s_or_b64 exec, exec, s[0:1]
	v_lshl_add_u64 v[70:71], v[130:131], 2, v[70:71]
	global_load_dword v118, v[70:71], off
	global_load_dword v85, v[70:71], off offset:128
	v_or_b32_e32 v84, 0x50, v136
	v_min_i32_e32 v70, 0x403f, v84
	v_mul_hi_i32 v71, v70, s83
	v_lshrrev_b32_e32 v72, 31, v71
	v_ashrrev_i32_e32 v71, 11, v71
	v_add_u32_e32 v72, v71, v72
	v_mad_i32_i24 v73, v72, s84, v70
	v_cmp_lt_i32_e64 s[0:1], 15, v73
	s_and_saveexec_b64 s[10:11], s[0:1]
	s_xor_b64 s[0:1], exec, s[10:11]
	v_lshlrev_b32_e32 v70, 12, v72
	v_add3_u32 v70, v70, v73, -16
	v_ashrrev_i32_e32 v71, 31, v70
	v_lshlrev_b64 v[70:71], 12, v[70:71]
	v_lshl_add_u64 v[70:71], s[88:89], 0, v[70:71]
	s_andn2_saveexec_b64 s[0:1], s[0:1]
	v_lshlrev_b32_e32 v70, 14, v72
	v_lshl_add_u32 v70, v73, 10, v70
	v_ashrrev_i32_e32 v71, 31, v70
	v_lshl_add_u64 v[70:71], v[70:71], 2, s[16:17]
	s_or_b64 exec, exec, s[0:1]
	v_lshl_add_u64 v[70:71], v[130:131], 2, v[70:71]
	global_load_dword v117, v[70:71], off
	global_load_dword v83, v[70:71], off offset:128
	v_or_b32_e32 v82, 0x51, v136
	v_min_i32_e32 v70, 0x403f, v82
	v_mul_hi_i32 v71, v70, s83
	v_lshrrev_b32_e32 v72, 31, v71
	v_ashrrev_i32_e32 v71, 11, v71
	v_add_u32_e32 v72, v71, v72
	v_mad_i32_i24 v73, v72, s84, v70
	v_cmp_lt_i32_e64 s[0:1], 15, v73
	s_and_saveexec_b64 s[10:11], s[0:1]
	s_xor_b64 s[0:1], exec, s[10:11]
	v_lshlrev_b32_e32 v70, 12, v72
	v_add3_u32 v70, v70, v73, -16
	v_ashrrev_i32_e32 v71, 31, v70
	v_lshlrev_b64 v[70:71], 12, v[70:71]
	v_lshl_add_u64 v[70:71], s[88:89], 0, v[70:71]
	s_andn2_saveexec_b64 s[0:1], s[0:1]
	v_lshlrev_b32_e32 v70, 14, v72
	v_lshl_add_u32 v70, v73, 10, v70
	v_ashrrev_i32_e32 v71, 31, v70
	v_lshl_add_u64 v[70:71], v[70:71], 2, s[16:17]
	s_or_b64 exec, exec, s[0:1]
	v_lshl_add_u64 v[70:71], v[130:131], 2, v[70:71]
	global_load_dword v116, v[70:71], off
	global_load_dword v81, v[70:71], off offset:128
	v_or_b32_e32 v80, 0x52, v136
	v_min_i32_e32 v70, 0x403f, v80
	v_mul_hi_i32 v71, v70, s83
	v_lshrrev_b32_e32 v72, 31, v71
	v_ashrrev_i32_e32 v71, 11, v71
	v_add_u32_e32 v72, v71, v72
	v_mad_i32_i24 v73, v72, s84, v70
	v_cmp_lt_i32_e64 s[0:1], 15, v73
	s_and_saveexec_b64 s[10:11], s[0:1]
	s_xor_b64 s[0:1], exec, s[10:11]
	v_lshlrev_b32_e32 v70, 12, v72
	v_add3_u32 v70, v70, v73, -16
	v_ashrrev_i32_e32 v71, 31, v70
	v_lshlrev_b64 v[70:71], 12, v[70:71]
	v_lshl_add_u64 v[70:71], s[88:89], 0, v[70:71]
	s_andn2_saveexec_b64 s[0:1], s[0:1]
	v_lshlrev_b32_e32 v70, 14, v72
	v_lshl_add_u32 v70, v73, 10, v70
	v_ashrrev_i32_e32 v71, 31, v70
	v_lshl_add_u64 v[70:71], v[70:71], 2, s[16:17]
	s_or_b64 exec, exec, s[0:1]
	v_lshl_add_u64 v[70:71], v[130:131], 2, v[70:71]
	global_load_dword v115, v[70:71], off
	global_load_dword v79, v[70:71], off offset:128
	v_or_b32_e32 v78, 0x53, v136
	v_min_i32_e32 v70, 0x403f, v78
	v_mul_hi_i32 v71, v70, s83
	v_lshrrev_b32_e32 v72, 31, v71
	v_ashrrev_i32_e32 v71, 11, v71
	v_add_u32_e32 v72, v71, v72
	v_mad_i32_i24 v73, v72, s84, v70
	v_cmp_lt_i32_e64 s[0:1], 15, v73
	s_and_saveexec_b64 s[10:11], s[0:1]
	s_xor_b64 s[0:1], exec, s[10:11]
	v_lshlrev_b32_e32 v70, 12, v72
	v_add3_u32 v70, v70, v73, -16
	v_ashrrev_i32_e32 v71, 31, v70
	v_lshlrev_b64 v[70:71], 12, v[70:71]
	v_lshl_add_u64 v[70:71], s[88:89], 0, v[70:71]
	s_andn2_saveexec_b64 s[0:1], s[0:1]
	v_lshlrev_b32_e32 v70, 14, v72
	v_lshl_add_u32 v70, v73, 10, v70
	v_ashrrev_i32_e32 v71, 31, v70
	v_lshl_add_u64 v[70:71], v[70:71], 2, s[16:17]
	s_or_b64 exec, exec, s[0:1]
	v_lshl_add_u64 v[70:71], v[130:131], 2, v[70:71]
	global_load_dword v114, v[70:71], off
	global_load_dword v77, v[70:71], off offset:128
	v_or_b32_e32 v76, 0x58, v136
	v_min_i32_e32 v70, 0x403f, v76
	v_mul_hi_i32 v71, v70, s83
	v_lshrrev_b32_e32 v72, 31, v71
	v_ashrrev_i32_e32 v71, 11, v71
	v_add_u32_e32 v72, v71, v72
	v_mad_i32_i24 v73, v72, s84, v70
	v_cmp_lt_i32_e64 s[0:1], 15, v73
	s_and_saveexec_b64 s[10:11], s[0:1]
	s_xor_b64 s[0:1], exec, s[10:11]
	v_lshlrev_b32_e32 v70, 12, v72
	v_add3_u32 v70, v70, v73, -16
	v_ashrrev_i32_e32 v71, 31, v70
	v_lshlrev_b64 v[70:71], 12, v[70:71]
	v_lshl_add_u64 v[70:71], s[88:89], 0, v[70:71]
	s_andn2_saveexec_b64 s[0:1], s[0:1]
	v_lshlrev_b32_e32 v70, 14, v72
	v_lshl_add_u32 v70, v73, 10, v70
	v_ashrrev_i32_e32 v71, 31, v70
	v_lshl_add_u64 v[70:71], v[70:71], 2, s[16:17]
	s_or_b64 exec, exec, s[0:1]
	v_lshl_add_u64 v[70:71], v[130:131], 2, v[70:71]
	global_load_dword v113, v[70:71], off
	global_load_dword v75, v[70:71], off offset:128
	v_or_b32_e32 v74, 0x59, v136
	v_min_i32_e32 v70, 0x403f, v74
	v_mul_hi_i32 v71, v70, s83
	v_lshrrev_b32_e32 v72, 31, v71
	v_ashrrev_i32_e32 v71, 11, v71
	v_add_u32_e32 v72, v71, v72
	v_mad_i32_i24 v73, v72, s84, v70
	v_cmp_lt_i32_e64 s[0:1], 15, v73
	s_and_saveexec_b64 s[10:11], s[0:1]
	s_xor_b64 s[0:1], exec, s[10:11]
	v_lshlrev_b32_e32 v70, 12, v72
	v_add3_u32 v70, v70, v73, -16
	v_ashrrev_i32_e32 v71, 31, v70
	v_lshlrev_b64 v[70:71], 12, v[70:71]
	v_lshl_add_u64 v[70:71], s[88:89], 0, v[70:71]
	s_andn2_saveexec_b64 s[0:1], s[0:1]
	v_lshlrev_b32_e32 v70, 14, v72
	v_lshl_add_u32 v70, v73, 10, v70
	v_ashrrev_i32_e32 v71, 31, v70
	v_lshl_add_u64 v[70:71], v[70:71], 2, s[16:17]
	s_or_b64 exec, exec, s[0:1]
	v_lshl_add_u64 v[70:71], v[130:131], 2, v[70:71]
	global_load_dword v112, v[70:71], off
	global_load_dword v73, v[70:71], off offset:128
	v_or_b32_e32 v72, 0x5a, v136
	v_min_i32_e32 v70, 0x403f, v72
	v_mul_hi_i32 v71, v70, s83
	v_lshrrev_b32_e32 v99, 31, v71
	v_ashrrev_i32_e32 v71, 11, v71
	v_add_u32_e32 v99, v71, v99
	v_mad_i32_i24 v101, v99, s84, v70
	v_cmp_lt_i32_e64 s[0:1], 15, v101
	s_and_saveexec_b64 s[10:11], s[0:1]
	s_xor_b64 s[0:1], exec, s[10:11]
	v_lshlrev_b32_e32 v70, 12, v99
	v_add3_u32 v70, v70, v101, -16
	v_ashrrev_i32_e32 v71, 31, v70
	v_lshlrev_b64 v[70:71], 12, v[70:71]
	v_lshl_add_u64 v[70:71], s[88:89], 0, v[70:71]
	s_andn2_saveexec_b64 s[0:1], s[0:1]
	v_lshlrev_b32_e32 v70, 14, v99
	v_lshl_add_u32 v70, v101, 10, v70
	v_ashrrev_i32_e32 v71, 31, v70
	v_lshl_add_u64 v[70:71], v[70:71], 2, s[16:17]
	s_or_b64 exec, exec, s[0:1]
	v_lshl_add_u64 v[70:71], v[130:131], 2, v[70:71]
	global_load_dword v111, v[70:71], off
	s_nop 0
	global_load_dword v71, v[70:71], off offset:128
	v_or_b32_e32 v70, 0x5b, v136
	v_min_i32_e32 v101, 0x403f, v70
	v_mul_hi_i32 v99, v101, s83
	v_lshrrev_b32_e32 v102, 31, v99
	v_ashrrev_i32_e32 v99, 11, v99
	v_add_u32_e32 v99, v99, v102
	v_mad_i32_i24 v101, v99, s84, v101
	v_cmp_lt_i32_e64 s[0:1], 15, v101
	s_and_saveexec_b64 s[10:11], s[0:1]
	s_xor_b64 s[0:1], exec, s[10:11]
	v_lshlrev_b32_e32 v99, 12, v99
	v_add3_u32 v102, v99, v101, -16
	v_ashrrev_i32_e32 v103, 31, v102
	v_lshlrev_b64 v[102:103], 12, v[102:103]
	v_lshl_add_u64 v[102:103], s[88:89], 0, v[102:103]
	s_andn2_saveexec_b64 s[0:1], s[0:1]
	v_lshlrev_b32_e32 v99, 14, v99
	v_lshl_add_u32 v102, v101, 10, v99
	v_ashrrev_i32_e32 v103, 31, v102
	v_lshl_add_u64 v[102:103], v[102:103], 2, s[16:17]
	s_or_b64 exec, exec, s[0:1]
	v_lshl_add_u64 v[102:103], v[130:131], 2, v[102:103]
	global_load_dword v110, v[102:103], off
	global_load_dword v109, v[102:103], off offset:128
	v_cmp_gt_i32_e64 s[10:11], s85, v100
	s_nop 1
	v_cndmask_b32_e64 v101, v181, v100, s[10:11]
	v_mul_hi_i32 v99, v101, s83
	v_lshrrev_b32_e32 v102, 31, v99
	v_ashrrev_i32_e32 v99, 11, v99
	v_add_u32_e32 v99, v99, v102
	v_mad_i32_i24 v101, v99, s84, v101
	v_cmp_lt_i32_e64 s[0:1], 15, v101
	s_and_saveexec_b64 s[22:23], s[0:1]
	s_xor_b64 s[0:1], exec, s[22:23]
	v_lshlrev_b32_e32 v99, 12, v99
	v_add3_u32 v102, v99, v101, -16
	v_ashrrev_i32_e32 v103, 31, v102
	v_lshlrev_b64 v[102:103], 12, v[102:103]
	v_lshl_add_u64 v[102:103], s[88:89], 0, v[102:103]
	s_andn2_saveexec_b64 s[0:1], s[0:1]
	v_lshlrev_b32_e32 v99, 14, v99
	v_lshl_add_u32 v102, v101, 10, v99
	v_ashrrev_i32_e32 v103, 31, v102
	v_lshl_add_u64 v[102:103], v[102:103], 2, s[16:17]
	s_or_b64 exec, exec, s[0:1]
	v_ashrrev_i32_e32 v101, 31, v100
	v_lshlrev_b64 v[100:101], 11, v[100:101]
	v_lshl_add_u64 v[100:101], s[62:63], 0, v[100:101]
	s_waitcnt vmcnt(31)
	v_add_f32_e32 v0, v50, v0
	v_lshl_add_u64 v[100:101], v[130:131], 1, v[100:101]
	v_lshl_add_u64 v[102:103], v[102:103], 0, v[134:135]
	global_store_dword v[102:103], v0, off
	v_mul_f32_e32 v50, v0, v242
	v_cvt_pk_bf16_f32 v50, v50, s0
	global_store_short v[100:101], v50, off
.LBB0_4095:
	s_waitcnt vmcnt(30)
	v_add_f32_e32 v67, v34, v67
	global_store_dword v[102:103], v67, off offset:128
	v_mul_f32_e32 v34, v67, v243
	v_cvt_pk_bf16_f32 v34, v34, s0
	global_store_short v[100:101], v34, off offset:64
.LBB0_4097:
	v_cmp_gt_i32_e64 s[10:11], s85, v98
	s_nop 1
	v_cndmask_b32_e64 v50, v181, v98, s[10:11]
	v_mul_hi_i32 v34, v50, s83
	v_lshrrev_b32_e32 v99, 31, v34
	v_ashrrev_i32_e32 v34, 11, v34
	v_add_u32_e32 v34, v34, v99
	v_mad_i32_i24 v50, v34, s84, v50
	v_cmp_lt_i32_e64 s[0:1], 15, v50
	s_and_saveexec_b64 s[22:23], s[0:1]
	s_xor_b64 s[0:1], exec, s[22:23]
	v_lshlrev_b32_e32 v34, 12, v34
	v_add3_u32 v100, v34, v50, -16
	v_ashrrev_i32_e32 v101, 31, v100
	v_lshlrev_b64 v[100:101], 12, v[100:101]
	v_lshl_add_u64 v[100:101], s[88:89], 0, v[100:101]
	s_andn2_saveexec_b64 s[0:1], s[0:1]
	v_lshlrev_b32_e32 v34, 14, v34
	v_lshl_add_u32 v100, v50, 10, v34
	v_ashrrev_i32_e32 v101, 31, v100
	v_lshl_add_u64 v[100:101], v[100:101], 2, s[16:17]
	s_or_b64 exec, exec, s[0:1]
	v_ashrrev_i32_e32 v99, 31, v98
	v_lshlrev_b64 v[98:99], 11, v[98:99]
	v_lshl_add_u64 v[98:99], s[62:63], 0, v[98:99]
	s_waitcnt vmcnt(29)
	v_add_f32_e32 v102, v51, v124
	v_lshl_add_u64 v[50:51], v[130:131], 1, v[98:99]
	v_lshl_add_u64 v[98:99], v[100:101], 0, v[134:135]
	global_store_dword v[98:99], v102, off
	v_mul_f32_e32 v34, v102, v242
	v_cvt_pk_bf16_f32 v34, v34, s0
	global_store_short v[50:51], v34, off
.LBB0_4103:
	s_waitcnt vmcnt(28)
	v_add_f32_e32 v100, v35, v97
	global_store_dword v[98:99], v100, off offset:128
	v_mul_f32_e32 v34, v100, v243
	v_cvt_pk_bf16_f32 v34, v34, s0
	global_store_short v[50:51], v34, off offset:64
.LBB0_4105:
	v_cmp_gt_i32_e64 s[10:11], s85, v96
	s_nop 1
	v_cndmask_b32_e64 v34, v181, v96, s[10:11]
	v_mul_hi_i32 v35, v34, s83
	v_lshrrev_b32_e32 v50, 31, v35
	v_ashrrev_i32_e32 v35, 11, v35
	v_add_u32_e32 v50, v35, v50
	v_mad_i32_i24 v51, v50, s84, v34
	v_cmp_lt_i32_e64 s[0:1], 15, v51
	s_and_saveexec_b64 s[22:23], s[0:1]
	s_xor_b64 s[0:1], exec, s[22:23]
	v_lshlrev_b32_e32 v34, 12, v50
	v_add3_u32 v34, v34, v51, -16
	v_ashrrev_i32_e32 v35, 31, v34
	v_lshlrev_b64 v[34:35], 12, v[34:35]
	v_lshl_add_u64 v[34:35], s[88:89], 0, v[34:35]
	s_andn2_saveexec_b64 s[0:1], s[0:1]
	v_lshlrev_b32_e32 v34, 14, v50
	v_lshl_add_u32 v34, v51, 10, v34
	v_ashrrev_i32_e32 v35, 31, v34
	v_lshl_add_u64 v[34:35], v[34:35], 2, s[16:17]
	s_or_b64 exec, exec, s[0:1]
	v_ashrrev_i32_e32 v97, 31, v96
	v_lshlrev_b64 v[50:51], 11, v[96:97]
	v_lshl_add_u64 v[50:51], s[62:63], 0, v[50:51]
	s_waitcnt vmcnt(27)
	v_add_f32_e32 v96, v52, v123
	v_lshl_add_u64 v[50:51], v[130:131], 1, v[50:51]
	v_lshl_add_u64 v[34:35], v[34:35], 0, v[134:135]
	global_store_dword v[34:35], v96, off
	v_mul_f32_e32 v52, v96, v242
	v_cvt_pk_bf16_f32 v52, v52, s0
	global_store_short v[50:51], v52, off
.LBB0_4111:
	s_waitcnt vmcnt(26)
	v_add_f32_e32 v97, v36, v95
	global_store_dword v[34:35], v97, off offset:128
	v_mul_f32_e32 v34, v97, v243
	v_cvt_pk_bf16_f32 v34, v34, s0
	global_store_short v[50:51], v34, off offset:64
.LBB0_4113:
	v_cmp_gt_i32_e64 s[10:11], s85, v94
	s_nop 1
	v_cndmask_b32_e64 v34, v181, v94, s[10:11]
	v_mul_hi_i32 v35, v34, s83
	v_lshrrev_b32_e32 v36, 31, v35
	v_ashrrev_i32_e32 v35, 11, v35
	v_add_u32_e32 v36, v35, v36
	v_mad_i32_i24 v50, v36, s84, v34
	v_cmp_lt_i32_e64 s[0:1], 15, v50
	s_and_saveexec_b64 s[22:23], s[0:1]
	s_xor_b64 s[0:1], exec, s[22:23]
	v_lshlrev_b32_e32 v34, 12, v36
	v_add3_u32 v34, v34, v50, -16
	v_ashrrev_i32_e32 v35, 31, v34
	v_lshlrev_b64 v[34:35], 12, v[34:35]
	v_lshl_add_u64 v[34:35], s[88:89], 0, v[34:35]
	s_andn2_saveexec_b64 s[0:1], s[0:1]
	v_lshlrev_b32_e32 v34, 14, v36
	v_lshl_add_u32 v34, v50, 10, v34
	v_ashrrev_i32_e32 v35, 31, v34
	v_lshl_add_u64 v[34:35], v[34:35], 2, s[16:17]
	s_or_b64 exec, exec, s[0:1]
	v_ashrrev_i32_e32 v95, 31, v94
	v_lshlrev_b64 v[50:51], 11, v[94:95]
	v_lshl_add_u64 v[50:51], s[62:63], 0, v[50:51]
	s_waitcnt vmcnt(25)
	v_add_f32_e32 v94, v53, v122
	v_lshl_add_u64 v[50:51], v[130:131], 1, v[50:51]
	v_lshl_add_u64 v[34:35], v[34:35], 0, v[134:135]
	global_store_dword v[34:35], v94, off
	v_mul_f32_e32 v36, v94, v242
	v_cvt_pk_bf16_f32 v36, v36, s0
	global_store_short v[50:51], v36, off
.LBB0_4119:
	s_waitcnt vmcnt(24)
	v_add_f32_e32 v95, v37, v93
	global_store_dword v[34:35], v95, off offset:128
	v_mul_f32_e32 v34, v95, v243
	v_cvt_pk_bf16_f32 v34, v34, s0
	global_store_short v[50:51], v34, off offset:64
.LBB0_4121:
	v_cmp_gt_i32_e64 s[10:11], s85, v92
	s_nop 1
	v_cndmask_b32_e64 v34, v181, v92, s[10:11]
	v_mul_hi_i32 v35, v34, s83
	v_lshrrev_b32_e32 v36, 31, v35
	v_ashrrev_i32_e32 v35, 11, v35
	v_add_u32_e32 v36, v35, v36
	v_mad_i32_i24 v37, v36, s84, v34
	v_cmp_lt_i32_e64 s[0:1], 15, v37
	s_and_saveexec_b64 s[22:23], s[0:1]
	s_xor_b64 s[0:1], exec, s[22:23]
	v_lshlrev_b32_e32 v34, 12, v36
	v_add3_u32 v34, v34, v37, -16
	v_ashrrev_i32_e32 v35, 31, v34
	v_lshlrev_b64 v[34:35], 12, v[34:35]
	v_lshl_add_u64 v[34:35], s[88:89], 0, v[34:35]
	s_andn2_saveexec_b64 s[0:1], s[0:1]
	v_lshlrev_b32_e32 v34, 14, v36
	v_lshl_add_u32 v34, v37, 10, v34
	v_ashrrev_i32_e32 v35, 31, v34
	v_lshl_add_u64 v[34:35], v[34:35], 2, s[16:17]
	s_or_b64 exec, exec, s[0:1]
	v_ashrrev_i32_e32 v93, 31, v92
	v_lshlrev_b64 v[36:37], 11, v[92:93]
	v_lshl_add_u64 v[36:37], s[62:63], 0, v[36:37]
	s_waitcnt vmcnt(23)
	v_add_f32_e32 v92, v54, v121
	v_lshl_add_u64 v[36:37], v[130:131], 1, v[36:37]
	v_lshl_add_u64 v[34:35], v[34:35], 0, v[134:135]
	global_store_dword v[34:35], v92, off
	v_mul_f32_e32 v50, v92, v242
	v_cvt_pk_bf16_f32 v50, v50, s0
	global_store_short v[36:37], v50, off
.LBB0_4127:
	s_waitcnt vmcnt(22)
	v_add_f32_e32 v93, v38, v91
	global_store_dword v[34:35], v93, off offset:128
	v_mul_f32_e32 v34, v93, v243
	v_cvt_pk_bf16_f32 v34, v34, s0
	global_store_short v[36:37], v34, off offset:64
.LBB0_4129:
	v_cmp_gt_i32_e64 s[10:11], s85, v90
	s_nop 1
	v_cndmask_b32_e64 v34, v181, v90, s[10:11]
	v_mul_hi_i32 v35, v34, s83
	v_lshrrev_b32_e32 v36, 31, v35
	v_ashrrev_i32_e32 v35, 11, v35
	v_add_u32_e32 v36, v35, v36
	v_mad_i32_i24 v37, v36, s84, v34
	v_cmp_lt_i32_e64 s[0:1], 15, v37
	s_and_saveexec_b64 s[22:23], s[0:1]
	s_xor_b64 s[0:1], exec, s[22:23]
	v_lshlrev_b32_e32 v34, 12, v36
	v_add3_u32 v34, v34, v37, -16
	v_ashrrev_i32_e32 v35, 31, v34
	v_lshlrev_b64 v[34:35], 12, v[34:35]
	v_lshl_add_u64 v[34:35], s[88:89], 0, v[34:35]
	s_andn2_saveexec_b64 s[0:1], s[0:1]
	v_lshlrev_b32_e32 v34, 14, v36
	v_lshl_add_u32 v34, v37, 10, v34
	v_ashrrev_i32_e32 v35, 31, v34
	v_lshl_add_u64 v[34:35], v[34:35], 2, s[16:17]
	s_or_b64 exec, exec, s[0:1]
	v_ashrrev_i32_e32 v91, 31, v90
	v_lshlrev_b64 v[36:37], 11, v[90:91]
	v_lshl_add_u64 v[36:37], s[62:63], 0, v[36:37]
	s_waitcnt vmcnt(21)
	v_add_f32_e32 v90, v55, v120
	v_lshl_add_u64 v[36:37], v[130:131], 1, v[36:37]
	v_lshl_add_u64 v[34:35], v[34:35], 0, v[134:135]
	global_store_dword v[34:35], v90, off
	v_mul_f32_e32 v38, v90, v242
	v_cvt_pk_bf16_f32 v38, v38, s0
	global_store_short v[36:37], v38, off
.LBB0_4135:
	s_waitcnt vmcnt(20)
	v_add_f32_e32 v91, v39, v89
	global_store_dword v[34:35], v91, off offset:128
	v_mul_f32_e32 v34, v91, v243
	v_cvt_pk_bf16_f32 v34, v34, s0
	global_store_short v[36:37], v34, off offset:64
.LBB0_4137:
	v_cmp_gt_i32_e64 s[10:11], s85, v88
	s_nop 1
	v_cndmask_b32_e64 v34, v181, v88, s[10:11]
	v_mul_hi_i32 v35, v34, s83
	v_lshrrev_b32_e32 v36, 31, v35
	v_ashrrev_i32_e32 v35, 11, v35
	v_add_u32_e32 v36, v35, v36
	v_mad_i32_i24 v37, v36, s84, v34
	v_cmp_lt_i32_e64 s[0:1], 15, v37
	s_and_saveexec_b64 s[22:23], s[0:1]
	s_xor_b64 s[0:1], exec, s[22:23]
	v_lshlrev_b32_e32 v34, 12, v36
	v_add3_u32 v34, v34, v37, -16
	v_ashrrev_i32_e32 v35, 31, v34
	v_lshlrev_b64 v[34:35], 12, v[34:35]
	v_lshl_add_u64 v[34:35], s[88:89], 0, v[34:35]
	s_andn2_saveexec_b64 s[0:1], s[0:1]
	v_lshlrev_b32_e32 v34, 14, v36
	v_lshl_add_u32 v34, v37, 10, v34
	v_ashrrev_i32_e32 v35, 31, v34
	v_lshl_add_u64 v[34:35], v[34:35], 2, s[16:17]
	s_or_b64 exec, exec, s[0:1]
	v_ashrrev_i32_e32 v89, 31, v88
	v_lshlrev_b64 v[36:37], 11, v[88:89]
	v_lshl_add_u64 v[36:37], s[62:63], 0, v[36:37]
	s_waitcnt vmcnt(19)
	v_add_f32_e32 v88, v56, v119
	v_lshl_add_u64 v[36:37], v[130:131], 1, v[36:37]
	v_lshl_add_u64 v[34:35], v[34:35], 0, v[134:135]
	global_store_dword v[34:35], v88, off
	v_mul_f32_e32 v38, v88, v242
	v_cvt_pk_bf16_f32 v38, v38, s0
	global_store_short v[36:37], v38, off
.LBB0_4143:
	s_waitcnt vmcnt(18)
	v_add_f32_e32 v89, v40, v87
	global_store_dword v[34:35], v89, off offset:128
	v_mul_f32_e32 v34, v89, v243
	v_cvt_pk_bf16_f32 v34, v34, s0
	global_store_short v[36:37], v34, off offset:64
.LBB0_4145:
	v_cmp_gt_i32_e64 s[10:11], s85, v86
	s_nop 1
	v_cndmask_b32_e64 v34, v181, v86, s[10:11]
	v_mul_hi_i32 v35, v34, s83
	v_lshrrev_b32_e32 v36, 31, v35
	v_ashrrev_i32_e32 v35, 11, v35
	v_add_u32_e32 v36, v35, v36
	v_mad_i32_i24 v37, v36, s84, v34
	v_cmp_lt_i32_e64 s[0:1], 15, v37
	s_and_saveexec_b64 s[22:23], s[0:1]
	s_xor_b64 s[0:1], exec, s[22:23]
	v_lshlrev_b32_e32 v34, 12, v36
	v_add3_u32 v34, v34, v37, -16
	v_ashrrev_i32_e32 v35, 31, v34
	v_lshlrev_b64 v[34:35], 12, v[34:35]
	v_lshl_add_u64 v[34:35], s[88:89], 0, v[34:35]
	s_andn2_saveexec_b64 s[0:1], s[0:1]
	v_lshlrev_b32_e32 v34, 14, v36
	v_lshl_add_u32 v34, v37, 10, v34
	v_ashrrev_i32_e32 v35, 31, v34
	v_lshl_add_u64 v[34:35], v[34:35], 2, s[16:17]
	s_or_b64 exec, exec, s[0:1]
	v_ashrrev_i32_e32 v87, 31, v86
	v_lshlrev_b64 v[36:37], 11, v[86:87]
	v_lshl_add_u64 v[36:37], s[62:63], 0, v[36:37]
	s_waitcnt vmcnt(17)
	v_add_f32_e32 v86, v57, v118
	v_lshl_add_u64 v[36:37], v[130:131], 1, v[36:37]
	v_lshl_add_u64 v[34:35], v[34:35], 0, v[134:135]
	global_store_dword v[34:35], v86, off
	v_mul_f32_e32 v38, v86, v242
	v_cvt_pk_bf16_f32 v38, v38, s0
	global_store_short v[36:37], v38, off
.LBB0_4151:
	s_waitcnt vmcnt(16)
	v_add_f32_e32 v87, v41, v85
	global_store_dword v[34:35], v87, off offset:128
	v_mul_f32_e32 v34, v87, v243
	v_cvt_pk_bf16_f32 v34, v34, s0
	global_store_short v[36:37], v34, off offset:64
.LBB0_4153:
	v_cmp_gt_i32_e64 s[10:11], s85, v84
	s_nop 1
	v_cndmask_b32_e64 v34, v181, v84, s[10:11]
	v_mul_hi_i32 v35, v34, s83
	v_lshrrev_b32_e32 v36, 31, v35
	v_ashrrev_i32_e32 v35, 11, v35
	v_add_u32_e32 v36, v35, v36
	v_mad_i32_i24 v37, v36, s84, v34
	v_cmp_lt_i32_e64 s[0:1], 15, v37
	s_and_saveexec_b64 s[22:23], s[0:1]
	s_xor_b64 s[0:1], exec, s[22:23]
	v_lshlrev_b32_e32 v34, 12, v36
	v_add3_u32 v34, v34, v37, -16
	v_ashrrev_i32_e32 v35, 31, v34
	v_lshlrev_b64 v[34:35], 12, v[34:35]
	v_lshl_add_u64 v[34:35], s[88:89], 0, v[34:35]
	s_andn2_saveexec_b64 s[0:1], s[0:1]
	v_lshlrev_b32_e32 v34, 14, v36
	v_lshl_add_u32 v34, v37, 10, v34
	v_ashrrev_i32_e32 v35, 31, v34
	v_lshl_add_u64 v[34:35], v[34:35], 2, s[16:17]
	s_or_b64 exec, exec, s[0:1]
	v_ashrrev_i32_e32 v85, 31, v84
	v_lshlrev_b64 v[36:37], 11, v[84:85]
	v_lshl_add_u64 v[36:37], s[62:63], 0, v[36:37]
	s_waitcnt vmcnt(15)
	v_add_f32_e32 v84, v58, v117
	v_lshl_add_u64 v[36:37], v[130:131], 1, v[36:37]
	v_lshl_add_u64 v[34:35], v[34:35], 0, v[134:135]
	global_store_dword v[34:35], v84, off
	v_mul_f32_e32 v38, v84, v242
	v_cvt_pk_bf16_f32 v38, v38, s0
	global_store_short v[36:37], v38, off
.LBB0_4159:
	s_waitcnt vmcnt(14)
	v_add_f32_e32 v85, v42, v83
	global_store_dword v[34:35], v85, off offset:128
	v_mul_f32_e32 v34, v85, v243
	v_cvt_pk_bf16_f32 v34, v34, s0
	global_store_short v[36:37], v34, off offset:64
.LBB0_4161:
	v_cmp_gt_i32_e64 s[10:11], s85, v82
	s_nop 1
	v_cndmask_b32_e64 v34, v181, v82, s[10:11]
	v_mul_hi_i32 v35, v34, s83
	v_lshrrev_b32_e32 v36, 31, v35
	v_ashrrev_i32_e32 v35, 11, v35
	v_add_u32_e32 v36, v35, v36
	v_mad_i32_i24 v37, v36, s84, v34
	v_cmp_lt_i32_e64 s[0:1], 15, v37
	s_and_saveexec_b64 s[22:23], s[0:1]
	s_xor_b64 s[0:1], exec, s[22:23]
	v_lshlrev_b32_e32 v34, 12, v36
	v_add3_u32 v34, v34, v37, -16
	v_ashrrev_i32_e32 v35, 31, v34
	v_lshlrev_b64 v[34:35], 12, v[34:35]
	v_lshl_add_u64 v[34:35], s[88:89], 0, v[34:35]
	s_andn2_saveexec_b64 s[0:1], s[0:1]
	v_lshlrev_b32_e32 v34, 14, v36
	v_lshl_add_u32 v34, v37, 10, v34
	v_ashrrev_i32_e32 v35, 31, v34
	v_lshl_add_u64 v[34:35], v[34:35], 2, s[16:17]
	s_or_b64 exec, exec, s[0:1]
	v_ashrrev_i32_e32 v83, 31, v82
	v_lshlrev_b64 v[36:37], 11, v[82:83]
	v_lshl_add_u64 v[36:37], s[62:63], 0, v[36:37]
	s_waitcnt vmcnt(13)
	v_add_f32_e32 v82, v59, v116
	v_lshl_add_u64 v[36:37], v[130:131], 1, v[36:37]
	v_lshl_add_u64 v[34:35], v[34:35], 0, v[134:135]
	global_store_dword v[34:35], v82, off
	v_mul_f32_e32 v38, v82, v242
	v_cvt_pk_bf16_f32 v38, v38, s0
	global_store_short v[36:37], v38, off
.LBB0_4167:
	s_waitcnt vmcnt(12)
	v_add_f32_e32 v83, v43, v81
	global_store_dword v[34:35], v83, off offset:128
	v_mul_f32_e32 v34, v83, v243
	v_cvt_pk_bf16_f32 v34, v34, s0
	global_store_short v[36:37], v34, off offset:64
.LBB0_4169:
	v_cmp_gt_i32_e64 s[10:11], s85, v80
	s_nop 1
	v_cndmask_b32_e64 v34, v181, v80, s[10:11]
	v_mul_hi_i32 v35, v34, s83
	v_lshrrev_b32_e32 v36, 31, v35
	v_ashrrev_i32_e32 v35, 11, v35
	v_add_u32_e32 v36, v35, v36
	v_mad_i32_i24 v37, v36, s84, v34
	v_cmp_lt_i32_e64 s[0:1], 15, v37
	s_and_saveexec_b64 s[22:23], s[0:1]
	s_xor_b64 s[0:1], exec, s[22:23]
	v_lshlrev_b32_e32 v34, 12, v36
	v_add3_u32 v34, v34, v37, -16
	v_ashrrev_i32_e32 v35, 31, v34
	v_lshlrev_b64 v[34:35], 12, v[34:35]
	v_lshl_add_u64 v[34:35], s[88:89], 0, v[34:35]
	s_andn2_saveexec_b64 s[0:1], s[0:1]
	v_lshlrev_b32_e32 v34, 14, v36
	v_lshl_add_u32 v34, v37, 10, v34
	v_ashrrev_i32_e32 v35, 31, v34
	v_lshl_add_u64 v[34:35], v[34:35], 2, s[16:17]
	s_or_b64 exec, exec, s[0:1]
	v_ashrrev_i32_e32 v81, 31, v80
	v_lshlrev_b64 v[36:37], 11, v[80:81]
	v_lshl_add_u64 v[36:37], s[62:63], 0, v[36:37]
	s_waitcnt vmcnt(11)
	v_add_f32_e32 v80, v60, v115
	v_lshl_add_u64 v[36:37], v[130:131], 1, v[36:37]
	v_lshl_add_u64 v[34:35], v[34:35], 0, v[134:135]
	global_store_dword v[34:35], v80, off
	v_mul_f32_e32 v38, v80, v242
	v_cvt_pk_bf16_f32 v38, v38, s0
	global_store_short v[36:37], v38, off
.LBB0_4175:
	s_waitcnt vmcnt(10)
	v_add_f32_e32 v81, v44, v79
	global_store_dword v[34:35], v81, off offset:128
	v_mul_f32_e32 v34, v81, v243
	v_cvt_pk_bf16_f32 v34, v34, s0
	global_store_short v[36:37], v34, off offset:64
.LBB0_4177:
	v_cmp_gt_i32_e64 s[10:11], s85, v78
	s_nop 1
	v_cndmask_b32_e64 v34, v181, v78, s[10:11]
	v_mul_hi_i32 v35, v34, s83
	v_lshrrev_b32_e32 v36, 31, v35
	v_ashrrev_i32_e32 v35, 11, v35
	v_add_u32_e32 v36, v35, v36
	v_mad_i32_i24 v37, v36, s84, v34
	v_cmp_lt_i32_e64 s[0:1], 15, v37
	s_and_saveexec_b64 s[22:23], s[0:1]
	s_xor_b64 s[0:1], exec, s[22:23]
	v_lshlrev_b32_e32 v34, 12, v36
	v_add3_u32 v34, v34, v37, -16
	v_ashrrev_i32_e32 v35, 31, v34
	v_lshlrev_b64 v[34:35], 12, v[34:35]
	v_lshl_add_u64 v[34:35], s[88:89], 0, v[34:35]
	s_andn2_saveexec_b64 s[0:1], s[0:1]
	v_lshlrev_b32_e32 v34, 14, v36
	v_lshl_add_u32 v34, v37, 10, v34
	v_ashrrev_i32_e32 v35, 31, v34
	v_lshl_add_u64 v[34:35], v[34:35], 2, s[16:17]
	s_or_b64 exec, exec, s[0:1]
	v_ashrrev_i32_e32 v79, 31, v78
	v_lshlrev_b64 v[36:37], 11, v[78:79]
	v_lshl_add_u64 v[36:37], s[62:63], 0, v[36:37]
	s_waitcnt vmcnt(9)
	v_add_f32_e32 v78, v61, v114
	v_lshl_add_u64 v[36:37], v[130:131], 1, v[36:37]
	v_lshl_add_u64 v[34:35], v[34:35], 0, v[134:135]
	global_store_dword v[34:35], v78, off
	v_mul_f32_e32 v38, v78, v242
	v_cvt_pk_bf16_f32 v38, v38, s0
	global_store_short v[36:37], v38, off
.LBB0_4183:
	s_waitcnt vmcnt(8)
	v_add_f32_e32 v79, v45, v77
	global_store_dword v[34:35], v79, off offset:128
	v_mul_f32_e32 v34, v79, v243
	v_cvt_pk_bf16_f32 v34, v34, s0
	global_store_short v[36:37], v34, off offset:64
.LBB0_4185:
	v_cmp_gt_i32_e64 s[10:11], s85, v76
	s_nop 1
	v_cndmask_b32_e64 v34, v181, v76, s[10:11]
	v_mul_hi_i32 v35, v34, s83
	v_lshrrev_b32_e32 v36, 31, v35
	v_ashrrev_i32_e32 v35, 11, v35
	v_add_u32_e32 v36, v35, v36
	v_mad_i32_i24 v37, v36, s84, v34
	v_cmp_lt_i32_e64 s[0:1], 15, v37
	s_and_saveexec_b64 s[22:23], s[0:1]
	s_xor_b64 s[0:1], exec, s[22:23]
	v_lshlrev_b32_e32 v34, 12, v36
	v_add3_u32 v34, v34, v37, -16
	v_ashrrev_i32_e32 v35, 31, v34
	v_lshlrev_b64 v[34:35], 12, v[34:35]
	v_lshl_add_u64 v[34:35], s[88:89], 0, v[34:35]
	s_andn2_saveexec_b64 s[0:1], s[0:1]
	v_lshlrev_b32_e32 v34, 14, v36
	v_lshl_add_u32 v34, v37, 10, v34
	v_ashrrev_i32_e32 v35, 31, v34
	v_lshl_add_u64 v[34:35], v[34:35], 2, s[16:17]
	s_or_b64 exec, exec, s[0:1]
	v_ashrrev_i32_e32 v77, 31, v76
	v_lshlrev_b64 v[36:37], 11, v[76:77]
	v_lshl_add_u64 v[36:37], s[62:63], 0, v[36:37]
	s_waitcnt vmcnt(7)
	v_add_f32_e32 v76, v62, v113
	v_lshl_add_u64 v[36:37], v[130:131], 1, v[36:37]
	v_lshl_add_u64 v[34:35], v[34:35], 0, v[134:135]
	global_store_dword v[34:35], v76, off
	v_mul_f32_e32 v38, v76, v242
	v_cvt_pk_bf16_f32 v38, v38, s0
	global_store_short v[36:37], v38, off
.LBB0_4191:
	s_waitcnt vmcnt(6)
	v_add_f32_e32 v77, v46, v75
	global_store_dword v[34:35], v77, off offset:128
	v_mul_f32_e32 v34, v77, v243
	v_cvt_pk_bf16_f32 v34, v34, s0
	global_store_short v[36:37], v34, off offset:64
.LBB0_4193:
	v_cmp_gt_i32_e64 s[10:11], s85, v74
	s_nop 1
	v_cndmask_b32_e64 v34, v181, v74, s[10:11]
	v_mul_hi_i32 v35, v34, s83
	v_lshrrev_b32_e32 v36, 31, v35
	v_ashrrev_i32_e32 v35, 11, v35
	v_add_u32_e32 v36, v35, v36
	v_mad_i32_i24 v37, v36, s84, v34
	v_cmp_lt_i32_e64 s[0:1], 15, v37
	s_and_saveexec_b64 s[22:23], s[0:1]
	s_xor_b64 s[0:1], exec, s[22:23]
	v_lshlrev_b32_e32 v34, 12, v36
	v_add3_u32 v34, v34, v37, -16
	v_ashrrev_i32_e32 v35, 31, v34
	v_lshlrev_b64 v[34:35], 12, v[34:35]
	v_lshl_add_u64 v[34:35], s[88:89], 0, v[34:35]
	s_andn2_saveexec_b64 s[0:1], s[0:1]
	v_lshlrev_b32_e32 v34, 14, v36
	v_lshl_add_u32 v34, v37, 10, v34
	v_ashrrev_i32_e32 v35, 31, v34
	v_lshl_add_u64 v[34:35], v[34:35], 2, s[16:17]
	s_or_b64 exec, exec, s[0:1]
	v_ashrrev_i32_e32 v75, 31, v74
	v_lshlrev_b64 v[36:37], 11, v[74:75]
	v_lshl_add_u64 v[36:37], s[62:63], 0, v[36:37]
	s_waitcnt vmcnt(5)
	v_add_f32_e32 v74, v63, v112
	v_lshl_add_u64 v[36:37], v[130:131], 1, v[36:37]
	v_lshl_add_u64 v[34:35], v[34:35], 0, v[134:135]
	global_store_dword v[34:35], v74, off
	v_mul_f32_e32 v38, v74, v242
	v_cvt_pk_bf16_f32 v38, v38, s0
	global_store_short v[36:37], v38, off
.LBB0_4199:
	s_waitcnt vmcnt(4)
	v_add_f32_e32 v75, v47, v73
	global_store_dword v[34:35], v75, off offset:128
	v_mul_f32_e32 v34, v75, v243
	v_cvt_pk_bf16_f32 v34, v34, s0
	global_store_short v[36:37], v34, off offset:64
.LBB0_4201:
	v_cmp_gt_i32_e64 s[10:11], s85, v72
	s_nop 1
	v_cndmask_b32_e64 v34, v181, v72, s[10:11]
	v_mul_hi_i32 v35, v34, s83
	v_lshrrev_b32_e32 v36, 31, v35
	v_ashrrev_i32_e32 v35, 11, v35
	v_add_u32_e32 v36, v35, v36
	v_mad_i32_i24 v37, v36, s84, v34
	v_cmp_lt_i32_e64 s[0:1], 15, v37
	s_and_saveexec_b64 s[22:23], s[0:1]
	s_xor_b64 s[0:1], exec, s[22:23]
	v_lshlrev_b32_e32 v34, 12, v36
	v_add3_u32 v34, v34, v37, -16
	v_ashrrev_i32_e32 v35, 31, v34
	v_lshlrev_b64 v[34:35], 12, v[34:35]
	v_lshl_add_u64 v[34:35], s[88:89], 0, v[34:35]
	s_andn2_saveexec_b64 s[0:1], s[0:1]
	v_lshlrev_b32_e32 v34, 14, v36
	v_lshl_add_u32 v34, v37, 10, v34
	v_ashrrev_i32_e32 v35, 31, v34
	v_lshl_add_u64 v[34:35], v[34:35], 2, s[16:17]
	s_or_b64 exec, exec, s[0:1]
	v_ashrrev_i32_e32 v73, 31, v72
	v_lshlrev_b64 v[36:37], 11, v[72:73]
	v_lshl_add_u64 v[36:37], s[62:63], 0, v[36:37]
	s_waitcnt vmcnt(3)
	v_add_f32_e32 v72, v64, v111
	v_lshl_add_u64 v[36:37], v[130:131], 1, v[36:37]
	v_lshl_add_u64 v[34:35], v[34:35], 0, v[134:135]
	global_store_dword v[34:35], v72, off
	v_mul_f32_e32 v38, v72, v242
	v_cvt_pk_bf16_f32 v38, v38, s0
	global_store_short v[36:37], v38, off
.LBB0_4207:
	s_waitcnt vmcnt(2)
	v_add_f32_e32 v73, v48, v71
	global_store_dword v[34:35], v73, off offset:128
	v_mul_f32_e32 v34, v73, v243
	v_cvt_pk_bf16_f32 v34, v34, s0
	global_store_short v[36:37], v34, off offset:64
.LBB0_4209:
	v_cmp_gt_i32_e64 s[10:11], s85, v70
	s_nop 1
	v_cndmask_b32_e64 v34, v181, v70, s[10:11]
	v_mul_hi_i32 v35, v34, s83
	v_lshrrev_b32_e32 v36, 31, v35
	v_ashrrev_i32_e32 v35, 11, v35
	v_add_u32_e32 v36, v35, v36
	v_mad_i32_i24 v37, v36, s84, v34
	v_cmp_lt_i32_e64 s[0:1], 15, v37
	s_and_saveexec_b64 s[22:23], s[0:1]
	s_xor_b64 s[0:1], exec, s[22:23]
	v_lshlrev_b32_e32 v34, 12, v36
	v_add3_u32 v34, v34, v37, -16
	v_ashrrev_i32_e32 v35, 31, v34
	v_lshlrev_b64 v[34:35], 12, v[34:35]
	v_lshl_add_u64 v[34:35], s[88:89], 0, v[34:35]
	s_andn2_saveexec_b64 s[0:1], s[0:1]
	v_lshlrev_b32_e32 v34, 14, v36
	v_lshl_add_u32 v34, v37, 10, v34
	v_ashrrev_i32_e32 v35, 31, v34
	v_lshl_add_u64 v[34:35], v[34:35], 2, s[16:17]
	s_or_b64 exec, exec, s[0:1]
	v_ashrrev_i32_e32 v71, 31, v70
	v_lshlrev_b64 v[36:37], 11, v[70:71]
	v_lshl_add_u64 v[36:37], s[62:63], 0, v[36:37]
	s_waitcnt vmcnt(1)
	v_add_f32_e32 v98, v65, v110
	v_lshl_add_u64 v[36:37], v[130:131], 1, v[36:37]
	v_lshl_add_u64 v[34:35], v[34:35], 0, v[134:135]
	global_store_dword v[34:35], v98, off
	v_mul_f32_e32 v38, v98, v242
	v_cvt_pk_bf16_f32 v38, v38, s0
	global_store_short v[36:37], v38, off
.LBB0_4215:
	s_waitcnt vmcnt(0)
	v_add_f32_e32 v99, v49, v109
	global_store_dword v[34:35], v99, off offset:128
	v_mul_f32_e32 v34, v99, v243
	v_cvt_pk_bf16_f32 v34, v34, s0
	global_store_short v[36:37], v34, off offset:64
.LBB0_4217:
	v_or_b32_e32 v64, 0x60, v136
	v_min_i32_e32 v34, 0x403f, v64
	v_mul_hi_i32 v35, v34, s83
	v_lshrrev_b32_e32 v36, 31, v35
	v_ashrrev_i32_e32 v35, 11, v35
	v_add_u32_e32 v36, v35, v36
	v_mad_i32_i24 v37, v36, s84, v34
	v_cmp_lt_i32_e64 s[0:1], 15, v37
	s_and_saveexec_b64 s[10:11], s[0:1]
	s_xor_b64 s[0:1], exec, s[10:11]
	v_lshlrev_b32_e32 v34, 12, v36
	v_add3_u32 v34, v34, v37, -16
	v_ashrrev_i32_e32 v35, 31, v34
	v_lshlrev_b64 v[34:35], 12, v[34:35]
	v_lshl_add_u64 v[34:35], s[88:89], 0, v[34:35]
	s_andn2_saveexec_b64 s[0:1], s[0:1]
	v_lshlrev_b32_e32 v34, 14, v36
	v_lshl_add_u32 v34, v37, 10, v34
	v_ashrrev_i32_e32 v35, 31, v34
	v_lshl_add_u64 v[34:35], v[34:35], 2, s[16:17]
	s_or_b64 exec, exec, s[0:1]
	v_lshl_add_u64 v[34:35], v[130:131], 2, v[34:35]
	global_load_dword v101, v[34:35], off
	global_load_dword v63, v[34:35], off offset:128
	v_or_b32_e32 v62, 0x61, v136
	v_min_i32_e32 v34, 0x403f, v62
	v_mul_hi_i32 v35, v34, s83
	v_lshrrev_b32_e32 v36, 31, v35
	v_ashrrev_i32_e32 v35, 11, v35
	v_add_u32_e32 v36, v35, v36
	v_mad_i32_i24 v37, v36, s84, v34
	v_cmp_lt_i32_e64 s[0:1], 15, v37
	s_and_saveexec_b64 s[10:11], s[0:1]
	s_xor_b64 s[0:1], exec, s[10:11]
	v_lshlrev_b32_e32 v34, 12, v36
	v_add3_u32 v34, v34, v37, -16
	v_ashrrev_i32_e32 v35, 31, v34
	v_lshlrev_b64 v[34:35], 12, v[34:35]
	v_lshl_add_u64 v[34:35], s[88:89], 0, v[34:35]
	s_andn2_saveexec_b64 s[0:1], s[0:1]
	v_lshlrev_b32_e32 v34, 14, v36
	v_lshl_add_u32 v34, v37, 10, v34
	v_ashrrev_i32_e32 v35, 31, v34
	v_lshl_add_u64 v[34:35], v[34:35], 2, s[16:17]
	s_or_b64 exec, exec, s[0:1]
	v_lshl_add_u64 v[34:35], v[130:131], 2, v[34:35]
	global_load_dword v124, v[34:35], off
	global_load_dword v61, v[34:35], off offset:128
	v_or_b32_e32 v60, 0x62, v136
	v_min_i32_e32 v34, 0x403f, v60
	v_mul_hi_i32 v35, v34, s83
	v_lshrrev_b32_e32 v36, 31, v35
	v_ashrrev_i32_e32 v35, 11, v35
	v_add_u32_e32 v36, v35, v36
	v_mad_i32_i24 v37, v36, s84, v34
	v_cmp_lt_i32_e64 s[0:1], 15, v37
	s_and_saveexec_b64 s[10:11], s[0:1]
	s_xor_b64 s[0:1], exec, s[10:11]
	v_lshlrev_b32_e32 v34, 12, v36
	v_add3_u32 v34, v34, v37, -16
	v_ashrrev_i32_e32 v35, 31, v34
	v_lshlrev_b64 v[34:35], 12, v[34:35]
	v_lshl_add_u64 v[34:35], s[88:89], 0, v[34:35]
	s_andn2_saveexec_b64 s[0:1], s[0:1]
	v_lshlrev_b32_e32 v34, 14, v36
	v_lshl_add_u32 v34, v37, 10, v34
	v_ashrrev_i32_e32 v35, 31, v34
	v_lshl_add_u64 v[34:35], v[34:35], 2, s[16:17]
	s_or_b64 exec, exec, s[0:1]
	v_lshl_add_u64 v[34:35], v[130:131], 2, v[34:35]
	global_load_dword v123, v[34:35], off
	global_load_dword v59, v[34:35], off offset:128
	v_or_b32_e32 v58, 0x63, v136
	v_min_i32_e32 v34, 0x403f, v58
	v_mul_hi_i32 v35, v34, s83
	v_lshrrev_b32_e32 v36, 31, v35
	v_ashrrev_i32_e32 v35, 11, v35
	v_add_u32_e32 v36, v35, v36
	v_mad_i32_i24 v37, v36, s84, v34
	v_cmp_lt_i32_e64 s[0:1], 15, v37
	s_and_saveexec_b64 s[10:11], s[0:1]
	s_xor_b64 s[0:1], exec, s[10:11]
	v_lshlrev_b32_e32 v34, 12, v36
	v_add3_u32 v34, v34, v37, -16
	v_ashrrev_i32_e32 v35, 31, v34
	v_lshlrev_b64 v[34:35], 12, v[34:35]
	v_lshl_add_u64 v[34:35], s[88:89], 0, v[34:35]
	s_andn2_saveexec_b64 s[0:1], s[0:1]
	v_lshlrev_b32_e32 v34, 14, v36
	v_lshl_add_u32 v34, v37, 10, v34
	v_ashrrev_i32_e32 v35, 31, v34
	v_lshl_add_u64 v[34:35], v[34:35], 2, s[16:17]
	s_or_b64 exec, exec, s[0:1]
	v_lshl_add_u64 v[34:35], v[130:131], 2, v[34:35]
	global_load_dword v122, v[34:35], off
	global_load_dword v57, v[34:35], off offset:128
	v_or_b32_e32 v56, 0x68, v136
	v_min_i32_e32 v34, 0x403f, v56
	v_mul_hi_i32 v35, v34, s83
	v_lshrrev_b32_e32 v36, 31, v35
	v_ashrrev_i32_e32 v35, 11, v35
	v_add_u32_e32 v36, v35, v36
	v_mad_i32_i24 v37, v36, s84, v34
	v_cmp_lt_i32_e64 s[0:1], 15, v37
	s_and_saveexec_b64 s[10:11], s[0:1]
	s_xor_b64 s[0:1], exec, s[10:11]
	v_lshlrev_b32_e32 v34, 12, v36
	v_add3_u32 v34, v34, v37, -16
	v_ashrrev_i32_e32 v35, 31, v34
	v_lshlrev_b64 v[34:35], 12, v[34:35]
	v_lshl_add_u64 v[34:35], s[88:89], 0, v[34:35]
	s_andn2_saveexec_b64 s[0:1], s[0:1]
	v_lshlrev_b32_e32 v34, 14, v36
	v_lshl_add_u32 v34, v37, 10, v34
	v_ashrrev_i32_e32 v35, 31, v34
	v_lshl_add_u64 v[34:35], v[34:35], 2, s[16:17]
	s_or_b64 exec, exec, s[0:1]
	v_lshl_add_u64 v[34:35], v[130:131], 2, v[34:35]
	global_load_dword v121, v[34:35], off
	global_load_dword v55, v[34:35], off offset:128
	v_or_b32_e32 v54, 0x69, v136
	v_min_i32_e32 v34, 0x403f, v54
	v_mul_hi_i32 v35, v34, s83
	v_lshrrev_b32_e32 v36, 31, v35
	v_ashrrev_i32_e32 v35, 11, v35
	v_add_u32_e32 v36, v35, v36
	v_mad_i32_i24 v37, v36, s84, v34
	v_cmp_lt_i32_e64 s[0:1], 15, v37
	s_and_saveexec_b64 s[10:11], s[0:1]
	s_xor_b64 s[0:1], exec, s[10:11]
	v_lshlrev_b32_e32 v34, 12, v36
	v_add3_u32 v34, v34, v37, -16
	v_ashrrev_i32_e32 v35, 31, v34
	v_lshlrev_b64 v[34:35], 12, v[34:35]
	v_lshl_add_u64 v[34:35], s[88:89], 0, v[34:35]
	s_andn2_saveexec_b64 s[0:1], s[0:1]
	v_lshlrev_b32_e32 v34, 14, v36
	v_lshl_add_u32 v34, v37, 10, v34
	v_ashrrev_i32_e32 v35, 31, v34
	v_lshl_add_u64 v[34:35], v[34:35], 2, s[16:17]
	s_or_b64 exec, exec, s[0:1]
	v_lshl_add_u64 v[34:35], v[130:131], 2, v[34:35]
	global_load_dword v120, v[34:35], off
	global_load_dword v53, v[34:35], off offset:128
	v_or_b32_e32 v52, 0x6a, v136
	v_min_i32_e32 v34, 0x403f, v52
	v_mul_hi_i32 v35, v34, s83
	v_lshrrev_b32_e32 v36, 31, v35
	v_ashrrev_i32_e32 v35, 11, v35
	v_add_u32_e32 v36, v35, v36
	v_mad_i32_i24 v37, v36, s84, v34
	v_cmp_lt_i32_e64 s[0:1], 15, v37
	s_and_saveexec_b64 s[10:11], s[0:1]
	s_xor_b64 s[0:1], exec, s[10:11]
	v_lshlrev_b32_e32 v34, 12, v36
	v_add3_u32 v34, v34, v37, -16
	v_ashrrev_i32_e32 v35, 31, v34
	v_lshlrev_b64 v[34:35], 12, v[34:35]
	v_lshl_add_u64 v[34:35], s[88:89], 0, v[34:35]
	s_andn2_saveexec_b64 s[0:1], s[0:1]
	v_lshlrev_b32_e32 v34, 14, v36
	v_lshl_add_u32 v34, v37, 10, v34
	v_ashrrev_i32_e32 v35, 31, v34
	v_lshl_add_u64 v[34:35], v[34:35], 2, s[16:17]
	s_or_b64 exec, exec, s[0:1]
	v_lshl_add_u64 v[34:35], v[130:131], 2, v[34:35]
	global_load_dword v119, v[34:35], off
	global_load_dword v51, v[34:35], off offset:128
	v_or_b32_e32 v50, 0x6b, v136
	v_min_i32_e32 v34, 0x403f, v50
	v_mul_hi_i32 v35, v34, s83
	v_lshrrev_b32_e32 v36, 31, v35
	v_ashrrev_i32_e32 v35, 11, v35
	v_add_u32_e32 v36, v35, v36
	v_mad_i32_i24 v37, v36, s84, v34
	v_cmp_lt_i32_e64 s[0:1], 15, v37
	s_and_saveexec_b64 s[10:11], s[0:1]
	s_xor_b64 s[0:1], exec, s[10:11]
	v_lshlrev_b32_e32 v34, 12, v36
	v_add3_u32 v34, v34, v37, -16
	v_ashrrev_i32_e32 v35, 31, v34
	v_lshlrev_b64 v[34:35], 12, v[34:35]
	v_lshl_add_u64 v[34:35], s[88:89], 0, v[34:35]
	s_andn2_saveexec_b64 s[0:1], s[0:1]
	v_lshlrev_b32_e32 v34, 14, v36
	v_lshl_add_u32 v34, v37, 10, v34
	v_ashrrev_i32_e32 v35, 31, v34
	v_lshl_add_u64 v[34:35], v[34:35], 2, s[16:17]
	s_or_b64 exec, exec, s[0:1]
	v_lshl_add_u64 v[34:35], v[130:131], 2, v[34:35]
	global_load_dword v118, v[34:35], off
	global_load_dword v49, v[34:35], off offset:128
	v_or_b32_e32 v48, 0x70, v136
	v_min_i32_e32 v34, 0x403f, v48
	v_mul_hi_i32 v35, v34, s83
	v_lshrrev_b32_e32 v36, 31, v35
	v_ashrrev_i32_e32 v35, 11, v35
	v_add_u32_e32 v36, v35, v36
	v_mad_i32_i24 v37, v36, s84, v34
	v_cmp_lt_i32_e64 s[0:1], 15, v37
	s_and_saveexec_b64 s[10:11], s[0:1]
	s_xor_b64 s[0:1], exec, s[10:11]
	v_lshlrev_b32_e32 v34, 12, v36
	v_add3_u32 v34, v34, v37, -16
	v_ashrrev_i32_e32 v35, 31, v34
	v_lshlrev_b64 v[34:35], 12, v[34:35]
	v_lshl_add_u64 v[34:35], s[88:89], 0, v[34:35]
	s_andn2_saveexec_b64 s[0:1], s[0:1]
	v_lshlrev_b32_e32 v34, 14, v36
	v_lshl_add_u32 v34, v37, 10, v34
	v_ashrrev_i32_e32 v35, 31, v34
	v_lshl_add_u64 v[34:35], v[34:35], 2, s[16:17]
	s_or_b64 exec, exec, s[0:1]
	v_lshl_add_u64 v[34:35], v[130:131], 2, v[34:35]
	global_load_dword v117, v[34:35], off
	global_load_dword v47, v[34:35], off offset:128
	v_or_b32_e32 v46, 0x71, v136
	v_min_i32_e32 v34, 0x403f, v46
	v_mul_hi_i32 v35, v34, s83
	v_lshrrev_b32_e32 v36, 31, v35
	v_ashrrev_i32_e32 v35, 11, v35
	v_add_u32_e32 v36, v35, v36
	v_mad_i32_i24 v37, v36, s84, v34
	v_cmp_lt_i32_e64 s[0:1], 15, v37
	s_and_saveexec_b64 s[10:11], s[0:1]
	s_xor_b64 s[0:1], exec, s[10:11]
	v_lshlrev_b32_e32 v34, 12, v36
	v_add3_u32 v34, v34, v37, -16
	v_ashrrev_i32_e32 v35, 31, v34
	v_lshlrev_b64 v[34:35], 12, v[34:35]
	v_lshl_add_u64 v[34:35], s[88:89], 0, v[34:35]
	s_andn2_saveexec_b64 s[0:1], s[0:1]
	v_lshlrev_b32_e32 v34, 14, v36
	v_lshl_add_u32 v34, v37, 10, v34
	v_ashrrev_i32_e32 v35, 31, v34
	v_lshl_add_u64 v[34:35], v[34:35], 2, s[16:17]
	s_or_b64 exec, exec, s[0:1]
	v_lshl_add_u64 v[34:35], v[130:131], 2, v[34:35]
	global_load_dword v116, v[34:35], off
	global_load_dword v45, v[34:35], off offset:128
	v_or_b32_e32 v44, 0x72, v136
	v_min_i32_e32 v34, 0x403f, v44
	v_mul_hi_i32 v35, v34, s83
	v_lshrrev_b32_e32 v36, 31, v35
	v_ashrrev_i32_e32 v35, 11, v35
	v_add_u32_e32 v36, v35, v36
	v_mad_i32_i24 v37, v36, s84, v34
	v_cmp_lt_i32_e64 s[0:1], 15, v37
	s_and_saveexec_b64 s[10:11], s[0:1]
	s_xor_b64 s[0:1], exec, s[10:11]
	v_lshlrev_b32_e32 v34, 12, v36
	v_add3_u32 v34, v34, v37, -16
	v_ashrrev_i32_e32 v35, 31, v34
	v_lshlrev_b64 v[34:35], 12, v[34:35]
	v_lshl_add_u64 v[34:35], s[88:89], 0, v[34:35]
	s_andn2_saveexec_b64 s[0:1], s[0:1]
	v_lshlrev_b32_e32 v34, 14, v36
	v_lshl_add_u32 v34, v37, 10, v34
	v_ashrrev_i32_e32 v35, 31, v34
	v_lshl_add_u64 v[34:35], v[34:35], 2, s[16:17]
	s_or_b64 exec, exec, s[0:1]
	v_lshl_add_u64 v[34:35], v[130:131], 2, v[34:35]
	global_load_dword v115, v[34:35], off
	global_load_dword v43, v[34:35], off offset:128
	v_or_b32_e32 v42, 0x73, v136
	v_min_i32_e32 v34, 0x403f, v42
	v_mul_hi_i32 v35, v34, s83
	v_lshrrev_b32_e32 v36, 31, v35
	v_ashrrev_i32_e32 v35, 11, v35
	v_add_u32_e32 v36, v35, v36
	v_mad_i32_i24 v37, v36, s84, v34
	v_cmp_lt_i32_e64 s[0:1], 15, v37
	s_and_saveexec_b64 s[10:11], s[0:1]
	s_xor_b64 s[0:1], exec, s[10:11]
	v_lshlrev_b32_e32 v34, 12, v36
	v_add3_u32 v34, v34, v37, -16
	v_ashrrev_i32_e32 v35, 31, v34
	v_lshlrev_b64 v[34:35], 12, v[34:35]
	v_lshl_add_u64 v[34:35], s[88:89], 0, v[34:35]
	s_andn2_saveexec_b64 s[0:1], s[0:1]
	v_lshlrev_b32_e32 v34, 14, v36
	v_lshl_add_u32 v34, v37, 10, v34
	v_ashrrev_i32_e32 v35, 31, v34
	v_lshl_add_u64 v[34:35], v[34:35], 2, s[16:17]
	s_or_b64 exec, exec, s[0:1]
	v_lshl_add_u64 v[34:35], v[130:131], 2, v[34:35]
	global_load_dword v114, v[34:35], off
	global_load_dword v41, v[34:35], off offset:128
	v_or_b32_e32 v40, 0x78, v136
	v_min_i32_e32 v34, 0x403f, v40
	v_mul_hi_i32 v35, v34, s83
	v_lshrrev_b32_e32 v36, 31, v35
	v_ashrrev_i32_e32 v35, 11, v35
	v_add_u32_e32 v36, v35, v36
	v_mad_i32_i24 v37, v36, s84, v34
	v_cmp_lt_i32_e64 s[0:1], 15, v37
	s_and_saveexec_b64 s[10:11], s[0:1]
	s_xor_b64 s[0:1], exec, s[10:11]
	v_lshlrev_b32_e32 v34, 12, v36
	v_add3_u32 v34, v34, v37, -16
	v_ashrrev_i32_e32 v35, 31, v34
	v_lshlrev_b64 v[34:35], 12, v[34:35]
	v_lshl_add_u64 v[34:35], s[88:89], 0, v[34:35]
	s_andn2_saveexec_b64 s[0:1], s[0:1]
	v_lshlrev_b32_e32 v34, 14, v36
	v_lshl_add_u32 v34, v37, 10, v34
	v_ashrrev_i32_e32 v35, 31, v34
	v_lshl_add_u64 v[34:35], v[34:35], 2, s[16:17]
	s_or_b64 exec, exec, s[0:1]
	v_lshl_add_u64 v[34:35], v[130:131], 2, v[34:35]
	global_load_dword v113, v[34:35], off
	global_load_dword v39, v[34:35], off offset:128
	v_or_b32_e32 v38, 0x79, v136
	v_min_i32_e32 v34, 0x403f, v38
	v_mul_hi_i32 v35, v34, s83
	v_lshrrev_b32_e32 v36, 31, v35
	v_ashrrev_i32_e32 v35, 11, v35
	v_add_u32_e32 v36, v35, v36
	v_mad_i32_i24 v37, v36, s84, v34
	v_cmp_lt_i32_e64 s[0:1], 15, v37
	s_and_saveexec_b64 s[10:11], s[0:1]
	s_xor_b64 s[0:1], exec, s[10:11]
	v_lshlrev_b32_e32 v34, 12, v36
	v_add3_u32 v34, v34, v37, -16
	v_ashrrev_i32_e32 v35, 31, v34
	v_lshlrev_b64 v[34:35], 12, v[34:35]
	v_lshl_add_u64 v[34:35], s[88:89], 0, v[34:35]
	s_andn2_saveexec_b64 s[0:1], s[0:1]
	v_lshlrev_b32_e32 v34, 14, v36
	v_lshl_add_u32 v34, v37, 10, v34
	v_ashrrev_i32_e32 v35, 31, v34
	v_lshl_add_u64 v[34:35], v[34:35], 2, s[16:17]
	s_or_b64 exec, exec, s[0:1]
	v_lshl_add_u64 v[34:35], v[130:131], 2, v[34:35]
	global_load_dword v112, v[34:35], off
	global_load_dword v37, v[34:35], off offset:128
	v_or_b32_e32 v36, 0x7a, v136
	v_min_i32_e32 v34, 0x403f, v36
	v_mul_hi_i32 v35, v34, s83
	v_lshrrev_b32_e32 v65, 31, v35
	v_ashrrev_i32_e32 v35, 11, v35
	v_add_u32_e32 v65, v35, v65
	v_mad_i32_i24 v70, v65, s84, v34
	v_cmp_lt_i32_e64 s[0:1], 15, v70
	s_and_saveexec_b64 s[10:11], s[0:1]
	s_xor_b64 s[0:1], exec, s[10:11]
	v_lshlrev_b32_e32 v34, 12, v65
	v_add3_u32 v34, v34, v70, -16
	v_ashrrev_i32_e32 v35, 31, v34
	v_lshlrev_b64 v[34:35], 12, v[34:35]
	v_lshl_add_u64 v[34:35], s[88:89], 0, v[34:35]
	s_andn2_saveexec_b64 s[0:1], s[0:1]
	v_lshlrev_b32_e32 v34, 14, v65
	v_lshl_add_u32 v34, v70, 10, v34
	v_ashrrev_i32_e32 v35, 31, v34
	v_lshl_add_u64 v[34:35], v[34:35], 2, s[16:17]
	s_or_b64 exec, exec, s[0:1]
	v_lshl_add_u64 v[34:35], v[130:131], 2, v[34:35]
	global_load_dword v111, v[34:35], off
	s_nop 0
	global_load_dword v35, v[34:35], off offset:128
	v_or_b32_e32 v34, 0x7b, v136
	v_min_i32_e32 v70, 0x403f, v34
	v_mul_hi_i32 v65, v70, s83
	v_lshrrev_b32_e32 v71, 31, v65
	v_ashrrev_i32_e32 v65, 11, v65
	v_add_u32_e32 v65, v65, v71
	v_mad_i32_i24 v103, v65, s84, v70
	v_cmp_lt_i32_e64 s[0:1], 15, v103
	s_and_saveexec_b64 s[10:11], s[0:1]
	s_xor_b64 s[0:1], exec, s[10:11]
	v_lshlrev_b32_e32 v65, 12, v65
	v_add3_u32 v70, v65, v103, -16
	v_ashrrev_i32_e32 v71, 31, v70
	v_lshlrev_b64 v[70:71], 12, v[70:71]
	v_lshl_add_u64 v[70:71], s[88:89], 0, v[70:71]
	s_andn2_saveexec_b64 s[0:1], s[0:1]
	v_lshlrev_b32_e32 v65, 14, v65
	v_lshl_add_u32 v70, v103, 10, v65
	v_ashrrev_i32_e32 v71, 31, v70
	v_lshl_add_u64 v[70:71], v[70:71], 2, s[16:17]
	s_or_b64 exec, exec, s[0:1]
	v_lshl_add_u64 v[70:71], v[130:131], 2, v[70:71]
	global_load_dword v109, v[70:71], off
	global_load_dword v103, v[70:71], off offset:128
	v_cmp_gt_i32_e64 s[10:11], s85, v64
	s_nop 1
	v_cndmask_b32_e64 v70, v181, v64, s[10:11]
	v_mul_hi_i32 v65, v70, s83
	v_lshrrev_b32_e32 v71, 31, v65
	v_ashrrev_i32_e32 v65, 11, v65
	v_add_u32_e32 v65, v65, v71
	v_mad_i32_i24 v110, v65, s84, v70
	v_cmp_lt_i32_e64 s[0:1], 15, v110
	s_and_saveexec_b64 s[22:23], s[0:1]
	s_xor_b64 s[0:1], exec, s[22:23]
	v_lshlrev_b32_e32 v65, 12, v65
	v_add3_u32 v70, v65, v110, -16
	v_ashrrev_i32_e32 v71, 31, v70
	v_lshlrev_b64 v[70:71], 12, v[70:71]
	v_lshl_add_u64 v[70:71], s[88:89], 0, v[70:71]
	s_andn2_saveexec_b64 s[0:1], s[0:1]
	v_lshlrev_b32_e32 v65, 14, v65
	v_lshl_add_u32 v70, v110, 10, v65
	v_ashrrev_i32_e32 v71, 31, v70
	v_lshl_add_u64 v[70:71], v[70:71], 2, s[16:17]
	s_or_b64 exec, exec, s[0:1]
	v_ashrrev_i32_e32 v65, 31, v64
	v_lshlrev_b64 v[64:65], 11, v[64:65]
	v_lshl_add_u64 v[64:65], s[62:63], 0, v[64:65]
	s_waitcnt vmcnt(31)
	v_add_f32_e32 v101, v18, v101
	v_lshl_add_u64 v[64:65], v[130:131], 1, v[64:65]
	v_lshl_add_u64 v[70:71], v[70:71], 0, v[134:135]
	global_store_dword v[70:71], v101, off
	v_mul_f32_e32 v18, v101, v242
	v_cvt_pk_bf16_f32 v18, v18, s0
	global_store_short v[64:65], v18, off
.LBB0_4287:
	s_waitcnt vmcnt(30)
	v_add_f32_e32 v110, v2, v63
	global_store_dword v[70:71], v110, off offset:128
	v_mul_f32_e32 v2, v110, v243
	v_cvt_pk_bf16_f32 v2, v2, s0
	global_store_short v[64:65], v2, off offset:64
.LBB0_4289:
	v_cmp_gt_i32_e64 s[10:11], s85, v62
	s_nop 1
	v_cndmask_b32_e64 v18, v181, v62, s[10:11]
	v_mul_hi_i32 v2, v18, s83
	v_lshrrev_b32_e32 v63, 31, v2
	v_ashrrev_i32_e32 v2, 11, v2
	v_add_u32_e32 v2, v2, v63
	v_mad_i32_i24 v18, v2, s84, v18
	v_cmp_lt_i32_e64 s[0:1], 15, v18
	s_and_saveexec_b64 s[22:23], s[0:1]
	s_xor_b64 s[0:1], exec, s[22:23]
	v_lshlrev_b32_e32 v2, 12, v2
	v_add3_u32 v64, v2, v18, -16
	v_ashrrev_i32_e32 v65, 31, v64
	v_lshlrev_b64 v[64:65], 12, v[64:65]
	v_lshl_add_u64 v[64:65], s[88:89], 0, v[64:65]
	s_andn2_saveexec_b64 s[0:1], s[0:1]
	v_lshlrev_b32_e32 v2, 14, v2
	v_lshl_add_u32 v64, v18, 10, v2
	v_ashrrev_i32_e32 v65, 31, v64
	v_lshl_add_u64 v[64:65], v[64:65], 2, s[16:17]
	s_or_b64 exec, exec, s[0:1]
	v_ashrrev_i32_e32 v63, 31, v62
	v_lshlrev_b64 v[62:63], 11, v[62:63]
	v_lshl_add_u64 v[62:63], s[62:63], 0, v[62:63]
	s_waitcnt vmcnt(29)
	v_add_f32_e32 v70, v19, v124
	v_lshl_add_u64 v[18:19], v[130:131], 1, v[62:63]
	v_lshl_add_u64 v[62:63], v[64:65], 0, v[134:135]
	global_store_dword v[62:63], v70, off
	v_mul_f32_e32 v2, v70, v242
	v_cvt_pk_bf16_f32 v2, v2, s0
	global_store_short v[18:19], v2, off
.LBB0_4295:
	s_waitcnt vmcnt(28)
	v_add_f32_e32 v64, v3, v61
	global_store_dword v[62:63], v64, off offset:128
	v_mul_f32_e32 v2, v64, v243
	v_cvt_pk_bf16_f32 v2, v2, s0
	global_store_short v[18:19], v2, off offset:64
.LBB0_4297:
	v_cmp_gt_i32_e64 s[10:11], s85, v60
	s_nop 1
	v_cndmask_b32_e64 v2, v181, v60, s[10:11]
	v_mul_hi_i32 v3, v2, s83
	v_lshrrev_b32_e32 v18, 31, v3
	v_ashrrev_i32_e32 v3, 11, v3
	v_add_u32_e32 v18, v3, v18
	v_mad_i32_i24 v19, v18, s84, v2
	v_cmp_lt_i32_e64 s[0:1], 15, v19
	s_and_saveexec_b64 s[22:23], s[0:1]
	s_xor_b64 s[0:1], exec, s[22:23]
	v_lshlrev_b32_e32 v2, 12, v18
	v_add3_u32 v2, v2, v19, -16
	v_ashrrev_i32_e32 v3, 31, v2
	v_lshlrev_b64 v[2:3], 12, v[2:3]
	v_lshl_add_u64 v[2:3], s[88:89], 0, v[2:3]
	s_andn2_saveexec_b64 s[0:1], s[0:1]
	v_lshlrev_b32_e32 v2, 14, v18
	v_lshl_add_u32 v2, v19, 10, v2
	v_ashrrev_i32_e32 v3, 31, v2
	v_lshl_add_u64 v[2:3], v[2:3], 2, s[16:17]
	s_or_b64 exec, exec, s[0:1]
	v_ashrrev_i32_e32 v61, 31, v60
	v_lshlrev_b64 v[18:19], 11, v[60:61]
	v_lshl_add_u64 v[18:19], s[62:63], 0, v[18:19]
	s_waitcnt vmcnt(27)
	v_add_f32_e32 v20, v20, v123
	v_lshl_add_u64 v[18:19], v[130:131], 1, v[18:19]
	v_lshl_add_u64 v[2:3], v[2:3], 0, v[134:135]
	global_store_dword v[2:3], v20, off
	v_mul_f32_e32 v60, v20, v242
	v_cvt_pk_bf16_f32 v60, v60, s0
	global_store_short v[18:19], v60, off
.LBB0_4303:
	s_waitcnt vmcnt(26)
	v_add_f32_e32 v60, v4, v59
	global_store_dword v[2:3], v60, off offset:128
	v_mul_f32_e32 v2, v60, v243
	v_cvt_pk_bf16_f32 v2, v2, s0
	global_store_short v[18:19], v2, off offset:64
.LBB0_4305:
	v_cmp_gt_i32_e64 s[10:11], s85, v58
	s_nop 1
	v_cndmask_b32_e64 v2, v181, v58, s[10:11]
	v_mul_hi_i32 v3, v2, s83
	v_lshrrev_b32_e32 v4, 31, v3
	v_ashrrev_i32_e32 v3, 11, v3
	v_add_u32_e32 v4, v3, v4
	v_mad_i32_i24 v18, v4, s84, v2
	v_cmp_lt_i32_e64 s[0:1], 15, v18
	s_and_saveexec_b64 s[22:23], s[0:1]
	s_xor_b64 s[0:1], exec, s[22:23]
	v_lshlrev_b32_e32 v2, 12, v4
	v_add3_u32 v2, v2, v18, -16
	v_ashrrev_i32_e32 v3, 31, v2
	v_lshlrev_b64 v[2:3], 12, v[2:3]
	v_lshl_add_u64 v[2:3], s[88:89], 0, v[2:3]
	s_andn2_saveexec_b64 s[0:1], s[0:1]
	v_lshlrev_b32_e32 v2, 14, v4
	v_lshl_add_u32 v2, v18, 10, v2
	v_ashrrev_i32_e32 v3, 31, v2
	v_lshl_add_u64 v[2:3], v[2:3], 2, s[16:17]
	s_or_b64 exec, exec, s[0:1]
	v_ashrrev_i32_e32 v59, 31, v58
	v_lshlrev_b64 v[18:19], 11, v[58:59]
	v_lshl_add_u64 v[18:19], s[62:63], 0, v[18:19]
	s_waitcnt vmcnt(25)
	v_add_f32_e32 v21, v21, v122
	v_lshl_add_u64 v[18:19], v[130:131], 1, v[18:19]
	v_lshl_add_u64 v[2:3], v[2:3], 0, v[134:135]
	global_store_dword v[2:3], v21, off
	v_mul_f32_e32 v4, v21, v242
	v_cvt_pk_bf16_f32 v4, v4, s0
	global_store_short v[18:19], v4, off
.LBB0_4311:
	s_waitcnt vmcnt(24)
	v_add_f32_e32 v58, v5, v57
	global_store_dword v[2:3], v58, off offset:128
	v_mul_f32_e32 v2, v58, v243
	v_cvt_pk_bf16_f32 v2, v2, s0
	global_store_short v[18:19], v2, off offset:64
.LBB0_4313:
	v_cmp_gt_i32_e64 s[10:11], s85, v56
	s_nop 1
	v_cndmask_b32_e64 v2, v181, v56, s[10:11]
	v_mul_hi_i32 v3, v2, s83
	v_lshrrev_b32_e32 v4, 31, v3
	v_ashrrev_i32_e32 v3, 11, v3
	v_add_u32_e32 v4, v3, v4
	v_mad_i32_i24 v5, v4, s84, v2
	v_cmp_lt_i32_e64 s[0:1], 15, v5
	s_and_saveexec_b64 s[22:23], s[0:1]
	s_xor_b64 s[0:1], exec, s[22:23]
	v_lshlrev_b32_e32 v2, 12, v4
	v_add3_u32 v2, v2, v5, -16
	v_ashrrev_i32_e32 v3, 31, v2
	v_lshlrev_b64 v[2:3], 12, v[2:3]
	v_lshl_add_u64 v[2:3], s[88:89], 0, v[2:3]
	s_andn2_saveexec_b64 s[0:1], s[0:1]
	v_lshlrev_b32_e32 v2, 14, v4
	v_lshl_add_u32 v2, v5, 10, v2
	v_ashrrev_i32_e32 v3, 31, v2
	v_lshl_add_u64 v[2:3], v[2:3], 2, s[16:17]
	s_or_b64 exec, exec, s[0:1]
	v_ashrrev_i32_e32 v57, 31, v56
	v_lshlrev_b64 v[4:5], 11, v[56:57]
	v_lshl_add_u64 v[4:5], s[62:63], 0, v[4:5]
	s_waitcnt vmcnt(23)
	v_add_f32_e32 v18, v22, v121
	v_lshl_add_u64 v[4:5], v[130:131], 1, v[4:5]
	v_lshl_add_u64 v[2:3], v[2:3], 0, v[134:135]
	global_store_dword v[2:3], v18, off
	v_mul_f32_e32 v19, v18, v242
	v_cvt_pk_bf16_f32 v19, v19, s0
	global_store_short v[4:5], v19, off
.LBB0_4319:
	s_waitcnt vmcnt(22)
	v_add_f32_e32 v6, v6, v55
	global_store_dword v[2:3], v6, off offset:128
	v_mul_f32_e32 v2, v6, v243
	v_cvt_pk_bf16_f32 v2, v2, s0
	global_store_short v[4:5], v2, off offset:64
.LBB0_4321:
	v_cmp_gt_i32_e64 s[10:11], s85, v54
	s_nop 1
	v_cndmask_b32_e64 v2, v181, v54, s[10:11]
	v_mul_hi_i32 v3, v2, s83
	v_lshrrev_b32_e32 v4, 31, v3
	v_ashrrev_i32_e32 v3, 11, v3
	v_add_u32_e32 v4, v3, v4
	v_mad_i32_i24 v5, v4, s84, v2
	v_cmp_lt_i32_e64 s[0:1], 15, v5
	s_and_saveexec_b64 s[22:23], s[0:1]
	s_xor_b64 s[0:1], exec, s[22:23]
	v_lshlrev_b32_e32 v2, 12, v4
	v_add3_u32 v2, v2, v5, -16
	v_ashrrev_i32_e32 v3, 31, v2
	v_lshlrev_b64 v[2:3], 12, v[2:3]
	v_lshl_add_u64 v[2:3], s[88:89], 0, v[2:3]
	s_andn2_saveexec_b64 s[0:1], s[0:1]
	v_lshlrev_b32_e32 v2, 14, v4
	v_lshl_add_u32 v2, v5, 10, v2
	v_ashrrev_i32_e32 v3, 31, v2
	v_lshl_add_u64 v[2:3], v[2:3], 2, s[16:17]
	s_or_b64 exec, exec, s[0:1]
	v_ashrrev_i32_e32 v55, 31, v54
	v_lshlrev_b64 v[4:5], 11, v[54:55]
	v_lshl_add_u64 v[4:5], s[62:63], 0, v[4:5]
	s_waitcnt vmcnt(21)
	v_add_f32_e32 v19, v23, v120
	v_lshl_add_u64 v[4:5], v[130:131], 1, v[4:5]
	v_lshl_add_u64 v[2:3], v[2:3], 0, v[134:135]
	global_store_dword v[2:3], v19, off
	v_mul_f32_e32 v22, v19, v242
	v_cvt_pk_bf16_f32 v22, v22, s0
	global_store_short v[4:5], v22, off
.LBB0_4327:
	s_waitcnt vmcnt(20)
	v_add_f32_e32 v7, v7, v53
	global_store_dword v[2:3], v7, off offset:128
	v_mul_f32_e32 v2, v7, v243
	v_cvt_pk_bf16_f32 v2, v2, s0
	global_store_short v[4:5], v2, off offset:64
.LBB0_4329:
	v_cmp_gt_i32_e64 s[10:11], s85, v52
	s_nop 1
	v_cndmask_b32_e64 v2, v181, v52, s[10:11]
	v_mul_hi_i32 v3, v2, s83
	v_lshrrev_b32_e32 v4, 31, v3
	v_ashrrev_i32_e32 v3, 11, v3
	v_add_u32_e32 v4, v3, v4
	v_mad_i32_i24 v5, v4, s84, v2
	v_cmp_lt_i32_e64 s[0:1], 15, v5
	s_and_saveexec_b64 s[22:23], s[0:1]
	s_xor_b64 s[0:1], exec, s[22:23]
	v_lshlrev_b32_e32 v2, 12, v4
	v_add3_u32 v2, v2, v5, -16
	v_ashrrev_i32_e32 v3, 31, v2
	v_lshlrev_b64 v[2:3], 12, v[2:3]
	v_lshl_add_u64 v[2:3], s[88:89], 0, v[2:3]
	s_andn2_saveexec_b64 s[0:1], s[0:1]
	v_lshlrev_b32_e32 v2, 14, v4
	v_lshl_add_u32 v2, v5, 10, v2
	v_ashrrev_i32_e32 v3, 31, v2
	v_lshl_add_u64 v[2:3], v[2:3], 2, s[16:17]
	s_or_b64 exec, exec, s[0:1]
	v_ashrrev_i32_e32 v53, 31, v52
	v_lshlrev_b64 v[4:5], 11, v[52:53]
	v_lshl_add_u64 v[4:5], s[62:63], 0, v[4:5]
	s_waitcnt vmcnt(19)
	v_add_f32_e32 v22, v24, v119
	v_lshl_add_u64 v[4:5], v[130:131], 1, v[4:5]
	v_lshl_add_u64 v[2:3], v[2:3], 0, v[134:135]
	global_store_dword v[2:3], v22, off
	v_mul_f32_e32 v23, v22, v242
	v_cvt_pk_bf16_f32 v23, v23, s0
	global_store_short v[4:5], v23, off
.LBB0_4335:
	s_waitcnt vmcnt(18)
	v_add_f32_e32 v8, v8, v51
	global_store_dword v[2:3], v8, off offset:128
	v_mul_f32_e32 v2, v8, v243
	v_cvt_pk_bf16_f32 v2, v2, s0
	global_store_short v[4:5], v2, off offset:64
.LBB0_4337:
	v_cmp_gt_i32_e64 s[10:11], s85, v50
	s_nop 1
	v_cndmask_b32_e64 v2, v181, v50, s[10:11]
	v_mul_hi_i32 v3, v2, s83
	v_lshrrev_b32_e32 v4, 31, v3
	v_ashrrev_i32_e32 v3, 11, v3
	v_add_u32_e32 v4, v3, v4
	v_mad_i32_i24 v5, v4, s84, v2
	v_cmp_lt_i32_e64 s[0:1], 15, v5
	s_and_saveexec_b64 s[22:23], s[0:1]
	s_xor_b64 s[0:1], exec, s[22:23]
	v_lshlrev_b32_e32 v2, 12, v4
	v_add3_u32 v2, v2, v5, -16
	v_ashrrev_i32_e32 v3, 31, v2
	v_lshlrev_b64 v[2:3], 12, v[2:3]
	v_lshl_add_u64 v[2:3], s[88:89], 0, v[2:3]
	s_andn2_saveexec_b64 s[0:1], s[0:1]
	v_lshlrev_b32_e32 v2, 14, v4
	v_lshl_add_u32 v2, v5, 10, v2
	v_ashrrev_i32_e32 v3, 31, v2
	v_lshl_add_u64 v[2:3], v[2:3], 2, s[16:17]
	s_or_b64 exec, exec, s[0:1]
	v_ashrrev_i32_e32 v51, 31, v50
	v_lshlrev_b64 v[4:5], 11, v[50:51]
	v_lshl_add_u64 v[4:5], s[62:63], 0, v[4:5]
	s_waitcnt vmcnt(17)
	v_add_f32_e32 v23, v25, v118
	v_lshl_add_u64 v[4:5], v[130:131], 1, v[4:5]
	v_lshl_add_u64 v[2:3], v[2:3], 0, v[134:135]
	global_store_dword v[2:3], v23, off
	v_mul_f32_e32 v24, v23, v242
	v_cvt_pk_bf16_f32 v24, v24, s0
	global_store_short v[4:5], v24, off
.LBB0_4343:
	s_waitcnt vmcnt(16)
	v_add_f32_e32 v9, v9, v49
	global_store_dword v[2:3], v9, off offset:128
	v_mul_f32_e32 v2, v9, v243
	v_cvt_pk_bf16_f32 v2, v2, s0
	global_store_short v[4:5], v2, off offset:64
.LBB0_4345:
	v_cmp_gt_i32_e64 s[10:11], s85, v48
	s_nop 1
	v_cndmask_b32_e64 v2, v181, v48, s[10:11]
	v_mul_hi_i32 v3, v2, s83
	v_lshrrev_b32_e32 v4, 31, v3
	v_ashrrev_i32_e32 v3, 11, v3
	v_add_u32_e32 v4, v3, v4
	v_mad_i32_i24 v5, v4, s84, v2
	v_cmp_lt_i32_e64 s[0:1], 15, v5
	s_and_saveexec_b64 s[22:23], s[0:1]
	s_xor_b64 s[0:1], exec, s[22:23]
	v_lshlrev_b32_e32 v2, 12, v4
	v_add3_u32 v2, v2, v5, -16
	v_ashrrev_i32_e32 v3, 31, v2
	v_lshlrev_b64 v[2:3], 12, v[2:3]
	v_lshl_add_u64 v[2:3], s[88:89], 0, v[2:3]
	s_andn2_saveexec_b64 s[0:1], s[0:1]
	v_lshlrev_b32_e32 v2, 14, v4
	v_lshl_add_u32 v2, v5, 10, v2
	v_ashrrev_i32_e32 v3, 31, v2
	v_lshl_add_u64 v[2:3], v[2:3], 2, s[16:17]
	s_or_b64 exec, exec, s[0:1]
	v_ashrrev_i32_e32 v49, 31, v48
	v_lshlrev_b64 v[4:5], 11, v[48:49]
	v_lshl_add_u64 v[4:5], s[62:63], 0, v[4:5]
	s_waitcnt vmcnt(15)
	v_add_f32_e32 v24, v26, v117
	v_lshl_add_u64 v[4:5], v[130:131], 1, v[4:5]
	v_lshl_add_u64 v[2:3], v[2:3], 0, v[134:135]
	global_store_dword v[2:3], v24, off
	v_mul_f32_e32 v25, v24, v242
	v_cvt_pk_bf16_f32 v25, v25, s0
	global_store_short v[4:5], v25, off
.LBB0_4351:
	s_waitcnt vmcnt(14)
	v_add_f32_e32 v10, v10, v47
	global_store_dword v[2:3], v10, off offset:128
	v_mul_f32_e32 v2, v10, v243
	v_cvt_pk_bf16_f32 v2, v2, s0
	global_store_short v[4:5], v2, off offset:64
.LBB0_4353:
	v_cmp_gt_i32_e64 s[10:11], s85, v46
	s_nop 1
	v_cndmask_b32_e64 v2, v181, v46, s[10:11]
	v_mul_hi_i32 v3, v2, s83
	v_lshrrev_b32_e32 v4, 31, v3
	v_ashrrev_i32_e32 v3, 11, v3
	v_add_u32_e32 v4, v3, v4
	v_mad_i32_i24 v5, v4, s84, v2
	v_cmp_lt_i32_e64 s[0:1], 15, v5
	s_and_saveexec_b64 s[22:23], s[0:1]
	s_xor_b64 s[0:1], exec, s[22:23]
	v_lshlrev_b32_e32 v2, 12, v4
	v_add3_u32 v2, v2, v5, -16
	v_ashrrev_i32_e32 v3, 31, v2
	v_lshlrev_b64 v[2:3], 12, v[2:3]
	v_lshl_add_u64 v[2:3], s[88:89], 0, v[2:3]
	s_andn2_saveexec_b64 s[0:1], s[0:1]
	v_lshlrev_b32_e32 v2, 14, v4
	v_lshl_add_u32 v2, v5, 10, v2
	v_ashrrev_i32_e32 v3, 31, v2
	v_lshl_add_u64 v[2:3], v[2:3], 2, s[16:17]
	s_or_b64 exec, exec, s[0:1]
	v_ashrrev_i32_e32 v47, 31, v46
	v_lshlrev_b64 v[4:5], 11, v[46:47]
	v_lshl_add_u64 v[4:5], s[62:63], 0, v[4:5]
	s_waitcnt vmcnt(13)
	v_add_f32_e32 v25, v27, v116
	v_lshl_add_u64 v[4:5], v[130:131], 1, v[4:5]
	v_lshl_add_u64 v[2:3], v[2:3], 0, v[134:135]
	global_store_dword v[2:3], v25, off
	v_mul_f32_e32 v26, v25, v242
	v_cvt_pk_bf16_f32 v26, v26, s0
	global_store_short v[4:5], v26, off
.LBB0_4359:
	s_waitcnt vmcnt(12)
	v_add_f32_e32 v11, v11, v45
	global_store_dword v[2:3], v11, off offset:128
	v_mul_f32_e32 v2, v11, v243
	v_cvt_pk_bf16_f32 v2, v2, s0
	global_store_short v[4:5], v2, off offset:64
.LBB0_4361:
	v_cmp_gt_i32_e64 s[10:11], s85, v44
	s_nop 1
	v_cndmask_b32_e64 v2, v181, v44, s[10:11]
	v_mul_hi_i32 v3, v2, s83
	v_lshrrev_b32_e32 v4, 31, v3
	v_ashrrev_i32_e32 v3, 11, v3
	v_add_u32_e32 v4, v3, v4
	v_mad_i32_i24 v5, v4, s84, v2
	v_cmp_lt_i32_e64 s[0:1], 15, v5
	s_and_saveexec_b64 s[22:23], s[0:1]
	s_xor_b64 s[0:1], exec, s[22:23]
	v_lshlrev_b32_e32 v2, 12, v4
	v_add3_u32 v2, v2, v5, -16
	v_ashrrev_i32_e32 v3, 31, v2
	v_lshlrev_b64 v[2:3], 12, v[2:3]
	v_lshl_add_u64 v[2:3], s[88:89], 0, v[2:3]
	s_andn2_saveexec_b64 s[0:1], s[0:1]
	v_lshlrev_b32_e32 v2, 14, v4
	v_lshl_add_u32 v2, v5, 10, v2
	v_ashrrev_i32_e32 v3, 31, v2
	v_lshl_add_u64 v[2:3], v[2:3], 2, s[16:17]
	s_or_b64 exec, exec, s[0:1]
	v_ashrrev_i32_e32 v45, 31, v44
	v_lshlrev_b64 v[4:5], 11, v[44:45]
	v_lshl_add_u64 v[4:5], s[62:63], 0, v[4:5]
	s_waitcnt vmcnt(11)
	v_add_f32_e32 v26, v28, v115
	v_lshl_add_u64 v[4:5], v[130:131], 1, v[4:5]
	v_lshl_add_u64 v[2:3], v[2:3], 0, v[134:135]
	global_store_dword v[2:3], v26, off
	v_mul_f32_e32 v27, v26, v242
	v_cvt_pk_bf16_f32 v27, v27, s0
	global_store_short v[4:5], v27, off
.LBB0_4367:
	s_waitcnt vmcnt(10)
	v_add_f32_e32 v12, v12, v43
	global_store_dword v[2:3], v12, off offset:128
	v_mul_f32_e32 v2, v12, v243
	v_cvt_pk_bf16_f32 v2, v2, s0
	global_store_short v[4:5], v2, off offset:64
.LBB0_4369:
	v_cmp_gt_i32_e64 s[10:11], s85, v42
	s_nop 1
	v_cndmask_b32_e64 v2, v181, v42, s[10:11]
	v_mul_hi_i32 v3, v2, s83
	v_lshrrev_b32_e32 v4, 31, v3
	v_ashrrev_i32_e32 v3, 11, v3
	v_add_u32_e32 v4, v3, v4
	v_mad_i32_i24 v5, v4, s84, v2
	v_cmp_lt_i32_e64 s[0:1], 15, v5
	s_and_saveexec_b64 s[22:23], s[0:1]
	s_xor_b64 s[0:1], exec, s[22:23]
	v_lshlrev_b32_e32 v2, 12, v4
	v_add3_u32 v2, v2, v5, -16
	v_ashrrev_i32_e32 v3, 31, v2
	v_lshlrev_b64 v[2:3], 12, v[2:3]
	v_lshl_add_u64 v[2:3], s[88:89], 0, v[2:3]
	s_andn2_saveexec_b64 s[0:1], s[0:1]
	v_lshlrev_b32_e32 v2, 14, v4
	v_lshl_add_u32 v2, v5, 10, v2
	v_ashrrev_i32_e32 v3, 31, v2
	v_lshl_add_u64 v[2:3], v[2:3], 2, s[16:17]
	s_or_b64 exec, exec, s[0:1]
	v_ashrrev_i32_e32 v43, 31, v42
	v_lshlrev_b64 v[4:5], 11, v[42:43]
	v_lshl_add_u64 v[4:5], s[62:63], 0, v[4:5]
	s_waitcnt vmcnt(9)
	v_add_f32_e32 v27, v29, v114
	v_lshl_add_u64 v[4:5], v[130:131], 1, v[4:5]
	v_lshl_add_u64 v[2:3], v[2:3], 0, v[134:135]
	global_store_dword v[2:3], v27, off
	v_mul_f32_e32 v28, v27, v242
	v_cvt_pk_bf16_f32 v28, v28, s0
	global_store_short v[4:5], v28, off
.LBB0_4375:
	s_waitcnt vmcnt(8)
	v_add_f32_e32 v13, v13, v41
	global_store_dword v[2:3], v13, off offset:128
	v_mul_f32_e32 v2, v13, v243
	v_cvt_pk_bf16_f32 v2, v2, s0
	global_store_short v[4:5], v2, off offset:64
.LBB0_4377:
	v_cmp_gt_i32_e64 s[10:11], s85, v40
	s_nop 1
	v_cndmask_b32_e64 v2, v181, v40, s[10:11]
	v_mul_hi_i32 v3, v2, s83
	v_lshrrev_b32_e32 v4, 31, v3
	v_ashrrev_i32_e32 v3, 11, v3
	v_add_u32_e32 v4, v3, v4
	v_mad_i32_i24 v5, v4, s84, v2
	v_cmp_lt_i32_e64 s[0:1], 15, v5
	s_and_saveexec_b64 s[22:23], s[0:1]
	s_xor_b64 s[0:1], exec, s[22:23]
	v_lshlrev_b32_e32 v2, 12, v4
	v_add3_u32 v2, v2, v5, -16
	v_ashrrev_i32_e32 v3, 31, v2
	v_lshlrev_b64 v[2:3], 12, v[2:3]
	v_lshl_add_u64 v[2:3], s[88:89], 0, v[2:3]
	s_andn2_saveexec_b64 s[0:1], s[0:1]
	v_lshlrev_b32_e32 v2, 14, v4
	v_lshl_add_u32 v2, v5, 10, v2
	v_ashrrev_i32_e32 v3, 31, v2
	v_lshl_add_u64 v[2:3], v[2:3], 2, s[16:17]
	s_or_b64 exec, exec, s[0:1]
	v_ashrrev_i32_e32 v41, 31, v40
	v_lshlrev_b64 v[4:5], 11, v[40:41]
	v_lshl_add_u64 v[4:5], s[62:63], 0, v[4:5]
	s_waitcnt vmcnt(7)
	v_add_f32_e32 v28, v30, v113
	v_lshl_add_u64 v[4:5], v[130:131], 1, v[4:5]
	v_lshl_add_u64 v[2:3], v[2:3], 0, v[134:135]
	global_store_dword v[2:3], v28, off
	v_mul_f32_e32 v29, v28, v242
	v_cvt_pk_bf16_f32 v29, v29, s0
	global_store_short v[4:5], v29, off
.LBB0_4383:
	s_waitcnt vmcnt(6)
	v_add_f32_e32 v14, v14, v39
	global_store_dword v[2:3], v14, off offset:128
	v_mul_f32_e32 v2, v14, v243
	v_cvt_pk_bf16_f32 v2, v2, s0
	global_store_short v[4:5], v2, off offset:64
.LBB0_4385:
	v_cmp_gt_i32_e64 s[10:11], s85, v38
	s_nop 1
	v_cndmask_b32_e64 v2, v181, v38, s[10:11]
	v_mul_hi_i32 v3, v2, s83
	v_lshrrev_b32_e32 v4, 31, v3
	v_ashrrev_i32_e32 v3, 11, v3
	v_add_u32_e32 v4, v3, v4
	v_mad_i32_i24 v5, v4, s84, v2
	v_cmp_lt_i32_e64 s[0:1], 15, v5
	s_and_saveexec_b64 s[22:23], s[0:1]
	s_xor_b64 s[0:1], exec, s[22:23]
	v_lshlrev_b32_e32 v2, 12, v4
	v_add3_u32 v2, v2, v5, -16
	v_ashrrev_i32_e32 v3, 31, v2
	v_lshlrev_b64 v[2:3], 12, v[2:3]
	v_lshl_add_u64 v[2:3], s[88:89], 0, v[2:3]
	s_andn2_saveexec_b64 s[0:1], s[0:1]
	v_lshlrev_b32_e32 v2, 14, v4
	v_lshl_add_u32 v2, v5, 10, v2
	v_ashrrev_i32_e32 v3, 31, v2
	v_lshl_add_u64 v[2:3], v[2:3], 2, s[16:17]
	s_or_b64 exec, exec, s[0:1]
	v_ashrrev_i32_e32 v39, 31, v38
	v_lshlrev_b64 v[4:5], 11, v[38:39]
	v_lshl_add_u64 v[4:5], s[62:63], 0, v[4:5]
	s_waitcnt vmcnt(5)
	v_add_f32_e32 v29, v31, v112
	v_lshl_add_u64 v[4:5], v[130:131], 1, v[4:5]
	v_lshl_add_u64 v[2:3], v[2:3], 0, v[134:135]
	global_store_dword v[2:3], v29, off
	v_mul_f32_e32 v30, v29, v242
	v_cvt_pk_bf16_f32 v30, v30, s0
	global_store_short v[4:5], v30, off
.LBB0_4391:
	s_waitcnt vmcnt(4)
	v_add_f32_e32 v15, v15, v37
	global_store_dword v[2:3], v15, off offset:128
	v_mul_f32_e32 v2, v15, v243
	v_cvt_pk_bf16_f32 v2, v2, s0
	global_store_short v[4:5], v2, off offset:64
.LBB0_4393:
	v_cmp_gt_i32_e64 s[10:11], s85, v36
	s_nop 1
	v_cndmask_b32_e64 v2, v181, v36, s[10:11]
	v_mul_hi_i32 v3, v2, s83
	v_lshrrev_b32_e32 v4, 31, v3
	v_ashrrev_i32_e32 v3, 11, v3
	v_add_u32_e32 v4, v3, v4
	v_mad_i32_i24 v5, v4, s84, v2
	v_cmp_lt_i32_e64 s[0:1], 15, v5
	s_and_saveexec_b64 s[22:23], s[0:1]
	s_xor_b64 s[0:1], exec, s[22:23]
	v_lshlrev_b32_e32 v2, 12, v4
	v_add3_u32 v2, v2, v5, -16
	v_ashrrev_i32_e32 v3, 31, v2
	v_lshlrev_b64 v[2:3], 12, v[2:3]
	v_lshl_add_u64 v[2:3], s[88:89], 0, v[2:3]
	s_andn2_saveexec_b64 s[0:1], s[0:1]
	v_lshlrev_b32_e32 v2, 14, v4
	v_lshl_add_u32 v2, v5, 10, v2
	v_ashrrev_i32_e32 v3, 31, v2
	v_lshl_add_u64 v[2:3], v[2:3], 2, s[16:17]
	s_or_b64 exec, exec, s[0:1]
	v_ashrrev_i32_e32 v37, 31, v36
	v_lshlrev_b64 v[4:5], 11, v[36:37]
	v_lshl_add_u64 v[4:5], s[62:63], 0, v[4:5]
	s_waitcnt vmcnt(3)
	v_add_f32_e32 v30, v32, v111
	v_lshl_add_u64 v[4:5], v[130:131], 1, v[4:5]
	v_lshl_add_u64 v[2:3], v[2:3], 0, v[134:135]
	global_store_dword v[2:3], v30, off
	v_mul_f32_e32 v31, v30, v242
	v_cvt_pk_bf16_f32 v31, v31, s0
	global_store_short v[4:5], v31, off
.LBB0_4399:
	s_waitcnt vmcnt(2)
	v_add_f32_e32 v31, v16, v35
	global_store_dword v[2:3], v31, off offset:128
	v_mul_f32_e32 v2, v31, v243
	v_cvt_pk_bf16_f32 v2, v2, s0
	global_store_short v[4:5], v2, off offset:64
.LBB0_4401:
	v_cmp_gt_i32_e64 s[10:11], s85, v34
	s_nop 1
	v_cndmask_b32_e64 v2, v181, v34, s[10:11]
	v_mul_hi_i32 v3, v2, s83
	v_lshrrev_b32_e32 v4, 31, v3
	v_ashrrev_i32_e32 v3, 11, v3
	v_add_u32_e32 v4, v3, v4
	v_mad_i32_i24 v5, v4, s84, v2
	v_cmp_lt_i32_e64 s[0:1], 15, v5
	s_and_saveexec_b64 s[22:23], s[0:1]
	s_xor_b64 s[0:1], exec, s[22:23]
	v_lshlrev_b32_e32 v2, 12, v4
	v_add3_u32 v2, v2, v5, -16
	v_ashrrev_i32_e32 v3, 31, v2
	v_lshlrev_b64 v[2:3], 12, v[2:3]
	v_lshl_add_u64 v[2:3], s[88:89], 0, v[2:3]
	s_andn2_saveexec_b64 s[0:1], s[0:1]
	v_lshlrev_b32_e32 v2, 14, v4
	v_lshl_add_u32 v2, v5, 10, v2
	v_ashrrev_i32_e32 v3, 31, v2
	v_lshl_add_u64 v[2:3], v[2:3], 2, s[16:17]
	s_or_b64 exec, exec, s[0:1]
	v_ashrrev_i32_e32 v35, 31, v34
	v_lshlrev_b64 v[4:5], 11, v[34:35]
	v_lshl_add_u64 v[4:5], s[62:63], 0, v[4:5]
	s_waitcnt vmcnt(1)
	v_add_f32_e32 v16, v33, v109
	v_lshl_add_u64 v[4:5], v[130:131], 1, v[4:5]
	v_lshl_add_u64 v[2:3], v[2:3], 0, v[134:135]
	global_store_dword v[2:3], v16, off
	v_mul_f32_e32 v32, v16, v242
	v_cvt_pk_bf16_f32 v32, v32, s0
	global_store_short v[4:5], v32, off
.LBB0_4407:
	s_waitcnt vmcnt(0)
	v_add_f32_e32 v17, v17, v103
	s_and_saveexec_b64 s[0:1], s[10:11]
	s_cbranch_execz .LBB0_3577
	global_store_dword v[2:3], v17, off offset:128
	global_load_dword v2, v[132:133], off offset:128
	s_waitcnt vmcnt(0)
	v_mul_f32_e32 v2, v17, v2
	v_cvt_pk_bf16_f32 v2, v2, s0
	global_store_short v[4:5], v2, off offset:64
	s_branch .LBB0_3577

.Lrt2_f:
	s_waitcnt vmcnt(6)
	v_mov_b32_e32 v135, v208
	s_nop 0
	v_ashrrev_i32_e32 v0, 1, v135
	v_and_b32_e32 v0, 0xffffff80, v0
	v_lshrrev_b32_e32 v130, 3, v135
	v_and_b32_e32 v136, 4, v130
	v_add_u32_e32 v137, s9, v0
	v_or_b32_e32 v134, v137, v136
	v_min_i32_e32 v130, 0x403f, v134
	v_mul_hi_i32 v0, v130, s80
	v_lshrrev_b32_e32 v131, 31, v0
	v_ashrrev_i32_e32 v0, 11, v0
	v_add_u32_e32 v0, v0, v131
	v_mad_i32_i24 v130, v0, s81, v130
	v_cmp_lt_i32_e32 vcc, 15, v130
	s_and_saveexec_b64 s[0:1], vcc
	s_xor_b64 s[0:1], exec, s[0:1]
	v_lshlrev_b32_e32 v0, 12, v0
	v_add3_u32 v130, v0, v130, -16
	v_ashrrev_i32_e32 v131, 31, v130
	v_lshlrev_b64 v[130:131], 12, v[130:131]
	v_lshl_add_u64 v[132:133], s[88:89], 0, v[130:131]
	s_andn2_saveexec_b64 s[0:1], s[0:1]
	v_lshlrev_b32_e32 v0, 14, v0
	v_lshl_add_u32 v130, v130, 10, v0
	v_ashrrev_i32_e32 v131, 31, v130
	v_lshl_add_u64 v[132:133], v[130:131], 2, s[16:17]
	s_or_b64 exec, exec, s[0:1]
	v_bfe_u32 v0, v135, 6, 2
	s_waitcnt vmcnt(2)
	v_and_b32_e32 v138, 31, v135
	v_lshlrev_b32_e32 v130, 6, v0
	v_or3_b32 v130, v130, s8, v138
	v_ashrrev_i32_e32 v131, 31, v130
	v_lshl_add_u64 v[132:133], v[130:131], 2, v[132:133]
	global_load_dword v139, v[132:133], off
	global_load_dword v140, v[132:133], off offset:128
	v_or_b32_e32 v187, 1, v134
	v_min_i32_e32 v132, 0x403f, v187
	v_mul_hi_i32 v133, v132, s80
	v_lshrrev_b32_e32 v141, 31, v133
	v_ashrrev_i32_e32 v133, 11, v133
	v_add_u32_e32 v141, v133, v141
	v_mad_i32_i24 v142, v141, s81, v132
	v_cmp_lt_i32_e32 vcc, 15, v142
	s_and_saveexec_b64 s[0:1], vcc
	s_xor_b64 s[0:1], exec, s[0:1]
	v_lshlrev_b32_e32 v132, 12, v141
	v_add3_u32 v132, v132, v142, -16
	v_ashrrev_i32_e32 v133, 31, v132
	v_lshlrev_b64 v[132:133], 12, v[132:133]
	v_lshl_add_u64 v[132:133], s[88:89], 0, v[132:133]
	s_andn2_saveexec_b64 s[0:1], s[0:1]
	v_lshlrev_b32_e32 v132, 14, v141
	v_lshl_add_u32 v132, v142, 10, v132
	v_ashrrev_i32_e32 v133, 31, v132
	v_lshl_add_u64 v[132:133], v[132:133], 2, s[16:17]
	s_or_b64 exec, exec, s[0:1]
	v_lshl_add_u64 v[132:133], v[130:131], 2, v[132:133]
	global_load_dword v141, v[132:133], off
	global_load_dword v142, v[132:133], off offset:128
	v_or_b32_e32 v186, 2, v134
	v_min_i32_e32 v132, 0x403f, v186
	v_mul_hi_i32 v133, v132, s80
	v_lshrrev_b32_e32 v143, 31, v133
	v_ashrrev_i32_e32 v133, 11, v133
	v_add_u32_e32 v143, v133, v143
	v_mad_i32_i24 v144, v143, s81, v132
	v_cmp_lt_i32_e32 vcc, 15, v144
	s_and_saveexec_b64 s[0:1], vcc
	s_xor_b64 s[0:1], exec, s[0:1]
	v_lshlrev_b32_e32 v132, 12, v143
	v_add3_u32 v132, v132, v144, -16
	v_ashrrev_i32_e32 v133, 31, v132
	v_lshlrev_b64 v[132:133], 12, v[132:133]
	v_lshl_add_u64 v[132:133], s[88:89], 0, v[132:133]
	s_andn2_saveexec_b64 s[0:1], s[0:1]
	v_lshlrev_b32_e32 v132, 14, v143
	v_lshl_add_u32 v132, v144, 10, v132
	v_ashrrev_i32_e32 v133, 31, v132
	v_lshl_add_u64 v[132:133], v[132:133], 2, s[16:17]
	s_or_b64 exec, exec, s[0:1]
	v_lshl_add_u64 v[132:133], v[130:131], 2, v[132:133]
	global_load_dword v143, v[132:133], off
	global_load_dword v144, v[132:133], off offset:128
	v_or_b32_e32 v185, 3, v134
	v_min_i32_e32 v132, 0x403f, v185
	v_mul_hi_i32 v133, v132, s80
	v_lshrrev_b32_e32 v145, 31, v133
	v_ashrrev_i32_e32 v133, 11, v133
	v_add_u32_e32 v145, v133, v145
	s_waitcnt vmcnt(7)
	v_mad_i32_i24 v146, v145, s81, v132
	v_cmp_lt_i32_e32 vcc, 15, v146
	s_and_saveexec_b64 s[0:1], vcc
	s_xor_b64 s[0:1], exec, s[0:1]
	v_lshlrev_b32_e32 v132, 12, v145
	v_add3_u32 v132, v132, v146, -16
	v_ashrrev_i32_e32 v133, 31, v132
	v_lshlrev_b64 v[132:133], 12, v[132:133]
	v_lshl_add_u64 v[132:133], s[88:89], 0, v[132:133]
	s_andn2_saveexec_b64 s[0:1], s[0:1]
	v_lshlrev_b32_e32 v132, 14, v145
	v_lshl_add_u32 v132, v146, 10, v132
	v_ashrrev_i32_e32 v133, 31, v132
	v_lshl_add_u64 v[132:133], v[132:133], 2, s[16:17]
	s_or_b64 exec, exec, s[0:1]
	v_lshl_add_u64 v[132:133], v[130:131], 2, v[132:133]
	global_load_dword v145, v[132:133], off
	global_load_dword v146, v[132:133], off offset:128
	v_or_b32_e32 v184, 8, v134
	v_min_i32_e32 v132, 0x403f, v184
	v_mul_hi_i32 v133, v132, s80
	v_lshrrev_b32_e32 v147, 31, v133
	v_ashrrev_i32_e32 v133, 11, v133
	v_add_u32_e32 v147, v133, v147
	v_mad_i32_i24 v148, v147, s81, v132
	v_cmp_lt_i32_e32 vcc, 15, v148
	s_and_saveexec_b64 s[0:1], vcc
	s_xor_b64 s[0:1], exec, s[0:1]
	v_lshlrev_b32_e32 v132, 12, v147
	v_add3_u32 v132, v132, v148, -16
	v_ashrrev_i32_e32 v133, 31, v132
	v_lshlrev_b64 v[132:133], 12, v[132:133]
	v_lshl_add_u64 v[132:133], s[88:89], 0, v[132:133]
	s_andn2_saveexec_b64 s[0:1], s[0:1]
	v_lshlrev_b32_e32 v132, 14, v147
	v_lshl_add_u32 v132, v148, 10, v132
	v_ashrrev_i32_e32 v133, 31, v132
	v_lshl_add_u64 v[132:133], v[132:133], 2, s[16:17]
	s_or_b64 exec, exec, s[0:1]
	v_lshl_add_u64 v[132:133], v[130:131], 2, v[132:133]
	global_load_dword v147, v[132:133], off
	global_load_dword v148, v[132:133], off offset:128
	v_or_b32_e32 v183, 9, v134
	v_min_i32_e32 v132, 0x403f, v183
	v_mul_hi_i32 v133, v132, s80
	v_lshrrev_b32_e32 v149, 31, v133
	v_ashrrev_i32_e32 v133, 11, v133
	v_add_u32_e32 v149, v133, v149
	v_mad_i32_i24 v150, v149, s81, v132
	v_cmp_lt_i32_e32 vcc, 15, v150
	s_and_saveexec_b64 s[0:1], vcc
	s_xor_b64 s[0:1], exec, s[0:1]
	v_lshlrev_b32_e32 v132, 12, v149
	v_add3_u32 v132, v132, v150, -16
	v_ashrrev_i32_e32 v133, 31, v132
	v_lshlrev_b64 v[132:133], 12, v[132:133]
	v_lshl_add_u64 v[132:133], s[88:89], 0, v[132:133]
	s_andn2_saveexec_b64 s[0:1], s[0:1]
	v_lshlrev_b32_e32 v132, 14, v149
	v_lshl_add_u32 v132, v150, 10, v132
	v_ashrrev_i32_e32 v133, 31, v132
	v_lshl_add_u64 v[132:133], v[132:133], 2, s[16:17]
	s_or_b64 exec, exec, s[0:1]
	v_lshl_add_u64 v[132:133], v[130:131], 2, v[132:133]
	global_load_dword v149, v[132:133], off
	global_load_dword v150, v[132:133], off offset:128
	v_or_b32_e32 v182, 10, v134
	v_min_i32_e32 v132, 0x403f, v182
	v_mul_hi_i32 v133, v132, s80
	v_lshrrev_b32_e32 v151, 31, v133
	v_ashrrev_i32_e32 v133, 11, v133
	v_add_u32_e32 v151, v133, v151
	v_mad_i32_i24 v152, v151, s81, v132
	v_cmp_lt_i32_e32 vcc, 15, v152
	s_and_saveexec_b64 s[0:1], vcc
	s_xor_b64 s[0:1], exec, s[0:1]
	v_lshlrev_b32_e32 v132, 12, v151
	v_add3_u32 v132, v132, v152, -16
	v_ashrrev_i32_e32 v133, 31, v132
	v_lshlrev_b64 v[132:133], 12, v[132:133]
	v_lshl_add_u64 v[132:133], s[88:89], 0, v[132:133]
	s_andn2_saveexec_b64 s[0:1], s[0:1]
	v_lshlrev_b32_e32 v132, 14, v151
	v_lshl_add_u32 v132, v152, 10, v132
	v_ashrrev_i32_e32 v133, 31, v132
	v_lshl_add_u64 v[132:133], v[132:133], 2, s[16:17]
	s_or_b64 exec, exec, s[0:1]
	v_lshl_add_u64 v[132:133], v[130:131], 2, v[132:133]
	global_load_dword v151, v[132:133], off
	global_load_dword v152, v[132:133], off offset:128
	v_or_b32_e32 v181, 11, v134
	v_min_i32_e32 v132, 0x403f, v181
	v_mul_hi_i32 v133, v132, s80
	v_lshrrev_b32_e32 v153, 31, v133
	v_ashrrev_i32_e32 v133, 11, v133
	v_add_u32_e32 v153, v133, v153
	s_waitcnt vmcnt(14)
	v_mad_i32_i24 v154, v153, s81, v132
	v_cmp_lt_i32_e32 vcc, 15, v154
	s_and_saveexec_b64 s[0:1], vcc
	s_xor_b64 s[0:1], exec, s[0:1]
	v_lshlrev_b32_e32 v132, 12, v153
	v_add3_u32 v132, v132, v154, -16
	v_ashrrev_i32_e32 v133, 31, v132
	v_lshlrev_b64 v[132:133], 12, v[132:133]
	v_lshl_add_u64 v[132:133], s[88:89], 0, v[132:133]
	s_andn2_saveexec_b64 s[0:1], s[0:1]
	v_lshlrev_b32_e32 v132, 14, v153
	v_lshl_add_u32 v132, v154, 10, v132
	v_ashrrev_i32_e32 v133, 31, v132
	v_lshl_add_u64 v[132:133], v[132:133], 2, s[16:17]
	s_or_b64 exec, exec, s[0:1]
	v_lshl_add_u64 v[132:133], v[130:131], 2, v[132:133]
	global_load_dword v153, v[132:133], off
	global_load_dword v154, v[132:133], off offset:128
	v_or_b32_e32 v180, 16, v134
	v_min_i32_e32 v132, 0x403f, v180
	v_mul_hi_i32 v133, v132, s80
	v_lshrrev_b32_e32 v155, 31, v133
	v_ashrrev_i32_e32 v133, 11, v133
	v_add_u32_e32 v155, v133, v155
	v_mad_i32_i24 v156, v155, s81, v132
	v_cmp_lt_i32_e32 vcc, 15, v156
	s_and_saveexec_b64 s[0:1], vcc
	s_xor_b64 s[0:1], exec, s[0:1]
	v_lshlrev_b32_e32 v132, 12, v155
	v_add3_u32 v132, v132, v156, -16
	v_ashrrev_i32_e32 v133, 31, v132
	v_lshlrev_b64 v[132:133], 12, v[132:133]
	v_lshl_add_u64 v[132:133], s[88:89], 0, v[132:133]
	s_andn2_saveexec_b64 s[0:1], s[0:1]
	v_lshlrev_b32_e32 v132, 14, v155
	v_lshl_add_u32 v132, v156, 10, v132
	v_ashrrev_i32_e32 v133, 31, v132
	v_lshl_add_u64 v[132:133], v[132:133], 2, s[16:17]
	s_or_b64 exec, exec, s[0:1]
	v_lshl_add_u64 v[132:133], v[130:131], 2, v[132:133]
	global_load_dword v155, v[132:133], off
	global_load_dword v156, v[132:133], off offset:128
	v_or_b32_e32 v177, 17, v134
	v_min_i32_e32 v132, 0x403f, v177
	v_mul_hi_i32 v133, v132, s80
	v_lshrrev_b32_e32 v157, 31, v133
	v_ashrrev_i32_e32 v133, 11, v133
	v_add_u32_e32 v157, v133, v157
	v_mad_i32_i24 v158, v157, s81, v132
	v_cmp_lt_i32_e32 vcc, 15, v158
	s_and_saveexec_b64 s[0:1], vcc
	s_xor_b64 s[0:1], exec, s[0:1]
	v_lshlrev_b32_e32 v132, 12, v157
	v_add3_u32 v132, v132, v158, -16
	v_ashrrev_i32_e32 v133, 31, v132
	v_lshlrev_b64 v[132:133], 12, v[132:133]
	v_lshl_add_u64 v[132:133], s[88:89], 0, v[132:133]
	s_andn2_saveexec_b64 s[0:1], s[0:1]
	v_lshlrev_b32_e32 v132, 14, v157
	v_lshl_add_u32 v132, v158, 10, v132
	v_ashrrev_i32_e32 v133, 31, v132
	v_lshl_add_u64 v[132:133], v[132:133], 2, s[16:17]
	s_or_b64 exec, exec, s[0:1]
	v_lshl_add_u64 v[132:133], v[130:131], 2, v[132:133]
	global_load_dword v157, v[132:133], off
	global_load_dword v158, v[132:133], off offset:128
	v_or_b32_e32 v176, 18, v134
	v_min_i32_e32 v132, 0x403f, v176
	v_mul_hi_i32 v133, v132, s80
	v_lshrrev_b32_e32 v159, 31, v133
	v_ashrrev_i32_e32 v133, 11, v133
	v_add_u32_e32 v159, v133, v159
	v_mad_i32_i24 v160, v159, s81, v132
	v_cmp_lt_i32_e32 vcc, 15, v160
	s_and_saveexec_b64 s[0:1], vcc
	s_xor_b64 s[0:1], exec, s[0:1]
	v_lshlrev_b32_e32 v132, 12, v159
	v_add3_u32 v132, v132, v160, -16
	v_ashrrev_i32_e32 v133, 31, v132
	v_lshlrev_b64 v[132:133], 12, v[132:133]
	v_lshl_add_u64 v[132:133], s[88:89], 0, v[132:133]
	s_andn2_saveexec_b64 s[0:1], s[0:1]
	v_lshlrev_b32_e32 v132, 14, v159
	v_lshl_add_u32 v132, v160, 10, v132
	v_ashrrev_i32_e32 v133, 31, v132
	v_lshl_add_u64 v[132:133], v[132:133], 2, s[16:17]
	s_or_b64 exec, exec, s[0:1]
	v_lshl_add_u64 v[132:133], v[130:131], 2, v[132:133]
	global_load_dword v159, v[132:133], off
	global_load_dword v160, v[132:133], off offset:128
	v_or_b32_e32 v175, 19, v134
	v_min_i32_e32 v132, 0x403f, v175
	v_mul_hi_i32 v133, v132, s80
	v_lshrrev_b32_e32 v161, 31, v133
	v_ashrrev_i32_e32 v133, 11, v133
	v_add_u32_e32 v161, v133, v161
	v_mad_i32_i24 v162, v161, s81, v132
	v_cmp_lt_i32_e32 vcc, 15, v162
	s_and_saveexec_b64 s[0:1], vcc
	s_xor_b64 s[0:1], exec, s[0:1]
	v_lshlrev_b32_e32 v132, 12, v161
	v_add3_u32 v132, v132, v162, -16
	v_ashrrev_i32_e32 v133, 31, v132
	v_lshlrev_b64 v[132:133], 12, v[132:133]
	v_lshl_add_u64 v[132:133], s[88:89], 0, v[132:133]
	s_andn2_saveexec_b64 s[0:1], s[0:1]
	v_lshlrev_b32_e32 v132, 14, v161
	v_lshl_add_u32 v132, v162, 10, v132
	v_ashrrev_i32_e32 v133, 31, v132
	v_lshl_add_u64 v[132:133], v[132:133], 2, s[16:17]
	s_or_b64 exec, exec, s[0:1]
	v_lshl_add_u64 v[132:133], v[130:131], 2, v[132:133]
	global_load_dword v161, v[132:133], off
	global_load_dword v162, v[132:133], off offset:128
	v_or_b32_e32 v174, 24, v134
	v_min_i32_e32 v132, 0x403f, v174
	v_mul_hi_i32 v133, v132, s80
	v_lshrrev_b32_e32 v163, 31, v133
	v_ashrrev_i32_e32 v133, 11, v133
	v_add_u32_e32 v163, v133, v163
	v_mad_i32_i24 v164, v163, s81, v132
	v_cmp_lt_i32_e32 vcc, 15, v164
	s_and_saveexec_b64 s[0:1], vcc
	s_xor_b64 s[0:1], exec, s[0:1]
	v_lshlrev_b32_e32 v132, 12, v163
	v_add3_u32 v132, v132, v164, -16
	v_ashrrev_i32_e32 v133, 31, v132
	v_lshlrev_b64 v[132:133], 12, v[132:133]
	v_lshl_add_u64 v[132:133], s[88:89], 0, v[132:133]
	s_andn2_saveexec_b64 s[0:1], s[0:1]
	v_lshlrev_b32_e32 v132, 14, v163
	v_lshl_add_u32 v132, v164, 10, v132
	v_ashrrev_i32_e32 v133, 31, v132
	v_lshl_add_u64 v[132:133], v[132:133], 2, s[16:17]
	s_or_b64 exec, exec, s[0:1]
	v_lshl_add_u64 v[132:133], v[130:131], 2, v[132:133]
	global_load_dword v163, v[132:133], off
	global_load_dword v164, v[132:133], off offset:128
	v_or_b32_e32 v173, 25, v134
	v_min_i32_e32 v132, 0x403f, v173
	v_mul_hi_i32 v133, v132, s80
	v_lshrrev_b32_e32 v165, 31, v133
	v_ashrrev_i32_e32 v133, 11, v133
	v_add_u32_e32 v165, v133, v165
	v_mad_i32_i24 v166, v165, s81, v132
	v_cmp_lt_i32_e32 vcc, 15, v166
	s_and_saveexec_b64 s[0:1], vcc
	s_xor_b64 s[0:1], exec, s[0:1]
	v_lshlrev_b32_e32 v132, 12, v165
	v_add3_u32 v132, v132, v166, -16
	v_ashrrev_i32_e32 v133, 31, v132
	v_lshlrev_b64 v[132:133], 12, v[132:133]
	v_lshl_add_u64 v[132:133], s[88:89], 0, v[132:133]
	s_andn2_saveexec_b64 s[0:1], s[0:1]
	v_lshlrev_b32_e32 v132, 14, v165
	v_lshl_add_u32 v132, v166, 10, v132
	v_ashrrev_i32_e32 v133, 31, v132
	v_lshl_add_u64 v[132:133], v[132:133], 2, s[16:17]
	s_or_b64 exec, exec, s[0:1]
	v_lshl_add_u64 v[132:133], v[130:131], 2, v[132:133]
	global_load_dword v165, v[132:133], off
	global_load_dword v166, v[132:133], off offset:128
	v_or_b32_e32 v172, 26, v134
	v_min_i32_e32 v132, 0x403f, v172
	v_mul_hi_i32 v133, v132, s80
	v_lshrrev_b32_e32 v167, 31, v133
	v_ashrrev_i32_e32 v133, 11, v133
	v_add_u32_e32 v167, v133, v167
	v_mad_i32_i24 v168, v167, s81, v132
	v_cmp_lt_i32_e32 vcc, 15, v168
	s_and_saveexec_b64 s[0:1], vcc
	s_xor_b64 s[0:1], exec, s[0:1]
	v_lshlrev_b32_e32 v132, 12, v167
	v_add3_u32 v132, v132, v168, -16
	v_ashrrev_i32_e32 v133, 31, v132
	v_lshlrev_b64 v[132:133], 12, v[132:133]
	v_lshl_add_u64 v[132:133], s[88:89], 0, v[132:133]
	s_andn2_saveexec_b64 s[0:1], s[0:1]
	v_lshlrev_b32_e32 v132, 14, v167
	v_lshl_add_u32 v132, v168, 10, v132
	v_ashrrev_i32_e32 v133, 31, v132
	v_lshl_add_u64 v[132:133], v[132:133], 2, s[16:17]
	s_or_b64 exec, exec, s[0:1]
	v_lshl_add_u64 v[132:133], v[130:131], 2, v[132:133]
	global_load_dword v167, v[132:133], off
	global_load_dword v168, v[132:133], off offset:128
	v_or_b32_e32 v171, 27, v134
	v_min_i32_e32 v132, 0x403f, v171
	v_mul_hi_i32 v133, v132, s80
	v_lshrrev_b32_e32 v169, 31, v133
	v_ashrrev_i32_e32 v133, 11, v133
	v_add_u32_e32 v169, v133, v169
	v_mad_i32_i24 v170, v169, s81, v132
	v_cmp_lt_i32_e32 vcc, 15, v170
	s_and_saveexec_b64 s[0:1], vcc
	s_xor_b64 s[0:1], exec, s[0:1]
	v_lshlrev_b32_e32 v132, 12, v169
	v_add3_u32 v132, v132, v170, -16
	v_ashrrev_i32_e32 v133, 31, v132
	v_lshlrev_b64 v[132:133], 12, v[132:133]
	v_lshl_add_u64 v[132:133], s[88:89], 0, v[132:133]
	s_andn2_saveexec_b64 s[0:1], s[0:1]
	v_lshlrev_b32_e32 v132, 14, v169
	v_lshl_add_u32 v132, v170, 10, v132
	v_ashrrev_i32_e32 v133, 31, v132
	v_lshl_add_u64 v[132:133], v[132:133], 2, s[16:17]
	s_or_b64 exec, exec, s[0:1]
	v_lshl_add_u64 v[132:133], v[130:131], 2, v[132:133]
	global_load_dword v169, v[132:133], off
	global_load_dword v170, v[132:133], off offset:128
	v_cmp_gt_i32_e32 vcc, s82, v134
	s_nop 1
	v_cndmask_b32_e32 v132, v179, v134, vcc
	v_mul_hi_i32 v133, v132, s80
	v_lshrrev_b32_e32 v188, 31, v133
	v_ashrrev_i32_e32 v133, 11, v133
	v_add_u32_e32 v188, v133, v188
	v_mad_i32_i24 v189, v188, s81, v132
	v_cmp_lt_i32_e64 s[0:1], 15, v189
	s_and_saveexec_b64 s[2:3], s[0:1]
	s_xor_b64 s[0:1], exec, s[2:3]
	v_lshlrev_b32_e32 v132, 12, v188
	v_add3_u32 v132, v132, v189, -16
	v_ashrrev_i32_e32 v133, 31, v132
	v_lshlrev_b64 v[132:133], 12, v[132:133]
	v_lshl_add_u64 v[132:133], s[88:89], 0, v[132:133]
	s_andn2_saveexec_b64 s[0:1], s[0:1]
	v_lshlrev_b32_e32 v132, 14, v188
	v_lshl_add_u32 v132, v189, 10, v132
	v_ashrrev_i32_e32 v133, 31, v132
	v_lshl_add_u64 v[132:133], v[132:133], 2, s[16:17]
	s_or_b64 exec, exec, s[0:1]
	s_waitcnt vmcnt(31)
	v_fmac_f32_e32 v139, 0.5, v114
	v_lshl_add_u64 v[132:133], v[130:131], 2, v[132:133]
	global_store_dword v[132:133], v139, off
.LBB0_4681:
	s_waitcnt vmcnt(30)
	v_fmac_f32_e32 v140, 0.5, v98
	global_store_dword v[132:133], v140, off offset:128
.LBB0_4683:
	v_cmp_gt_i32_e32 vcc, s82, v187
	s_nop 1
	v_cndmask_b32_e32 v114, v179, v187, vcc
	v_mul_hi_i32 v98, v114, s80
	v_lshrrev_b32_e32 v132, 31, v98
	v_ashrrev_i32_e32 v98, 11, v98
	v_add_u32_e32 v98, v98, v132
	v_mad_i32_i24 v114, v98, s81, v114
	v_cmp_lt_i32_e64 s[0:1], 15, v114
	s_and_saveexec_b64 s[2:3], s[0:1]
	s_xor_b64 s[0:1], exec, s[2:3]
	v_lshlrev_b32_e32 v98, 12, v98
	v_add3_u32 v132, v98, v114, -16
	v_ashrrev_i32_e32 v133, 31, v132
	v_lshlrev_b64 v[132:133], 12, v[132:133]
	v_lshl_add_u64 v[132:133], s[88:89], 0, v[132:133]
	s_andn2_saveexec_b64 s[0:1], s[0:1]
	v_lshlrev_b32_e32 v98, 14, v98
	v_lshl_add_u32 v132, v114, 10, v98
	v_ashrrev_i32_e32 v133, 31, v132
	v_lshl_add_u64 v[132:133], v[132:133], 2, s[16:17]
	s_or_b64 exec, exec, s[0:1]
	s_waitcnt vmcnt(29)
	v_fmac_f32_e32 v141, 0.5, v115
	v_lshl_add_u64 v[114:115], v[130:131], 2, v[132:133]
	global_store_dword v[114:115], v141, off
.LBB0_4689:
	s_waitcnt vmcnt(28)
	v_fmac_f32_e32 v142, 0.5, v99
	global_store_dword v[114:115], v142, off offset:128
.LBB0_4691:
	v_cmp_gt_i32_e32 vcc, s82, v186
	s_nop 1
	v_cndmask_b32_e32 v98, v179, v186, vcc
	v_mul_hi_i32 v99, v98, s80
	v_lshrrev_b32_e32 v114, 31, v99
	v_ashrrev_i32_e32 v99, 11, v99
	v_add_u32_e32 v114, v99, v114
	v_mad_i32_i24 v115, v114, s81, v98
	v_cmp_lt_i32_e64 s[0:1], 15, v115
	s_and_saveexec_b64 s[2:3], s[0:1]
	s_xor_b64 s[0:1], exec, s[2:3]
	v_lshlrev_b32_e32 v98, 12, v114
	v_add3_u32 v98, v98, v115, -16
	v_ashrrev_i32_e32 v99, 31, v98
	v_lshlrev_b64 v[98:99], 12, v[98:99]
	v_lshl_add_u64 v[98:99], s[88:89], 0, v[98:99]
	s_andn2_saveexec_b64 s[0:1], s[0:1]
	v_lshlrev_b32_e32 v98, 14, v114
	v_lshl_add_u32 v98, v115, 10, v98
	v_ashrrev_i32_e32 v99, 31, v98
	v_lshl_add_u64 v[98:99], v[98:99], 2, s[16:17]
	s_or_b64 exec, exec, s[0:1]
	s_waitcnt vmcnt(27)
	v_fmac_f32_e32 v143, 0.5, v116
	v_lshl_add_u64 v[98:99], v[130:131], 2, v[98:99]
	global_store_dword v[98:99], v143, off
.LBB0_4697:
	s_waitcnt vmcnt(26)
	v_fmac_f32_e32 v144, 0.5, v100
	global_store_dword v[98:99], v144, off offset:128
.LBB0_4699:
	v_cmp_gt_i32_e32 vcc, s82, v185
	s_nop 1
	v_cndmask_b32_e32 v98, v179, v185, vcc
	v_mul_hi_i32 v99, v98, s80
	v_lshrrev_b32_e32 v100, 31, v99
	v_ashrrev_i32_e32 v99, 11, v99
	v_add_u32_e32 v100, v99, v100
	v_mad_i32_i24 v114, v100, s81, v98
	v_cmp_lt_i32_e64 s[0:1], 15, v114
	s_and_saveexec_b64 s[2:3], s[0:1]
	s_xor_b64 s[0:1], exec, s[2:3]
	v_lshlrev_b32_e32 v98, 12, v100
	v_add3_u32 v98, v98, v114, -16
	v_ashrrev_i32_e32 v99, 31, v98
	v_lshlrev_b64 v[98:99], 12, v[98:99]
	v_lshl_add_u64 v[98:99], s[88:89], 0, v[98:99]
	s_andn2_saveexec_b64 s[0:1], s[0:1]
	v_lshlrev_b32_e32 v98, 14, v100
	v_lshl_add_u32 v98, v114, 10, v98
	v_ashrrev_i32_e32 v99, 31, v98
	v_lshl_add_u64 v[98:99], v[98:99], 2, s[16:17]
	s_or_b64 exec, exec, s[0:1]
	s_waitcnt vmcnt(25)
	v_fmac_f32_e32 v145, 0.5, v117
	v_lshl_add_u64 v[98:99], v[130:131], 2, v[98:99]
	global_store_dword v[98:99], v145, off
.LBB0_4705:
	s_waitcnt vmcnt(24)
	v_fmac_f32_e32 v146, 0.5, v101
	global_store_dword v[98:99], v146, off offset:128
.LBB0_4707:
	v_cmp_gt_i32_e32 vcc, s82, v184
	s_nop 1
	v_cndmask_b32_e32 v98, v179, v184, vcc
	v_mul_hi_i32 v99, v98, s80
	v_lshrrev_b32_e32 v100, 31, v99
	v_ashrrev_i32_e32 v99, 11, v99
	v_add_u32_e32 v100, v99, v100
	v_mad_i32_i24 v101, v100, s81, v98
	v_cmp_lt_i32_e64 s[0:1], 15, v101
	s_and_saveexec_b64 s[2:3], s[0:1]
	s_xor_b64 s[0:1], exec, s[2:3]
	v_lshlrev_b32_e32 v98, 12, v100
	v_add3_u32 v98, v98, v101, -16
	v_ashrrev_i32_e32 v99, 31, v98
	v_lshlrev_b64 v[98:99], 12, v[98:99]
	v_lshl_add_u64 v[98:99], s[88:89], 0, v[98:99]
	s_andn2_saveexec_b64 s[0:1], s[0:1]
	v_lshlrev_b32_e32 v98, 14, v100
	v_lshl_add_u32 v98, v101, 10, v98
	v_ashrrev_i32_e32 v99, 31, v98
	v_lshl_add_u64 v[98:99], v[98:99], 2, s[16:17]
	s_or_b64 exec, exec, s[0:1]
	s_waitcnt vmcnt(23)
	v_fmac_f32_e32 v147, 0.5, v118
	v_lshl_add_u64 v[98:99], v[130:131], 2, v[98:99]
	global_store_dword v[98:99], v147, off
.LBB0_4713:
	s_waitcnt vmcnt(22)
	v_fmac_f32_e32 v148, 0.5, v102
	global_store_dword v[98:99], v148, off offset:128
.LBB0_4715:
	v_cmp_gt_i32_e32 vcc, s82, v183
	s_nop 1
	v_cndmask_b32_e32 v98, v179, v183, vcc
	v_mul_hi_i32 v99, v98, s80
	v_lshrrev_b32_e32 v100, 31, v99
	v_ashrrev_i32_e32 v99, 11, v99
	v_add_u32_e32 v100, v99, v100
	v_mad_i32_i24 v101, v100, s81, v98
	v_cmp_lt_i32_e64 s[0:1], 15, v101
	s_and_saveexec_b64 s[2:3], s[0:1]
	s_xor_b64 s[0:1], exec, s[2:3]
	v_lshlrev_b32_e32 v98, 12, v100
	v_add3_u32 v98, v98, v101, -16
	v_ashrrev_i32_e32 v99, 31, v98
	v_lshlrev_b64 v[98:99], 12, v[98:99]
	v_lshl_add_u64 v[98:99], s[88:89], 0, v[98:99]
	s_andn2_saveexec_b64 s[0:1], s[0:1]
	v_lshlrev_b32_e32 v98, 14, v100
	v_lshl_add_u32 v98, v101, 10, v98
	v_ashrrev_i32_e32 v99, 31, v98
	v_lshl_add_u64 v[98:99], v[98:99], 2, s[16:17]
	s_or_b64 exec, exec, s[0:1]
	s_waitcnt vmcnt(21)
	v_fmac_f32_e32 v149, 0.5, v119
	v_lshl_add_u64 v[98:99], v[130:131], 2, v[98:99]
	global_store_dword v[98:99], v149, off
.LBB0_4721:
	s_waitcnt vmcnt(20)
	v_fmac_f32_e32 v150, 0.5, v103
	global_store_dword v[98:99], v150, off offset:128
.LBB0_4723:
	v_cmp_gt_i32_e32 vcc, s82, v182
	s_nop 1
	v_cndmask_b32_e32 v98, v179, v182, vcc
	v_mul_hi_i32 v99, v98, s80
	v_lshrrev_b32_e32 v100, 31, v99
	v_ashrrev_i32_e32 v99, 11, v99
	v_add_u32_e32 v100, v99, v100
	v_mad_i32_i24 v101, v100, s81, v98
	v_cmp_lt_i32_e64 s[0:1], 15, v101
	s_and_saveexec_b64 s[2:3], s[0:1]
	s_xor_b64 s[0:1], exec, s[2:3]
	v_lshlrev_b32_e32 v98, 12, v100
	v_add3_u32 v98, v98, v101, -16
	v_ashrrev_i32_e32 v99, 31, v98
	v_lshlrev_b64 v[98:99], 12, v[98:99]
	v_lshl_add_u64 v[98:99], s[88:89], 0, v[98:99]
	s_andn2_saveexec_b64 s[0:1], s[0:1]
	v_lshlrev_b32_e32 v98, 14, v100
	v_lshl_add_u32 v98, v101, 10, v98
	v_ashrrev_i32_e32 v99, 31, v98
	v_lshl_add_u64 v[98:99], v[98:99], 2, s[16:17]
	s_or_b64 exec, exec, s[0:1]
	s_waitcnt vmcnt(19)
	v_fmac_f32_e32 v151, 0.5, v120
	v_lshl_add_u64 v[98:99], v[130:131], 2, v[98:99]
	global_store_dword v[98:99], v151, off
.LBB0_4729:
	s_waitcnt vmcnt(18)
	v_fmac_f32_e32 v152, 0.5, v104
	global_store_dword v[98:99], v152, off offset:128
.LBB0_4731:
	v_cmp_gt_i32_e32 vcc, s82, v181
	s_nop 1
	v_cndmask_b32_e32 v98, v179, v181, vcc
	v_mul_hi_i32 v99, v98, s80
	v_lshrrev_b32_e32 v100, 31, v99
	v_ashrrev_i32_e32 v99, 11, v99
	v_add_u32_e32 v100, v99, v100
	v_mad_i32_i24 v101, v100, s81, v98
	v_cmp_lt_i32_e64 s[0:1], 15, v101
	s_and_saveexec_b64 s[2:3], s[0:1]
	s_xor_b64 s[0:1], exec, s[2:3]
	v_lshlrev_b32_e32 v98, 12, v100
	v_add3_u32 v98, v98, v101, -16
	v_ashrrev_i32_e32 v99, 31, v98
	v_lshlrev_b64 v[98:99], 12, v[98:99]
	v_lshl_add_u64 v[98:99], s[88:89], 0, v[98:99]
	s_andn2_saveexec_b64 s[0:1], s[0:1]
	v_lshlrev_b32_e32 v98, 14, v100
	v_lshl_add_u32 v98, v101, 10, v98
	v_ashrrev_i32_e32 v99, 31, v98
	v_lshl_add_u64 v[98:99], v[98:99], 2, s[16:17]
	s_or_b64 exec, exec, s[0:1]
	s_waitcnt vmcnt(17)
	v_fmac_f32_e32 v153, 0.5, v121
	v_lshl_add_u64 v[98:99], v[130:131], 2, v[98:99]
	global_store_dword v[98:99], v153, off
.LBB0_4737:
	s_waitcnt vmcnt(16)
	v_fmac_f32_e32 v154, 0.5, v105
	global_store_dword v[98:99], v154, off offset:128
.LBB0_4739:
	v_cmp_gt_i32_e32 vcc, s82, v180
	s_nop 1
	v_cndmask_b32_e32 v98, v179, v180, vcc
	v_mul_hi_i32 v99, v98, s80
	v_lshrrev_b32_e32 v100, 31, v99
	v_ashrrev_i32_e32 v99, 11, v99
	v_add_u32_e32 v100, v99, v100
	v_mad_i32_i24 v101, v100, s81, v98
	v_cmp_lt_i32_e64 s[0:1], 15, v101
	s_and_saveexec_b64 s[2:3], s[0:1]
	s_xor_b64 s[0:1], exec, s[2:3]
	v_lshlrev_b32_e32 v98, 12, v100
	v_add3_u32 v98, v98, v101, -16
	v_ashrrev_i32_e32 v99, 31, v98
	v_lshlrev_b64 v[98:99], 12, v[98:99]
	v_lshl_add_u64 v[98:99], s[88:89], 0, v[98:99]
	s_andn2_saveexec_b64 s[0:1], s[0:1]
	v_lshlrev_b32_e32 v98, 14, v100
	v_lshl_add_u32 v98, v101, 10, v98
	v_ashrrev_i32_e32 v99, 31, v98
	v_lshl_add_u64 v[98:99], v[98:99], 2, s[16:17]
	s_or_b64 exec, exec, s[0:1]
	s_waitcnt vmcnt(15)
	v_fmac_f32_e32 v155, 0.5, v122
	v_lshl_add_u64 v[98:99], v[130:131], 2, v[98:99]
	global_store_dword v[98:99], v155, off
.LBB0_4745:
	s_waitcnt vmcnt(14)
	v_fmac_f32_e32 v156, 0.5, v106
	global_store_dword v[98:99], v156, off offset:128
.LBB0_4747:
	v_cmp_gt_i32_e32 vcc, s82, v177
	s_nop 1
	v_cndmask_b32_e32 v98, v179, v177, vcc
	v_mul_hi_i32 v99, v98, s80
	v_lshrrev_b32_e32 v100, 31, v99
	v_ashrrev_i32_e32 v99, 11, v99
	v_add_u32_e32 v100, v99, v100
	v_mad_i32_i24 v101, v100, s81, v98
	v_cmp_lt_i32_e64 s[0:1], 15, v101
	s_and_saveexec_b64 s[2:3], s[0:1]
	s_xor_b64 s[0:1], exec, s[2:3]
	v_lshlrev_b32_e32 v98, 12, v100
	v_add3_u32 v98, v98, v101, -16
	v_ashrrev_i32_e32 v99, 31, v98
	v_lshlrev_b64 v[98:99], 12, v[98:99]
	v_lshl_add_u64 v[98:99], s[88:89], 0, v[98:99]
	s_andn2_saveexec_b64 s[0:1], s[0:1]
	v_lshlrev_b32_e32 v98, 14, v100
	v_lshl_add_u32 v98, v101, 10, v98
	v_ashrrev_i32_e32 v99, 31, v98
	v_lshl_add_u64 v[98:99], v[98:99], 2, s[16:17]
	s_or_b64 exec, exec, s[0:1]
	s_waitcnt vmcnt(13)
	v_fmac_f32_e32 v157, 0.5, v123
	v_lshl_add_u64 v[98:99], v[130:131], 2, v[98:99]
	global_store_dword v[98:99], v157, off
.LBB0_4753:
	s_waitcnt vmcnt(12)
	v_fmac_f32_e32 v158, 0.5, v107
	global_store_dword v[98:99], v158, off offset:128
.LBB0_4755:
	v_cmp_gt_i32_e32 vcc, s82, v176
	s_nop 1
	v_cndmask_b32_e32 v98, v179, v176, vcc
	v_mul_hi_i32 v99, v98, s80
	v_lshrrev_b32_e32 v100, 31, v99
	v_ashrrev_i32_e32 v99, 11, v99
	v_add_u32_e32 v100, v99, v100
	v_mad_i32_i24 v101, v100, s81, v98
	v_cmp_lt_i32_e64 s[0:1], 15, v101
	s_and_saveexec_b64 s[2:3], s[0:1]
	s_xor_b64 s[0:1], exec, s[2:3]
	v_lshlrev_b32_e32 v98, 12, v100
	v_add3_u32 v98, v98, v101, -16
	v_ashrrev_i32_e32 v99, 31, v98
	v_lshlrev_b64 v[98:99], 12, v[98:99]
	v_lshl_add_u64 v[98:99], s[88:89], 0, v[98:99]
	s_andn2_saveexec_b64 s[0:1], s[0:1]
	v_lshlrev_b32_e32 v98, 14, v100
	v_lshl_add_u32 v98, v101, 10, v98
	v_ashrrev_i32_e32 v99, 31, v98
	v_lshl_add_u64 v[98:99], v[98:99], 2, s[16:17]
	s_or_b64 exec, exec, s[0:1]
	s_waitcnt vmcnt(11)
	v_fmac_f32_e32 v159, 0.5, v124
	v_lshl_add_u64 v[98:99], v[130:131], 2, v[98:99]
	global_store_dword v[98:99], v159, off
.LBB0_4761:
	s_waitcnt vmcnt(10)
	v_fmac_f32_e32 v160, 0.5, v108
	global_store_dword v[98:99], v160, off offset:128
.LBB0_4763:
	v_cmp_gt_i32_e32 vcc, s82, v175
	s_nop 1
	v_cndmask_b32_e32 v98, v179, v175, vcc
	v_mul_hi_i32 v99, v98, s80
	v_lshrrev_b32_e32 v100, 31, v99
	v_ashrrev_i32_e32 v99, 11, v99
	v_add_u32_e32 v100, v99, v100
	v_mad_i32_i24 v101, v100, s81, v98
	v_cmp_lt_i32_e64 s[0:1], 15, v101
	s_and_saveexec_b64 s[2:3], s[0:1]
	s_xor_b64 s[0:1], exec, s[2:3]
	v_lshlrev_b32_e32 v98, 12, v100
	v_add3_u32 v98, v98, v101, -16
	v_ashrrev_i32_e32 v99, 31, v98
	v_lshlrev_b64 v[98:99], 12, v[98:99]
	v_lshl_add_u64 v[98:99], s[88:89], 0, v[98:99]
	s_andn2_saveexec_b64 s[0:1], s[0:1]
	v_lshlrev_b32_e32 v98, 14, v100
	v_lshl_add_u32 v98, v101, 10, v98
	v_ashrrev_i32_e32 v99, 31, v98
	v_lshl_add_u64 v[98:99], v[98:99], 2, s[16:17]
	s_or_b64 exec, exec, s[0:1]
	s_waitcnt vmcnt(9)
	v_fmac_f32_e32 v161, 0.5, v125
	v_lshl_add_u64 v[98:99], v[130:131], 2, v[98:99]
	global_store_dword v[98:99], v161, off
.LBB0_4769:
	s_waitcnt vmcnt(8)
	v_fmac_f32_e32 v162, 0.5, v109
	global_store_dword v[98:99], v162, off offset:128
.LBB0_4771:
	v_cmp_gt_i32_e32 vcc, s82, v174
	s_nop 1
	v_cndmask_b32_e32 v98, v179, v174, vcc
	v_mul_hi_i32 v99, v98, s80
	v_lshrrev_b32_e32 v100, 31, v99
	v_ashrrev_i32_e32 v99, 11, v99
	v_add_u32_e32 v100, v99, v100
	v_mad_i32_i24 v101, v100, s81, v98
	v_cmp_lt_i32_e64 s[0:1], 15, v101
	s_and_saveexec_b64 s[2:3], s[0:1]
	s_xor_b64 s[0:1], exec, s[2:3]
	v_lshlrev_b32_e32 v98, 12, v100
	v_add3_u32 v98, v98, v101, -16
	v_ashrrev_i32_e32 v99, 31, v98
	v_lshlrev_b64 v[98:99], 12, v[98:99]
	v_lshl_add_u64 v[98:99], s[88:89], 0, v[98:99]
	s_andn2_saveexec_b64 s[0:1], s[0:1]
	v_lshlrev_b32_e32 v98, 14, v100
	v_lshl_add_u32 v98, v101, 10, v98
	v_ashrrev_i32_e32 v99, 31, v98
	v_lshl_add_u64 v[98:99], v[98:99], 2, s[16:17]
	s_or_b64 exec, exec, s[0:1]
	s_waitcnt vmcnt(7)
	v_fmac_f32_e32 v163, 0.5, v126
	v_lshl_add_u64 v[98:99], v[130:131], 2, v[98:99]
	global_store_dword v[98:99], v163, off
.LBB0_4777:
	s_waitcnt vmcnt(6)
	v_fmac_f32_e32 v164, 0.5, v110
	global_store_dword v[98:99], v164, off offset:128
.LBB0_4779:
	v_cmp_gt_i32_e32 vcc, s82, v173
	s_nop 1
	v_cndmask_b32_e32 v98, v179, v173, vcc
	v_mul_hi_i32 v99, v98, s80
	v_lshrrev_b32_e32 v100, 31, v99
	v_ashrrev_i32_e32 v99, 11, v99
	v_add_u32_e32 v100, v99, v100
	v_mad_i32_i24 v101, v100, s81, v98
	v_cmp_lt_i32_e64 s[0:1], 15, v101
	s_and_saveexec_b64 s[2:3], s[0:1]
	s_xor_b64 s[0:1], exec, s[2:3]
	v_lshlrev_b32_e32 v98, 12, v100
	v_add3_u32 v98, v98, v101, -16
	v_ashrrev_i32_e32 v99, 31, v98
	v_lshlrev_b64 v[98:99], 12, v[98:99]
	v_lshl_add_u64 v[98:99], s[88:89], 0, v[98:99]
	s_andn2_saveexec_b64 s[0:1], s[0:1]
	v_lshlrev_b32_e32 v98, 14, v100
	v_lshl_add_u32 v98, v101, 10, v98
	v_ashrrev_i32_e32 v99, 31, v98
	v_lshl_add_u64 v[98:99], v[98:99], 2, s[16:17]
	s_or_b64 exec, exec, s[0:1]
	s_waitcnt vmcnt(5)
	v_fmac_f32_e32 v165, 0.5, v127
	v_lshl_add_u64 v[98:99], v[130:131], 2, v[98:99]
	global_store_dword v[98:99], v165, off
.LBB0_4785:
	s_waitcnt vmcnt(4)
	v_fmac_f32_e32 v166, 0.5, v111
	global_store_dword v[98:99], v166, off offset:128
.LBB0_4787:
	v_cmp_gt_i32_e32 vcc, s82, v172
	s_nop 1
	v_cndmask_b32_e32 v98, v179, v172, vcc
	v_mul_hi_i32 v99, v98, s80
	v_lshrrev_b32_e32 v100, 31, v99
	v_ashrrev_i32_e32 v99, 11, v99
	v_add_u32_e32 v100, v99, v100
	v_mad_i32_i24 v101, v100, s81, v98
	v_cmp_lt_i32_e64 s[0:1], 15, v101
	s_and_saveexec_b64 s[2:3], s[0:1]
	s_xor_b64 s[0:1], exec, s[2:3]
	v_lshlrev_b32_e32 v98, 12, v100
	v_add3_u32 v98, v98, v101, -16
	v_ashrrev_i32_e32 v99, 31, v98
	v_lshlrev_b64 v[98:99], 12, v[98:99]
	v_lshl_add_u64 v[98:99], s[88:89], 0, v[98:99]
	s_andn2_saveexec_b64 s[0:1], s[0:1]
	v_lshlrev_b32_e32 v98, 14, v100
	v_lshl_add_u32 v98, v101, 10, v98
	v_ashrrev_i32_e32 v99, 31, v98
	v_lshl_add_u64 v[98:99], v[98:99], 2, s[16:17]
	s_or_b64 exec, exec, s[0:1]
	s_waitcnt vmcnt(3)
	v_fmac_f32_e32 v167, 0.5, v128
	v_lshl_add_u64 v[98:99], v[130:131], 2, v[98:99]
	global_store_dword v[98:99], v167, off
.LBB0_4793:
	s_waitcnt vmcnt(2)
	v_fmac_f32_e32 v168, 0.5, v112
	global_store_dword v[98:99], v168, off offset:128
.LBB0_4795:
	v_cmp_gt_i32_e32 vcc, s82, v171
	s_nop 1
	v_cndmask_b32_e32 v98, v179, v171, vcc
	v_mul_hi_i32 v99, v98, s80
	v_lshrrev_b32_e32 v100, 31, v99
	v_ashrrev_i32_e32 v99, 11, v99
	v_add_u32_e32 v100, v99, v100
	v_mad_i32_i24 v101, v100, s81, v98
	v_cmp_lt_i32_e64 s[0:1], 15, v101
	s_and_saveexec_b64 s[2:3], s[0:1]
	s_xor_b64 s[0:1], exec, s[2:3]
	v_lshlrev_b32_e32 v98, 12, v100
	v_add3_u32 v98, v98, v101, -16
	v_ashrrev_i32_e32 v99, 31, v98
	v_lshlrev_b64 v[98:99], 12, v[98:99]
	v_lshl_add_u64 v[98:99], s[88:89], 0, v[98:99]
	s_andn2_saveexec_b64 s[0:1], s[0:1]
	v_lshlrev_b32_e32 v98, 14, v100
	v_lshl_add_u32 v98, v101, 10, v98
	v_ashrrev_i32_e32 v99, 31, v98
	v_lshl_add_u64 v[98:99], v[98:99], 2, s[16:17]
	s_or_b64 exec, exec, s[0:1]
	s_waitcnt vmcnt(1)
	v_fmac_f32_e32 v169, 0.5, v129
	v_lshl_add_u64 v[98:99], v[130:131], 2, v[98:99]
	global_store_dword v[98:99], v169, off
.LBB0_4801:
	s_waitcnt vmcnt(0)
	v_fmac_f32_e32 v170, 0.5, v113
	global_store_dword v[98:99], v170, off offset:128
.LBB0_4803:
	v_or_b32_e32 v188, 32, v134
	v_min_i32_e32 v98, 0x403f, v188
	v_mul_hi_i32 v99, v98, s80
	v_lshrrev_b32_e32 v100, 31, v99
	v_ashrrev_i32_e32 v99, 11, v99
	v_add_u32_e32 v100, v99, v100
	v_mad_i32_i24 v101, v100, s81, v98
	v_cmp_lt_i32_e32 vcc, 15, v101
	s_and_saveexec_b64 s[0:1], vcc
	s_xor_b64 s[0:1], exec, s[0:1]
	v_lshlrev_b32_e32 v98, 12, v100
	v_add3_u32 v98, v98, v101, -16
	v_ashrrev_i32_e32 v99, 31, v98
	v_lshlrev_b64 v[98:99], 12, v[98:99]
	v_lshl_add_u64 v[98:99], s[88:89], 0, v[98:99]
	s_andn2_saveexec_b64 s[0:1], s[0:1]
	v_lshlrev_b32_e32 v98, 14, v100
	v_lshl_add_u32 v98, v101, 10, v98
	v_ashrrev_i32_e32 v99, 31, v98
	v_lshl_add_u64 v[98:99], v[98:99], 2, s[16:17]
	s_or_b64 exec, exec, s[0:1]
	v_lshl_add_u64 v[98:99], v[130:131], 2, v[98:99]
	global_load_dword v100, v[98:99], off
	global_load_dword v101, v[98:99], off offset:128
	v_or_b32_e32 v187, 33, v134
	v_min_i32_e32 v98, 0x403f, v187
	v_mul_hi_i32 v99, v98, s80
	v_lshrrev_b32_e32 v102, 31, v99
	v_ashrrev_i32_e32 v99, 11, v99
	v_add_u32_e32 v102, v99, v102
	v_mad_i32_i24 v103, v102, s81, v98
	v_cmp_lt_i32_e32 vcc, 15, v103
	s_and_saveexec_b64 s[0:1], vcc
	s_xor_b64 s[0:1], exec, s[0:1]
	v_lshlrev_b32_e32 v98, 12, v102
	v_add3_u32 v98, v98, v103, -16
	v_ashrrev_i32_e32 v99, 31, v98
	v_lshlrev_b64 v[98:99], 12, v[98:99]
	v_lshl_add_u64 v[98:99], s[88:89], 0, v[98:99]
	s_andn2_saveexec_b64 s[0:1], s[0:1]
	v_lshlrev_b32_e32 v98, 14, v102
	v_lshl_add_u32 v98, v103, 10, v98
	v_ashrrev_i32_e32 v99, 31, v98
	v_lshl_add_u64 v[98:99], v[98:99], 2, s[16:17]
	s_or_b64 exec, exec, s[0:1]
	v_lshl_add_u64 v[98:99], v[130:131], 2, v[98:99]
	global_load_dword v102, v[98:99], off
	global_load_dword v103, v[98:99], off offset:128
	v_or_b32_e32 v186, 34, v134
	v_min_i32_e32 v98, 0x403f, v186
	v_mul_hi_i32 v99, v98, s80
	v_lshrrev_b32_e32 v104, 31, v99
	v_ashrrev_i32_e32 v99, 11, v99
	v_add_u32_e32 v104, v99, v104
	v_mad_i32_i24 v105, v104, s81, v98
	v_cmp_lt_i32_e32 vcc, 15, v105
	s_and_saveexec_b64 s[0:1], vcc
	s_xor_b64 s[0:1], exec, s[0:1]
	v_lshlrev_b32_e32 v98, 12, v104
	v_add3_u32 v98, v98, v105, -16
	v_ashrrev_i32_e32 v99, 31, v98
	v_lshlrev_b64 v[98:99], 12, v[98:99]
	v_lshl_add_u64 v[98:99], s[88:89], 0, v[98:99]
	s_andn2_saveexec_b64 s[0:1], s[0:1]
	v_lshlrev_b32_e32 v98, 14, v104
	v_lshl_add_u32 v98, v105, 10, v98
	v_ashrrev_i32_e32 v99, 31, v98
	v_lshl_add_u64 v[98:99], v[98:99], 2, s[16:17]
	s_or_b64 exec, exec, s[0:1]
	v_lshl_add_u64 v[98:99], v[130:131], 2, v[98:99]
	global_load_dword v104, v[98:99], off
	global_load_dword v105, v[98:99], off offset:128
	v_or_b32_e32 v185, 35, v134
	v_min_i32_e32 v98, 0x403f, v185
	v_mul_hi_i32 v99, v98, s80
	v_lshrrev_b32_e32 v106, 31, v99
	v_ashrrev_i32_e32 v99, 11, v99
	v_add_u32_e32 v106, v99, v106
	v_mad_i32_i24 v107, v106, s81, v98
	v_cmp_lt_i32_e32 vcc, 15, v107
	s_and_saveexec_b64 s[0:1], vcc
	s_xor_b64 s[0:1], exec, s[0:1]
	v_lshlrev_b32_e32 v98, 12, v106
	v_add3_u32 v98, v98, v107, -16
	v_ashrrev_i32_e32 v99, 31, v98
	v_lshlrev_b64 v[98:99], 12, v[98:99]
	v_lshl_add_u64 v[98:99], s[88:89], 0, v[98:99]
	s_andn2_saveexec_b64 s[0:1], s[0:1]
	v_lshlrev_b32_e32 v98, 14, v106
	v_lshl_add_u32 v98, v107, 10, v98
	v_ashrrev_i32_e32 v99, 31, v98
	v_lshl_add_u64 v[98:99], v[98:99], 2, s[16:17]
	s_or_b64 exec, exec, s[0:1]
	v_lshl_add_u64 v[98:99], v[130:131], 2, v[98:99]
	global_load_dword v106, v[98:99], off
	global_load_dword v107, v[98:99], off offset:128
	v_or_b32_e32 v184, 40, v134
	v_min_i32_e32 v98, 0x403f, v184
	v_mul_hi_i32 v99, v98, s80
	v_lshrrev_b32_e32 v108, 31, v99
	v_ashrrev_i32_e32 v99, 11, v99
	v_add_u32_e32 v108, v99, v108
	v_mad_i32_i24 v109, v108, s81, v98
	v_cmp_lt_i32_e32 vcc, 15, v109
	s_and_saveexec_b64 s[0:1], vcc
	s_xor_b64 s[0:1], exec, s[0:1]
	v_lshlrev_b32_e32 v98, 12, v108
	v_add3_u32 v98, v98, v109, -16
	v_ashrrev_i32_e32 v99, 31, v98
	v_lshlrev_b64 v[98:99], 12, v[98:99]
	v_lshl_add_u64 v[98:99], s[88:89], 0, v[98:99]
	s_andn2_saveexec_b64 s[0:1], s[0:1]
	v_lshlrev_b32_e32 v98, 14, v108
	v_lshl_add_u32 v98, v109, 10, v98
	v_ashrrev_i32_e32 v99, 31, v98
	v_lshl_add_u64 v[98:99], v[98:99], 2, s[16:17]
	s_or_b64 exec, exec, s[0:1]
	v_lshl_add_u64 v[98:99], v[130:131], 2, v[98:99]
	global_load_dword v108, v[98:99], off
	global_load_dword v109, v[98:99], off offset:128
	v_or_b32_e32 v183, 41, v134
	v_min_i32_e32 v98, 0x403f, v183
	v_mul_hi_i32 v99, v98, s80
	v_lshrrev_b32_e32 v110, 31, v99
	v_ashrrev_i32_e32 v99, 11, v99
	v_add_u32_e32 v110, v99, v110
	v_mad_i32_i24 v111, v110, s81, v98
	v_cmp_lt_i32_e32 vcc, 15, v111
	s_and_saveexec_b64 s[0:1], vcc
	s_xor_b64 s[0:1], exec, s[0:1]
	v_lshlrev_b32_e32 v98, 12, v110
	v_add3_u32 v98, v98, v111, -16
	v_ashrrev_i32_e32 v99, 31, v98
	v_lshlrev_b64 v[98:99], 12, v[98:99]
	v_lshl_add_u64 v[98:99], s[88:89], 0, v[98:99]
	s_andn2_saveexec_b64 s[0:1], s[0:1]
	v_lshlrev_b32_e32 v98, 14, v110
	v_lshl_add_u32 v98, v111, 10, v98
	v_ashrrev_i32_e32 v99, 31, v98
	v_lshl_add_u64 v[98:99], v[98:99], 2, s[16:17]
	s_or_b64 exec, exec, s[0:1]
	v_lshl_add_u64 v[98:99], v[130:131], 2, v[98:99]
	global_load_dword v110, v[98:99], off
	global_load_dword v111, v[98:99], off offset:128
	v_or_b32_e32 v182, 42, v134
	v_min_i32_e32 v98, 0x403f, v182
	v_mul_hi_i32 v99, v98, s80
	v_lshrrev_b32_e32 v112, 31, v99
	v_ashrrev_i32_e32 v99, 11, v99
	v_add_u32_e32 v112, v99, v112
	v_mad_i32_i24 v113, v112, s81, v98
	v_cmp_lt_i32_e32 vcc, 15, v113
	s_and_saveexec_b64 s[0:1], vcc
	s_xor_b64 s[0:1], exec, s[0:1]
	v_lshlrev_b32_e32 v98, 12, v112
	v_add3_u32 v98, v98, v113, -16
	v_ashrrev_i32_e32 v99, 31, v98
	v_lshlrev_b64 v[98:99], 12, v[98:99]
	v_lshl_add_u64 v[98:99], s[88:89], 0, v[98:99]
	s_andn2_saveexec_b64 s[0:1], s[0:1]
	v_lshlrev_b32_e32 v98, 14, v112
	v_lshl_add_u32 v98, v113, 10, v98
	v_ashrrev_i32_e32 v99, 31, v98
	v_lshl_add_u64 v[98:99], v[98:99], 2, s[16:17]
	s_or_b64 exec, exec, s[0:1]
	v_lshl_add_u64 v[98:99], v[130:131], 2, v[98:99]
	global_load_dword v112, v[98:99], off
	global_load_dword v113, v[98:99], off offset:128
	v_or_b32_e32 v181, 43, v134
	v_min_i32_e32 v98, 0x403f, v181
	v_mul_hi_i32 v99, v98, s80
	v_lshrrev_b32_e32 v114, 31, v99
	v_ashrrev_i32_e32 v99, 11, v99
	v_add_u32_e32 v114, v99, v114
	v_mad_i32_i24 v115, v114, s81, v98
	v_cmp_lt_i32_e32 vcc, 15, v115
	s_and_saveexec_b64 s[0:1], vcc
	s_xor_b64 s[0:1], exec, s[0:1]
	v_lshlrev_b32_e32 v98, 12, v114
	v_add3_u32 v98, v98, v115, -16
	v_ashrrev_i32_e32 v99, 31, v98
	v_lshlrev_b64 v[98:99], 12, v[98:99]
	v_lshl_add_u64 v[98:99], s[88:89], 0, v[98:99]
	s_andn2_saveexec_b64 s[0:1], s[0:1]
	v_lshlrev_b32_e32 v98, 14, v114
	v_lshl_add_u32 v98, v115, 10, v98
	v_ashrrev_i32_e32 v99, 31, v98
	v_lshl_add_u64 v[98:99], v[98:99], 2, s[16:17]
	s_or_b64 exec, exec, s[0:1]
	v_lshl_add_u64 v[98:99], v[130:131], 2, v[98:99]
	global_load_dword v114, v[98:99], off
	global_load_dword v115, v[98:99], off offset:128
	v_or_b32_e32 v180, 48, v134
	v_min_i32_e32 v98, 0x403f, v180
	v_mul_hi_i32 v99, v98, s80
	v_lshrrev_b32_e32 v116, 31, v99
	v_ashrrev_i32_e32 v99, 11, v99
	v_add_u32_e32 v116, v99, v116
	v_mad_i32_i24 v117, v116, s81, v98
	v_cmp_lt_i32_e32 vcc, 15, v117
	s_and_saveexec_b64 s[0:1], vcc
	s_xor_b64 s[0:1], exec, s[0:1]
	v_lshlrev_b32_e32 v98, 12, v116
	v_add3_u32 v98, v98, v117, -16
	v_ashrrev_i32_e32 v99, 31, v98
	v_lshlrev_b64 v[98:99], 12, v[98:99]
	v_lshl_add_u64 v[98:99], s[88:89], 0, v[98:99]
	s_andn2_saveexec_b64 s[0:1], s[0:1]
	v_lshlrev_b32_e32 v98, 14, v116
	v_lshl_add_u32 v98, v117, 10, v98
	v_ashrrev_i32_e32 v99, 31, v98
	v_lshl_add_u64 v[98:99], v[98:99], 2, s[16:17]
	s_or_b64 exec, exec, s[0:1]
	v_lshl_add_u64 v[98:99], v[130:131], 2, v[98:99]
	global_load_dword v116, v[98:99], off
	global_load_dword v117, v[98:99], off offset:128
	v_or_b32_e32 v177, 49, v134
	v_min_i32_e32 v98, 0x403f, v177
	v_mul_hi_i32 v99, v98, s80
	v_lshrrev_b32_e32 v118, 31, v99
	v_ashrrev_i32_e32 v99, 11, v99
	v_add_u32_e32 v118, v99, v118
	v_mad_i32_i24 v119, v118, s81, v98
	v_cmp_lt_i32_e32 vcc, 15, v119
	s_and_saveexec_b64 s[0:1], vcc
	s_xor_b64 s[0:1], exec, s[0:1]
	v_lshlrev_b32_e32 v98, 12, v118
	v_add3_u32 v98, v98, v119, -16
	v_ashrrev_i32_e32 v99, 31, v98
	v_lshlrev_b64 v[98:99], 12, v[98:99]
	v_lshl_add_u64 v[98:99], s[88:89], 0, v[98:99]
	s_andn2_saveexec_b64 s[0:1], s[0:1]
	v_lshlrev_b32_e32 v98, 14, v118
	v_lshl_add_u32 v98, v119, 10, v98
	v_ashrrev_i32_e32 v99, 31, v98
	v_lshl_add_u64 v[98:99], v[98:99], 2, s[16:17]
	s_or_b64 exec, exec, s[0:1]
	v_lshl_add_u64 v[98:99], v[130:131], 2, v[98:99]
	global_load_dword v118, v[98:99], off
	global_load_dword v119, v[98:99], off offset:128
	v_or_b32_e32 v176, 50, v134
	v_min_i32_e32 v98, 0x403f, v176
	v_mul_hi_i32 v99, v98, s80
	v_lshrrev_b32_e32 v120, 31, v99
	v_ashrrev_i32_e32 v99, 11, v99
	v_add_u32_e32 v120, v99, v120
	v_mad_i32_i24 v121, v120, s81, v98
	v_cmp_lt_i32_e32 vcc, 15, v121
	s_and_saveexec_b64 s[0:1], vcc
	s_xor_b64 s[0:1], exec, s[0:1]
	v_lshlrev_b32_e32 v98, 12, v120
	v_add3_u32 v98, v98, v121, -16
	v_ashrrev_i32_e32 v99, 31, v98
	v_lshlrev_b64 v[98:99], 12, v[98:99]
	v_lshl_add_u64 v[98:99], s[88:89], 0, v[98:99]
	s_andn2_saveexec_b64 s[0:1], s[0:1]
	v_lshlrev_b32_e32 v98, 14, v120
	v_lshl_add_u32 v98, v121, 10, v98
	v_ashrrev_i32_e32 v99, 31, v98
	v_lshl_add_u64 v[98:99], v[98:99], 2, s[16:17]
	s_or_b64 exec, exec, s[0:1]
	v_lshl_add_u64 v[98:99], v[130:131], 2, v[98:99]
	global_load_dword v120, v[98:99], off
	global_load_dword v121, v[98:99], off offset:128
	v_or_b32_e32 v175, 51, v134
	v_min_i32_e32 v98, 0x403f, v175
	v_mul_hi_i32 v99, v98, s80
	v_lshrrev_b32_e32 v122, 31, v99
	v_ashrrev_i32_e32 v99, 11, v99
	v_add_u32_e32 v122, v99, v122
	v_mad_i32_i24 v123, v122, s81, v98
	v_cmp_lt_i32_e32 vcc, 15, v123
	s_and_saveexec_b64 s[0:1], vcc
	s_xor_b64 s[0:1], exec, s[0:1]
	v_lshlrev_b32_e32 v98, 12, v122
	v_add3_u32 v98, v98, v123, -16
	v_ashrrev_i32_e32 v99, 31, v98
	v_lshlrev_b64 v[98:99], 12, v[98:99]
	v_lshl_add_u64 v[98:99], s[88:89], 0, v[98:99]
	s_andn2_saveexec_b64 s[0:1], s[0:1]
	v_lshlrev_b32_e32 v98, 14, v122
	v_lshl_add_u32 v98, v123, 10, v98
	v_ashrrev_i32_e32 v99, 31, v98
	v_lshl_add_u64 v[98:99], v[98:99], 2, s[16:17]
	s_or_b64 exec, exec, s[0:1]
	v_lshl_add_u64 v[98:99], v[130:131], 2, v[98:99]
	global_load_dword v122, v[98:99], off
	global_load_dword v123, v[98:99], off offset:128
	v_or_b32_e32 v174, 56, v134
	v_min_i32_e32 v98, 0x403f, v174
	v_mul_hi_i32 v99, v98, s80
	v_lshrrev_b32_e32 v124, 31, v99
	v_ashrrev_i32_e32 v99, 11, v99
	v_add_u32_e32 v124, v99, v124
	v_mad_i32_i24 v125, v124, s81, v98
	v_cmp_lt_i32_e32 vcc, 15, v125
	s_and_saveexec_b64 s[0:1], vcc
	s_xor_b64 s[0:1], exec, s[0:1]
	v_lshlrev_b32_e32 v98, 12, v124
	v_add3_u32 v98, v98, v125, -16
	v_ashrrev_i32_e32 v99, 31, v98
	v_lshlrev_b64 v[98:99], 12, v[98:99]
	v_lshl_add_u64 v[98:99], s[88:89], 0, v[98:99]
	s_andn2_saveexec_b64 s[0:1], s[0:1]
	v_lshlrev_b32_e32 v98, 14, v124
	v_lshl_add_u32 v98, v125, 10, v98
	v_ashrrev_i32_e32 v99, 31, v98
	v_lshl_add_u64 v[98:99], v[98:99], 2, s[16:17]
	s_or_b64 exec, exec, s[0:1]
	v_lshl_add_u64 v[98:99], v[130:131], 2, v[98:99]
	global_load_dword v124, v[98:99], off
	global_load_dword v125, v[98:99], off offset:128
	v_or_b32_e32 v173, 57, v134
	v_min_i32_e32 v98, 0x403f, v173
	v_mul_hi_i32 v99, v98, s80
	v_lshrrev_b32_e32 v126, 31, v99
	v_ashrrev_i32_e32 v99, 11, v99
	v_add_u32_e32 v126, v99, v126
	v_mad_i32_i24 v127, v126, s81, v98
	v_cmp_lt_i32_e32 vcc, 15, v127
	s_and_saveexec_b64 s[0:1], vcc
	s_xor_b64 s[0:1], exec, s[0:1]
	v_lshlrev_b32_e32 v98, 12, v126
	v_add3_u32 v98, v98, v127, -16
	v_ashrrev_i32_e32 v99, 31, v98
	v_lshlrev_b64 v[98:99], 12, v[98:99]
	v_lshl_add_u64 v[98:99], s[88:89], 0, v[98:99]
	s_andn2_saveexec_b64 s[0:1], s[0:1]
	v_lshlrev_b32_e32 v98, 14, v126
	v_lshl_add_u32 v98, v127, 10, v98
	v_ashrrev_i32_e32 v99, 31, v98
	v_lshl_add_u64 v[98:99], v[98:99], 2, s[16:17]
	s_or_b64 exec, exec, s[0:1]
	v_lshl_add_u64 v[98:99], v[130:131], 2, v[98:99]
	global_load_dword v128, v[98:99], off
	global_load_dword v129, v[98:99], off offset:128
	v_or_b32_e32 v172, 58, v134
	v_min_i32_e32 v98, 0x403f, v172
	v_mul_hi_i32 v99, v98, s80
	v_lshrrev_b32_e32 v126, 31, v99
	v_ashrrev_i32_e32 v99, 11, v99
	v_add_u32_e32 v126, v99, v126
	v_mad_i32_i24 v127, v126, s81, v98
	v_cmp_lt_i32_e32 vcc, 15, v127
	s_and_saveexec_b64 s[0:1], vcc
	s_xor_b64 s[0:1], exec, s[0:1]
	v_lshlrev_b32_e32 v98, 12, v126
	v_add3_u32 v98, v98, v127, -16
	v_ashrrev_i32_e32 v99, 31, v98
	v_lshlrev_b64 v[98:99], 12, v[98:99]
	v_lshl_add_u64 v[98:99], s[88:89], 0, v[98:99]
	s_andn2_saveexec_b64 s[0:1], s[0:1]
	v_lshlrev_b32_e32 v98, 14, v126
	v_lshl_add_u32 v98, v127, 10, v98
	v_ashrrev_i32_e32 v99, 31, v98
	v_lshl_add_u64 v[98:99], v[98:99], 2, s[16:17]
	s_or_b64 exec, exec, s[0:1]
	v_lshl_add_u64 v[98:99], v[130:131], 2, v[98:99]
	global_load_dword v132, v[98:99], off
	global_load_dword v133, v[98:99], off offset:128
	v_or_b32_e32 v171, 59, v134
	v_min_i32_e32 v98, 0x403f, v171
	v_mul_hi_i32 v99, v98, s80
	v_lshrrev_b32_e32 v126, 31, v99
	v_ashrrev_i32_e32 v99, 11, v99
	v_add_u32_e32 v126, v99, v126
	v_mad_i32_i24 v127, v126, s81, v98
	v_cmp_lt_i32_e32 vcc, 15, v127
	s_and_saveexec_b64 s[0:1], vcc
	s_xor_b64 s[0:1], exec, s[0:1]
	v_lshlrev_b32_e32 v98, 12, v126
	v_add3_u32 v98, v98, v127, -16
	v_ashrrev_i32_e32 v99, 31, v98
	v_lshlrev_b64 v[98:99], 12, v[98:99]
	v_lshl_add_u64 v[98:99], s[88:89], 0, v[98:99]
	s_andn2_saveexec_b64 s[0:1], s[0:1]
	v_lshlrev_b32_e32 v98, 14, v126
	v_lshl_add_u32 v98, v127, 10, v98
	v_ashrrev_i32_e32 v99, 31, v98
	v_lshl_add_u64 v[98:99], v[98:99], 2, s[16:17]
	s_or_b64 exec, exec, s[0:1]
	v_lshl_add_u64 v[98:99], v[130:131], 2, v[98:99]
	global_load_dword v126, v[98:99], off
	global_load_dword v127, v[98:99], off offset:128
	v_cmp_gt_i32_e32 vcc, s82, v188
	s_nop 1
	v_cndmask_b32_e32 v98, v179, v188, vcc
	v_mul_hi_i32 v99, v98, s80
	v_lshrrev_b32_e32 v188, 31, v99
	v_ashrrev_i32_e32 v99, 11, v99
	v_add_u32_e32 v188, v99, v188
	v_mad_i32_i24 v189, v188, s81, v98
	v_cmp_lt_i32_e64 s[0:1], 15, v189
	s_and_saveexec_b64 s[2:3], s[0:1]
	s_xor_b64 s[0:1], exec, s[2:3]
	v_lshlrev_b32_e32 v98, 12, v188
	v_add3_u32 v98, v98, v189, -16
	v_ashrrev_i32_e32 v99, 31, v98
	v_lshlrev_b64 v[98:99], 12, v[98:99]
	v_lshl_add_u64 v[98:99], s[88:89], 0, v[98:99]
	s_andn2_saveexec_b64 s[0:1], s[0:1]
	v_lshlrev_b32_e32 v98, 14, v188
	v_lshl_add_u32 v98, v189, 10, v98
	v_ashrrev_i32_e32 v99, 31, v98
	v_lshl_add_u64 v[98:99], v[98:99], 2, s[16:17]
	s_or_b64 exec, exec, s[0:1]
	s_waitcnt vmcnt(31)
	v_fmac_f32_e32 v100, 0.5, v82
	v_lshl_add_u64 v[98:99], v[130:131], 2, v[98:99]
	global_store_dword v[98:99], v100, off
.LBB0_4873:
	s_waitcnt vmcnt(30)
	v_fmac_f32_e32 v101, 0.5, v66
	global_store_dword v[98:99], v101, off offset:128
.LBB0_4875:
	v_cmp_gt_i32_e32 vcc, s82, v187
	s_nop 1
	v_cndmask_b32_e32 v82, v179, v187, vcc
	v_mul_hi_i32 v66, v82, s80
	v_lshrrev_b32_e32 v98, 31, v66
	v_ashrrev_i32_e32 v66, 11, v66
	v_add_u32_e32 v66, v66, v98
	v_mad_i32_i24 v82, v66, s81, v82
	v_cmp_lt_i32_e64 s[0:1], 15, v82
	s_and_saveexec_b64 s[2:3], s[0:1]
	s_xor_b64 s[0:1], exec, s[2:3]
	v_lshlrev_b32_e32 v66, 12, v66
	v_add3_u32 v98, v66, v82, -16
	v_ashrrev_i32_e32 v99, 31, v98
	v_lshlrev_b64 v[98:99], 12, v[98:99]
	v_lshl_add_u64 v[98:99], s[88:89], 0, v[98:99]
	s_andn2_saveexec_b64 s[0:1], s[0:1]
	v_lshlrev_b32_e32 v66, 14, v66
	v_lshl_add_u32 v98, v82, 10, v66
	v_ashrrev_i32_e32 v99, 31, v98
	v_lshl_add_u64 v[98:99], v[98:99], 2, s[16:17]
	s_or_b64 exec, exec, s[0:1]
	s_waitcnt vmcnt(29)
	v_fmac_f32_e32 v102, 0.5, v83
	v_lshl_add_u64 v[82:83], v[130:131], 2, v[98:99]
	global_store_dword v[82:83], v102, off
.LBB0_4881:
	s_waitcnt vmcnt(28)
	v_fmac_f32_e32 v103, 0.5, v67
	global_store_dword v[82:83], v103, off offset:128
.LBB0_4883:
	v_cmp_gt_i32_e32 vcc, s82, v186
	s_nop 1
	v_cndmask_b32_e32 v66, v179, v186, vcc
	v_mul_hi_i32 v67, v66, s80
	v_lshrrev_b32_e32 v82, 31, v67
	v_ashrrev_i32_e32 v67, 11, v67
	v_add_u32_e32 v82, v67, v82
	v_mad_i32_i24 v83, v82, s81, v66
	v_cmp_lt_i32_e64 s[0:1], 15, v83
	s_and_saveexec_b64 s[2:3], s[0:1]
	s_xor_b64 s[0:1], exec, s[2:3]
	v_lshlrev_b32_e32 v66, 12, v82
	v_add3_u32 v66, v66, v83, -16
	v_ashrrev_i32_e32 v67, 31, v66
	v_lshlrev_b64 v[66:67], 12, v[66:67]
	v_lshl_add_u64 v[66:67], s[88:89], 0, v[66:67]
	s_andn2_saveexec_b64 s[0:1], s[0:1]
	v_lshlrev_b32_e32 v66, 14, v82
	v_lshl_add_u32 v66, v83, 10, v66
	v_ashrrev_i32_e32 v67, 31, v66
	v_lshl_add_u64 v[66:67], v[66:67], 2, s[16:17]
	s_or_b64 exec, exec, s[0:1]
	s_waitcnt vmcnt(27)
	v_fmac_f32_e32 v104, 0.5, v84
	v_lshl_add_u64 v[66:67], v[130:131], 2, v[66:67]
	global_store_dword v[66:67], v104, off
.LBB0_4889:
	s_waitcnt vmcnt(26)
	v_fmac_f32_e32 v105, 0.5, v68
	global_store_dword v[66:67], v105, off offset:128
.LBB0_4891:
	v_cmp_gt_i32_e32 vcc, s82, v185
	s_nop 1
	v_cndmask_b32_e32 v66, v179, v185, vcc
	v_mul_hi_i32 v67, v66, s80
	v_lshrrev_b32_e32 v68, 31, v67
	v_ashrrev_i32_e32 v67, 11, v67
	v_add_u32_e32 v68, v67, v68
	v_mad_i32_i24 v82, v68, s81, v66
	v_cmp_lt_i32_e64 s[0:1], 15, v82
	s_and_saveexec_b64 s[2:3], s[0:1]
	s_xor_b64 s[0:1], exec, s[2:3]
	v_lshlrev_b32_e32 v66, 12, v68
	v_add3_u32 v66, v66, v82, -16
	v_ashrrev_i32_e32 v67, 31, v66
	v_lshlrev_b64 v[66:67], 12, v[66:67]
	v_lshl_add_u64 v[66:67], s[88:89], 0, v[66:67]
	s_andn2_saveexec_b64 s[0:1], s[0:1]
	v_lshlrev_b32_e32 v66, 14, v68
	v_lshl_add_u32 v66, v82, 10, v66
	v_ashrrev_i32_e32 v67, 31, v66
	v_lshl_add_u64 v[66:67], v[66:67], 2, s[16:17]
	s_or_b64 exec, exec, s[0:1]
	s_waitcnt vmcnt(25)
	v_fmac_f32_e32 v106, 0.5, v85
	v_lshl_add_u64 v[66:67], v[130:131], 2, v[66:67]
	global_store_dword v[66:67], v106, off
.LBB0_4897:
	s_waitcnt vmcnt(24)
	v_fmac_f32_e32 v107, 0.5, v69
	global_store_dword v[66:67], v107, off offset:128
.LBB0_4899:
	v_cmp_gt_i32_e32 vcc, s82, v184
	s_nop 1
	v_cndmask_b32_e32 v66, v179, v184, vcc
	v_mul_hi_i32 v67, v66, s80
	v_lshrrev_b32_e32 v68, 31, v67
	v_ashrrev_i32_e32 v67, 11, v67
	v_add_u32_e32 v68, v67, v68
	v_mad_i32_i24 v69, v68, s81, v66
	v_cmp_lt_i32_e64 s[0:1], 15, v69
	s_and_saveexec_b64 s[2:3], s[0:1]
	s_xor_b64 s[0:1], exec, s[2:3]
	v_lshlrev_b32_e32 v66, 12, v68
	v_add3_u32 v66, v66, v69, -16
	v_ashrrev_i32_e32 v67, 31, v66
	v_lshlrev_b64 v[66:67], 12, v[66:67]
	v_lshl_add_u64 v[66:67], s[88:89], 0, v[66:67]
	s_andn2_saveexec_b64 s[0:1], s[0:1]
	v_lshlrev_b32_e32 v66, 14, v68
	v_lshl_add_u32 v66, v69, 10, v66
	v_ashrrev_i32_e32 v67, 31, v66
	v_lshl_add_u64 v[66:67], v[66:67], 2, s[16:17]
	s_or_b64 exec, exec, s[0:1]
	s_waitcnt vmcnt(23)
	v_fmac_f32_e32 v108, 0.5, v86
	v_lshl_add_u64 v[66:67], v[130:131], 2, v[66:67]
	global_store_dword v[66:67], v108, off
.LBB0_4905:
	s_waitcnt vmcnt(22)
	v_fmac_f32_e32 v109, 0.5, v70
	global_store_dword v[66:67], v109, off offset:128
.LBB0_4907:
	v_cmp_gt_i32_e32 vcc, s82, v183
	s_nop 1
	v_cndmask_b32_e32 v66, v179, v183, vcc
	v_mul_hi_i32 v67, v66, s80
	v_lshrrev_b32_e32 v68, 31, v67
	v_ashrrev_i32_e32 v67, 11, v67
	v_add_u32_e32 v68, v67, v68
	v_mad_i32_i24 v69, v68, s81, v66
	v_cmp_lt_i32_e64 s[0:1], 15, v69
	s_and_saveexec_b64 s[2:3], s[0:1]
	s_xor_b64 s[0:1], exec, s[2:3]
	v_lshlrev_b32_e32 v66, 12, v68
	v_add3_u32 v66, v66, v69, -16
	v_ashrrev_i32_e32 v67, 31, v66
	v_lshlrev_b64 v[66:67], 12, v[66:67]
	v_lshl_add_u64 v[66:67], s[88:89], 0, v[66:67]
	s_andn2_saveexec_b64 s[0:1], s[0:1]
	v_lshlrev_b32_e32 v66, 14, v68
	v_lshl_add_u32 v66, v69, 10, v66
	v_ashrrev_i32_e32 v67, 31, v66
	v_lshl_add_u64 v[66:67], v[66:67], 2, s[16:17]
	s_or_b64 exec, exec, s[0:1]
	s_waitcnt vmcnt(21)
	v_fmac_f32_e32 v110, 0.5, v87
	v_lshl_add_u64 v[66:67], v[130:131], 2, v[66:67]
	global_store_dword v[66:67], v110, off
.LBB0_4913:
	s_waitcnt vmcnt(20)
	v_fmac_f32_e32 v111, 0.5, v71
	global_store_dword v[66:67], v111, off offset:128
.LBB0_4915:
	v_cmp_gt_i32_e32 vcc, s82, v182
	s_nop 1
	v_cndmask_b32_e32 v66, v179, v182, vcc
	v_mul_hi_i32 v67, v66, s80
	v_lshrrev_b32_e32 v68, 31, v67
	v_ashrrev_i32_e32 v67, 11, v67
	v_add_u32_e32 v68, v67, v68
	v_mad_i32_i24 v69, v68, s81, v66
	v_cmp_lt_i32_e64 s[0:1], 15, v69
	s_and_saveexec_b64 s[2:3], s[0:1]
	s_xor_b64 s[0:1], exec, s[2:3]
	v_lshlrev_b32_e32 v66, 12, v68
	v_add3_u32 v66, v66, v69, -16
	v_ashrrev_i32_e32 v67, 31, v66
	v_lshlrev_b64 v[66:67], 12, v[66:67]
	v_lshl_add_u64 v[66:67], s[88:89], 0, v[66:67]
	s_andn2_saveexec_b64 s[0:1], s[0:1]
	v_lshlrev_b32_e32 v66, 14, v68
	v_lshl_add_u32 v66, v69, 10, v66
	v_ashrrev_i32_e32 v67, 31, v66
	v_lshl_add_u64 v[66:67], v[66:67], 2, s[16:17]
	s_or_b64 exec, exec, s[0:1]
	s_waitcnt vmcnt(19)
	v_fmac_f32_e32 v112, 0.5, v88
	v_lshl_add_u64 v[66:67], v[130:131], 2, v[66:67]
	global_store_dword v[66:67], v112, off
.LBB0_4921:
	s_waitcnt vmcnt(18)
	v_fmac_f32_e32 v113, 0.5, v72
	global_store_dword v[66:67], v113, off offset:128
.LBB0_4923:
	v_cmp_gt_i32_e32 vcc, s82, v181
	s_nop 1
	v_cndmask_b32_e32 v66, v179, v181, vcc
	v_mul_hi_i32 v67, v66, s80
	v_lshrrev_b32_e32 v68, 31, v67
	v_ashrrev_i32_e32 v67, 11, v67
	v_add_u32_e32 v68, v67, v68
	v_mad_i32_i24 v69, v68, s81, v66
	v_cmp_lt_i32_e64 s[0:1], 15, v69
	s_and_saveexec_b64 s[2:3], s[0:1]
	s_xor_b64 s[0:1], exec, s[2:3]
	v_lshlrev_b32_e32 v66, 12, v68
	v_add3_u32 v66, v66, v69, -16
	v_ashrrev_i32_e32 v67, 31, v66
	v_lshlrev_b64 v[66:67], 12, v[66:67]
	v_lshl_add_u64 v[66:67], s[88:89], 0, v[66:67]
	s_andn2_saveexec_b64 s[0:1], s[0:1]
	v_lshlrev_b32_e32 v66, 14, v68
	v_lshl_add_u32 v66, v69, 10, v66
	v_ashrrev_i32_e32 v67, 31, v66
	v_lshl_add_u64 v[66:67], v[66:67], 2, s[16:17]
	s_or_b64 exec, exec, s[0:1]
	s_waitcnt vmcnt(17)
	v_fmac_f32_e32 v114, 0.5, v89
	v_lshl_add_u64 v[66:67], v[130:131], 2, v[66:67]
	global_store_dword v[66:67], v114, off
.LBB0_4929:
	s_waitcnt vmcnt(16)
	v_fmac_f32_e32 v115, 0.5, v73
	global_store_dword v[66:67], v115, off offset:128
.LBB0_4931:
	v_cmp_gt_i32_e32 vcc, s82, v180
	s_nop 1
	v_cndmask_b32_e32 v66, v179, v180, vcc
	v_mul_hi_i32 v67, v66, s80
	v_lshrrev_b32_e32 v68, 31, v67
	v_ashrrev_i32_e32 v67, 11, v67
	v_add_u32_e32 v68, v67, v68
	v_mad_i32_i24 v69, v68, s81, v66
	v_cmp_lt_i32_e64 s[0:1], 15, v69
	s_and_saveexec_b64 s[2:3], s[0:1]
	s_xor_b64 s[0:1], exec, s[2:3]
	v_lshlrev_b32_e32 v66, 12, v68
	v_add3_u32 v66, v66, v69, -16
	v_ashrrev_i32_e32 v67, 31, v66
	v_lshlrev_b64 v[66:67], 12, v[66:67]
	v_lshl_add_u64 v[66:67], s[88:89], 0, v[66:67]
	s_andn2_saveexec_b64 s[0:1], s[0:1]
	v_lshlrev_b32_e32 v66, 14, v68
	v_lshl_add_u32 v66, v69, 10, v66
	v_ashrrev_i32_e32 v67, 31, v66
	v_lshl_add_u64 v[66:67], v[66:67], 2, s[16:17]
	s_or_b64 exec, exec, s[0:1]
	s_waitcnt vmcnt(15)
	v_fmac_f32_e32 v116, 0.5, v90
	v_lshl_add_u64 v[66:67], v[130:131], 2, v[66:67]
	global_store_dword v[66:67], v116, off
.LBB0_4937:
	s_waitcnt vmcnt(14)
	v_fmac_f32_e32 v117, 0.5, v74
	global_store_dword v[66:67], v117, off offset:128
.LBB0_4939:
	v_cmp_gt_i32_e32 vcc, s82, v177
	s_nop 1
	v_cndmask_b32_e32 v66, v179, v177, vcc
	v_mul_hi_i32 v67, v66, s80
	v_lshrrev_b32_e32 v68, 31, v67
	v_ashrrev_i32_e32 v67, 11, v67
	v_add_u32_e32 v68, v67, v68
	v_mad_i32_i24 v69, v68, s81, v66
	v_cmp_lt_i32_e64 s[0:1], 15, v69
	s_and_saveexec_b64 s[2:3], s[0:1]
	s_xor_b64 s[0:1], exec, s[2:3]
	v_lshlrev_b32_e32 v66, 12, v68
	v_add3_u32 v66, v66, v69, -16
	v_ashrrev_i32_e32 v67, 31, v66
	v_lshlrev_b64 v[66:67], 12, v[66:67]
	v_lshl_add_u64 v[66:67], s[88:89], 0, v[66:67]
	s_andn2_saveexec_b64 s[0:1], s[0:1]
	v_lshlrev_b32_e32 v66, 14, v68
	v_lshl_add_u32 v66, v69, 10, v66
	v_ashrrev_i32_e32 v67, 31, v66
	v_lshl_add_u64 v[66:67], v[66:67], 2, s[16:17]
	s_or_b64 exec, exec, s[0:1]
	s_waitcnt vmcnt(13)
	v_fmac_f32_e32 v118, 0.5, v91
	v_lshl_add_u64 v[66:67], v[130:131], 2, v[66:67]
	global_store_dword v[66:67], v118, off
.LBB0_4945:
	s_waitcnt vmcnt(12)
	v_fmac_f32_e32 v119, 0.5, v75
	global_store_dword v[66:67], v119, off offset:128
.LBB0_4947:
	v_cmp_gt_i32_e32 vcc, s82, v176
	s_nop 1
	v_cndmask_b32_e32 v66, v179, v176, vcc
	v_mul_hi_i32 v67, v66, s80
	v_lshrrev_b32_e32 v68, 31, v67
	v_ashrrev_i32_e32 v67, 11, v67
	v_add_u32_e32 v68, v67, v68
	v_mad_i32_i24 v69, v68, s81, v66
	v_cmp_lt_i32_e64 s[0:1], 15, v69
	s_and_saveexec_b64 s[2:3], s[0:1]
	s_xor_b64 s[0:1], exec, s[2:3]
	v_lshlrev_b32_e32 v66, 12, v68
	v_add3_u32 v66, v66, v69, -16
	v_ashrrev_i32_e32 v67, 31, v66
	v_lshlrev_b64 v[66:67], 12, v[66:67]
	v_lshl_add_u64 v[66:67], s[88:89], 0, v[66:67]
	s_andn2_saveexec_b64 s[0:1], s[0:1]
	v_lshlrev_b32_e32 v66, 14, v68
	v_lshl_add_u32 v66, v69, 10, v66
	v_ashrrev_i32_e32 v67, 31, v66
	v_lshl_add_u64 v[66:67], v[66:67], 2, s[16:17]
	s_or_b64 exec, exec, s[0:1]
	s_waitcnt vmcnt(11)
	v_fmac_f32_e32 v120, 0.5, v92
	v_lshl_add_u64 v[66:67], v[130:131], 2, v[66:67]
	global_store_dword v[66:67], v120, off
.LBB0_4953:
	s_waitcnt vmcnt(10)
	v_fmac_f32_e32 v121, 0.5, v76
	global_store_dword v[66:67], v121, off offset:128
.LBB0_4955:
	v_cmp_gt_i32_e32 vcc, s82, v175
	s_nop 1
	v_cndmask_b32_e32 v66, v179, v175, vcc
	v_mul_hi_i32 v67, v66, s80
	v_lshrrev_b32_e32 v68, 31, v67
	v_ashrrev_i32_e32 v67, 11, v67
	v_add_u32_e32 v68, v67, v68
	v_mad_i32_i24 v69, v68, s81, v66
	v_cmp_lt_i32_e64 s[0:1], 15, v69
	s_and_saveexec_b64 s[2:3], s[0:1]
	s_xor_b64 s[0:1], exec, s[2:3]
	v_lshlrev_b32_e32 v66, 12, v68
	v_add3_u32 v66, v66, v69, -16
	v_ashrrev_i32_e32 v67, 31, v66
	v_lshlrev_b64 v[66:67], 12, v[66:67]
	v_lshl_add_u64 v[66:67], s[88:89], 0, v[66:67]
	s_andn2_saveexec_b64 s[0:1], s[0:1]
	v_lshlrev_b32_e32 v66, 14, v68
	v_lshl_add_u32 v66, v69, 10, v66
	v_ashrrev_i32_e32 v67, 31, v66
	v_lshl_add_u64 v[66:67], v[66:67], 2, s[16:17]
	s_or_b64 exec, exec, s[0:1]
	s_waitcnt vmcnt(9)
	v_fmac_f32_e32 v122, 0.5, v93
	v_lshl_add_u64 v[66:67], v[130:131], 2, v[66:67]
	global_store_dword v[66:67], v122, off
.LBB0_4961:
	s_waitcnt vmcnt(8)
	v_fmac_f32_e32 v123, 0.5, v77
	global_store_dword v[66:67], v123, off offset:128
.LBB0_4963:
	v_cmp_gt_i32_e32 vcc, s82, v174
	s_nop 1
	v_cndmask_b32_e32 v66, v179, v174, vcc
	v_mul_hi_i32 v67, v66, s80
	v_lshrrev_b32_e32 v68, 31, v67
	v_ashrrev_i32_e32 v67, 11, v67
	v_add_u32_e32 v68, v67, v68
	v_mad_i32_i24 v69, v68, s81, v66
	v_cmp_lt_i32_e64 s[0:1], 15, v69
	s_and_saveexec_b64 s[2:3], s[0:1]
	s_xor_b64 s[0:1], exec, s[2:3]
	v_lshlrev_b32_e32 v66, 12, v68
	v_add3_u32 v66, v66, v69, -16
	v_ashrrev_i32_e32 v67, 31, v66
	v_lshlrev_b64 v[66:67], 12, v[66:67]
	v_lshl_add_u64 v[66:67], s[88:89], 0, v[66:67]
	s_andn2_saveexec_b64 s[0:1], s[0:1]
	v_lshlrev_b32_e32 v66, 14, v68
	v_lshl_add_u32 v66, v69, 10, v66
	v_ashrrev_i32_e32 v67, 31, v66
	v_lshl_add_u64 v[66:67], v[66:67], 2, s[16:17]
	s_or_b64 exec, exec, s[0:1]
	s_waitcnt vmcnt(7)
	v_fmac_f32_e32 v124, 0.5, v94
	v_lshl_add_u64 v[66:67], v[130:131], 2, v[66:67]
	global_store_dword v[66:67], v124, off
.LBB0_4969:
	s_waitcnt vmcnt(6)
	v_fmac_f32_e32 v125, 0.5, v78
	global_store_dword v[66:67], v125, off offset:128
.LBB0_4971:
	v_cmp_gt_i32_e32 vcc, s82, v173
	s_nop 1
	v_cndmask_b32_e32 v66, v179, v173, vcc
	v_mul_hi_i32 v67, v66, s80
	v_lshrrev_b32_e32 v68, 31, v67
	v_ashrrev_i32_e32 v67, 11, v67
	v_add_u32_e32 v68, v67, v68
	v_mad_i32_i24 v69, v68, s81, v66
	v_cmp_lt_i32_e64 s[0:1], 15, v69
	s_and_saveexec_b64 s[2:3], s[0:1]
	s_xor_b64 s[0:1], exec, s[2:3]
	v_lshlrev_b32_e32 v66, 12, v68
	v_add3_u32 v66, v66, v69, -16
	v_ashrrev_i32_e32 v67, 31, v66
	v_lshlrev_b64 v[66:67], 12, v[66:67]
	v_lshl_add_u64 v[66:67], s[88:89], 0, v[66:67]
	s_andn2_saveexec_b64 s[0:1], s[0:1]
	v_lshlrev_b32_e32 v66, 14, v68
	v_lshl_add_u32 v66, v69, 10, v66
	v_ashrrev_i32_e32 v67, 31, v66
	v_lshl_add_u64 v[66:67], v[66:67], 2, s[16:17]
	s_or_b64 exec, exec, s[0:1]
	s_waitcnt vmcnt(5)
	v_fmac_f32_e32 v128, 0.5, v95
	v_lshl_add_u64 v[66:67], v[130:131], 2, v[66:67]
	global_store_dword v[66:67], v128, off
.LBB0_4977:
	s_waitcnt vmcnt(4)
	v_fmac_f32_e32 v129, 0.5, v79
	global_store_dword v[66:67], v129, off offset:128
.LBB0_4979:
	v_cmp_gt_i32_e32 vcc, s82, v172
	s_nop 1
	v_cndmask_b32_e32 v66, v179, v172, vcc
	v_mul_hi_i32 v67, v66, s80
	v_lshrrev_b32_e32 v68, 31, v67
	v_ashrrev_i32_e32 v67, 11, v67
	v_add_u32_e32 v68, v67, v68
	v_mad_i32_i24 v69, v68, s81, v66
	v_cmp_lt_i32_e64 s[0:1], 15, v69
	s_and_saveexec_b64 s[2:3], s[0:1]
	s_xor_b64 s[0:1], exec, s[2:3]
	v_lshlrev_b32_e32 v66, 12, v68
	v_add3_u32 v66, v66, v69, -16
	v_ashrrev_i32_e32 v67, 31, v66
	v_lshlrev_b64 v[66:67], 12, v[66:67]
	v_lshl_add_u64 v[66:67], s[88:89], 0, v[66:67]
	s_andn2_saveexec_b64 s[0:1], s[0:1]
	v_lshlrev_b32_e32 v66, 14, v68
	v_lshl_add_u32 v66, v69, 10, v66
	v_ashrrev_i32_e32 v67, 31, v66
	v_lshl_add_u64 v[66:67], v[66:67], 2, s[16:17]
	s_or_b64 exec, exec, s[0:1]
	s_waitcnt vmcnt(3)
	v_fmac_f32_e32 v132, 0.5, v96
	v_lshl_add_u64 v[66:67], v[130:131], 2, v[66:67]
	global_store_dword v[66:67], v132, off
.LBB0_4985:
	s_waitcnt vmcnt(2)
	v_fmac_f32_e32 v133, 0.5, v80
	global_store_dword v[66:67], v133, off offset:128
.LBB0_4987:
	v_cmp_gt_i32_e32 vcc, s82, v171
	s_nop 1
	v_cndmask_b32_e32 v66, v179, v171, vcc
	v_mul_hi_i32 v67, v66, s80
	v_lshrrev_b32_e32 v68, 31, v67
	v_ashrrev_i32_e32 v67, 11, v67
	v_add_u32_e32 v68, v67, v68
	v_mad_i32_i24 v69, v68, s81, v66
	v_cmp_lt_i32_e64 s[0:1], 15, v69
	s_and_saveexec_b64 s[2:3], s[0:1]
	s_xor_b64 s[0:1], exec, s[2:3]
	v_lshlrev_b32_e32 v66, 12, v68
	v_add3_u32 v66, v66, v69, -16
	v_ashrrev_i32_e32 v67, 31, v66
	v_lshlrev_b64 v[66:67], 12, v[66:67]
	v_lshl_add_u64 v[66:67], s[88:89], 0, v[66:67]
	s_andn2_saveexec_b64 s[0:1], s[0:1]
	v_lshlrev_b32_e32 v66, 14, v68
	v_lshl_add_u32 v66, v69, 10, v66
	v_ashrrev_i32_e32 v67, 31, v66
	v_lshl_add_u64 v[66:67], v[66:67], 2, s[16:17]
	s_or_b64 exec, exec, s[0:1]
	s_waitcnt vmcnt(1)
	v_fmac_f32_e32 v126, 0.5, v97
	v_lshl_add_u64 v[66:67], v[130:131], 2, v[66:67]
	global_store_dword v[66:67], v126, off
.LBB0_4993:
	s_waitcnt vmcnt(0)
	v_fmac_f32_e32 v127, 0.5, v81
	global_store_dword v[66:67], v127, off offset:128
.LBB0_4995:
	v_mul_f32_e32 v80, v105, v105
	v_lshlrev_b32_e32 v66, 1, v138
	v_lshlrev_b32_e32 v72, 1, v135
	v_fmac_f32_e32 v80, v104, v104
	v_and_b32_e32 v66, 32, v66
	v_and_b32_e32 v72, 24, v72
	v_and_b32_e32 v104, 3, v135
	v_or3_b32 v66, v104, v72, v66
	v_and_b32_e32 v104, 64, v200
	v_xor_b32_e32 v72, 16, v200
	v_add_u32_e32 v104, 64, v104
	v_mul_f32_e32 v82, v101, v101
	v_mul_f32_e32 v98, v140, v140
	v_and_b32_e32 v99, 16, v135
	v_cmp_lt_i32_e32 vcc, v72, v104
	v_fmac_f32_e32 v82, v100, v100
	v_fmac_f32_e32 v98, v139, v139
	v_cndmask_b32_e32 v72, v200, v72, vcc
	v_cmp_eq_u32_e32 vcc, 0, v99
	v_lshlrev_b32_e32 v72, 2, v72
	v_mul_f32_e32 v78, v109, v109
	v_cndmask_b32_e32 v99, v98, v82, vcc
	ds_bpermute_b32 v99, v72, v99
	v_mul_f32_e32 v79, v107, v107
	v_mul_f32_e32 v94, v148, v148
	v_mul_f32_e32 v95, v146, v146
	v_mul_f32_e32 v73, v119, v119
	v_mul_f32_e32 v77, v111, v111
	v_fmac_f32_e32 v78, v108, v108
	v_fmac_f32_e32 v79, v106, v106
	v_mul_f32_e32 v89, v158, v158
	v_mul_f32_e32 v93, v150, v150
	v_fmac_f32_e32 v94, v147, v147
	v_fmac_f32_e32 v95, v145, v145
	v_cndmask_b32_e32 v82, v82, v98, vcc
	v_fmac_f32_e32 v73, v118, v118
	v_fmac_f32_e32 v77, v110, v110
	v_fmac_f32_e32 v89, v157, v157
	v_fmac_f32_e32 v93, v149, v149
	s_waitcnt lgkmcnt(0)
	v_add_f32_e32 v82, v82, v99
	v_cndmask_b32_e32 v99, v95, v79, vcc
	v_cndmask_b32_e32 v79, v79, v95, vcc
	v_cndmask_b32_e32 v95, v94, v78, vcc
	v_cndmask_b32_e32 v78, v78, v94, vcc
	ds_bpermute_b32 v94, v72, v95
	v_cndmask_b32_e32 v95, v93, v77, vcc
	v_cndmask_b32_e32 v77, v77, v93, vcc
	v_cndmask_b32_e32 v93, v89, v73, vcc
	ds_bpermute_b32 v93, v72, v93
	v_mul_f32_e32 v71, v121, v121
	v_mul_f32_e32 v88, v160, v160
	v_fmac_f32_e32 v71, v120, v120
	v_fmac_f32_e32 v88, v159, v159
	v_cndmask_b32_e32 v73, v73, v89, vcc
	s_waitcnt lgkmcnt(0)
	v_add_f32_e32 v89, v73, v93
	v_cndmask_b32_e32 v73, v88, v71, vcc
	ds_bpermute_b32 v73, v72, v73
	v_mul_f32_e32 v81, v103, v103
	v_mul_f32_e32 v97, v142, v142
	v_mul_f32_e32 v68, v129, v129
	v_mul_f32_e32 v75, v115, v115
	v_mul_f32_e32 v76, v113, v113
	v_fmac_f32_e32 v81, v102, v102
	v_mul_f32_e32 v85, v166, v166
	v_mul_f32_e32 v91, v154, v154
	v_mul_f32_e32 v92, v152, v152
	v_mul_f32_e32 v96, v144, v144
	v_fmac_f32_e32 v97, v141, v141
	v_fmac_f32_e32 v68, v128, v128
	v_mul_f32_e32 v69, v125, v125
	v_mul_f32_e32 v74, v117, v117
	v_fmac_f32_e32 v75, v114, v114
	v_fmac_f32_e32 v76, v112, v112
	v_mul_f32_e32 v83, v170, v170
	v_fmac_f32_e32 v85, v165, v165
	v_mul_f32_e32 v86, v164, v164
	v_mul_f32_e32 v90, v156, v156
	v_fmac_f32_e32 v91, v153, v153
	v_fmac_f32_e32 v92, v151, v151
	v_fmac_f32_e32 v96, v143, v143
	v_mul_f32_e32 v105, v127, v127
	v_cndmask_b32_e32 v98, v97, v81, vcc
	v_cndmask_b32_e32 v71, v71, v88, vcc
	v_fmac_f32_e32 v69, v124, v124
	v_fmac_f32_e32 v74, v116, v116
	v_fmac_f32_e32 v83, v169, v169
	v_fmac_f32_e32 v86, v163, v163
	v_fmac_f32_e32 v90, v155, v155
	v_fmac_f32_e32 v105, v126, v126
	v_cndmask_b32_e32 v81, v81, v97, vcc
	ds_bpermute_b32 v97, v72, v98
	v_cndmask_b32_e32 v98, v96, v80, vcc
	v_cndmask_b32_e32 v80, v80, v96, vcc
	v_cndmask_b32_e32 v96, v92, v76, vcc
	v_cndmask_b32_e32 v76, v76, v92, vcc
	v_cndmask_b32_e32 v92, v91, v75, vcc
	s_waitcnt lgkmcnt(1)
	v_add_f32_e32 v71, v71, v73
	v_cndmask_b32_e32 v73, v85, v68, vcc
	v_cndmask_b32_e32 v75, v75, v91, vcc
	ds_bpermute_b32 v91, v72, v92
	v_cndmask_b32_e32 v92, v90, v74, vcc
	v_cndmask_b32_e32 v74, v74, v90, vcc
	v_cndmask_b32_e32 v90, v86, v69, vcc
	v_cndmask_b32_e32 v69, v69, v86, vcc
	ds_bpermute_b32 v73, v72, v73
	v_cndmask_b32_e32 v86, v83, v105, vcc
	ds_bpermute_b32 v86, v72, v86
	ds_bpermute_b32 v92, v72, v92
	v_cndmask_b32_e32 v68, v68, v85, vcc
	s_lshl_b32 s0, s4, 2
	s_waitcnt lgkmcnt(2)
	v_add_f32_e32 v68, v68, v73
	v_cndmask_b32_e32 v73, v105, v83, vcc
	s_ashr_i32 s1, s0, 31
	s_waitcnt lgkmcnt(1)
	v_add_f32_e32 v83, v73, v86
	v_xor_b32_e32 v73, 8, v200
	v_mul_f32_e32 v67, v133, v133
	v_mul_f32_e32 v70, v123, v123
	v_mul_f32_e32 v84, v168, v168
	v_mul_f32_e32 v87, v162, v162
	v_and_b32_e32 v100, 8, v135
	s_lshl_b64 s[8:9], s[0:1], 2
	v_cmp_lt_i32_e64 s[0:1], v73, v104
	v_fmac_f32_e32 v67, v132, v132
	v_fmac_f32_e32 v70, v122, v122
	v_fmac_f32_e32 v84, v167, v167
	v_fmac_f32_e32 v87, v161, v161
	s_waitcnt lgkmcnt(0)
	v_add_f32_e32 v74, v74, v92
	v_cndmask_b32_e64 v73, v200, v73, s[0:1]
	v_cmp_eq_u32_e64 s[2:3], 0, v100
	v_add_f32_e32 v81, v81, v97
	v_cndmask_b32_e32 v88, v87, v70, vcc
	v_cndmask_b32_e32 v85, v84, v67, vcc
	v_cndmask_b32_e32 v67, v67, v84, vcc
	v_lshlrev_b32_e32 v73, 2, v73
	v_cndmask_b32_e64 v84, v82, v74, s[2:3]
	ds_bpermute_b32 v99, v72, v99
	ds_bpermute_b32 v88, v72, v88
	v_cndmask_b32_e64 v74, v74, v82, s[2:3]
	ds_bpermute_b32 v82, v73, v84
	v_cndmask_b32_e64 v84, v81, v89, s[2:3]
	ds_bpermute_b32 v84, v73, v84
	ds_bpermute_b32 v90, v72, v90
	v_cndmask_b32_e32 v70, v70, v87, vcc
	s_waitcnt lgkmcnt(4)
	v_add_f32_e32 v79, v79, v99
	s_waitcnt lgkmcnt(3)
	v_add_f32_e32 v70, v70, v88
	s_waitcnt lgkmcnt(2)
	v_add_f32_e32 v82, v74, v82
	v_cndmask_b32_e64 v74, v89, v81, s[2:3]
	ds_bpermute_b32 v96, v72, v96
	ds_bpermute_b32 v85, v72, v85
	s_waitcnt lgkmcnt(3)
	v_add_f32_e32 v81, v74, v84
	v_cndmask_b32_e64 v74, v79, v70, s[2:3]
	ds_bpermute_b32 v74, v73, v74
	ds_bpermute_b32 v98, v72, v98
	ds_bpermute_b32 v95, v72, v95
	v_add_f32_e32 v78, v78, v94
	s_waitcnt lgkmcnt(5)
	v_add_f32_e32 v69, v69, v90
	v_cndmask_b32_e64 v70, v70, v79, s[2:3]
	v_cndmask_b32_e64 v79, v78, v69, s[2:3]
	s_waitcnt lgkmcnt(4)
	v_add_f32_e32 v76, v76, v96
	s_waitcnt lgkmcnt(3)
	v_add_f32_e32 v67, v67, v85
	ds_bpermute_b32 v79, v73, v79
	v_add_f32_e32 v75, v75, v91
	s_waitcnt lgkmcnt(3)
	v_add_f32_e32 v70, v70, v74
	v_cndmask_b32_e64 v74, v76, v67, s[2:3]
	s_waitcnt lgkmcnt(2)
	v_add_f32_e32 v80, v80, v98
	s_waitcnt lgkmcnt(1)
	v_add_f32_e32 v77, v77, v95
	v_cndmask_b32_e64 v67, v67, v76, s[2:3]
	ds_bpermute_b32 v76, v73, v74
	v_cndmask_b32_e64 v74, v75, v83, s[2:3]
	v_cndmask_b32_e64 v85, v80, v71, s[2:3]
	v_cndmask_b32_e64 v71, v71, v80, s[2:3]
	v_cndmask_b32_e64 v80, v77, v68, s[2:3]
	v_cndmask_b32_e64 v68, v68, v77, s[2:3]
	ds_bpermute_b32 v77, v73, v74
	v_xor_b32_e32 v74, 4, v200
	v_and_b32_e32 v101, 4, v135
	v_cndmask_b32_e64 v69, v69, v78, s[2:3]
	v_cmp_lt_i32_e64 s[0:1], v74, v104
	s_waitcnt lgkmcnt(2)
	v_add_f32_e32 v69, v69, v79
	v_cmp_eq_u32_e64 s[4:5], 0, v101
	v_cndmask_b32_e64 v74, v200, v74, s[0:1]
	ds_bpermute_b32 v85, v73, v85
	ds_bpermute_b32 v80, v73, v80
	v_lshlrev_b32_e32 v74, 2, v74
	v_cndmask_b32_e64 v78, v82, v69, s[4:5]
	ds_bpermute_b32 v78, v74, v78
	v_cndmask_b32_e64 v75, v83, v75, s[2:3]
	s_waitcnt lgkmcnt(2)
	v_add_f32_e32 v71, v71, v85
	s_waitcnt lgkmcnt(1)
	v_add_f32_e32 v68, v68, v80
	v_add_f32_e32 v67, v67, v76
	v_add_f32_e32 v75, v75, v77
	v_cndmask_b32_e64 v69, v69, v82, s[4:5]
	s_waitcnt lgkmcnt(0)
	v_add_f32_e32 v69, v69, v78
	v_cndmask_b32_e64 v76, v81, v68, s[4:5]
	v_cndmask_b32_e64 v77, v71, v67, s[4:5]
	v_cndmask_b32_e64 v78, v70, v75, s[4:5]
	ds_bpermute_b32 v76, v74, v76
	ds_bpermute_b32 v77, v74, v77
	ds_bpermute_b32 v78, v74, v78
	v_cndmask_b32_e64 v67, v67, v71, s[4:5]
	v_xor_b32_e32 v71, 2, v200
	v_and_b32_e32 v102, 2, v135
	v_cndmask_b32_e64 v68, v68, v81, s[4:5]
	v_cndmask_b32_e64 v70, v75, v70, s[4:5]
	v_cmp_lt_i32_e64 s[0:1], v71, v104
	s_waitcnt lgkmcnt(2)
	v_add_f32_e32 v68, v68, v76
	s_waitcnt lgkmcnt(1)
	v_add_f32_e32 v67, v67, v77
	s_waitcnt lgkmcnt(0)
	v_add_f32_e32 v70, v70, v78
	v_cndmask_b32_e64 v71, v200, v71, s[0:1]
	v_cmp_eq_u32_e64 s[6:7], 0, v102
	v_lshlrev_b32_e32 v75, 2, v71
	v_and_b32_e32 v103, 1, v135
	v_cndmask_b32_e64 v71, v69, v67, s[6:7]
	v_cndmask_b32_e64 v76, v68, v70, s[6:7]
	ds_bpermute_b32 v71, v75, v71
	ds_bpermute_b32 v76, v75, v76
	v_cndmask_b32_e64 v67, v67, v69, s[6:7]
	v_xor_b32_e32 v69, 1, v200
	s_add_u32 s10, s12, s8
	v_cndmask_b32_e64 v68, v70, v68, s[6:7]
	v_cmp_lt_i32_e64 s[0:1], v69, v104
	s_addc_u32 s11, s13, s9
	s_waitcnt lgkmcnt(1)
	v_add_f32_e32 v67, v67, v71
	s_waitcnt lgkmcnt(0)
	v_add_f32_e32 v70, v68, v76
	v_cmp_eq_u32_e64 s[8:9], 0, v103
	v_cndmask_b32_e64 v69, v200, v69, s[0:1]
	v_lshlrev_b32_e32 v76, 2, v69
	v_cndmask_b32_e64 v68, v67, v70, s[8:9]
	ds_bpermute_b32 v71, v76, v68
	v_or3_b32 v66, v66, v136, v137
	v_lshlrev_b32_e32 v0, 2, v0
	v_lshl_add_u64 v[68:69], s[10:11], 0, v[0:1]
	v_cndmask_b32_e64 v0, v70, v67, s[8:9]
	v_ashrrev_i32_e32 v67, 31, v66
	s_waitcnt lgkmcnt(0)
	v_add_f32_e32 v0, v0, v71
	v_lshlrev_b64 v[70:71], 6, v[66:67]
	v_or_b32_e32 v122, 64, v134
	v_lshl_add_u64 v[70:71], v[68:69], 0, v[70:71]
	v_min_i32_e32 v67, 0x403f, v122
	global_store_dword v[70:71], v0, off
	s_cmp_lg_u32 s32, 0
	s_cbranch_scc0 .Lrt2_c
	s_branch .LBB0_4548
.Lrt2_c:
	v_mul_hi_i32 v0, v67, s80
	v_lshrrev_b32_e32 v70, 31, v0
	v_ashrrev_i32_e32 v0, 11, v0
	v_add_u32_e32 v0, v0, v70
	v_mad_i32_i24 v67, v0, s81, v67
	v_cmp_lt_i32_e64 s[0:1], 15, v67
	s_and_saveexec_b64 s[10:11], s[0:1]
	s_xor_b64 s[0:1], exec, s[10:11]
	v_lshlrev_b32_e32 v0, 12, v0
	v_add3_u32 v70, v0, v67, -16
	v_ashrrev_i32_e32 v71, 31, v70
	v_lshlrev_b64 v[70:71], 12, v[70:71]
	v_lshl_add_u64 v[70:71], s[88:89], 0, v[70:71]
	s_andn2_saveexec_b64 s[0:1], s[0:1]
	v_lshlrev_b32_e32 v0, 14, v0
	v_lshl_add_u32 v70, v67, 10, v0
	v_ashrrev_i32_e32 v71, 31, v70
	v_lshl_add_u64 v[70:71], v[70:71], 2, s[16:17]
	s_or_b64 exec, exec, s[0:1]
	v_lshl_add_u64 v[70:71], v[130:131], 2, v[70:71]
	global_load_dword v0, v[70:71], off
	global_load_dword v67, v[70:71], off offset:128
	v_or_b32_e32 v121, 0x41, v134
	v_min_i32_e32 v70, 0x403f, v121
	v_mul_hi_i32 v71, v70, s80
	v_lshrrev_b32_e32 v77, 31, v71
	v_ashrrev_i32_e32 v71, 11, v71
	v_add_u32_e32 v77, v71, v77
	v_mad_i32_i24 v78, v77, s81, v70
	v_cmp_lt_i32_e64 s[0:1], 15, v78
	s_and_saveexec_b64 s[10:11], s[0:1]
	s_xor_b64 s[0:1], exec, s[10:11]
	v_lshlrev_b32_e32 v70, 12, v77
	v_add3_u32 v70, v70, v78, -16
	v_ashrrev_i32_e32 v71, 31, v70
	v_lshlrev_b64 v[70:71], 12, v[70:71]
	v_lshl_add_u64 v[70:71], s[88:89], 0, v[70:71]
	s_andn2_saveexec_b64 s[0:1], s[0:1]
	v_lshlrev_b32_e32 v70, 14, v77
	v_lshl_add_u32 v70, v78, 10, v70
	v_ashrrev_i32_e32 v71, 31, v70
	v_lshl_add_u64 v[70:71], v[70:71], 2, s[16:17]
	s_or_b64 exec, exec, s[0:1]
	v_lshl_add_u64 v[70:71], v[130:131], 2, v[70:71]
	global_load_dword v77, v[70:71], off
	global_load_dword v78, v[70:71], off offset:128
	v_or_b32_e32 v120, 0x42, v134
	v_min_i32_e32 v70, 0x403f, v120
	v_mul_hi_i32 v71, v70, s80
	v_lshrrev_b32_e32 v79, 31, v71
	v_ashrrev_i32_e32 v71, 11, v71
	v_add_u32_e32 v79, v71, v79
	v_mad_i32_i24 v80, v79, s81, v70
	v_cmp_lt_i32_e64 s[0:1], 15, v80
	s_and_saveexec_b64 s[10:11], s[0:1]
	s_xor_b64 s[0:1], exec, s[10:11]
	v_lshlrev_b32_e32 v70, 12, v79
	v_add3_u32 v70, v70, v80, -16
	v_ashrrev_i32_e32 v71, 31, v70
	v_lshlrev_b64 v[70:71], 12, v[70:71]
	v_lshl_add_u64 v[70:71], s[88:89], 0, v[70:71]
	s_andn2_saveexec_b64 s[0:1], s[0:1]
	v_lshlrev_b32_e32 v70, 14, v79
	v_lshl_add_u32 v70, v80, 10, v70
	v_ashrrev_i32_e32 v71, 31, v70
	v_lshl_add_u64 v[70:71], v[70:71], 2, s[16:17]
	s_or_b64 exec, exec, s[0:1]
	v_lshl_add_u64 v[70:71], v[130:131], 2, v[70:71]
	global_load_dword v79, v[70:71], off
	global_load_dword v80, v[70:71], off offset:128
	v_or_b32_e32 v119, 0x43, v134
	v_min_i32_e32 v70, 0x403f, v119
	v_mul_hi_i32 v71, v70, s80
	v_lshrrev_b32_e32 v81, 31, v71
	v_ashrrev_i32_e32 v71, 11, v71
	v_add_u32_e32 v81, v71, v81
	v_mad_i32_i24 v82, v81, s81, v70
	v_cmp_lt_i32_e64 s[0:1], 15, v82
	s_and_saveexec_b64 s[10:11], s[0:1]
	s_xor_b64 s[0:1], exec, s[10:11]
	v_lshlrev_b32_e32 v70, 12, v81
	v_add3_u32 v70, v70, v82, -16
	v_ashrrev_i32_e32 v71, 31, v70
	v_lshlrev_b64 v[70:71], 12, v[70:71]
	v_lshl_add_u64 v[70:71], s[88:89], 0, v[70:71]
	s_andn2_saveexec_b64 s[0:1], s[0:1]
	v_lshlrev_b32_e32 v70, 14, v81
	v_lshl_add_u32 v70, v82, 10, v70
	v_ashrrev_i32_e32 v71, 31, v70
	v_lshl_add_u64 v[70:71], v[70:71], 2, s[16:17]
	s_or_b64 exec, exec, s[0:1]
	v_lshl_add_u64 v[70:71], v[130:131], 2, v[70:71]
	global_load_dword v81, v[70:71], off
	global_load_dword v82, v[70:71], off offset:128
	v_or_b32_e32 v118, 0x48, v134
	v_min_i32_e32 v70, 0x403f, v118
	v_mul_hi_i32 v71, v70, s80
	v_lshrrev_b32_e32 v83, 31, v71
	v_ashrrev_i32_e32 v71, 11, v71
	v_add_u32_e32 v83, v71, v83
	v_mad_i32_i24 v84, v83, s81, v70
	v_cmp_lt_i32_e64 s[0:1], 15, v84
	s_and_saveexec_b64 s[10:11], s[0:1]
	s_xor_b64 s[0:1], exec, s[10:11]
	v_lshlrev_b32_e32 v70, 12, v83
	v_add3_u32 v70, v70, v84, -16
	v_ashrrev_i32_e32 v71, 31, v70
	v_lshlrev_b64 v[70:71], 12, v[70:71]
	v_lshl_add_u64 v[70:71], s[88:89], 0, v[70:71]
	s_andn2_saveexec_b64 s[0:1], s[0:1]
	v_lshlrev_b32_e32 v70, 14, v83
	v_lshl_add_u32 v70, v84, 10, v70
	v_ashrrev_i32_e32 v71, 31, v70
	v_lshl_add_u64 v[70:71], v[70:71], 2, s[16:17]
	s_or_b64 exec, exec, s[0:1]
	v_lshl_add_u64 v[70:71], v[130:131], 2, v[70:71]
	global_load_dword v83, v[70:71], off
	global_load_dword v84, v[70:71], off offset:128
	v_or_b32_e32 v117, 0x49, v134
	v_min_i32_e32 v70, 0x403f, v117
	v_mul_hi_i32 v71, v70, s80
	v_lshrrev_b32_e32 v85, 31, v71
	v_ashrrev_i32_e32 v71, 11, v71
	v_add_u32_e32 v85, v71, v85
	v_mad_i32_i24 v86, v85, s81, v70
	v_cmp_lt_i32_e64 s[0:1], 15, v86
	s_and_saveexec_b64 s[10:11], s[0:1]
	s_xor_b64 s[0:1], exec, s[10:11]
	v_lshlrev_b32_e32 v70, 12, v85
	v_add3_u32 v70, v70, v86, -16
	v_ashrrev_i32_e32 v71, 31, v70
	v_lshlrev_b64 v[70:71], 12, v[70:71]
	v_lshl_add_u64 v[70:71], s[88:89], 0, v[70:71]
	s_andn2_saveexec_b64 s[0:1], s[0:1]
	v_lshlrev_b32_e32 v70, 14, v85
	v_lshl_add_u32 v70, v86, 10, v70
	v_ashrrev_i32_e32 v71, 31, v70
	v_lshl_add_u64 v[70:71], v[70:71], 2, s[16:17]
	s_or_b64 exec, exec, s[0:1]
	v_lshl_add_u64 v[70:71], v[130:131], 2, v[70:71]
	global_load_dword v85, v[70:71], off
	global_load_dword v86, v[70:71], off offset:128
	v_or_b32_e32 v116, 0x4a, v134
	v_min_i32_e32 v70, 0x403f, v116
	v_mul_hi_i32 v71, v70, s80
	v_lshrrev_b32_e32 v87, 31, v71
	v_ashrrev_i32_e32 v71, 11, v71
	v_add_u32_e32 v87, v71, v87
	v_mad_i32_i24 v88, v87, s81, v70
	v_cmp_lt_i32_e64 s[0:1], 15, v88
	s_and_saveexec_b64 s[10:11], s[0:1]
	s_xor_b64 s[0:1], exec, s[10:11]
	v_lshlrev_b32_e32 v70, 12, v87
	v_add3_u32 v70, v70, v88, -16
	v_ashrrev_i32_e32 v71, 31, v70
	v_lshlrev_b64 v[70:71], 12, v[70:71]
	v_lshl_add_u64 v[70:71], s[88:89], 0, v[70:71]
	s_andn2_saveexec_b64 s[0:1], s[0:1]
	v_lshlrev_b32_e32 v70, 14, v87
	v_lshl_add_u32 v70, v88, 10, v70
	v_ashrrev_i32_e32 v71, 31, v70
	v_lshl_add_u64 v[70:71], v[70:71], 2, s[16:17]
	s_or_b64 exec, exec, s[0:1]
	v_lshl_add_u64 v[70:71], v[130:131], 2, v[70:71]
	global_load_dword v87, v[70:71], off
	global_load_dword v88, v[70:71], off offset:128
	v_or_b32_e32 v115, 0x4b, v134
	v_min_i32_e32 v70, 0x403f, v115
	v_mul_hi_i32 v71, v70, s80
	v_lshrrev_b32_e32 v89, 31, v71
	v_ashrrev_i32_e32 v71, 11, v71
	v_add_u32_e32 v89, v71, v89
	v_mad_i32_i24 v90, v89, s81, v70
	v_cmp_lt_i32_e64 s[0:1], 15, v90
	s_and_saveexec_b64 s[10:11], s[0:1]
	s_xor_b64 s[0:1], exec, s[10:11]
	v_lshlrev_b32_e32 v70, 12, v89
	v_add3_u32 v70, v70, v90, -16
	v_ashrrev_i32_e32 v71, 31, v70
	v_lshlrev_b64 v[70:71], 12, v[70:71]
	v_lshl_add_u64 v[70:71], s[88:89], 0, v[70:71]
	s_andn2_saveexec_b64 s[0:1], s[0:1]
	v_lshlrev_b32_e32 v70, 14, v89
	v_lshl_add_u32 v70, v90, 10, v70
	v_ashrrev_i32_e32 v71, 31, v70
	v_lshl_add_u64 v[70:71], v[70:71], 2, s[16:17]
	s_or_b64 exec, exec, s[0:1]
	v_lshl_add_u64 v[70:71], v[130:131], 2, v[70:71]
	global_load_dword v89, v[70:71], off
	global_load_dword v90, v[70:71], off offset:128
	v_or_b32_e32 v114, 0x50, v134
	v_min_i32_e32 v70, 0x403f, v114
	v_mul_hi_i32 v71, v70, s80
	v_lshrrev_b32_e32 v91, 31, v71
	v_ashrrev_i32_e32 v71, 11, v71
	v_add_u32_e32 v91, v71, v91
	v_mad_i32_i24 v92, v91, s81, v70
	v_cmp_lt_i32_e64 s[0:1], 15, v92
	s_and_saveexec_b64 s[10:11], s[0:1]
	s_xor_b64 s[0:1], exec, s[10:11]
	v_lshlrev_b32_e32 v70, 12, v91
	v_add3_u32 v70, v70, v92, -16
	v_ashrrev_i32_e32 v71, 31, v70
	v_lshlrev_b64 v[70:71], 12, v[70:71]
	v_lshl_add_u64 v[70:71], s[88:89], 0, v[70:71]
	s_andn2_saveexec_b64 s[0:1], s[0:1]
	v_lshlrev_b32_e32 v70, 14, v91
	v_lshl_add_u32 v70, v92, 10, v70
	v_ashrrev_i32_e32 v71, 31, v70
	v_lshl_add_u64 v[70:71], v[70:71], 2, s[16:17]
	s_or_b64 exec, exec, s[0:1]
	v_lshl_add_u64 v[70:71], v[130:131], 2, v[70:71]
	global_load_dword v91, v[70:71], off
	global_load_dword v92, v[70:71], off offset:128
	v_or_b32_e32 v113, 0x51, v134
	v_min_i32_e32 v70, 0x403f, v113
	v_mul_hi_i32 v71, v70, s80
	v_lshrrev_b32_e32 v93, 31, v71
	v_ashrrev_i32_e32 v71, 11, v71
	v_add_u32_e32 v93, v71, v93
	v_mad_i32_i24 v94, v93, s81, v70
	v_cmp_lt_i32_e64 s[0:1], 15, v94
	s_and_saveexec_b64 s[10:11], s[0:1]
	s_xor_b64 s[0:1], exec, s[10:11]
	v_lshlrev_b32_e32 v70, 12, v93
	v_add3_u32 v70, v70, v94, -16
	v_ashrrev_i32_e32 v71, 31, v70
	v_lshlrev_b64 v[70:71], 12, v[70:71]
	v_lshl_add_u64 v[70:71], s[88:89], 0, v[70:71]
	s_andn2_saveexec_b64 s[0:1], s[0:1]
	v_lshlrev_b32_e32 v70, 14, v93
	v_lshl_add_u32 v70, v94, 10, v70
	v_ashrrev_i32_e32 v71, 31, v70
	v_lshl_add_u64 v[70:71], v[70:71], 2, s[16:17]
	s_or_b64 exec, exec, s[0:1]
	v_lshl_add_u64 v[70:71], v[130:131], 2, v[70:71]
	global_load_dword v93, v[70:71], off
	global_load_dword v94, v[70:71], off offset:128
	v_or_b32_e32 v112, 0x52, v134
	v_min_i32_e32 v70, 0x403f, v112
	v_mul_hi_i32 v71, v70, s80
	v_lshrrev_b32_e32 v95, 31, v71
	v_ashrrev_i32_e32 v71, 11, v71
	v_add_u32_e32 v95, v71, v95
	v_mad_i32_i24 v96, v95, s81, v70
	v_cmp_lt_i32_e64 s[0:1], 15, v96
	s_and_saveexec_b64 s[10:11], s[0:1]
	s_xor_b64 s[0:1], exec, s[10:11]
	v_lshlrev_b32_e32 v70, 12, v95
	v_add3_u32 v70, v70, v96, -16
	v_ashrrev_i32_e32 v71, 31, v70
	v_lshlrev_b64 v[70:71], 12, v[70:71]
	v_lshl_add_u64 v[70:71], s[88:89], 0, v[70:71]
	s_andn2_saveexec_b64 s[0:1], s[0:1]
	v_lshlrev_b32_e32 v70, 14, v95
	v_lshl_add_u32 v70, v96, 10, v70
	v_ashrrev_i32_e32 v71, 31, v70
	v_lshl_add_u64 v[70:71], v[70:71], 2, s[16:17]
	s_or_b64 exec, exec, s[0:1]
	v_lshl_add_u64 v[70:71], v[130:131], 2, v[70:71]
	global_load_dword v95, v[70:71], off
	global_load_dword v96, v[70:71], off offset:128
	v_or_b32_e32 v111, 0x53, v134
	v_min_i32_e32 v70, 0x403f, v111
	v_mul_hi_i32 v71, v70, s80
	v_lshrrev_b32_e32 v97, 31, v71
	v_ashrrev_i32_e32 v71, 11, v71
	v_add_u32_e32 v97, v71, v97
	v_mad_i32_i24 v98, v97, s81, v70
	v_cmp_lt_i32_e64 s[0:1], 15, v98
	s_and_saveexec_b64 s[10:11], s[0:1]
	s_xor_b64 s[0:1], exec, s[10:11]
	v_lshlrev_b32_e32 v70, 12, v97
	v_add3_u32 v70, v70, v98, -16
	v_ashrrev_i32_e32 v71, 31, v70
	v_lshlrev_b64 v[70:71], 12, v[70:71]
	v_lshl_add_u64 v[70:71], s[88:89], 0, v[70:71]
	s_andn2_saveexec_b64 s[0:1], s[0:1]
	v_lshlrev_b32_e32 v70, 14, v97
	v_lshl_add_u32 v70, v98, 10, v70
	v_ashrrev_i32_e32 v71, 31, v70
	v_lshl_add_u64 v[70:71], v[70:71], 2, s[16:17]
	s_or_b64 exec, exec, s[0:1]
	v_lshl_add_u64 v[70:71], v[130:131], 2, v[70:71]
	global_load_dword v97, v[70:71], off
	global_load_dword v98, v[70:71], off offset:128
	v_or_b32_e32 v110, 0x58, v134
	v_min_i32_e32 v70, 0x403f, v110
	v_mul_hi_i32 v71, v70, s80
	v_lshrrev_b32_e32 v99, 31, v71
	v_ashrrev_i32_e32 v71, 11, v71
	v_add_u32_e32 v99, v71, v99
	v_mad_i32_i24 v100, v99, s81, v70
	v_cmp_lt_i32_e64 s[0:1], 15, v100
	s_and_saveexec_b64 s[10:11], s[0:1]
	s_xor_b64 s[0:1], exec, s[10:11]
	v_lshlrev_b32_e32 v70, 12, v99
	v_add3_u32 v70, v70, v100, -16
	v_ashrrev_i32_e32 v71, 31, v70
	v_lshlrev_b64 v[70:71], 12, v[70:71]
	v_lshl_add_u64 v[70:71], s[88:89], 0, v[70:71]
	s_andn2_saveexec_b64 s[0:1], s[0:1]
	v_lshlrev_b32_e32 v70, 14, v99
	v_lshl_add_u32 v70, v100, 10, v70
	v_ashrrev_i32_e32 v71, 31, v70
	v_lshl_add_u64 v[70:71], v[70:71], 2, s[16:17]
	s_or_b64 exec, exec, s[0:1]
	v_lshl_add_u64 v[70:71], v[130:131], 2, v[70:71]
	global_load_dword v99, v[70:71], off
	global_load_dword v100, v[70:71], off offset:128
	v_or_b32_e32 v109, 0x59, v134
	v_min_i32_e32 v70, 0x403f, v109
	v_mul_hi_i32 v71, v70, s80
	v_lshrrev_b32_e32 v101, 31, v71
	v_ashrrev_i32_e32 v71, 11, v71
	v_add_u32_e32 v101, v71, v101
	v_mad_i32_i24 v102, v101, s81, v70
	v_cmp_lt_i32_e64 s[0:1], 15, v102
	s_and_saveexec_b64 s[10:11], s[0:1]
	s_xor_b64 s[0:1], exec, s[10:11]
	v_lshlrev_b32_e32 v70, 12, v101
	v_add3_u32 v70, v70, v102, -16
	v_ashrrev_i32_e32 v71, 31, v70
	v_lshlrev_b64 v[70:71], 12, v[70:71]
	v_lshl_add_u64 v[70:71], s[88:89], 0, v[70:71]
	s_andn2_saveexec_b64 s[0:1], s[0:1]
	v_lshlrev_b32_e32 v70, 14, v101
	v_lshl_add_u32 v70, v102, 10, v70
	v_ashrrev_i32_e32 v71, 31, v70
	v_lshl_add_u64 v[70:71], v[70:71], 2, s[16:17]
	s_or_b64 exec, exec, s[0:1]
	v_lshl_add_u64 v[70:71], v[130:131], 2, v[70:71]
	global_load_dword v101, v[70:71], off
	global_load_dword v102, v[70:71], off offset:128
	v_or_b32_e32 v108, 0x5a, v134
	v_min_i32_e32 v70, 0x403f, v108
	v_mul_hi_i32 v71, v70, s80
	v_lshrrev_b32_e32 v103, 31, v71
	v_ashrrev_i32_e32 v71, 11, v71
	v_add_u32_e32 v103, v71, v103
	v_mad_i32_i24 v104, v103, s81, v70
	v_cmp_lt_i32_e64 s[0:1], 15, v104
	s_and_saveexec_b64 s[10:11], s[0:1]
	s_xor_b64 s[0:1], exec, s[10:11]
	v_lshlrev_b32_e32 v70, 12, v103
	v_add3_u32 v70, v70, v104, -16
	v_ashrrev_i32_e32 v71, 31, v70
	v_lshlrev_b64 v[70:71], 12, v[70:71]
	v_lshl_add_u64 v[70:71], s[88:89], 0, v[70:71]
	s_andn2_saveexec_b64 s[0:1], s[0:1]
	v_lshlrev_b32_e32 v70, 14, v103
	v_lshl_add_u32 v70, v104, 10, v70
	v_ashrrev_i32_e32 v71, 31, v70
	v_lshl_add_u64 v[70:71], v[70:71], 2, s[16:17]
	s_or_b64 exec, exec, s[0:1]
	v_lshl_add_u64 v[70:71], v[130:131], 2, v[70:71]
	global_load_dword v103, v[70:71], off
	global_load_dword v104, v[70:71], off offset:128
	v_or_b32_e32 v107, 0x5b, v134
	v_min_i32_e32 v70, 0x403f, v107
	v_mul_hi_i32 v71, v70, s80
	v_lshrrev_b32_e32 v105, 31, v71
	v_ashrrev_i32_e32 v71, 11, v71
	v_add_u32_e32 v105, v71, v105
	v_mad_i32_i24 v106, v105, s81, v70
	v_cmp_lt_i32_e64 s[0:1], 15, v106
	s_and_saveexec_b64 s[10:11], s[0:1]
	s_xor_b64 s[0:1], exec, s[10:11]
	v_lshlrev_b32_e32 v70, 12, v105
	v_add3_u32 v70, v70, v106, -16
	v_ashrrev_i32_e32 v71, 31, v70
	v_lshlrev_b64 v[70:71], 12, v[70:71]
	v_lshl_add_u64 v[70:71], s[88:89], 0, v[70:71]
	s_andn2_saveexec_b64 s[0:1], s[0:1]
	v_lshlrev_b32_e32 v70, 14, v105
	v_lshl_add_u32 v70, v106, 10, v70
	v_ashrrev_i32_e32 v71, 31, v70
	v_lshl_add_u64 v[70:71], v[70:71], 2, s[16:17]
	s_or_b64 exec, exec, s[0:1]
	v_lshl_add_u64 v[70:71], v[130:131], 2, v[70:71]
	global_load_dword v105, v[70:71], off
	global_load_dword v106, v[70:71], off offset:128
	v_cmp_gt_i32_e64 s[10:11], s82, v122
	s_nop 1
	v_cndmask_b32_e64 v70, v179, v122, s[10:11]
	v_mul_hi_i32 v71, v70, s80
	v_lshrrev_b32_e32 v122, 31, v71
	v_ashrrev_i32_e32 v71, 11, v71
	v_add_u32_e32 v122, v71, v122
	v_mad_i32_i24 v123, v122, s81, v70
	v_cmp_lt_i32_e64 s[0:1], 15, v123
	s_and_saveexec_b64 s[54:55], s[0:1]
	s_xor_b64 s[0:1], exec, s[54:55]
	v_lshlrev_b32_e32 v70, 12, v122
	v_add3_u32 v70, v70, v123, -16
	v_ashrrev_i32_e32 v71, 31, v70
	v_lshlrev_b64 v[70:71], 12, v[70:71]
	v_lshl_add_u64 v[70:71], s[88:89], 0, v[70:71]
	s_andn2_saveexec_b64 s[0:1], s[0:1]
	v_lshlrev_b32_e32 v70, 14, v122
	v_lshl_add_u32 v70, v123, 10, v70
	v_ashrrev_i32_e32 v71, 31, v70
	v_lshl_add_u64 v[70:71], v[70:71], 2, s[16:17]
	s_or_b64 exec, exec, s[0:1]
	s_waitcnt vmcnt(31)
	v_fmac_f32_e32 v0, 0.5, v50
	v_lshl_add_u64 v[70:71], v[130:131], 2, v[70:71]
	global_store_dword v[70:71], v0, off
.LBB0_5065:
	s_waitcnt vmcnt(30)
	v_fmac_f32_e32 v67, 0.5, v34
	global_store_dword v[70:71], v67, off offset:128
.LBB0_5067:
	v_cmp_gt_i32_e64 s[10:11], s82, v121
	s_nop 1
	v_cndmask_b32_e64 v50, v179, v121, s[10:11]
	v_mul_hi_i32 v34, v50, s80
	v_lshrrev_b32_e32 v70, 31, v34
	v_ashrrev_i32_e32 v34, 11, v34
	v_add_u32_e32 v34, v34, v70
	v_mad_i32_i24 v50, v34, s81, v50
	v_cmp_lt_i32_e64 s[0:1], 15, v50
	s_and_saveexec_b64 s[54:55], s[0:1]
	s_xor_b64 s[0:1], exec, s[54:55]
	v_lshlrev_b32_e32 v34, 12, v34
	v_add3_u32 v70, v34, v50, -16
	v_ashrrev_i32_e32 v71, 31, v70
	v_lshlrev_b64 v[70:71], 12, v[70:71]
	v_lshl_add_u64 v[70:71], s[88:89], 0, v[70:71]
	s_andn2_saveexec_b64 s[0:1], s[0:1]
	v_lshlrev_b32_e32 v34, 14, v34
	v_lshl_add_u32 v70, v50, 10, v34
	v_ashrrev_i32_e32 v71, 31, v70
	v_lshl_add_u64 v[70:71], v[70:71], 2, s[16:17]
	s_or_b64 exec, exec, s[0:1]
	s_waitcnt vmcnt(29)
	v_fmac_f32_e32 v77, 0.5, v51
	v_lshl_add_u64 v[50:51], v[130:131], 2, v[70:71]
	global_store_dword v[50:51], v77, off
.LBB0_5073:
	s_waitcnt vmcnt(28)
	v_fmac_f32_e32 v78, 0.5, v35
	global_store_dword v[50:51], v78, off offset:128
.LBB0_5075:
	v_cmp_gt_i32_e64 s[10:11], s82, v120
	s_nop 1
	v_cndmask_b32_e64 v34, v179, v120, s[10:11]
	v_mul_hi_i32 v35, v34, s80
	v_lshrrev_b32_e32 v50, 31, v35
	v_ashrrev_i32_e32 v35, 11, v35
	v_add_u32_e32 v50, v35, v50
	v_mad_i32_i24 v51, v50, s81, v34
	v_cmp_lt_i32_e64 s[0:1], 15, v51
	s_and_saveexec_b64 s[54:55], s[0:1]
	s_xor_b64 s[0:1], exec, s[54:55]
	v_lshlrev_b32_e32 v34, 12, v50
	v_add3_u32 v34, v34, v51, -16
	v_ashrrev_i32_e32 v35, 31, v34
	v_lshlrev_b64 v[34:35], 12, v[34:35]
	v_lshl_add_u64 v[34:35], s[88:89], 0, v[34:35]
	s_andn2_saveexec_b64 s[0:1], s[0:1]
	v_lshlrev_b32_e32 v34, 14, v50
	v_lshl_add_u32 v34, v51, 10, v34
	v_ashrrev_i32_e32 v35, 31, v34
	v_lshl_add_u64 v[34:35], v[34:35], 2, s[16:17]
	s_or_b64 exec, exec, s[0:1]
	s_waitcnt vmcnt(27)
	v_fmac_f32_e32 v79, 0.5, v52
	v_lshl_add_u64 v[34:35], v[130:131], 2, v[34:35]
	global_store_dword v[34:35], v79, off
.LBB0_5081:
	s_waitcnt vmcnt(26)
	v_fmac_f32_e32 v80, 0.5, v36
	global_store_dword v[34:35], v80, off offset:128
.LBB0_5083:
	v_cmp_gt_i32_e64 s[10:11], s82, v119
	s_nop 1
	v_cndmask_b32_e64 v34, v179, v119, s[10:11]
	v_mul_hi_i32 v35, v34, s80
	v_lshrrev_b32_e32 v36, 31, v35
	v_ashrrev_i32_e32 v35, 11, v35
	v_add_u32_e32 v36, v35, v36
	v_mad_i32_i24 v50, v36, s81, v34
	v_cmp_lt_i32_e64 s[0:1], 15, v50
	s_and_saveexec_b64 s[54:55], s[0:1]
	s_xor_b64 s[0:1], exec, s[54:55]
	v_lshlrev_b32_e32 v34, 12, v36
	v_add3_u32 v34, v34, v50, -16
	v_ashrrev_i32_e32 v35, 31, v34
	v_lshlrev_b64 v[34:35], 12, v[34:35]
	v_lshl_add_u64 v[34:35], s[88:89], 0, v[34:35]
	s_andn2_saveexec_b64 s[0:1], s[0:1]
	v_lshlrev_b32_e32 v34, 14, v36
	v_lshl_add_u32 v34, v50, 10, v34
	v_ashrrev_i32_e32 v35, 31, v34
	v_lshl_add_u64 v[34:35], v[34:35], 2, s[16:17]
	s_or_b64 exec, exec, s[0:1]
	s_waitcnt vmcnt(25)
	v_fmac_f32_e32 v81, 0.5, v53
	v_lshl_add_u64 v[34:35], v[130:131], 2, v[34:35]
	global_store_dword v[34:35], v81, off
.LBB0_5089:
	s_waitcnt vmcnt(24)
	v_fmac_f32_e32 v82, 0.5, v37
	global_store_dword v[34:35], v82, off offset:128
.LBB0_5091:
	v_cmp_gt_i32_e64 s[10:11], s82, v118
	s_nop 1
	v_cndmask_b32_e64 v34, v179, v118, s[10:11]
	v_mul_hi_i32 v35, v34, s80
	v_lshrrev_b32_e32 v36, 31, v35
	v_ashrrev_i32_e32 v35, 11, v35
	v_add_u32_e32 v36, v35, v36
	v_mad_i32_i24 v37, v36, s81, v34
	v_cmp_lt_i32_e64 s[0:1], 15, v37
	s_and_saveexec_b64 s[54:55], s[0:1]
	s_xor_b64 s[0:1], exec, s[54:55]
	v_lshlrev_b32_e32 v34, 12, v36
	v_add3_u32 v34, v34, v37, -16
	v_ashrrev_i32_e32 v35, 31, v34
	v_lshlrev_b64 v[34:35], 12, v[34:35]
	v_lshl_add_u64 v[34:35], s[88:89], 0, v[34:35]
	s_andn2_saveexec_b64 s[0:1], s[0:1]
	v_lshlrev_b32_e32 v34, 14, v36
	v_lshl_add_u32 v34, v37, 10, v34
	v_ashrrev_i32_e32 v35, 31, v34
	v_lshl_add_u64 v[34:35], v[34:35], 2, s[16:17]
	s_or_b64 exec, exec, s[0:1]
	s_waitcnt vmcnt(23)
	v_fmac_f32_e32 v83, 0.5, v54
	v_lshl_add_u64 v[34:35], v[130:131], 2, v[34:35]
	global_store_dword v[34:35], v83, off
.LBB0_5097:
	s_waitcnt vmcnt(22)
	v_fmac_f32_e32 v84, 0.5, v38
	global_store_dword v[34:35], v84, off offset:128
.LBB0_5099:
	v_cmp_gt_i32_e64 s[10:11], s82, v117
	s_nop 1
	v_cndmask_b32_e64 v34, v179, v117, s[10:11]
	v_mul_hi_i32 v35, v34, s80
	v_lshrrev_b32_e32 v36, 31, v35
	v_ashrrev_i32_e32 v35, 11, v35
	v_add_u32_e32 v36, v35, v36
	v_mad_i32_i24 v37, v36, s81, v34
	v_cmp_lt_i32_e64 s[0:1], 15, v37
	s_and_saveexec_b64 s[54:55], s[0:1]
	s_xor_b64 s[0:1], exec, s[54:55]
	v_lshlrev_b32_e32 v34, 12, v36
	v_add3_u32 v34, v34, v37, -16
	v_ashrrev_i32_e32 v35, 31, v34
	v_lshlrev_b64 v[34:35], 12, v[34:35]
	v_lshl_add_u64 v[34:35], s[88:89], 0, v[34:35]
	s_andn2_saveexec_b64 s[0:1], s[0:1]
	v_lshlrev_b32_e32 v34, 14, v36
	v_lshl_add_u32 v34, v37, 10, v34
	v_ashrrev_i32_e32 v35, 31, v34
	v_lshl_add_u64 v[34:35], v[34:35], 2, s[16:17]
	s_or_b64 exec, exec, s[0:1]
	s_waitcnt vmcnt(21)
	v_fmac_f32_e32 v85, 0.5, v55
	v_lshl_add_u64 v[34:35], v[130:131], 2, v[34:35]
	global_store_dword v[34:35], v85, off
.LBB0_5105:
	s_waitcnt vmcnt(20)
	v_fmac_f32_e32 v86, 0.5, v39
	global_store_dword v[34:35], v86, off offset:128
.LBB0_5107:
	v_cmp_gt_i32_e64 s[10:11], s82, v116
	s_nop 1
	v_cndmask_b32_e64 v34, v179, v116, s[10:11]
	v_mul_hi_i32 v35, v34, s80
	v_lshrrev_b32_e32 v36, 31, v35
	v_ashrrev_i32_e32 v35, 11, v35
	v_add_u32_e32 v36, v35, v36
	v_mad_i32_i24 v37, v36, s81, v34
	v_cmp_lt_i32_e64 s[0:1], 15, v37
	s_and_saveexec_b64 s[54:55], s[0:1]
	s_xor_b64 s[0:1], exec, s[54:55]
	v_lshlrev_b32_e32 v34, 12, v36
	v_add3_u32 v34, v34, v37, -16
	v_ashrrev_i32_e32 v35, 31, v34
	v_lshlrev_b64 v[34:35], 12, v[34:35]
	v_lshl_add_u64 v[34:35], s[88:89], 0, v[34:35]
	s_andn2_saveexec_b64 s[0:1], s[0:1]
	v_lshlrev_b32_e32 v34, 14, v36
	v_lshl_add_u32 v34, v37, 10, v34
	v_ashrrev_i32_e32 v35, 31, v34
	v_lshl_add_u64 v[34:35], v[34:35], 2, s[16:17]
	s_or_b64 exec, exec, s[0:1]
	s_waitcnt vmcnt(19)
	v_fmac_f32_e32 v87, 0.5, v56
	v_lshl_add_u64 v[34:35], v[130:131], 2, v[34:35]
	global_store_dword v[34:35], v87, off
.LBB0_5113:
	s_waitcnt vmcnt(18)
	v_fmac_f32_e32 v88, 0.5, v40
	global_store_dword v[34:35], v88, off offset:128
.LBB0_5115:
	v_cmp_gt_i32_e64 s[10:11], s82, v115
	s_nop 1
	v_cndmask_b32_e64 v34, v179, v115, s[10:11]
	v_mul_hi_i32 v35, v34, s80
	v_lshrrev_b32_e32 v36, 31, v35
	v_ashrrev_i32_e32 v35, 11, v35
	v_add_u32_e32 v36, v35, v36
	v_mad_i32_i24 v37, v36, s81, v34
	v_cmp_lt_i32_e64 s[0:1], 15, v37
	s_and_saveexec_b64 s[54:55], s[0:1]
	s_xor_b64 s[0:1], exec, s[54:55]
	v_lshlrev_b32_e32 v34, 12, v36
	v_add3_u32 v34, v34, v37, -16
	v_ashrrev_i32_e32 v35, 31, v34
	v_lshlrev_b64 v[34:35], 12, v[34:35]
	v_lshl_add_u64 v[34:35], s[88:89], 0, v[34:35]
	s_andn2_saveexec_b64 s[0:1], s[0:1]
	v_lshlrev_b32_e32 v34, 14, v36
	v_lshl_add_u32 v34, v37, 10, v34
	v_ashrrev_i32_e32 v35, 31, v34
	v_lshl_add_u64 v[34:35], v[34:35], 2, s[16:17]
	s_or_b64 exec, exec, s[0:1]
	s_waitcnt vmcnt(17)
	v_fmac_f32_e32 v89, 0.5, v57
	v_lshl_add_u64 v[34:35], v[130:131], 2, v[34:35]
	global_store_dword v[34:35], v89, off
.LBB0_5121:
	s_waitcnt vmcnt(16)
	v_fmac_f32_e32 v90, 0.5, v41
	global_store_dword v[34:35], v90, off offset:128
.LBB0_5123:
	v_cmp_gt_i32_e64 s[10:11], s82, v114
	s_nop 1
	v_cndmask_b32_e64 v34, v179, v114, s[10:11]
	v_mul_hi_i32 v35, v34, s80
	v_lshrrev_b32_e32 v36, 31, v35
	v_ashrrev_i32_e32 v35, 11, v35
	v_add_u32_e32 v36, v35, v36
	v_mad_i32_i24 v37, v36, s81, v34
	v_cmp_lt_i32_e64 s[0:1], 15, v37
	s_and_saveexec_b64 s[54:55], s[0:1]
	s_xor_b64 s[0:1], exec, s[54:55]
	v_lshlrev_b32_e32 v34, 12, v36
	v_add3_u32 v34, v34, v37, -16
	v_ashrrev_i32_e32 v35, 31, v34
	v_lshlrev_b64 v[34:35], 12, v[34:35]
	v_lshl_add_u64 v[34:35], s[88:89], 0, v[34:35]
	s_andn2_saveexec_b64 s[0:1], s[0:1]
	v_lshlrev_b32_e32 v34, 14, v36
	v_lshl_add_u32 v34, v37, 10, v34
	v_ashrrev_i32_e32 v35, 31, v34
	v_lshl_add_u64 v[34:35], v[34:35], 2, s[16:17]
	s_or_b64 exec, exec, s[0:1]
	s_waitcnt vmcnt(15)
	v_fmac_f32_e32 v91, 0.5, v58
	v_lshl_add_u64 v[34:35], v[130:131], 2, v[34:35]
	global_store_dword v[34:35], v91, off
.LBB0_5129:
	s_waitcnt vmcnt(14)
	v_fmac_f32_e32 v92, 0.5, v42
	global_store_dword v[34:35], v92, off offset:128
.LBB0_5131:
	v_cmp_gt_i32_e64 s[10:11], s82, v113
	s_nop 1
	v_cndmask_b32_e64 v34, v179, v113, s[10:11]
	v_mul_hi_i32 v35, v34, s80
	v_lshrrev_b32_e32 v36, 31, v35
	v_ashrrev_i32_e32 v35, 11, v35
	v_add_u32_e32 v36, v35, v36
	v_mad_i32_i24 v37, v36, s81, v34
	v_cmp_lt_i32_e64 s[0:1], 15, v37
	s_and_saveexec_b64 s[54:55], s[0:1]
	s_xor_b64 s[0:1], exec, s[54:55]
	v_lshlrev_b32_e32 v34, 12, v36
	v_add3_u32 v34, v34, v37, -16
	v_ashrrev_i32_e32 v35, 31, v34
	v_lshlrev_b64 v[34:35], 12, v[34:35]
	v_lshl_add_u64 v[34:35], s[88:89], 0, v[34:35]
	s_andn2_saveexec_b64 s[0:1], s[0:1]
	v_lshlrev_b32_e32 v34, 14, v36
	v_lshl_add_u32 v34, v37, 10, v34
	v_ashrrev_i32_e32 v35, 31, v34
	v_lshl_add_u64 v[34:35], v[34:35], 2, s[16:17]
	s_or_b64 exec, exec, s[0:1]
	s_waitcnt vmcnt(13)
	v_fmac_f32_e32 v93, 0.5, v59
	v_lshl_add_u64 v[34:35], v[130:131], 2, v[34:35]
	global_store_dword v[34:35], v93, off
.LBB0_5137:
	s_waitcnt vmcnt(12)
	v_fmac_f32_e32 v94, 0.5, v43
	global_store_dword v[34:35], v94, off offset:128
.LBB0_5139:
	v_cmp_gt_i32_e64 s[10:11], s82, v112
	s_nop 1
	v_cndmask_b32_e64 v34, v179, v112, s[10:11]
	v_mul_hi_i32 v35, v34, s80
	v_lshrrev_b32_e32 v36, 31, v35
	v_ashrrev_i32_e32 v35, 11, v35
	v_add_u32_e32 v36, v35, v36
	v_mad_i32_i24 v37, v36, s81, v34
	v_cmp_lt_i32_e64 s[0:1], 15, v37
	s_and_saveexec_b64 s[54:55], s[0:1]
	s_xor_b64 s[0:1], exec, s[54:55]
	v_lshlrev_b32_e32 v34, 12, v36
	v_add3_u32 v34, v34, v37, -16
	v_ashrrev_i32_e32 v35, 31, v34
	v_lshlrev_b64 v[34:35], 12, v[34:35]
	v_lshl_add_u64 v[34:35], s[88:89], 0, v[34:35]
	s_andn2_saveexec_b64 s[0:1], s[0:1]
	v_lshlrev_b32_e32 v34, 14, v36
	v_lshl_add_u32 v34, v37, 10, v34
	v_ashrrev_i32_e32 v35, 31, v34
	v_lshl_add_u64 v[34:35], v[34:35], 2, s[16:17]
	s_or_b64 exec, exec, s[0:1]
	s_waitcnt vmcnt(11)
	v_fmac_f32_e32 v95, 0.5, v60
	v_lshl_add_u64 v[34:35], v[130:131], 2, v[34:35]
	global_store_dword v[34:35], v95, off
.LBB0_5145:
	s_waitcnt vmcnt(10)
	v_fmac_f32_e32 v96, 0.5, v44
	global_store_dword v[34:35], v96, off offset:128
.LBB0_5147:
	v_cmp_gt_i32_e64 s[10:11], s82, v111
	s_nop 1
	v_cndmask_b32_e64 v34, v179, v111, s[10:11]
	v_mul_hi_i32 v35, v34, s80
	v_lshrrev_b32_e32 v36, 31, v35
	v_ashrrev_i32_e32 v35, 11, v35
	v_add_u32_e32 v36, v35, v36
	v_mad_i32_i24 v37, v36, s81, v34
	v_cmp_lt_i32_e64 s[0:1], 15, v37
	s_and_saveexec_b64 s[54:55], s[0:1]
	s_xor_b64 s[0:1], exec, s[54:55]
	v_lshlrev_b32_e32 v34, 12, v36
	v_add3_u32 v34, v34, v37, -16
	v_ashrrev_i32_e32 v35, 31, v34
	v_lshlrev_b64 v[34:35], 12, v[34:35]
	v_lshl_add_u64 v[34:35], s[88:89], 0, v[34:35]
	s_andn2_saveexec_b64 s[0:1], s[0:1]
	v_lshlrev_b32_e32 v34, 14, v36
	v_lshl_add_u32 v34, v37, 10, v34
	v_ashrrev_i32_e32 v35, 31, v34
	v_lshl_add_u64 v[34:35], v[34:35], 2, s[16:17]
	s_or_b64 exec, exec, s[0:1]
	s_waitcnt vmcnt(9)
	v_fmac_f32_e32 v97, 0.5, v61
	v_lshl_add_u64 v[34:35], v[130:131], 2, v[34:35]
	global_store_dword v[34:35], v97, off
.LBB0_5153:
	s_waitcnt vmcnt(8)
	v_fmac_f32_e32 v98, 0.5, v45
	global_store_dword v[34:35], v98, off offset:128
.LBB0_5155:
	v_cmp_gt_i32_e64 s[10:11], s82, v110
	s_nop 1
	v_cndmask_b32_e64 v34, v179, v110, s[10:11]
	v_mul_hi_i32 v35, v34, s80
	v_lshrrev_b32_e32 v36, 31, v35
	v_ashrrev_i32_e32 v35, 11, v35
	v_add_u32_e32 v36, v35, v36
	v_mad_i32_i24 v37, v36, s81, v34
	v_cmp_lt_i32_e64 s[0:1], 15, v37
	s_and_saveexec_b64 s[54:55], s[0:1]
	s_xor_b64 s[0:1], exec, s[54:55]
	v_lshlrev_b32_e32 v34, 12, v36
	v_add3_u32 v34, v34, v37, -16
	v_ashrrev_i32_e32 v35, 31, v34
	v_lshlrev_b64 v[34:35], 12, v[34:35]
	v_lshl_add_u64 v[34:35], s[88:89], 0, v[34:35]
	s_andn2_saveexec_b64 s[0:1], s[0:1]
	v_lshlrev_b32_e32 v34, 14, v36
	v_lshl_add_u32 v34, v37, 10, v34
	v_ashrrev_i32_e32 v35, 31, v34
	v_lshl_add_u64 v[34:35], v[34:35], 2, s[16:17]
	s_or_b64 exec, exec, s[0:1]
	s_waitcnt vmcnt(7)
	v_fmac_f32_e32 v99, 0.5, v62
	v_lshl_add_u64 v[34:35], v[130:131], 2, v[34:35]
	global_store_dword v[34:35], v99, off
.LBB0_5161:
	s_waitcnt vmcnt(6)
	v_fmac_f32_e32 v100, 0.5, v46
	global_store_dword v[34:35], v100, off offset:128
.LBB0_5163:
	v_cmp_gt_i32_e64 s[10:11], s82, v109
	s_nop 1
	v_cndmask_b32_e64 v34, v179, v109, s[10:11]
	v_mul_hi_i32 v35, v34, s80
	v_lshrrev_b32_e32 v36, 31, v35
	v_ashrrev_i32_e32 v35, 11, v35
	v_add_u32_e32 v36, v35, v36
	v_mad_i32_i24 v37, v36, s81, v34
	v_cmp_lt_i32_e64 s[0:1], 15, v37
	s_and_saveexec_b64 s[54:55], s[0:1]
	s_xor_b64 s[0:1], exec, s[54:55]
	v_lshlrev_b32_e32 v34, 12, v36
	v_add3_u32 v34, v34, v37, -16
	v_ashrrev_i32_e32 v35, 31, v34
	v_lshlrev_b64 v[34:35], 12, v[34:35]
	v_lshl_add_u64 v[34:35], s[88:89], 0, v[34:35]
	s_andn2_saveexec_b64 s[0:1], s[0:1]
	v_lshlrev_b32_e32 v34, 14, v36
	v_lshl_add_u32 v34, v37, 10, v34
	v_ashrrev_i32_e32 v35, 31, v34
	v_lshl_add_u64 v[34:35], v[34:35], 2, s[16:17]
	s_or_b64 exec, exec, s[0:1]
	s_waitcnt vmcnt(5)
	v_fmac_f32_e32 v101, 0.5, v63
	v_lshl_add_u64 v[34:35], v[130:131], 2, v[34:35]
	global_store_dword v[34:35], v101, off
.LBB0_5169:
	s_waitcnt vmcnt(4)
	v_fmac_f32_e32 v102, 0.5, v47
	global_store_dword v[34:35], v102, off offset:128
.LBB0_5171:
	v_cmp_gt_i32_e64 s[10:11], s82, v108
	s_nop 1
	v_cndmask_b32_e64 v34, v179, v108, s[10:11]
	v_mul_hi_i32 v35, v34, s80
	v_lshrrev_b32_e32 v36, 31, v35
	v_ashrrev_i32_e32 v35, 11, v35
	v_add_u32_e32 v36, v35, v36
	v_mad_i32_i24 v37, v36, s81, v34
	v_cmp_lt_i32_e64 s[0:1], 15, v37
	s_and_saveexec_b64 s[54:55], s[0:1]
	s_xor_b64 s[0:1], exec, s[54:55]
	v_lshlrev_b32_e32 v34, 12, v36
	v_add3_u32 v34, v34, v37, -16
	v_ashrrev_i32_e32 v35, 31, v34
	v_lshlrev_b64 v[34:35], 12, v[34:35]
	v_lshl_add_u64 v[34:35], s[88:89], 0, v[34:35]
	s_andn2_saveexec_b64 s[0:1], s[0:1]
	v_lshlrev_b32_e32 v34, 14, v36
	v_lshl_add_u32 v34, v37, 10, v34
	v_ashrrev_i32_e32 v35, 31, v34
	v_lshl_add_u64 v[34:35], v[34:35], 2, s[16:17]
	s_or_b64 exec, exec, s[0:1]
	s_waitcnt vmcnt(3)
	v_fmac_f32_e32 v103, 0.5, v64
	v_lshl_add_u64 v[34:35], v[130:131], 2, v[34:35]
	global_store_dword v[34:35], v103, off
.LBB0_5177:
	s_waitcnt vmcnt(2)
	v_fmac_f32_e32 v104, 0.5, v48
	global_store_dword v[34:35], v104, off offset:128
.LBB0_5179:
	v_cmp_gt_i32_e64 s[10:11], s82, v107
	s_nop 1
	v_cndmask_b32_e64 v34, v179, v107, s[10:11]
	v_mul_hi_i32 v35, v34, s80
	v_lshrrev_b32_e32 v36, 31, v35
	v_ashrrev_i32_e32 v35, 11, v35
	v_add_u32_e32 v36, v35, v36
	v_mad_i32_i24 v37, v36, s81, v34
	v_cmp_lt_i32_e64 s[0:1], 15, v37
	s_and_saveexec_b64 s[54:55], s[0:1]
	s_xor_b64 s[0:1], exec, s[54:55]
	v_lshlrev_b32_e32 v34, 12, v36
	v_add3_u32 v34, v34, v37, -16
	v_ashrrev_i32_e32 v35, 31, v34
	v_lshlrev_b64 v[34:35], 12, v[34:35]
	v_lshl_add_u64 v[34:35], s[88:89], 0, v[34:35]
	s_andn2_saveexec_b64 s[0:1], s[0:1]
	v_lshlrev_b32_e32 v34, 14, v36
	v_lshl_add_u32 v34, v37, 10, v34
	v_ashrrev_i32_e32 v35, 31, v34
	v_lshl_add_u64 v[34:35], v[34:35], 2, s[16:17]
	s_or_b64 exec, exec, s[0:1]
	s_waitcnt vmcnt(1)
	v_fmac_f32_e32 v105, 0.5, v65
	v_lshl_add_u64 v[34:35], v[130:131], 2, v[34:35]
	global_store_dword v[34:35], v105, off
.LBB0_5185:
	s_waitcnt vmcnt(0)
	v_fmac_f32_e32 v106, 0.5, v49
	global_store_dword v[34:35], v106, off offset:128
.LBB0_5187:
	v_or_b32_e32 v122, 0x60, v134
	v_min_i32_e32 v34, 0x403f, v122
	v_mul_hi_i32 v35, v34, s80
	v_lshrrev_b32_e32 v36, 31, v35
	v_ashrrev_i32_e32 v35, 11, v35
	v_add_u32_e32 v36, v35, v36
	v_mad_i32_i24 v37, v36, s81, v34
	v_cmp_lt_i32_e64 s[0:1], 15, v37
	s_and_saveexec_b64 s[10:11], s[0:1]
	s_xor_b64 s[0:1], exec, s[10:11]
	v_lshlrev_b32_e32 v34, 12, v36
	v_add3_u32 v34, v34, v37, -16
	v_ashrrev_i32_e32 v35, 31, v34
	v_lshlrev_b64 v[34:35], 12, v[34:35]
	v_lshl_add_u64 v[34:35], s[88:89], 0, v[34:35]
	s_andn2_saveexec_b64 s[0:1], s[0:1]
	v_lshlrev_b32_e32 v34, 14, v36
	v_lshl_add_u32 v34, v37, 10, v34
	v_ashrrev_i32_e32 v35, 31, v34
	v_lshl_add_u64 v[34:35], v[34:35], 2, s[16:17]
	s_or_b64 exec, exec, s[0:1]
	v_lshl_add_u64 v[34:35], v[130:131], 2, v[34:35]
	global_load_dword v36, v[34:35], off
	global_load_dword v37, v[34:35], off offset:128
	v_or_b32_e32 v121, 0x61, v134
	v_min_i32_e32 v34, 0x403f, v121
	v_mul_hi_i32 v35, v34, s80
	v_lshrrev_b32_e32 v38, 31, v35
	v_ashrrev_i32_e32 v35, 11, v35
	v_add_u32_e32 v38, v35, v38
	v_mad_i32_i24 v39, v38, s81, v34
	v_cmp_lt_i32_e64 s[0:1], 15, v39
	s_and_saveexec_b64 s[10:11], s[0:1]
	s_xor_b64 s[0:1], exec, s[10:11]
	v_lshlrev_b32_e32 v34, 12, v38
	v_add3_u32 v34, v34, v39, -16
	v_ashrrev_i32_e32 v35, 31, v34
	v_lshlrev_b64 v[34:35], 12, v[34:35]
	v_lshl_add_u64 v[34:35], s[88:89], 0, v[34:35]
	s_andn2_saveexec_b64 s[0:1], s[0:1]
	v_lshlrev_b32_e32 v34, 14, v38
	v_lshl_add_u32 v34, v39, 10, v34
	v_ashrrev_i32_e32 v35, 31, v34
	v_lshl_add_u64 v[34:35], v[34:35], 2, s[16:17]
	s_or_b64 exec, exec, s[0:1]
	v_lshl_add_u64 v[34:35], v[130:131], 2, v[34:35]
	global_load_dword v38, v[34:35], off
	global_load_dword v39, v[34:35], off offset:128
	v_or_b32_e32 v120, 0x62, v134
	v_min_i32_e32 v34, 0x403f, v120
	v_mul_hi_i32 v35, v34, s80
	v_lshrrev_b32_e32 v40, 31, v35
	v_ashrrev_i32_e32 v35, 11, v35
	v_add_u32_e32 v40, v35, v40
	v_mad_i32_i24 v41, v40, s81, v34
	v_cmp_lt_i32_e64 s[0:1], 15, v41
	s_and_saveexec_b64 s[10:11], s[0:1]
	s_xor_b64 s[0:1], exec, s[10:11]
	v_lshlrev_b32_e32 v34, 12, v40
	v_add3_u32 v34, v34, v41, -16
	v_ashrrev_i32_e32 v35, 31, v34
	v_lshlrev_b64 v[34:35], 12, v[34:35]
	v_lshl_add_u64 v[34:35], s[88:89], 0, v[34:35]
	s_andn2_saveexec_b64 s[0:1], s[0:1]
	v_lshlrev_b32_e32 v34, 14, v40
	v_lshl_add_u32 v34, v41, 10, v34
	v_ashrrev_i32_e32 v35, 31, v34
	v_lshl_add_u64 v[34:35], v[34:35], 2, s[16:17]
	s_or_b64 exec, exec, s[0:1]
	v_lshl_add_u64 v[34:35], v[130:131], 2, v[34:35]
	global_load_dword v40, v[34:35], off
	global_load_dword v41, v[34:35], off offset:128
	v_or_b32_e32 v119, 0x63, v134
	v_min_i32_e32 v34, 0x403f, v119
	v_mul_hi_i32 v35, v34, s80
	v_lshrrev_b32_e32 v42, 31, v35
	v_ashrrev_i32_e32 v35, 11, v35
	v_add_u32_e32 v42, v35, v42
	v_mad_i32_i24 v43, v42, s81, v34
	v_cmp_lt_i32_e64 s[0:1], 15, v43
	s_and_saveexec_b64 s[10:11], s[0:1]
	s_xor_b64 s[0:1], exec, s[10:11]
	v_lshlrev_b32_e32 v34, 12, v42
	v_add3_u32 v34, v34, v43, -16
	v_ashrrev_i32_e32 v35, 31, v34
	v_lshlrev_b64 v[34:35], 12, v[34:35]
	v_lshl_add_u64 v[34:35], s[88:89], 0, v[34:35]
	s_andn2_saveexec_b64 s[0:1], s[0:1]
	v_lshlrev_b32_e32 v34, 14, v42
	v_lshl_add_u32 v34, v43, 10, v34
	v_ashrrev_i32_e32 v35, 31, v34
	v_lshl_add_u64 v[34:35], v[34:35], 2, s[16:17]
	s_or_b64 exec, exec, s[0:1]
	v_lshl_add_u64 v[34:35], v[130:131], 2, v[34:35]
	global_load_dword v42, v[34:35], off
	global_load_dword v43, v[34:35], off offset:128
	v_or_b32_e32 v118, 0x68, v134
	v_min_i32_e32 v34, 0x403f, v118
	v_mul_hi_i32 v35, v34, s80
	v_lshrrev_b32_e32 v44, 31, v35
	v_ashrrev_i32_e32 v35, 11, v35
	v_add_u32_e32 v44, v35, v44
	v_mad_i32_i24 v45, v44, s81, v34
	v_cmp_lt_i32_e64 s[0:1], 15, v45
	s_and_saveexec_b64 s[10:11], s[0:1]
	s_xor_b64 s[0:1], exec, s[10:11]
	v_lshlrev_b32_e32 v34, 12, v44
	v_add3_u32 v34, v34, v45, -16
	v_ashrrev_i32_e32 v35, 31, v34
	v_lshlrev_b64 v[34:35], 12, v[34:35]
	v_lshl_add_u64 v[34:35], s[88:89], 0, v[34:35]
	s_andn2_saveexec_b64 s[0:1], s[0:1]
	v_lshlrev_b32_e32 v34, 14, v44
	v_lshl_add_u32 v34, v45, 10, v34
	v_ashrrev_i32_e32 v35, 31, v34
	v_lshl_add_u64 v[34:35], v[34:35], 2, s[16:17]
	s_or_b64 exec, exec, s[0:1]
	v_lshl_add_u64 v[34:35], v[130:131], 2, v[34:35]
	global_load_dword v44, v[34:35], off
	global_load_dword v45, v[34:35], off offset:128
	v_or_b32_e32 v117, 0x69, v134
	v_min_i32_e32 v34, 0x403f, v117
	v_mul_hi_i32 v35, v34, s80
	v_lshrrev_b32_e32 v46, 31, v35
	v_ashrrev_i32_e32 v35, 11, v35
	v_add_u32_e32 v46, v35, v46
	v_mad_i32_i24 v47, v46, s81, v34
	v_cmp_lt_i32_e64 s[0:1], 15, v47
	s_and_saveexec_b64 s[10:11], s[0:1]
	s_xor_b64 s[0:1], exec, s[10:11]
	v_lshlrev_b32_e32 v34, 12, v46
	v_add3_u32 v34, v34, v47, -16
	v_ashrrev_i32_e32 v35, 31, v34
	v_lshlrev_b64 v[34:35], 12, v[34:35]
	v_lshl_add_u64 v[34:35], s[88:89], 0, v[34:35]
	s_andn2_saveexec_b64 s[0:1], s[0:1]
	v_lshlrev_b32_e32 v34, 14, v46
	v_lshl_add_u32 v34, v47, 10, v34
	v_ashrrev_i32_e32 v35, 31, v34
	v_lshl_add_u64 v[34:35], v[34:35], 2, s[16:17]
	s_or_b64 exec, exec, s[0:1]
	v_lshl_add_u64 v[34:35], v[130:131], 2, v[34:35]
	global_load_dword v46, v[34:35], off
	global_load_dword v47, v[34:35], off offset:128
	v_or_b32_e32 v116, 0x6a, v134
	v_min_i32_e32 v34, 0x403f, v116
	v_mul_hi_i32 v35, v34, s80
	v_lshrrev_b32_e32 v48, 31, v35
	v_ashrrev_i32_e32 v35, 11, v35
	v_add_u32_e32 v48, v35, v48
	v_mad_i32_i24 v49, v48, s81, v34
	v_cmp_lt_i32_e64 s[0:1], 15, v49
	s_and_saveexec_b64 s[10:11], s[0:1]
	s_xor_b64 s[0:1], exec, s[10:11]
	v_lshlrev_b32_e32 v34, 12, v48
	v_add3_u32 v34, v34, v49, -16
	v_ashrrev_i32_e32 v35, 31, v34
	v_lshlrev_b64 v[34:35], 12, v[34:35]
	v_lshl_add_u64 v[34:35], s[88:89], 0, v[34:35]
	s_andn2_saveexec_b64 s[0:1], s[0:1]
	v_lshlrev_b32_e32 v34, 14, v48
	v_lshl_add_u32 v34, v49, 10, v34
	v_ashrrev_i32_e32 v35, 31, v34
	v_lshl_add_u64 v[34:35], v[34:35], 2, s[16:17]
	s_or_b64 exec, exec, s[0:1]
	v_lshl_add_u64 v[34:35], v[130:131], 2, v[34:35]
	global_load_dword v48, v[34:35], off
	global_load_dword v49, v[34:35], off offset:128
	v_or_b32_e32 v115, 0x6b, v134
	v_min_i32_e32 v34, 0x403f, v115
	v_mul_hi_i32 v35, v34, s80
	v_lshrrev_b32_e32 v50, 31, v35
	v_ashrrev_i32_e32 v35, 11, v35
	v_add_u32_e32 v50, v35, v50
	v_mad_i32_i24 v51, v50, s81, v34
	v_cmp_lt_i32_e64 s[0:1], 15, v51
	s_and_saveexec_b64 s[10:11], s[0:1]
	s_xor_b64 s[0:1], exec, s[10:11]
	v_lshlrev_b32_e32 v34, 12, v50
	v_add3_u32 v34, v34, v51, -16
	v_ashrrev_i32_e32 v35, 31, v34
	v_lshlrev_b64 v[34:35], 12, v[34:35]
	v_lshl_add_u64 v[34:35], s[88:89], 0, v[34:35]
	s_andn2_saveexec_b64 s[0:1], s[0:1]
	v_lshlrev_b32_e32 v34, 14, v50
	v_lshl_add_u32 v34, v51, 10, v34
	v_ashrrev_i32_e32 v35, 31, v34
	v_lshl_add_u64 v[34:35], v[34:35], 2, s[16:17]
	s_or_b64 exec, exec, s[0:1]
	v_lshl_add_u64 v[34:35], v[130:131], 2, v[34:35]
	global_load_dword v50, v[34:35], off
	global_load_dword v51, v[34:35], off offset:128
	v_or_b32_e32 v114, 0x70, v134
	v_min_i32_e32 v34, 0x403f, v114
	v_mul_hi_i32 v35, v34, s80
	v_lshrrev_b32_e32 v52, 31, v35
	v_ashrrev_i32_e32 v35, 11, v35
	v_add_u32_e32 v52, v35, v52
	v_mad_i32_i24 v53, v52, s81, v34
	v_cmp_lt_i32_e64 s[0:1], 15, v53
	s_and_saveexec_b64 s[10:11], s[0:1]
	s_xor_b64 s[0:1], exec, s[10:11]
	v_lshlrev_b32_e32 v34, 12, v52
	v_add3_u32 v34, v34, v53, -16
	v_ashrrev_i32_e32 v35, 31, v34
	v_lshlrev_b64 v[34:35], 12, v[34:35]
	v_lshl_add_u64 v[34:35], s[88:89], 0, v[34:35]
	s_andn2_saveexec_b64 s[0:1], s[0:1]
	v_lshlrev_b32_e32 v34, 14, v52
	v_lshl_add_u32 v34, v53, 10, v34
	v_ashrrev_i32_e32 v35, 31, v34
	v_lshl_add_u64 v[34:35], v[34:35], 2, s[16:17]
	s_or_b64 exec, exec, s[0:1]
	v_lshl_add_u64 v[34:35], v[130:131], 2, v[34:35]
	global_load_dword v52, v[34:35], off
	global_load_dword v53, v[34:35], off offset:128
	v_or_b32_e32 v113, 0x71, v134
	v_min_i32_e32 v34, 0x403f, v113
	v_mul_hi_i32 v35, v34, s80
	v_lshrrev_b32_e32 v54, 31, v35
	v_ashrrev_i32_e32 v35, 11, v35
	v_add_u32_e32 v54, v35, v54
	v_mad_i32_i24 v55, v54, s81, v34
	v_cmp_lt_i32_e64 s[0:1], 15, v55
	s_and_saveexec_b64 s[10:11], s[0:1]
	s_xor_b64 s[0:1], exec, s[10:11]
	v_lshlrev_b32_e32 v34, 12, v54
	v_add3_u32 v34, v34, v55, -16
	v_ashrrev_i32_e32 v35, 31, v34
	v_lshlrev_b64 v[34:35], 12, v[34:35]
	v_lshl_add_u64 v[34:35], s[88:89], 0, v[34:35]
	s_andn2_saveexec_b64 s[0:1], s[0:1]
	v_lshlrev_b32_e32 v34, 14, v54
	v_lshl_add_u32 v34, v55, 10, v34
	v_ashrrev_i32_e32 v35, 31, v34
	v_lshl_add_u64 v[34:35], v[34:35], 2, s[16:17]
	s_or_b64 exec, exec, s[0:1]
	v_lshl_add_u64 v[34:35], v[130:131], 2, v[34:35]
	global_load_dword v54, v[34:35], off
	global_load_dword v55, v[34:35], off offset:128
	v_or_b32_e32 v112, 0x72, v134
	v_min_i32_e32 v34, 0x403f, v112
	v_mul_hi_i32 v35, v34, s80
	v_lshrrev_b32_e32 v56, 31, v35
	v_ashrrev_i32_e32 v35, 11, v35
	v_add_u32_e32 v56, v35, v56
	v_mad_i32_i24 v57, v56, s81, v34
	v_cmp_lt_i32_e64 s[0:1], 15, v57
	s_and_saveexec_b64 s[10:11], s[0:1]
	s_xor_b64 s[0:1], exec, s[10:11]
	v_lshlrev_b32_e32 v34, 12, v56
	v_add3_u32 v34, v34, v57, -16
	v_ashrrev_i32_e32 v35, 31, v34
	v_lshlrev_b64 v[34:35], 12, v[34:35]
	v_lshl_add_u64 v[34:35], s[88:89], 0, v[34:35]
	s_andn2_saveexec_b64 s[0:1], s[0:1]
	v_lshlrev_b32_e32 v34, 14, v56
	v_lshl_add_u32 v34, v57, 10, v34
	v_ashrrev_i32_e32 v35, 31, v34
	v_lshl_add_u64 v[34:35], v[34:35], 2, s[16:17]
	s_or_b64 exec, exec, s[0:1]
	v_lshl_add_u64 v[34:35], v[130:131], 2, v[34:35]
	global_load_dword v56, v[34:35], off
	global_load_dword v57, v[34:35], off offset:128
	v_or_b32_e32 v111, 0x73, v134
	v_min_i32_e32 v34, 0x403f, v111
	v_mul_hi_i32 v35, v34, s80
	v_lshrrev_b32_e32 v58, 31, v35
	v_ashrrev_i32_e32 v35, 11, v35
	v_add_u32_e32 v58, v35, v58
	v_mad_i32_i24 v59, v58, s81, v34
	v_cmp_lt_i32_e64 s[0:1], 15, v59
	s_and_saveexec_b64 s[10:11], s[0:1]
	s_xor_b64 s[0:1], exec, s[10:11]
	v_lshlrev_b32_e32 v34, 12, v58
	v_add3_u32 v34, v34, v59, -16
	v_ashrrev_i32_e32 v35, 31, v34
	v_lshlrev_b64 v[34:35], 12, v[34:35]
	v_lshl_add_u64 v[34:35], s[88:89], 0, v[34:35]
	s_andn2_saveexec_b64 s[0:1], s[0:1]
	v_lshlrev_b32_e32 v34, 14, v58
	v_lshl_add_u32 v34, v59, 10, v34
	v_ashrrev_i32_e32 v35, 31, v34
	v_lshl_add_u64 v[34:35], v[34:35], 2, s[16:17]
	s_or_b64 exec, exec, s[0:1]
	v_lshl_add_u64 v[34:35], v[130:131], 2, v[34:35]
	global_load_dword v58, v[34:35], off
	global_load_dword v59, v[34:35], off offset:128
	v_or_b32_e32 v110, 0x78, v134
	v_min_i32_e32 v34, 0x403f, v110
	v_mul_hi_i32 v35, v34, s80
	v_lshrrev_b32_e32 v60, 31, v35
	v_ashrrev_i32_e32 v35, 11, v35
	v_add_u32_e32 v60, v35, v60
	v_mad_i32_i24 v61, v60, s81, v34
	v_cmp_lt_i32_e64 s[0:1], 15, v61
	s_and_saveexec_b64 s[10:11], s[0:1]
	s_xor_b64 s[0:1], exec, s[10:11]
	v_lshlrev_b32_e32 v34, 12, v60
	v_add3_u32 v34, v34, v61, -16
	v_ashrrev_i32_e32 v35, 31, v34
	v_lshlrev_b64 v[34:35], 12, v[34:35]
	v_lshl_add_u64 v[34:35], s[88:89], 0, v[34:35]
	s_andn2_saveexec_b64 s[0:1], s[0:1]
	v_lshlrev_b32_e32 v34, 14, v60
	v_lshl_add_u32 v34, v61, 10, v34
	v_ashrrev_i32_e32 v35, 31, v34
	v_lshl_add_u64 v[34:35], v[34:35], 2, s[16:17]
	s_or_b64 exec, exec, s[0:1]
	v_lshl_add_u64 v[34:35], v[130:131], 2, v[34:35]
	global_load_dword v60, v[34:35], off
	global_load_dword v61, v[34:35], off offset:128
	v_or_b32_e32 v109, 0x79, v134
	v_min_i32_e32 v34, 0x403f, v109
	v_mul_hi_i32 v35, v34, s80
	v_lshrrev_b32_e32 v62, 31, v35
	v_ashrrev_i32_e32 v35, 11, v35
	v_add_u32_e32 v62, v35, v62
	v_mad_i32_i24 v63, v62, s81, v34
	v_cmp_lt_i32_e64 s[0:1], 15, v63
	s_and_saveexec_b64 s[10:11], s[0:1]
	s_xor_b64 s[0:1], exec, s[10:11]
	v_lshlrev_b32_e32 v34, 12, v62
	v_add3_u32 v34, v34, v63, -16
	v_ashrrev_i32_e32 v35, 31, v34
	v_lshlrev_b64 v[34:35], 12, v[34:35]
	v_lshl_add_u64 v[34:35], s[88:89], 0, v[34:35]
	s_andn2_saveexec_b64 s[0:1], s[0:1]
	v_lshlrev_b32_e32 v34, 14, v62
	v_lshl_add_u32 v34, v63, 10, v34
	v_ashrrev_i32_e32 v35, 31, v34
	v_lshl_add_u64 v[34:35], v[34:35], 2, s[16:17]
	s_or_b64 exec, exec, s[0:1]
	v_lshl_add_u64 v[34:35], v[130:131], 2, v[34:35]
	global_load_dword v62, v[34:35], off
	global_load_dword v63, v[34:35], off offset:128
	v_or_b32_e32 v108, 0x7a, v134
	v_min_i32_e32 v34, 0x403f, v108
	v_mul_hi_i32 v35, v34, s80
	v_lshrrev_b32_e32 v64, 31, v35
	v_ashrrev_i32_e32 v35, 11, v35
	v_add_u32_e32 v64, v35, v64
	v_mad_i32_i24 v65, v64, s81, v34
	v_cmp_lt_i32_e64 s[0:1], 15, v65
	s_and_saveexec_b64 s[10:11], s[0:1]
	s_xor_b64 s[0:1], exec, s[10:11]
	v_lshlrev_b32_e32 v34, 12, v64
	v_add3_u32 v34, v34, v65, -16
	v_ashrrev_i32_e32 v35, 31, v34
	v_lshlrev_b64 v[34:35], 12, v[34:35]
	v_lshl_add_u64 v[34:35], s[88:89], 0, v[34:35]
	s_andn2_saveexec_b64 s[0:1], s[0:1]
	v_lshlrev_b32_e32 v34, 14, v64
	v_lshl_add_u32 v34, v65, 10, v34
	v_ashrrev_i32_e32 v35, 31, v34
	v_lshl_add_u64 v[34:35], v[34:35], 2, s[16:17]
	s_or_b64 exec, exec, s[0:1]
	v_lshl_add_u64 v[34:35], v[130:131], 2, v[34:35]
	global_load_dword v70, v[34:35], off
	global_load_dword v71, v[34:35], off offset:128
	v_or_b32_e32 v107, 0x7b, v134
	v_min_i32_e32 v34, 0x403f, v107
	v_mul_hi_i32 v35, v34, s80
	v_lshrrev_b32_e32 v64, 31, v35
	v_ashrrev_i32_e32 v35, 11, v35
	v_add_u32_e32 v64, v35, v64
	v_mad_i32_i24 v65, v64, s81, v34
	v_cmp_lt_i32_e64 s[0:1], 15, v65
	s_and_saveexec_b64 s[10:11], s[0:1]
	s_xor_b64 s[0:1], exec, s[10:11]
	v_lshlrev_b32_e32 v34, 12, v64
	v_add3_u32 v34, v34, v65, -16
	v_ashrrev_i32_e32 v35, 31, v34
	v_lshlrev_b64 v[34:35], 12, v[34:35]
	v_lshl_add_u64 v[34:35], s[88:89], 0, v[34:35]
	s_andn2_saveexec_b64 s[0:1], s[0:1]
	v_lshlrev_b32_e32 v34, 14, v64
	v_lshl_add_u32 v34, v65, 10, v34
	v_ashrrev_i32_e32 v35, 31, v34
	v_lshl_add_u64 v[34:35], v[34:35], 2, s[16:17]
	s_or_b64 exec, exec, s[0:1]
	v_lshl_add_u64 v[34:35], v[130:131], 2, v[34:35]
	global_load_dword v64, v[34:35], off
	global_load_dword v65, v[34:35], off offset:128
	v_cmp_gt_i32_e64 s[10:11], s82, v122
	s_nop 1
	v_cndmask_b32_e64 v34, v179, v122, s[10:11]
	v_mul_hi_i32 v35, v34, s80
	v_lshrrev_b32_e32 v122, 31, v35
	v_ashrrev_i32_e32 v35, 11, v35
	v_add_u32_e32 v122, v35, v122
	v_mad_i32_i24 v123, v122, s81, v34
	v_cmp_lt_i32_e64 s[0:1], 15, v123
	s_and_saveexec_b64 s[54:55], s[0:1]
	s_xor_b64 s[0:1], exec, s[54:55]
	v_lshlrev_b32_e32 v34, 12, v122
	v_add3_u32 v34, v34, v123, -16
	v_ashrrev_i32_e32 v35, 31, v34
	v_lshlrev_b64 v[34:35], 12, v[34:35]
	v_lshl_add_u64 v[34:35], s[88:89], 0, v[34:35]
	s_andn2_saveexec_b64 s[0:1], s[0:1]
	v_lshlrev_b32_e32 v34, 14, v122
	v_lshl_add_u32 v34, v123, 10, v34
	v_ashrrev_i32_e32 v35, 31, v34
	v_lshl_add_u64 v[34:35], v[34:35], 2, s[16:17]
	s_or_b64 exec, exec, s[0:1]
	s_waitcnt vmcnt(31)
	v_fmac_f32_e32 v36, 0.5, v18
	v_lshl_add_u64 v[34:35], v[130:131], 2, v[34:35]
	global_store_dword v[34:35], v36, off
.LBB0_5257:
	s_waitcnt vmcnt(30)
	v_fmac_f32_e32 v37, 0.5, v2
	global_store_dword v[34:35], v37, off offset:128
.LBB0_5259:
	v_cmp_gt_i32_e64 s[10:11], s82, v121
	s_nop 1
	v_cndmask_b32_e64 v18, v179, v121, s[10:11]
	v_mul_hi_i32 v2, v18, s80
	v_lshrrev_b32_e32 v34, 31, v2
	v_ashrrev_i32_e32 v2, 11, v2
	v_add_u32_e32 v2, v2, v34
	v_mad_i32_i24 v18, v2, s81, v18
	v_cmp_lt_i32_e64 s[0:1], 15, v18
	s_and_saveexec_b64 s[54:55], s[0:1]
	s_xor_b64 s[0:1], exec, s[54:55]
	v_lshlrev_b32_e32 v2, 12, v2
	v_add3_u32 v34, v2, v18, -16
	v_ashrrev_i32_e32 v35, 31, v34
	v_lshlrev_b64 v[34:35], 12, v[34:35]
	v_lshl_add_u64 v[34:35], s[88:89], 0, v[34:35]
	s_andn2_saveexec_b64 s[0:1], s[0:1]
	v_lshlrev_b32_e32 v2, 14, v2
	v_lshl_add_u32 v34, v18, 10, v2
	v_ashrrev_i32_e32 v35, 31, v34
	v_lshl_add_u64 v[34:35], v[34:35], 2, s[16:17]
	s_or_b64 exec, exec, s[0:1]
	s_waitcnt vmcnt(29)
	v_fmac_f32_e32 v38, 0.5, v19
	v_lshl_add_u64 v[18:19], v[130:131], 2, v[34:35]
	global_store_dword v[18:19], v38, off
.LBB0_5265:
	s_waitcnt vmcnt(28)
	v_fmac_f32_e32 v39, 0.5, v3
	global_store_dword v[18:19], v39, off offset:128
.LBB0_5267:
	v_cmp_gt_i32_e64 s[10:11], s82, v120
	s_nop 1
	v_cndmask_b32_e64 v2, v179, v120, s[10:11]
	v_mul_hi_i32 v3, v2, s80
	v_lshrrev_b32_e32 v18, 31, v3
	v_ashrrev_i32_e32 v3, 11, v3
	v_add_u32_e32 v18, v3, v18
	v_mad_i32_i24 v19, v18, s81, v2
	v_cmp_lt_i32_e64 s[0:1], 15, v19
	s_and_saveexec_b64 s[54:55], s[0:1]
	s_xor_b64 s[0:1], exec, s[54:55]
	v_lshlrev_b32_e32 v2, 12, v18
	v_add3_u32 v2, v2, v19, -16
	v_ashrrev_i32_e32 v3, 31, v2
	v_lshlrev_b64 v[2:3], 12, v[2:3]
	v_lshl_add_u64 v[2:3], s[88:89], 0, v[2:3]
	s_andn2_saveexec_b64 s[0:1], s[0:1]
	v_lshlrev_b32_e32 v2, 14, v18
	v_lshl_add_u32 v2, v19, 10, v2
	v_ashrrev_i32_e32 v3, 31, v2
	v_lshl_add_u64 v[2:3], v[2:3], 2, s[16:17]
	s_or_b64 exec, exec, s[0:1]
	s_waitcnt vmcnt(27)
	v_fmac_f32_e32 v40, 0.5, v20
	v_lshl_add_u64 v[2:3], v[130:131], 2, v[2:3]
	global_store_dword v[2:3], v40, off
.LBB0_5273:
	s_waitcnt vmcnt(26)
	v_fmac_f32_e32 v41, 0.5, v4
	global_store_dword v[2:3], v41, off offset:128
.LBB0_5275:
	v_cmp_gt_i32_e64 s[10:11], s82, v119
	s_nop 1
	v_cndmask_b32_e64 v2, v179, v119, s[10:11]
	v_mul_hi_i32 v3, v2, s80
	v_lshrrev_b32_e32 v4, 31, v3
	v_ashrrev_i32_e32 v3, 11, v3
	v_add_u32_e32 v4, v3, v4
	v_mad_i32_i24 v18, v4, s81, v2
	v_cmp_lt_i32_e64 s[0:1], 15, v18
	s_and_saveexec_b64 s[54:55], s[0:1]
	s_xor_b64 s[0:1], exec, s[54:55]
	v_lshlrev_b32_e32 v2, 12, v4
	v_add3_u32 v2, v2, v18, -16
	v_ashrrev_i32_e32 v3, 31, v2
	v_lshlrev_b64 v[2:3], 12, v[2:3]
	v_lshl_add_u64 v[2:3], s[88:89], 0, v[2:3]
	s_andn2_saveexec_b64 s[0:1], s[0:1]
	v_lshlrev_b32_e32 v2, 14, v4
	v_lshl_add_u32 v2, v18, 10, v2
	v_ashrrev_i32_e32 v3, 31, v2
	v_lshl_add_u64 v[2:3], v[2:3], 2, s[16:17]
	s_or_b64 exec, exec, s[0:1]
	s_waitcnt vmcnt(25)
	v_fmac_f32_e32 v42, 0.5, v21
	v_lshl_add_u64 v[2:3], v[130:131], 2, v[2:3]
	global_store_dword v[2:3], v42, off
.LBB0_5281:
	s_waitcnt vmcnt(24)
	v_fmac_f32_e32 v43, 0.5, v5
	global_store_dword v[2:3], v43, off offset:128
.LBB0_5283:
	v_cmp_gt_i32_e64 s[10:11], s82, v118
	s_nop 1
	v_cndmask_b32_e64 v2, v179, v118, s[10:11]
	v_mul_hi_i32 v3, v2, s80
	v_lshrrev_b32_e32 v4, 31, v3
	v_ashrrev_i32_e32 v3, 11, v3
	v_add_u32_e32 v4, v3, v4
	v_mad_i32_i24 v5, v4, s81, v2
	v_cmp_lt_i32_e64 s[0:1], 15, v5
	s_and_saveexec_b64 s[54:55], s[0:1]
	s_xor_b64 s[0:1], exec, s[54:55]
	v_lshlrev_b32_e32 v2, 12, v4
	v_add3_u32 v2, v2, v5, -16
	v_ashrrev_i32_e32 v3, 31, v2
	v_lshlrev_b64 v[2:3], 12, v[2:3]
	v_lshl_add_u64 v[2:3], s[88:89], 0, v[2:3]
	s_andn2_saveexec_b64 s[0:1], s[0:1]
	v_lshlrev_b32_e32 v2, 14, v4
	v_lshl_add_u32 v2, v5, 10, v2
	v_ashrrev_i32_e32 v3, 31, v2
	v_lshl_add_u64 v[2:3], v[2:3], 2, s[16:17]
	s_or_b64 exec, exec, s[0:1]
	s_waitcnt vmcnt(23)
	v_fmac_f32_e32 v44, 0.5, v22
	v_lshl_add_u64 v[2:3], v[130:131], 2, v[2:3]
	global_store_dword v[2:3], v44, off
.LBB0_5289:
	s_waitcnt vmcnt(22)
	v_fmac_f32_e32 v45, 0.5, v6
	global_store_dword v[2:3], v45, off offset:128
.LBB0_5291:
	v_cmp_gt_i32_e64 s[10:11], s82, v117
	s_nop 1
	v_cndmask_b32_e64 v2, v179, v117, s[10:11]
	v_mul_hi_i32 v3, v2, s80
	v_lshrrev_b32_e32 v4, 31, v3
	v_ashrrev_i32_e32 v3, 11, v3
	v_add_u32_e32 v4, v3, v4
	v_mad_i32_i24 v5, v4, s81, v2
	v_cmp_lt_i32_e64 s[0:1], 15, v5
	s_and_saveexec_b64 s[54:55], s[0:1]
	s_xor_b64 s[0:1], exec, s[54:55]
	v_lshlrev_b32_e32 v2, 12, v4
	v_add3_u32 v2, v2, v5, -16
	v_ashrrev_i32_e32 v3, 31, v2
	v_lshlrev_b64 v[2:3], 12, v[2:3]
	v_lshl_add_u64 v[2:3], s[88:89], 0, v[2:3]
	s_andn2_saveexec_b64 s[0:1], s[0:1]
	v_lshlrev_b32_e32 v2, 14, v4
	v_lshl_add_u32 v2, v5, 10, v2
	v_ashrrev_i32_e32 v3, 31, v2
	v_lshl_add_u64 v[2:3], v[2:3], 2, s[16:17]
	s_or_b64 exec, exec, s[0:1]
	s_waitcnt vmcnt(21)
	v_fmac_f32_e32 v46, 0.5, v23
	v_lshl_add_u64 v[2:3], v[130:131], 2, v[2:3]
	global_store_dword v[2:3], v46, off
.LBB0_5297:
	s_waitcnt vmcnt(20)
	v_fmac_f32_e32 v47, 0.5, v7
	global_store_dword v[2:3], v47, off offset:128
.LBB0_5299:
	v_cmp_gt_i32_e64 s[10:11], s82, v116
	s_nop 1
	v_cndmask_b32_e64 v2, v179, v116, s[10:11]
	v_mul_hi_i32 v3, v2, s80
	v_lshrrev_b32_e32 v4, 31, v3
	v_ashrrev_i32_e32 v3, 11, v3
	v_add_u32_e32 v4, v3, v4
	v_mad_i32_i24 v5, v4, s81, v2
	v_cmp_lt_i32_e64 s[0:1], 15, v5
	s_and_saveexec_b64 s[54:55], s[0:1]
	s_xor_b64 s[0:1], exec, s[54:55]
	v_lshlrev_b32_e32 v2, 12, v4
	v_add3_u32 v2, v2, v5, -16
	v_ashrrev_i32_e32 v3, 31, v2
	v_lshlrev_b64 v[2:3], 12, v[2:3]
	v_lshl_add_u64 v[2:3], s[88:89], 0, v[2:3]
	s_andn2_saveexec_b64 s[0:1], s[0:1]
	v_lshlrev_b32_e32 v2, 14, v4
	v_lshl_add_u32 v2, v5, 10, v2
	v_ashrrev_i32_e32 v3, 31, v2
	v_lshl_add_u64 v[2:3], v[2:3], 2, s[16:17]
	s_or_b64 exec, exec, s[0:1]
	s_waitcnt vmcnt(19)
	v_fmac_f32_e32 v48, 0.5, v24
	v_lshl_add_u64 v[2:3], v[130:131], 2, v[2:3]
	global_store_dword v[2:3], v48, off
.LBB0_5305:
	s_waitcnt vmcnt(18)
	v_fmac_f32_e32 v49, 0.5, v8
	global_store_dword v[2:3], v49, off offset:128
.LBB0_5307:
	v_cmp_gt_i32_e64 s[10:11], s82, v115
	s_nop 1
	v_cndmask_b32_e64 v2, v179, v115, s[10:11]
	v_mul_hi_i32 v3, v2, s80
	v_lshrrev_b32_e32 v4, 31, v3
	v_ashrrev_i32_e32 v3, 11, v3
	v_add_u32_e32 v4, v3, v4
	v_mad_i32_i24 v5, v4, s81, v2
	v_cmp_lt_i32_e64 s[0:1], 15, v5
	s_and_saveexec_b64 s[54:55], s[0:1]
	s_xor_b64 s[0:1], exec, s[54:55]
	v_lshlrev_b32_e32 v2, 12, v4
	v_add3_u32 v2, v2, v5, -16
	v_ashrrev_i32_e32 v3, 31, v2
	v_lshlrev_b64 v[2:3], 12, v[2:3]
	v_lshl_add_u64 v[2:3], s[88:89], 0, v[2:3]
	s_andn2_saveexec_b64 s[0:1], s[0:1]
	v_lshlrev_b32_e32 v2, 14, v4
	v_lshl_add_u32 v2, v5, 10, v2
	v_ashrrev_i32_e32 v3, 31, v2
	v_lshl_add_u64 v[2:3], v[2:3], 2, s[16:17]
	s_or_b64 exec, exec, s[0:1]
	s_waitcnt vmcnt(17)
	v_fmac_f32_e32 v50, 0.5, v25
	v_lshl_add_u64 v[2:3], v[130:131], 2, v[2:3]
	global_store_dword v[2:3], v50, off
.LBB0_5313:
	s_waitcnt vmcnt(16)
	v_fmac_f32_e32 v51, 0.5, v9
	global_store_dword v[2:3], v51, off offset:128
.LBB0_5315:
	v_cmp_gt_i32_e64 s[10:11], s82, v114
	s_nop 1
	v_cndmask_b32_e64 v2, v179, v114, s[10:11]
	v_mul_hi_i32 v3, v2, s80
	v_lshrrev_b32_e32 v4, 31, v3
	v_ashrrev_i32_e32 v3, 11, v3
	v_add_u32_e32 v4, v3, v4
	v_mad_i32_i24 v5, v4, s81, v2
	v_cmp_lt_i32_e64 s[0:1], 15, v5
	s_and_saveexec_b64 s[54:55], s[0:1]
	s_xor_b64 s[0:1], exec, s[54:55]
	v_lshlrev_b32_e32 v2, 12, v4
	v_add3_u32 v2, v2, v5, -16
	v_ashrrev_i32_e32 v3, 31, v2
	v_lshlrev_b64 v[2:3], 12, v[2:3]
	v_lshl_add_u64 v[2:3], s[88:89], 0, v[2:3]
	s_andn2_saveexec_b64 s[0:1], s[0:1]
	v_lshlrev_b32_e32 v2, 14, v4
	v_lshl_add_u32 v2, v5, 10, v2
	v_ashrrev_i32_e32 v3, 31, v2
	v_lshl_add_u64 v[2:3], v[2:3], 2, s[16:17]
	s_or_b64 exec, exec, s[0:1]
	s_waitcnt vmcnt(15)
	v_fmac_f32_e32 v52, 0.5, v26
	v_lshl_add_u64 v[2:3], v[130:131], 2, v[2:3]
	global_store_dword v[2:3], v52, off
.LBB0_5321:
	s_waitcnt vmcnt(14)
	v_fmac_f32_e32 v53, 0.5, v10
	global_store_dword v[2:3], v53, off offset:128
.LBB0_5323:
	v_cmp_gt_i32_e64 s[10:11], s82, v113
	s_nop 1
	v_cndmask_b32_e64 v2, v179, v113, s[10:11]
	v_mul_hi_i32 v3, v2, s80
	v_lshrrev_b32_e32 v4, 31, v3
	v_ashrrev_i32_e32 v3, 11, v3
	v_add_u32_e32 v4, v3, v4
	v_mad_i32_i24 v5, v4, s81, v2
	v_cmp_lt_i32_e64 s[0:1], 15, v5
	s_and_saveexec_b64 s[54:55], s[0:1]
	s_xor_b64 s[0:1], exec, s[54:55]
	v_lshlrev_b32_e32 v2, 12, v4
	v_add3_u32 v2, v2, v5, -16
	v_ashrrev_i32_e32 v3, 31, v2
	v_lshlrev_b64 v[2:3], 12, v[2:3]
	v_lshl_add_u64 v[2:3], s[88:89], 0, v[2:3]
	s_andn2_saveexec_b64 s[0:1], s[0:1]
	v_lshlrev_b32_e32 v2, 14, v4
	v_lshl_add_u32 v2, v5, 10, v2
	v_ashrrev_i32_e32 v3, 31, v2
	v_lshl_add_u64 v[2:3], v[2:3], 2, s[16:17]
	s_or_b64 exec, exec, s[0:1]
	s_waitcnt vmcnt(13)
	v_fmac_f32_e32 v54, 0.5, v27
	v_lshl_add_u64 v[2:3], v[130:131], 2, v[2:3]
	global_store_dword v[2:3], v54, off
.LBB0_5329:
	s_waitcnt vmcnt(12)
	v_fmac_f32_e32 v55, 0.5, v11
	global_store_dword v[2:3], v55, off offset:128
.LBB0_5331:
	v_cmp_gt_i32_e64 s[10:11], s82, v112
	s_nop 1
	v_cndmask_b32_e64 v2, v179, v112, s[10:11]
	v_mul_hi_i32 v3, v2, s80
	v_lshrrev_b32_e32 v4, 31, v3
	v_ashrrev_i32_e32 v3, 11, v3
	v_add_u32_e32 v4, v3, v4
	v_mad_i32_i24 v5, v4, s81, v2
	v_cmp_lt_i32_e64 s[0:1], 15, v5
	s_and_saveexec_b64 s[54:55], s[0:1]
	s_xor_b64 s[0:1], exec, s[54:55]
	v_lshlrev_b32_e32 v2, 12, v4
	v_add3_u32 v2, v2, v5, -16
	v_ashrrev_i32_e32 v3, 31, v2
	v_lshlrev_b64 v[2:3], 12, v[2:3]
	v_lshl_add_u64 v[2:3], s[88:89], 0, v[2:3]
	s_andn2_saveexec_b64 s[0:1], s[0:1]
	v_lshlrev_b32_e32 v2, 14, v4
	v_lshl_add_u32 v2, v5, 10, v2
	v_ashrrev_i32_e32 v3, 31, v2
	v_lshl_add_u64 v[2:3], v[2:3], 2, s[16:17]
	s_or_b64 exec, exec, s[0:1]
	s_waitcnt vmcnt(11)
	v_fmac_f32_e32 v56, 0.5, v28
	v_lshl_add_u64 v[2:3], v[130:131], 2, v[2:3]
	global_store_dword v[2:3], v56, off
.LBB0_5337:
	s_waitcnt vmcnt(10)
	v_fmac_f32_e32 v57, 0.5, v12
	global_store_dword v[2:3], v57, off offset:128
.LBB0_5339:
	v_cmp_gt_i32_e64 s[10:11], s82, v111
	s_nop 1
	v_cndmask_b32_e64 v2, v179, v111, s[10:11]
	v_mul_hi_i32 v3, v2, s80
	v_lshrrev_b32_e32 v4, 31, v3
	v_ashrrev_i32_e32 v3, 11, v3
	v_add_u32_e32 v4, v3, v4
	v_mad_i32_i24 v5, v4, s81, v2
	v_cmp_lt_i32_e64 s[0:1], 15, v5
	s_and_saveexec_b64 s[54:55], s[0:1]
	s_xor_b64 s[0:1], exec, s[54:55]
	v_lshlrev_b32_e32 v2, 12, v4
	v_add3_u32 v2, v2, v5, -16
	v_ashrrev_i32_e32 v3, 31, v2
	v_lshlrev_b64 v[2:3], 12, v[2:3]
	v_lshl_add_u64 v[2:3], s[88:89], 0, v[2:3]
	s_andn2_saveexec_b64 s[0:1], s[0:1]
	v_lshlrev_b32_e32 v2, 14, v4
	v_lshl_add_u32 v2, v5, 10, v2
	v_ashrrev_i32_e32 v3, 31, v2
	v_lshl_add_u64 v[2:3], v[2:3], 2, s[16:17]
	s_or_b64 exec, exec, s[0:1]
	s_waitcnt vmcnt(9)
	v_fmac_f32_e32 v58, 0.5, v29
	v_lshl_add_u64 v[2:3], v[130:131], 2, v[2:3]
	global_store_dword v[2:3], v58, off
.LBB0_5345:
	s_waitcnt vmcnt(8)
	v_fmac_f32_e32 v59, 0.5, v13
	global_store_dword v[2:3], v59, off offset:128
.LBB0_5347:
	v_cmp_gt_i32_e64 s[10:11], s82, v110
	s_nop 1
	v_cndmask_b32_e64 v2, v179, v110, s[10:11]
	v_mul_hi_i32 v3, v2, s80
	v_lshrrev_b32_e32 v4, 31, v3
	v_ashrrev_i32_e32 v3, 11, v3
	v_add_u32_e32 v4, v3, v4
	v_mad_i32_i24 v5, v4, s81, v2
	v_cmp_lt_i32_e64 s[0:1], 15, v5
	s_and_saveexec_b64 s[54:55], s[0:1]
	s_xor_b64 s[0:1], exec, s[54:55]
	v_lshlrev_b32_e32 v2, 12, v4
	v_add3_u32 v2, v2, v5, -16
	v_ashrrev_i32_e32 v3, 31, v2
	v_lshlrev_b64 v[2:3], 12, v[2:3]
	v_lshl_add_u64 v[2:3], s[88:89], 0, v[2:3]
	s_andn2_saveexec_b64 s[0:1], s[0:1]
	v_lshlrev_b32_e32 v2, 14, v4
	v_lshl_add_u32 v2, v5, 10, v2
	v_ashrrev_i32_e32 v3, 31, v2
	v_lshl_add_u64 v[2:3], v[2:3], 2, s[16:17]
	s_or_b64 exec, exec, s[0:1]
	s_waitcnt vmcnt(7)
	v_fmac_f32_e32 v60, 0.5, v30
	v_lshl_add_u64 v[2:3], v[130:131], 2, v[2:3]
	global_store_dword v[2:3], v60, off
.LBB0_5353:
	s_waitcnt vmcnt(6)
	v_fmac_f32_e32 v61, 0.5, v14
	global_store_dword v[2:3], v61, off offset:128
.LBB0_5355:
	v_cmp_gt_i32_e64 s[10:11], s82, v109
	s_nop 1
	v_cndmask_b32_e64 v2, v179, v109, s[10:11]
	v_mul_hi_i32 v3, v2, s80
	v_lshrrev_b32_e32 v4, 31, v3
	v_ashrrev_i32_e32 v3, 11, v3
	v_add_u32_e32 v4, v3, v4
	v_mad_i32_i24 v5, v4, s81, v2
	v_cmp_lt_i32_e64 s[0:1], 15, v5
	s_and_saveexec_b64 s[54:55], s[0:1]
	s_xor_b64 s[0:1], exec, s[54:55]
	v_lshlrev_b32_e32 v2, 12, v4
	v_add3_u32 v2, v2, v5, -16
	v_ashrrev_i32_e32 v3, 31, v2
	v_lshlrev_b64 v[2:3], 12, v[2:3]
	v_lshl_add_u64 v[2:3], s[88:89], 0, v[2:3]
	s_andn2_saveexec_b64 s[0:1], s[0:1]
	v_lshlrev_b32_e32 v2, 14, v4
	v_lshl_add_u32 v2, v5, 10, v2
	v_ashrrev_i32_e32 v3, 31, v2
	v_lshl_add_u64 v[2:3], v[2:3], 2, s[16:17]
	s_or_b64 exec, exec, s[0:1]
	s_waitcnt vmcnt(5)
	v_fmac_f32_e32 v62, 0.5, v31
	v_lshl_add_u64 v[2:3], v[130:131], 2, v[2:3]
	global_store_dword v[2:3], v62, off
.LBB0_5361:
	s_waitcnt vmcnt(4)
	v_fmac_f32_e32 v63, 0.5, v15
	global_store_dword v[2:3], v63, off offset:128
.LBB0_5363:
	v_cmp_gt_i32_e64 s[10:11], s82, v108
	s_nop 1
	v_cndmask_b32_e64 v2, v179, v108, s[10:11]
	v_mul_hi_i32 v3, v2, s80
	v_lshrrev_b32_e32 v4, 31, v3
	v_ashrrev_i32_e32 v3, 11, v3
	v_add_u32_e32 v4, v3, v4
	v_mad_i32_i24 v5, v4, s81, v2
	v_cmp_lt_i32_e64 s[0:1], 15, v5
	s_and_saveexec_b64 s[54:55], s[0:1]
	s_xor_b64 s[0:1], exec, s[54:55]
	v_lshlrev_b32_e32 v2, 12, v4
	v_add3_u32 v2, v2, v5, -16
	v_ashrrev_i32_e32 v3, 31, v2
	v_lshlrev_b64 v[2:3], 12, v[2:3]
	v_lshl_add_u64 v[2:3], s[88:89], 0, v[2:3]
	s_andn2_saveexec_b64 s[0:1], s[0:1]
	v_lshlrev_b32_e32 v2, 14, v4
	v_lshl_add_u32 v2, v5, 10, v2
	v_ashrrev_i32_e32 v3, 31, v2
	v_lshl_add_u64 v[2:3], v[2:3], 2, s[16:17]
	s_or_b64 exec, exec, s[0:1]
	s_waitcnt vmcnt(3)
	v_fmac_f32_e32 v70, 0.5, v32
	v_lshl_add_u64 v[2:3], v[130:131], 2, v[2:3]
	global_store_dword v[2:3], v70, off
.LBB0_5369:
	s_waitcnt vmcnt(2)
	v_fmac_f32_e32 v71, 0.5, v16
	global_store_dword v[2:3], v71, off offset:128
.LBB0_5371:
	v_cmp_gt_i32_e64 s[10:11], s82, v107
	s_nop 1
	v_cndmask_b32_e64 v2, v179, v107, s[10:11]
	v_mul_hi_i32 v3, v2, s80
	v_lshrrev_b32_e32 v4, 31, v3
	v_ashrrev_i32_e32 v3, 11, v3
	v_add_u32_e32 v4, v3, v4
	v_mad_i32_i24 v5, v4, s81, v2
	v_cmp_lt_i32_e64 s[0:1], 15, v5
	s_and_saveexec_b64 s[54:55], s[0:1]
	s_xor_b64 s[0:1], exec, s[54:55]
	v_lshlrev_b32_e32 v2, 12, v4
	v_add3_u32 v2, v2, v5, -16
	v_ashrrev_i32_e32 v3, 31, v2
	v_lshlrev_b64 v[2:3], 12, v[2:3]
	v_lshl_add_u64 v[2:3], s[88:89], 0, v[2:3]
	s_andn2_saveexec_b64 s[0:1], s[0:1]
	v_lshlrev_b32_e32 v2, 14, v4
	v_lshl_add_u32 v2, v5, 10, v2
	v_ashrrev_i32_e32 v3, 31, v2
	v_lshl_add_u64 v[2:3], v[2:3], 2, s[16:17]
	s_or_b64 exec, exec, s[0:1]
	s_waitcnt vmcnt(1)
	v_fmac_f32_e32 v64, 0.5, v33
	v_lshl_add_u64 v[2:3], v[130:131], 2, v[2:3]
	global_store_dword v[2:3], v64, off
.LBB0_5377:
	s_waitcnt vmcnt(0)
	v_fmac_f32_e32 v65, 0.5, v17
	s_and_saveexec_b64 s[0:1], s[10:11]
	s_cbranch_execz .LBB0_4547
	global_store_dword v[2:3], v65, off offset:128
	s_branch .LBB0_4547
